# v046 with the per-MMA s_setprio 1/0 flips removed from the GEMM phases (hardware oldest-first arbitration)
# speedup vs baseline: 1.0065x; 1.0038x over previous
; #define PG8_STAGE(bufoff, gbase, voff) do { const char* _gb = (const char*)(gbase); asm volatile("" : "+s"(_gb));     \
;         _Pragma("unroll") for (int _i = 0; _i < 2; ++_i) \
;         __builtin_amdgcn_global_load_lds((const unsigned*)(_gb + (voff)[_i]), (LAS unsigned*)(lds + (bufoff) + ldsw + _i * 8192), 16, 0, 0); } while (0)
; #define PG8_LDA(dst, b, h) do { _Pragma("unroll") for (int m = 0; m < 4; ++m) _Pragma("unroll") for (int k = 0; k < 2; ++k) dst[m][k] = *(const LAS bf16x8*)(lds + PG8_SA(b, h) + aoff + m * 2048 + k * 1024); } while (0)
; #define PG8_LDB(dst, b, h) do { _Pragma("unroll") for (int n = 0; n < 2; ++n) _Pragma("unroll") for (int k = 0; k < 2; ++k) dst[n][k] = *(const LAS bf16x8*)(lds + PG8_SB(b, h) + boff + n * 2048 + k * 1024); } while (0)
; #define PG8_MMA(ai, bj, At, Bt) do { __builtin_amdgcn_s_setprio(1); _Pragma("unroll") for (int m = 0; m < 4; ++m) _Pragma("unroll") for (int n = 0; n < 2; ++n) _Pragma("unroll") for (int k = 0; k < 2; ++k) \
;         acc[ai][bj][m][n] = __builtin_amdgcn_mfma_f32_16x16x32_bf16(Bt[n][k], At[m][k], acc[ai][bj][m][n], 0, 0, 0); __builtin_amdgcn_s_setprio(0); } while (0)
; #define PG8_WAIT_V(n) asm volatile("s_waitcnt vmcnt(" #n ")" ::: "memory")
; template <class Epi>
; __device__ __forceinline__ void gemm_phase(LAS unsigned char* lds, const int wid, const Gemm g, const Epi& E) {
;     ...
;             PG8_LDB(B0, 0, 0); PG8_LDB(B1, 0, 1); PG8_SCHED; PG8_LDA(At, 0, 0); PG8_STAGE(PG8_SA(1, 1), a1 + hstepA, voffA);
;             PG8_WAIT_V(8); PG8_WAIT_L(0); PG8_BAR; PG8_MMA(0, 0, At, B0); PG8_MMA(0, 1, At, B1); PG8_BAR; PG8_SCHED;
;             PG8_LDA(At, 0, 1); PG8_STAGE(PG8_SB(0, 0), b2, voffB); PG8_STAGE(PG8_SB(0, 1), b2 + hstepB, voffB); PG8_STAGE(PG8_SA(0, 0), a2, voffA);
;             PG8_WAIT_V(8); PG8_WAIT_L(0); PG8_BAR; PG8_MMA(1, 0, At, B0); PG8_MMA(1, 1, At, B1); PG8_BAR; PG8_SCHED;
;             PG8_LDB(B0, 1, 0); PG8_LDB(B1, 1, 1); PG8_SCHED; PG8_LDA(At, 1, 0); PG8_STAGE(PG8_SA(0, 1), a2 + hstepA, voffA);
;             PG8_WAIT_V(8); PG8_WAIT_L(0); PG8_BAR; PG8_MMA(0, 0, At, B0); PG8_MMA(0, 1, At, B1); PG8_BAR; PG8_SCHED;
;             PG8_LDA(At, 1, 1); PG8_STAGE(PG8_SB(1, 0), b3, voffB); PG8_STAGE(PG8_SB(1, 1), b3 + hstepB, voffB); PG8_STAGE(PG8_SA(1, 0), a3, voffA);
;             PG8_WAIT_V(8); PG8_WAIT_L(0); PG8_BAR; PG8_MMA(1, 0, At, B0); PG8_MMA(1, 1, At, B1); PG8_BAR; PG8_SCHED;
.LBB0_120:
	ds_read_b128 v[128:131], v167
	ds_read_b128 v[132:135], v167 offset:1024
	ds_read_b128 v[136:139], v167 offset:2048
	ds_read_b128 v[140:143], v167 offset:3072
	ds_read_b128 v[156:159], v168
	ds_read_b128 v[172:175], v168 offset:1024
	ds_read_b128 v[176:179], v168 offset:2048
	ds_read_b128 v[180:183], v168 offset:3072
	s_add_u32 s38, s34, 0xfffc0080
	s_addc_u32 s39, s35, -1
	s_add_u32 s42, s72, 0xffffff80
	s_addc_u32 s43, s73, -1
	s_add_u32 s75, s34, 0xfffc0100
	s_addc_u32 s78, s35, -1
	s_add_i32 s80, s63, s47
	s_add_i32 m0, s31, 0xc000
	s_add_i32 s79, s31, 0xe000
	s_add_i32 s81, s80, 0x2000
	s_cmp_eq_u32 s74, 12
	s_cselect_b32 s41, s5, s39
	s_cselect_b32 s40, s25, s38
	s_cselect_b32 s77, s21, s43
	s_cselect_b32 s76, s67, s42
	s_cselect_b32 s39, s69, s78
	s_cselect_b32 s38, s68, s75
	s_mov_b64 s[42:43], s[34:35]
	ds_read_b128 v[184:187], v169
	ds_read_b128 v[188:191], v169 offset:1024
	ds_read_b128 v[192:195], v169 offset:2048
	ds_read_b128 v[196:199], v169 offset:3072
	ds_read_b128 v[200:203], v169 offset:4096
	ds_read_b128 v[206:209], v169 offset:5120
	ds_read_b128 v[210:213], v169 offset:6144
	ds_read_b128 v[214:217], v169 offset:7168
	s_nop 0
	v_lshl_add_u64 v[160:161], s[42:43], 0, v[144:145]
	global_load_lds_dwordx4 v[160:161], off
	v_lshl_add_u64 v[160:161], s[42:43], 0, v[148:149]
	s_mov_b32 m0, s79
	s_nop 0
	global_load_lds_dwordx4 v[160:161], off
	s_waitcnt vmcnt(8)
	s_waitcnt lgkmcnt(0)
	s_barrier
	s_waitcnt lgkmcnt(0)
	v_mfma_f32_16x16x32_bf16 v[124:127], v[128:131], v[184:187], v[124:127]
	v_mfma_f32_16x16x32_bf16 v[120:123], v[136:139], v[184:187], v[120:123]
	v_mfma_f32_16x16x32_bf16 v[108:111], v[128:131], v[192:195], v[108:111]
	v_mfma_f32_16x16x32_bf16 v[104:107], v[136:139], v[192:195], v[104:107]
	v_mfma_f32_16x16x32_bf16 v[92:95], v[128:131], v[200:203], v[92:95]
	v_mfma_f32_16x16x32_bf16 v[88:91], v[136:139], v[200:203], v[88:91]
	v_mfma_f32_16x16x32_bf16 v[80:83], v[128:131], v[210:213], v[80:83]
	v_mfma_f32_16x16x32_bf16 v[72:75], v[136:139], v[210:213], v[72:75]
	v_mfma_f32_16x16x32_bf16 v[124:127], v[132:135], v[188:191], v[124:127]
	v_mfma_f32_16x16x32_bf16 v[120:123], v[140:143], v[188:191], v[120:123]
	v_mfma_f32_16x16x32_bf16 v[108:111], v[132:135], v[196:199], v[108:111]
	v_mfma_f32_16x16x32_bf16 v[104:107], v[140:143], v[196:199], v[104:107]
	v_mfma_f32_16x16x32_bf16 v[92:95], v[132:135], v[206:209], v[92:95]
	v_mfma_f32_16x16x32_bf16 v[88:91], v[140:143], v[206:209], v[88:91]
	v_mfma_f32_16x16x32_bf16 v[80:83], v[132:135], v[214:217], v[80:83]
	v_mfma_f32_16x16x32_bf16 v[72:75], v[140:143], v[214:217], v[72:75]
	v_mfma_f32_16x16x32_bf16 v[116:119], v[156:159], v[184:187], v[116:119]
	v_mfma_f32_16x16x32_bf16 v[112:115], v[176:179], v[184:187], v[112:115]
	v_mfma_f32_16x16x32_bf16 v[100:103], v[156:159], v[192:195], v[100:103]
	v_mfma_f32_16x16x32_bf16 v[96:99], v[176:179], v[192:195], v[96:99]
	v_mfma_f32_16x16x32_bf16 v[84:87], v[156:159], v[200:203], v[84:87]
	v_mfma_f32_16x16x32_bf16 v[76:79], v[176:179], v[200:203], v[76:79]
	v_mfma_f32_16x16x32_bf16 v[68:71], v[156:159], v[210:213], v[68:71]
	v_mfma_f32_16x16x32_bf16 v[64:67], v[176:179], v[210:213], v[64:67]
	v_mfma_f32_16x16x32_bf16 v[116:119], v[172:175], v[188:191], v[116:119]
	v_mfma_f32_16x16x32_bf16 v[112:115], v[180:183], v[188:191], v[112:115]
	v_mfma_f32_16x16x32_bf16 v[100:103], v[172:175], v[196:199], v[100:103]
	v_mfma_f32_16x16x32_bf16 v[96:99], v[180:183], v[196:199], v[96:99]
	v_mfma_f32_16x16x32_bf16 v[84:87], v[172:175], v[206:209], v[84:87]
	v_mfma_f32_16x16x32_bf16 v[76:79], v[180:183], v[206:209], v[76:79]
	v_mfma_f32_16x16x32_bf16 v[68:71], v[172:175], v[214:217], v[68:71]
	v_mfma_f32_16x16x32_bf16 v[64:67], v[180:183], v[214:217], v[64:67]
	s_barrier
	s_mov_b64 s[42:43], s[76:77]
	s_mov_b32 m0, s80
	ds_read_b128 v[184:187], v169 offset:16384
	ds_read_b128 v[188:191], v169 offset:17408
	ds_read_b128 v[192:195], v169 offset:18432
	ds_read_b128 v[196:199], v169 offset:19456
	ds_read_b128 v[200:203], v169 offset:20480
	ds_read_b128 v[206:209], v169 offset:21504
	ds_read_b128 v[210:213], v169 offset:22528
	ds_read_b128 v[214:217], v169 offset:23552
	s_nop 0
	v_lshl_add_u64 v[160:161], s[42:43], 0, v[146:147]
	global_load_lds_dwordx4 v[160:161], off
	v_lshl_add_u64 v[160:161], s[42:43], 0, v[150:151]
	s_cselect_b32 s43, s71, s73
	s_cselect_b32 s42, s70, s72
	s_add_u32 s76, s76, 0x40000
	s_mov_b32 m0, s81
	s_addc_u32 s77, s77, 0
	s_add_i32 s75, s64, s47
	global_load_lds_dwordx4 v[160:161], off
	s_mov_b32 m0, s75
	v_lshl_add_u64 v[160:161], s[76:77], 0, v[146:147]
	global_load_lds_dwordx4 v[160:161], off
	v_lshl_add_u64 v[160:161], s[76:77], 0, v[150:151]
	s_add_i32 m0, s75, 0x2000
	s_mov_b64 s[76:77], s[40:41]
	global_load_lds_dwordx4 v[160:161], off
	s_mov_b32 m0, s31
	v_lshl_add_u64 v[160:161], s[76:77], 0, v[144:145]
	global_load_lds_dwordx4 v[160:161], off
	v_lshl_add_u64 v[160:161], s[76:77], 0, v[148:149]
	s_mov_b32 m0, s52
	s_nop 0
	global_load_lds_dwordx4 v[160:161], off
	s_waitcnt vmcnt(8)
	s_waitcnt lgkmcnt(0)
	s_barrier
; #define PG8_STAGE(bufoff, gbase, voff) do { const char* _gb = (const char*)(gbase); asm volatile("" : "+s"(_gb));     \
;         _Pragma("unroll") for (int _i = 0; _i < 2; ++_i) \
;         __builtin_amdgcn_global_load_lds((const unsigned*)(_gb + (voff)[_i]), (LAS unsigned*)(lds + (bufoff) + ldsw + _i * 8192), 16, 0, 0); } while (0)
; #define PG8_LDA(dst, b, h) do { _Pragma("unroll") for (int m = 0; m < 4; ++m) _Pragma("unroll") for (int k = 0; k < 2; ++k) dst[m][k] = *(const LAS bf16x8*)(lds + PG8_SA(b, h) + aoff + m * 2048 + k * 1024); } while (0)
; #define PG8_LDB(dst, b, h) do { _Pragma("unroll") for (int n = 0; n < 2; ++n) _Pragma("unroll") for (int k = 0; k < 2; ++k) dst[n][k] = *(const LAS bf16x8*)(lds + PG8_SB(b, h) + boff + n * 2048 + k * 1024); } while (0)
; #define PG8_MMA(ai, bj, At, Bt) do { __builtin_amdgcn_s_setprio(1); _Pragma("unroll") for (int m = 0; m < 4; ++m) _Pragma("unroll") for (int n = 0; n < 2; ++n) _Pragma("unroll") for (int k = 0; k < 2; ++k) \
;         acc[ai][bj][m][n] = __builtin_amdgcn_mfma_f32_16x16x32_bf16(Bt[n][k], At[m][k], acc[ai][bj][m][n], 0, 0, 0); __builtin_amdgcn_s_setprio(0); } while (0)
; #define PG8_WAIT_V(n) asm volatile("s_waitcnt vmcnt(" #n ")" ::: "memory")
; #define PG8_WAIT_L(n) asm volatile("s_waitcnt lgkmcnt(" #n ")" ::: "memory")
; #define PG8_BAR __builtin_amdgcn_s_barrier()
; #define PG8_SCHED __builtin_amdgcn_sched_barrier(0)
; template <class Epi>
; __device__ __forceinline__ void gemm_phase(LAS unsigned char* lds, const int wid, const Gemm g, const Epi& E) {
;     ...
;             PG8_WAIT_V(8); PG8_WAIT_L(0); PG8_BAR; PG8_MMA(1, 0, At, B0); PG8_MMA(1, 1, At, B1); PG8_BAR; PG8_SCHED;
;             PG8_LDB(B0, 1, 0); PG8_LDB(B1, 1, 1); PG8_SCHED; PG8_LDA(At, 1, 0); PG8_STAGE(PG8_SA(0, 1), a2 + hstepA, voffA);
;             PG8_WAIT_V(8); PG8_WAIT_L(0); PG8_BAR; PG8_MMA(0, 0, At, B0); PG8_MMA(0, 1, At, B1); PG8_BAR; PG8_SCHED;
	s_waitcnt lgkmcnt(0)
	v_mfma_f32_16x16x32_bf16 v[60:63], v[128:131], v[184:187], v[60:63]
	v_mfma_f32_16x16x32_bf16 v[56:59], v[136:139], v[184:187], v[56:59]
	v_mfma_f32_16x16x32_bf16 v[48:51], v[128:131], v[192:195], v[48:51]
	v_mfma_f32_16x16x32_bf16 v[40:43], v[136:139], v[192:195], v[40:43]
	v_mfma_f32_16x16x32_bf16 v[28:31], v[128:131], v[200:203], v[28:31]
	v_mfma_f32_16x16x32_bf16 v[24:27], v[136:139], v[200:203], v[24:27]
	v_mfma_f32_16x16x32_bf16 v[16:19], v[128:131], v[210:213], v[16:19]
	v_mfma_f32_16x16x32_bf16 v[8:11], v[136:139], v[210:213], v[8:11]
	v_mfma_f32_16x16x32_bf16 v[60:63], v[132:135], v[188:191], v[60:63]
	v_mfma_f32_16x16x32_bf16 v[56:59], v[140:143], v[188:191], v[56:59]
	v_mfma_f32_16x16x32_bf16 v[48:51], v[132:135], v[196:199], v[48:51]
	v_mfma_f32_16x16x32_bf16 v[40:43], v[140:143], v[196:199], v[40:43]
	v_mfma_f32_16x16x32_bf16 v[28:31], v[132:135], v[206:209], v[28:31]
	v_mfma_f32_16x16x32_bf16 v[24:27], v[140:143], v[206:209], v[24:27]
	v_mfma_f32_16x16x32_bf16 v[16:19], v[132:135], v[214:217], v[16:19]
	v_mfma_f32_16x16x32_bf16 v[8:11], v[140:143], v[214:217], v[8:11]
	v_mfma_f32_16x16x32_bf16 v[52:55], v[156:159], v[184:187], v[52:55]
	v_mfma_f32_16x16x32_bf16 v[44:47], v[176:179], v[184:187], v[44:47]
	v_mfma_f32_16x16x32_bf16 v[36:39], v[156:159], v[192:195], v[36:39]
	v_mfma_f32_16x16x32_bf16 v[32:35], v[176:179], v[192:195], v[32:35]
	v_mfma_f32_16x16x32_bf16 v[20:23], v[156:159], v[200:203], v[20:23]
	v_mfma_f32_16x16x32_bf16 v[12:15], v[176:179], v[200:203], v[12:15]
	v_mfma_f32_16x16x32_bf16 v[4:7], v[156:159], v[210:213], v[4:7]
	v_mfma_f32_16x16x32_bf16 v[0:3], v[176:179], v[210:213], v[0:3]
	v_mfma_f32_16x16x32_bf16 v[52:55], v[172:175], v[188:191], v[52:55]
	v_mfma_f32_16x16x32_bf16 v[44:47], v[180:183], v[188:191], v[44:47]
	v_mfma_f32_16x16x32_bf16 v[36:39], v[172:175], v[196:199], v[36:39]
	v_mfma_f32_16x16x32_bf16 v[32:35], v[180:183], v[196:199], v[32:35]
	v_mfma_f32_16x16x32_bf16 v[20:23], v[172:175], v[206:209], v[20:23]
	v_mfma_f32_16x16x32_bf16 v[12:15], v[180:183], v[206:209], v[12:15]
	v_mfma_f32_16x16x32_bf16 v[4:7], v[172:175], v[214:217], v[4:7]
	v_mfma_f32_16x16x32_bf16 v[0:3], v[180:183], v[214:217], v[0:3]
	s_barrier
	s_add_i32 s75, 0, 0x18000
	s_add_i32 s76, 0, 0x1c000
	v_add_u32_e32 v140, s75, v166
	v_add_u32_e32 v160, s76, v166
	ds_read_b128 v[128:131], v140
	ds_read_b128 v[132:135], v140 offset:1024
	ds_read_b128 v[136:139], v140 offset:2048
	ds_read_b128 v[140:143], v140 offset:3072
	ds_read_b128 v[156:159], v160
	ds_read_b128 v[172:175], v160 offset:1024
	ds_read_b128 v[176:179], v160 offset:2048
	ds_read_b128 v[180:183], v160 offset:3072
	s_add_u32 s40, s40, 0x40000
	s_addc_u32 s41, s41, 0
	s_mov_b32 m0, s53
	ds_read_b128 v[184:187], v169 offset:32768
	ds_read_b128 v[188:191], v169 offset:33792
	ds_read_b128 v[192:195], v169 offset:34816
	ds_read_b128 v[196:199], v169 offset:35840
	ds_read_b128 v[200:203], v169 offset:36864
	ds_read_b128 v[206:209], v169 offset:37888
	ds_read_b128 v[210:213], v169 offset:38912
	ds_read_b128 v[214:217], v169 offset:39936
	s_nop 0
	v_lshl_add_u64 v[160:161], s[40:41], 0, v[144:145]
	global_load_lds_dwordx4 v[160:161], off
	v_lshl_add_u64 v[160:161], s[40:41], 0, v[148:149]
	s_mov_b32 m0, s54
	s_nop 0
	global_load_lds_dwordx4 v[160:161], off
	s_waitcnt vmcnt(8)
	s_waitcnt lgkmcnt(0)
	s_barrier
	s_waitcnt lgkmcnt(0)
	v_mfma_f32_16x16x32_bf16 v[124:127], v[128:131], v[184:187], v[124:127]
	v_mfma_f32_16x16x32_bf16 v[120:123], v[136:139], v[184:187], v[120:123]
	v_mfma_f32_16x16x32_bf16 v[108:111], v[128:131], v[192:195], v[108:111]
	v_mfma_f32_16x16x32_bf16 v[104:107], v[136:139], v[192:195], v[104:107]
	v_mfma_f32_16x16x32_bf16 v[92:95], v[128:131], v[200:203], v[92:95]
	v_mfma_f32_16x16x32_bf16 v[88:91], v[136:139], v[200:203], v[88:91]
	v_mfma_f32_16x16x32_bf16 v[80:83], v[128:131], v[210:213], v[80:83]
	v_mfma_f32_16x16x32_bf16 v[72:75], v[136:139], v[210:213], v[72:75]
	v_mfma_f32_16x16x32_bf16 v[124:127], v[132:135], v[188:191], v[124:127]
	v_mfma_f32_16x16x32_bf16 v[120:123], v[140:143], v[188:191], v[120:123]
	v_mfma_f32_16x16x32_bf16 v[108:111], v[132:135], v[196:199], v[108:111]
	v_mfma_f32_16x16x32_bf16 v[104:107], v[140:143], v[196:199], v[104:107]
	v_mfma_f32_16x16x32_bf16 v[92:95], v[132:135], v[206:209], v[92:95]
	v_mfma_f32_16x16x32_bf16 v[88:91], v[140:143], v[206:209], v[88:91]
	v_mfma_f32_16x16x32_bf16 v[80:83], v[132:135], v[214:217], v[80:83]
	v_mfma_f32_16x16x32_bf16 v[72:75], v[140:143], v[214:217], v[72:75]
	v_mfma_f32_16x16x32_bf16 v[116:119], v[156:159], v[184:187], v[116:119]
	v_mfma_f32_16x16x32_bf16 v[112:115], v[176:179], v[184:187], v[112:115]
	v_mfma_f32_16x16x32_bf16 v[100:103], v[156:159], v[192:195], v[100:103]
	v_mfma_f32_16x16x32_bf16 v[96:99], v[176:179], v[192:195], v[96:99]
	v_mfma_f32_16x16x32_bf16 v[84:87], v[156:159], v[200:203], v[84:87]
	v_mfma_f32_16x16x32_bf16 v[76:79], v[176:179], v[200:203], v[76:79]
	v_mfma_f32_16x16x32_bf16 v[68:71], v[156:159], v[210:213], v[68:71]
	v_mfma_f32_16x16x32_bf16 v[64:67], v[176:179], v[210:213], v[64:67]
	v_mfma_f32_16x16x32_bf16 v[116:119], v[172:175], v[188:191], v[116:119]
	v_mfma_f32_16x16x32_bf16 v[112:115], v[180:183], v[188:191], v[112:115]
	v_mfma_f32_16x16x32_bf16 v[100:103], v[172:175], v[196:199], v[100:103]
	v_mfma_f32_16x16x32_bf16 v[96:99], v[180:183], v[196:199], v[96:99]
	v_mfma_f32_16x16x32_bf16 v[84:87], v[172:175], v[206:209], v[84:87]
	v_mfma_f32_16x16x32_bf16 v[76:79], v[180:183], v[206:209], v[76:79]
	v_mfma_f32_16x16x32_bf16 v[68:71], v[172:175], v[214:217], v[68:71]
	v_mfma_f32_16x16x32_bf16 v[64:67], v[180:183], v[214:217], v[64:67]
	s_barrier
; #define PG8_STAGE(bufoff, gbase, voff) do { const char* _gb = (const char*)(gbase); asm volatile("" : "+s"(_gb));     \
;         _Pragma("unroll") for (int _i = 0; _i < 2; ++_i) \
;         __builtin_amdgcn_global_load_lds((const unsigned*)(_gb + (voff)[_i]), (LAS unsigned*)(lds + (bufoff) + ldsw + _i * 8192), 16, 0, 0); } while (0)
; #define PG8_LDA(dst, b, h) do { _Pragma("unroll") for (int m = 0; m < 4; ++m) _Pragma("unroll") for (int k = 0; k < 2; ++k) dst[m][k] = *(const LAS bf16x8*)(lds + PG8_SA(b, h) + aoff + m * 2048 + k * 1024); } while (0)
; #define PG8_MMA(ai, bj, At, Bt) do { __builtin_amdgcn_s_setprio(1); _Pragma("unroll") for (int m = 0; m < 4; ++m) _Pragma("unroll") for (int n = 0; n < 2; ++n) _Pragma("unroll") for (int k = 0; k < 2; ++k) \
;         acc[ai][bj][m][n] = __builtin_amdgcn_mfma_f32_16x16x32_bf16(Bt[n][k], At[m][k], acc[ai][bj][m][n], 0, 0, 0); __builtin_amdgcn_s_setprio(0); } while (0)
; #define PG8_WAIT_V(n) asm volatile("s_waitcnt vmcnt(" #n ")" ::: "memory")
; #define PG8_WAIT_L(n) asm volatile("s_waitcnt lgkmcnt(" #n ")" ::: "memory")
; #define PG8_BAR __builtin_amdgcn_s_barrier()
; #define PG8_SCHED __builtin_amdgcn_sched_barrier(0)
; template <class Epi>
; __device__ __forceinline__ void gemm_phase(LAS unsigned char* lds, const int wid, const Gemm g, const Epi& E) {
;     ...
;             PG8_LDA(At, 1, 1); PG8_STAGE(PG8_SB(1, 0), b3, voffB); PG8_STAGE(PG8_SB(1, 1), b3 + hstepB, voffB); PG8_STAGE(PG8_SA(1, 0), a3, voffA);
;             PG8_WAIT_V(8); PG8_WAIT_L(0); PG8_BAR; PG8_MMA(1, 0, At, B0); PG8_MMA(1, 1, At, B1); PG8_BAR; PG8_SCHED;
;         }
	s_mov_b64 s[40:41], s[42:43]
	s_add_i32 s75, s75, s47
	ds_read_b128 v[184:187], v169 offset:49152
	ds_read_b128 v[188:191], v169 offset:50176
	ds_read_b128 v[192:195], v169 offset:51200
	ds_read_b128 v[196:199], v169 offset:52224
	ds_read_b128 v[200:203], v169 offset:53248
	ds_read_b128 v[206:209], v169 offset:54272
	ds_read_b128 v[210:213], v169 offset:55296
	ds_read_b128 v[214:217], v169 offset:56320
	s_mov_b32 m0, s75
	v_lshl_add_u64 v[160:161], s[40:41], 0, v[146:147]
	global_load_lds_dwordx4 v[160:161], off
	s_add_i32 m0, s75, 0x2000
	v_lshl_add_u64 v[160:161], s[40:41], 0, v[150:151]
	s_add_u32 s40, s42, 0x40000
	s_addc_u32 s41, s43, 0
	s_add_i32 s42, s76, s47
	global_load_lds_dwordx4 v[160:161], off
	s_mov_b32 m0, s42
	v_lshl_add_u64 v[160:161], s[40:41], 0, v[146:147]
	global_load_lds_dwordx4 v[160:161], off
	v_lshl_add_u64 v[160:161], s[40:41], 0, v[150:151]
	s_add_i32 m0, s42, 0x2000
	s_nop 0
	global_load_lds_dwordx4 v[160:161], off
	s_mov_b32 m0, s59
	v_lshl_add_u64 v[160:161], s[38:39], 0, v[144:145]
	global_load_lds_dwordx4 v[160:161], off
	v_lshl_add_u64 v[160:161], s[38:39], 0, v[148:149]
	s_mov_b32 m0, s60
	s_nop 0
	global_load_lds_dwordx4 v[160:161], off
	s_waitcnt vmcnt(8)
	s_waitcnt lgkmcnt(0)
	s_barrier
	s_waitcnt lgkmcnt(0)
	v_mfma_f32_16x16x32_bf16 v[60:63], v[128:131], v[184:187], v[60:63]
	v_mfma_f32_16x16x32_bf16 v[56:59], v[136:139], v[184:187], v[56:59]
	v_mfma_f32_16x16x32_bf16 v[48:51], v[128:131], v[192:195], v[48:51]
	v_mfma_f32_16x16x32_bf16 v[40:43], v[136:139], v[192:195], v[40:43]
	v_mfma_f32_16x16x32_bf16 v[28:31], v[128:131], v[200:203], v[28:31]
	v_mfma_f32_16x16x32_bf16 v[24:27], v[136:139], v[200:203], v[24:27]
	v_mfma_f32_16x16x32_bf16 v[16:19], v[128:131], v[210:213], v[16:19]
	v_mfma_f32_16x16x32_bf16 v[8:11], v[136:139], v[210:213], v[8:11]
	v_mfma_f32_16x16x32_bf16 v[60:63], v[132:135], v[188:191], v[60:63]
	v_mfma_f32_16x16x32_bf16 v[56:59], v[140:143], v[188:191], v[56:59]
	v_mfma_f32_16x16x32_bf16 v[48:51], v[132:135], v[196:199], v[48:51]
	v_mfma_f32_16x16x32_bf16 v[40:43], v[140:143], v[196:199], v[40:43]
	v_mfma_f32_16x16x32_bf16 v[28:31], v[132:135], v[206:209], v[28:31]
	v_mfma_f32_16x16x32_bf16 v[24:27], v[140:143], v[206:209], v[24:27]
	v_mfma_f32_16x16x32_bf16 v[16:19], v[132:135], v[214:217], v[16:19]
	v_mfma_f32_16x16x32_bf16 v[8:11], v[140:143], v[214:217], v[8:11]
	v_mfma_f32_16x16x32_bf16 v[52:55], v[156:159], v[184:187], v[52:55]
	v_mfma_f32_16x16x32_bf16 v[44:47], v[176:179], v[184:187], v[44:47]
	v_mfma_f32_16x16x32_bf16 v[36:39], v[156:159], v[192:195], v[36:39]
	v_mfma_f32_16x16x32_bf16 v[32:35], v[176:179], v[192:195], v[32:35]
	v_mfma_f32_16x16x32_bf16 v[20:23], v[156:159], v[200:203], v[20:23]
	v_mfma_f32_16x16x32_bf16 v[12:15], v[176:179], v[200:203], v[12:15]
	v_mfma_f32_16x16x32_bf16 v[4:7], v[156:159], v[210:213], v[4:7]
	v_mfma_f32_16x16x32_bf16 v[0:3], v[176:179], v[210:213], v[0:3]
	v_mfma_f32_16x16x32_bf16 v[52:55], v[172:175], v[188:191], v[52:55]
	v_mfma_f32_16x16x32_bf16 v[44:47], v[180:183], v[188:191], v[44:47]
	v_mfma_f32_16x16x32_bf16 v[36:39], v[172:175], v[196:199], v[36:39]
	v_mfma_f32_16x16x32_bf16 v[32:35], v[180:183], v[196:199], v[32:35]
	v_mfma_f32_16x16x32_bf16 v[20:23], v[172:175], v[206:209], v[20:23]
	v_mfma_f32_16x16x32_bf16 v[12:15], v[180:183], v[206:209], v[12:15]
	v_mfma_f32_16x16x32_bf16 v[4:7], v[172:175], v[214:217], v[4:7]
	v_mfma_f32_16x16x32_bf16 v[0:3], v[180:183], v[214:217], v[0:3]
	s_barrier
	s_add_i32 s74, s74, 2
	s_add_u32 s72, s72, 0x100
	s_addc_u32 s73, s73, 0
	s_add_u32 s34, s34, 0x100
	s_addc_u32 s35, s35, 0
	s_cmp_gt_u32 s74, 13
	s_cbranch_scc0 .LBB0_120
	s_and_b64 vcc, exec, s[10:11]
	s_cbranch_vccz .LBB0_123
	s_barrier

; #define PG8_STAGE(bufoff, gbase, voff) do { const char* _gb = (const char*)(gbase); asm volatile("" : "+s"(_gb));     \
;         _Pragma("unroll") for (int _i = 0; _i < 2; ++_i) \
;         __builtin_amdgcn_global_load_lds((const unsigned*)(_gb + (voff)[_i]), (LAS unsigned*)(lds + (bufoff) + ldsw + _i * 8192), 16, 0, 0); } while (0)
; #define PG8_LDA(dst, b, h) do { _Pragma("unroll") for (int m = 0; m < 4; ++m) _Pragma("unroll") for (int k = 0; k < 2; ++k) dst[m][k] = *(const LAS bf16x8*)(lds + PG8_SA(b, h) + aoff + m * 2048 + k * 1024); } while (0)
; #define PG8_LDB(dst, b, h) do { _Pragma("unroll") for (int n = 0; n < 2; ++n) _Pragma("unroll") for (int k = 0; k < 2; ++k) dst[n][k] = *(const LAS bf16x8*)(lds + PG8_SB(b, h) + boff + n * 2048 + k * 1024); } while (0)
; #define PG8_MMA(ai, bj, At, Bt) do { __builtin_amdgcn_s_setprio(1); _Pragma("unroll") for (int m = 0; m < 4; ++m) _Pragma("unroll") for (int n = 0; n < 2; ++n) _Pragma("unroll") for (int k = 0; k < 2; ++k) \
;         acc[ai][bj][m][n] = __builtin_amdgcn_mfma_f32_16x16x32_bf16(Bt[n][k], At[m][k], acc[ai][bj][m][n], 0, 0, 0); __builtin_amdgcn_s_setprio(0); } while (0)
; #define PG8_WAIT_V(n) asm volatile("s_waitcnt vmcnt(" #n ")" ::: "memory")
; template <class Epi>
; __device__ __forceinline__ void gemm_phase(LAS unsigned char* lds, const int wid, const Gemm g, const Epi& E) {
;     ...
;             PG8_LDB(B0, 0, 0); PG8_LDB(B1, 0, 1); PG8_SCHED; PG8_LDA(At, 0, 0); PG8_STAGE(PG8_SA(1, 1), a1 + hstepA, voffA);
;             PG8_WAIT_V(8); PG8_WAIT_L(0); PG8_BAR; PG8_MMA(0, 0, At, B0); PG8_MMA(0, 1, At, B1); PG8_BAR; PG8_SCHED;
;             PG8_LDA(At, 0, 1); PG8_STAGE(PG8_SB(0, 0), b2, voffB); PG8_STAGE(PG8_SB(0, 1), b2 + hstepB, voffB); PG8_STAGE(PG8_SA(0, 0), a2, voffA);
;             PG8_WAIT_V(8); PG8_WAIT_L(0); PG8_BAR; PG8_MMA(1, 0, At, B0); PG8_MMA(1, 1, At, B1); PG8_BAR; PG8_SCHED;
;             PG8_LDB(B0, 1, 0); PG8_LDB(B1, 1, 1); PG8_SCHED; PG8_LDA(At, 1, 0); PG8_STAGE(PG8_SA(0, 1), a2 + hstepA, voffA);
;             PG8_WAIT_V(8); PG8_WAIT_L(0); PG8_BAR; PG8_MMA(0, 0, At, B0); PG8_MMA(0, 1, At, B1); PG8_BAR; PG8_SCHED;
;             PG8_LDA(At, 1, 1); PG8_STAGE(PG8_SB(1, 0), b3, voffB); PG8_STAGE(PG8_SB(1, 1), b3 + hstepB, voffB); PG8_STAGE(PG8_SA(1, 0), a3, voffA);
;             PG8_WAIT_V(8); PG8_WAIT_L(0); PG8_BAR; PG8_MMA(1, 0, At, B0); PG8_MMA(1, 1, At, B1); PG8_BAR; PG8_SCHED;
.LBB0_349:
	ds_read_b128 v[148:151], v145
	ds_read_b128 v[152:155], v145 offset:1024
	ds_read_b128 v[156:159], v145 offset:2048
	ds_read_b128 v[160:163], v145 offset:3072
	ds_read_b128 v[164:167], v146
	ds_read_b128 v[168:171], v146 offset:1024
	ds_read_b128 v[172:175], v146 offset:2048
	ds_read_b128 v[176:179], v146 offset:3072
	s_add_u32 s40, s38, 0xfffc0080
	s_addc_u32 s41, s39, -1
	s_add_u32 s44, s70, 0xffffff80
	s_addc_u32 s45, s71, -1
	s_add_u32 s73, s38, 0xfffc0100
	s_addc_u32 s76, s39, -1
	s_add_i32 s78, s61, s23
	s_add_i32 m0, s35, 0xc000
	s_add_i32 s77, s35, 0xe000
	s_add_i32 s79, s78, 0x2000
	s_cmp_eq_u32 s72, 12
	s_cselect_b32 s43, s27, s41
	s_cselect_b32 s42, s64, s40
	s_cselect_b32 s75, s25, s45
	s_cselect_b32 s74, s65, s44
	s_cselect_b32 s41, s67, s76
	s_cselect_b32 s40, s66, s73
	s_mov_b64 s[44:45], s[38:39]
	ds_read_b128 v[180:183], v147
	ds_read_b128 v[184:187], v147 offset:1024
	ds_read_b128 v[188:191], v147 offset:2048
	ds_read_b128 v[192:195], v147 offset:3072
	ds_read_b128 v[196:199], v147 offset:4096
	ds_read_b128 v[200:203], v147 offset:5120
	ds_read_b128 v[206:209], v147 offset:6144
	ds_read_b128 v[210:213], v147 offset:7168
	s_nop 0
	v_lshl_add_u64 v[140:141], s[44:45], 0, v[134:135]
	global_load_lds_dwordx4 v[140:141], off
	v_lshl_add_u64 v[140:141], s[44:45], 0, v[130:131]
	s_mov_b32 m0, s77
	s_nop 0
	global_load_lds_dwordx4 v[140:141], off
	s_waitcnt vmcnt(8)
	s_waitcnt lgkmcnt(0)
	s_barrier
	s_waitcnt lgkmcnt(0)
	v_mfma_f32_16x16x32_bf16 v[124:127], v[148:151], v[180:183], v[124:127]
	v_mfma_f32_16x16x32_bf16 v[120:123], v[156:159], v[180:183], v[120:123]
	v_mfma_f32_16x16x32_bf16 v[108:111], v[148:151], v[188:191], v[108:111]
	v_mfma_f32_16x16x32_bf16 v[104:107], v[156:159], v[188:191], v[104:107]
	v_mfma_f32_16x16x32_bf16 v[92:95], v[148:151], v[196:199], v[92:95]
	v_mfma_f32_16x16x32_bf16 v[88:91], v[156:159], v[196:199], v[88:91]
	v_mfma_f32_16x16x32_bf16 v[76:79], v[148:151], v[206:209], v[76:79]
	v_mfma_f32_16x16x32_bf16 v[72:75], v[156:159], v[206:209], v[72:75]
	v_mfma_f32_16x16x32_bf16 v[124:127], v[152:155], v[184:187], v[124:127]
	v_mfma_f32_16x16x32_bf16 v[120:123], v[160:163], v[184:187], v[120:123]
	v_mfma_f32_16x16x32_bf16 v[108:111], v[152:155], v[192:195], v[108:111]
	v_mfma_f32_16x16x32_bf16 v[104:107], v[160:163], v[192:195], v[104:107]
	v_mfma_f32_16x16x32_bf16 v[92:95], v[152:155], v[200:203], v[92:95]
	v_mfma_f32_16x16x32_bf16 v[88:91], v[160:163], v[200:203], v[88:91]
	v_mfma_f32_16x16x32_bf16 v[76:79], v[152:155], v[210:213], v[76:79]
	v_mfma_f32_16x16x32_bf16 v[72:75], v[160:163], v[210:213], v[72:75]
	v_mfma_f32_16x16x32_bf16 v[116:119], v[164:167], v[180:183], v[116:119]
	v_mfma_f32_16x16x32_bf16 v[112:115], v[172:175], v[180:183], v[112:115]
	v_mfma_f32_16x16x32_bf16 v[100:103], v[164:167], v[188:191], v[100:103]
	v_mfma_f32_16x16x32_bf16 v[96:99], v[172:175], v[188:191], v[96:99]
	v_mfma_f32_16x16x32_bf16 v[84:87], v[164:167], v[196:199], v[84:87]
	v_mfma_f32_16x16x32_bf16 v[80:83], v[172:175], v[196:199], v[80:83]
	v_mfma_f32_16x16x32_bf16 v[68:71], v[164:167], v[206:209], v[68:71]
	v_mfma_f32_16x16x32_bf16 v[64:67], v[172:175], v[206:209], v[64:67]
	v_mfma_f32_16x16x32_bf16 v[116:119], v[168:171], v[184:187], v[116:119]
	v_mfma_f32_16x16x32_bf16 v[112:115], v[176:179], v[184:187], v[112:115]
	v_mfma_f32_16x16x32_bf16 v[100:103], v[168:171], v[192:195], v[100:103]
	v_mfma_f32_16x16x32_bf16 v[96:99], v[176:179], v[192:195], v[96:99]
	v_mfma_f32_16x16x32_bf16 v[84:87], v[168:171], v[200:203], v[84:87]
	v_mfma_f32_16x16x32_bf16 v[80:83], v[176:179], v[200:203], v[80:83]
	v_mfma_f32_16x16x32_bf16 v[68:71], v[168:171], v[210:213], v[68:71]
	v_mfma_f32_16x16x32_bf16 v[64:67], v[176:179], v[210:213], v[64:67]
	s_barrier
	s_mov_b64 s[44:45], s[74:75]
	s_mov_b32 m0, s78
	ds_read_b128 v[180:183], v147 offset:16384
	ds_read_b128 v[184:187], v147 offset:17408
	ds_read_b128 v[188:191], v147 offset:18432
	ds_read_b128 v[192:195], v147 offset:19456
	ds_read_b128 v[196:199], v147 offset:20480
	ds_read_b128 v[200:203], v147 offset:21504
	ds_read_b128 v[206:209], v147 offset:22528
	ds_read_b128 v[210:213], v147 offset:23552
	s_nop 0
	v_lshl_add_u64 v[140:141], s[44:45], 0, v[132:133]
	global_load_lds_dwordx4 v[140:141], off
	v_lshl_add_u64 v[140:141], s[44:45], 0, v[128:129]
	s_cselect_b32 s45, s69, s71
	s_cselect_b32 s44, s68, s70
	s_add_u32 s74, s74, 0x40000
	s_mov_b32 m0, s79
	s_addc_u32 s75, s75, 0
	s_add_i32 s73, s62, s23
	global_load_lds_dwordx4 v[140:141], off
	s_mov_b32 m0, s73
	v_lshl_add_u64 v[140:141], s[74:75], 0, v[132:133]
	global_load_lds_dwordx4 v[140:141], off
	v_lshl_add_u64 v[140:141], s[74:75], 0, v[128:129]
	s_add_i32 m0, s73, 0x2000
	s_mov_b64 s[74:75], s[42:43]
	global_load_lds_dwordx4 v[140:141], off
	s_mov_b32 m0, s35
	v_lshl_add_u64 v[140:141], s[74:75], 0, v[134:135]
	global_load_lds_dwordx4 v[140:141], off
	v_lshl_add_u64 v[140:141], s[74:75], 0, v[130:131]
	s_mov_b32 m0, s51
	s_nop 0
	global_load_lds_dwordx4 v[140:141], off
	s_waitcnt vmcnt(8)
	s_waitcnt lgkmcnt(0)
	s_barrier
; #define PG8_STAGE(bufoff, gbase, voff) do { const char* _gb = (const char*)(gbase); asm volatile("" : "+s"(_gb));     \
;         _Pragma("unroll") for (int _i = 0; _i < 2; ++_i) \
;         __builtin_amdgcn_global_load_lds((const unsigned*)(_gb + (voff)[_i]), (LAS unsigned*)(lds + (bufoff) + ldsw + _i * 8192), 16, 0, 0); } while (0)
; #define PG8_LDA(dst, b, h) do { _Pragma("unroll") for (int m = 0; m < 4; ++m) _Pragma("unroll") for (int k = 0; k < 2; ++k) dst[m][k] = *(const LAS bf16x8*)(lds + PG8_SA(b, h) + aoff + m * 2048 + k * 1024); } while (0)
; #define PG8_LDB(dst, b, h) do { _Pragma("unroll") for (int n = 0; n < 2; ++n) _Pragma("unroll") for (int k = 0; k < 2; ++k) dst[n][k] = *(const LAS bf16x8*)(lds + PG8_SB(b, h) + boff + n * 2048 + k * 1024); } while (0)
; #define PG8_MMA(ai, bj, At, Bt) do { __builtin_amdgcn_s_setprio(1); _Pragma("unroll") for (int m = 0; m < 4; ++m) _Pragma("unroll") for (int n = 0; n < 2; ++n) _Pragma("unroll") for (int k = 0; k < 2; ++k) \
;         acc[ai][bj][m][n] = __builtin_amdgcn_mfma_f32_16x16x32_bf16(Bt[n][k], At[m][k], acc[ai][bj][m][n], 0, 0, 0); __builtin_amdgcn_s_setprio(0); } while (0)
; #define PG8_WAIT_V(n) asm volatile("s_waitcnt vmcnt(" #n ")" ::: "memory")
; #define PG8_WAIT_L(n) asm volatile("s_waitcnt lgkmcnt(" #n ")" ::: "memory")
; #define PG8_BAR __builtin_amdgcn_s_barrier()
; #define PG8_SCHED __builtin_amdgcn_sched_barrier(0)
; template <class Epi>
; __device__ __forceinline__ void gemm_phase(LAS unsigned char* lds, const int wid, const Gemm g, const Epi& E) {
;     ...
;             PG8_WAIT_V(8); PG8_WAIT_L(0); PG8_BAR; PG8_MMA(1, 0, At, B0); PG8_MMA(1, 1, At, B1); PG8_BAR; PG8_SCHED;
;             PG8_LDB(B0, 1, 0); PG8_LDB(B1, 1, 1); PG8_SCHED; PG8_LDA(At, 1, 0); PG8_STAGE(PG8_SA(0, 1), a2 + hstepA, voffA);
;             PG8_WAIT_V(8); PG8_WAIT_L(0); PG8_BAR; PG8_MMA(0, 0, At, B0); PG8_MMA(0, 1, At, B1); PG8_BAR; PG8_SCHED;
	s_waitcnt lgkmcnt(0)
	v_mfma_f32_16x16x32_bf16 v[60:63], v[148:151], v[180:183], v[60:63]
	v_mfma_f32_16x16x32_bf16 v[56:59], v[156:159], v[180:183], v[56:59]
	v_mfma_f32_16x16x32_bf16 v[44:47], v[148:151], v[188:191], v[44:47]
	v_mfma_f32_16x16x32_bf16 v[40:43], v[156:159], v[188:191], v[40:43]
	v_mfma_f32_16x16x32_bf16 v[28:31], v[148:151], v[196:199], v[28:31]
	v_mfma_f32_16x16x32_bf16 v[24:27], v[156:159], v[196:199], v[24:27]
	v_mfma_f32_16x16x32_bf16 v[12:15], v[148:151], v[206:209], v[12:15]
	v_mfma_f32_16x16x32_bf16 v[8:11], v[156:159], v[206:209], v[8:11]
	v_mfma_f32_16x16x32_bf16 v[60:63], v[152:155], v[184:187], v[60:63]
	v_mfma_f32_16x16x32_bf16 v[56:59], v[160:163], v[184:187], v[56:59]
	v_mfma_f32_16x16x32_bf16 v[44:47], v[152:155], v[192:195], v[44:47]
	v_mfma_f32_16x16x32_bf16 v[40:43], v[160:163], v[192:195], v[40:43]
	v_mfma_f32_16x16x32_bf16 v[28:31], v[152:155], v[200:203], v[28:31]
	v_mfma_f32_16x16x32_bf16 v[24:27], v[160:163], v[200:203], v[24:27]
	v_mfma_f32_16x16x32_bf16 v[12:15], v[152:155], v[210:213], v[12:15]
	v_mfma_f32_16x16x32_bf16 v[8:11], v[160:163], v[210:213], v[8:11]
	v_mfma_f32_16x16x32_bf16 v[52:55], v[164:167], v[180:183], v[52:55]
	v_mfma_f32_16x16x32_bf16 v[48:51], v[172:175], v[180:183], v[48:51]
	v_mfma_f32_16x16x32_bf16 v[36:39], v[164:167], v[188:191], v[36:39]
	v_mfma_f32_16x16x32_bf16 v[32:35], v[172:175], v[188:191], v[32:35]
	v_mfma_f32_16x16x32_bf16 v[20:23], v[164:167], v[196:199], v[20:23]
	v_mfma_f32_16x16x32_bf16 v[16:19], v[172:175], v[196:199], v[16:19]
	v_mfma_f32_16x16x32_bf16 v[4:7], v[164:167], v[206:209], v[4:7]
	v_mfma_f32_16x16x32_bf16 v[0:3], v[172:175], v[206:209], v[0:3]
	v_mfma_f32_16x16x32_bf16 v[52:55], v[168:171], v[184:187], v[52:55]
	v_mfma_f32_16x16x32_bf16 v[48:51], v[176:179], v[184:187], v[48:51]
	v_mfma_f32_16x16x32_bf16 v[36:39], v[168:171], v[192:195], v[36:39]
	v_mfma_f32_16x16x32_bf16 v[32:35], v[176:179], v[192:195], v[32:35]
	v_mfma_f32_16x16x32_bf16 v[20:23], v[168:171], v[200:203], v[20:23]
	v_mfma_f32_16x16x32_bf16 v[16:19], v[176:179], v[200:203], v[16:19]
	v_mfma_f32_16x16x32_bf16 v[4:7], v[168:171], v[210:213], v[4:7]
	v_mfma_f32_16x16x32_bf16 v[0:3], v[176:179], v[210:213], v[0:3]
	s_barrier
	s_add_i32 s73, 0, 0x18000
	v_add_u32_e32 v140, s73, v144
	s_add_i32 s74, 0, 0x1c000
	ds_read_b128 v[148:151], v140
	ds_read_b128 v[152:155], v140 offset:1024
	ds_read_b128 v[156:159], v140 offset:2048
	ds_read_b128 v[160:163], v140 offset:3072
	v_add_u32_e32 v140, s74, v144
	ds_read_b128 v[164:167], v140
	ds_read_b128 v[168:171], v140 offset:1024
	ds_read_b128 v[172:175], v140 offset:2048
	ds_read_b128 v[176:179], v140 offset:3072
	s_add_u32 s42, s42, 0x40000
	s_addc_u32 s43, s43, 0
	s_mov_b32 m0, s52
	ds_read_b128 v[180:183], v147 offset:32768
	ds_read_b128 v[184:187], v147 offset:33792
	ds_read_b128 v[188:191], v147 offset:34816
	ds_read_b128 v[192:195], v147 offset:35840
	ds_read_b128 v[196:199], v147 offset:36864
	ds_read_b128 v[200:203], v147 offset:37888
	ds_read_b128 v[206:209], v147 offset:38912
	ds_read_b128 v[210:213], v147 offset:39936
	s_nop 0
	v_lshl_add_u64 v[140:141], s[42:43], 0, v[134:135]
	global_load_lds_dwordx4 v[140:141], off
	v_lshl_add_u64 v[140:141], s[42:43], 0, v[130:131]
	s_mov_b32 m0, s53
	s_nop 0
	global_load_lds_dwordx4 v[140:141], off
	s_waitcnt vmcnt(8)
	s_waitcnt lgkmcnt(0)
	s_barrier
	s_waitcnt lgkmcnt(0)
	v_mfma_f32_16x16x32_bf16 v[124:127], v[148:151], v[180:183], v[124:127]
	v_mfma_f32_16x16x32_bf16 v[120:123], v[156:159], v[180:183], v[120:123]
	v_mfma_f32_16x16x32_bf16 v[108:111], v[148:151], v[188:191], v[108:111]
	v_mfma_f32_16x16x32_bf16 v[104:107], v[156:159], v[188:191], v[104:107]
	v_mfma_f32_16x16x32_bf16 v[92:95], v[148:151], v[196:199], v[92:95]
	v_mfma_f32_16x16x32_bf16 v[88:91], v[156:159], v[196:199], v[88:91]
	v_mfma_f32_16x16x32_bf16 v[76:79], v[148:151], v[206:209], v[76:79]
	v_mfma_f32_16x16x32_bf16 v[72:75], v[156:159], v[206:209], v[72:75]
	v_mfma_f32_16x16x32_bf16 v[124:127], v[152:155], v[184:187], v[124:127]
	v_mfma_f32_16x16x32_bf16 v[120:123], v[160:163], v[184:187], v[120:123]
	v_mfma_f32_16x16x32_bf16 v[108:111], v[152:155], v[192:195], v[108:111]
	v_mfma_f32_16x16x32_bf16 v[104:107], v[160:163], v[192:195], v[104:107]
	v_mfma_f32_16x16x32_bf16 v[92:95], v[152:155], v[200:203], v[92:95]
	v_mfma_f32_16x16x32_bf16 v[88:91], v[160:163], v[200:203], v[88:91]
	v_mfma_f32_16x16x32_bf16 v[76:79], v[152:155], v[210:213], v[76:79]
	v_mfma_f32_16x16x32_bf16 v[72:75], v[160:163], v[210:213], v[72:75]
	v_mfma_f32_16x16x32_bf16 v[116:119], v[164:167], v[180:183], v[116:119]
	v_mfma_f32_16x16x32_bf16 v[112:115], v[172:175], v[180:183], v[112:115]
	v_mfma_f32_16x16x32_bf16 v[100:103], v[164:167], v[188:191], v[100:103]
	v_mfma_f32_16x16x32_bf16 v[96:99], v[172:175], v[188:191], v[96:99]
	v_mfma_f32_16x16x32_bf16 v[84:87], v[164:167], v[196:199], v[84:87]
	v_mfma_f32_16x16x32_bf16 v[80:83], v[172:175], v[196:199], v[80:83]
	v_mfma_f32_16x16x32_bf16 v[68:71], v[164:167], v[206:209], v[68:71]
	v_mfma_f32_16x16x32_bf16 v[64:67], v[172:175], v[206:209], v[64:67]
	v_mfma_f32_16x16x32_bf16 v[116:119], v[168:171], v[184:187], v[116:119]
	v_mfma_f32_16x16x32_bf16 v[112:115], v[176:179], v[184:187], v[112:115]
	v_mfma_f32_16x16x32_bf16 v[100:103], v[168:171], v[192:195], v[100:103]
	v_mfma_f32_16x16x32_bf16 v[96:99], v[176:179], v[192:195], v[96:99]
	v_mfma_f32_16x16x32_bf16 v[84:87], v[168:171], v[200:203], v[84:87]
	v_mfma_f32_16x16x32_bf16 v[80:83], v[176:179], v[200:203], v[80:83]
	v_mfma_f32_16x16x32_bf16 v[68:71], v[168:171], v[210:213], v[68:71]
	v_mfma_f32_16x16x32_bf16 v[64:67], v[176:179], v[210:213], v[64:67]
	s_barrier
; #define PG8_STAGE(bufoff, gbase, voff) do { const char* _gb = (const char*)(gbase); asm volatile("" : "+s"(_gb));     \
;         _Pragma("unroll") for (int _i = 0; _i < 2; ++_i) \
;         __builtin_amdgcn_global_load_lds((const unsigned*)(_gb + (voff)[_i]), (LAS unsigned*)(lds + (bufoff) + ldsw + _i * 8192), 16, 0, 0); } while (0)
; #define PG8_LDA(dst, b, h) do { _Pragma("unroll") for (int m = 0; m < 4; ++m) _Pragma("unroll") for (int k = 0; k < 2; ++k) dst[m][k] = *(const LAS bf16x8*)(lds + PG8_SA(b, h) + aoff + m * 2048 + k * 1024); } while (0)
; #define PG8_MMA(ai, bj, At, Bt) do { __builtin_amdgcn_s_setprio(1); _Pragma("unroll") for (int m = 0; m < 4; ++m) _Pragma("unroll") for (int n = 0; n < 2; ++n) _Pragma("unroll") for (int k = 0; k < 2; ++k) \
;         acc[ai][bj][m][n] = __builtin_amdgcn_mfma_f32_16x16x32_bf16(Bt[n][k], At[m][k], acc[ai][bj][m][n], 0, 0, 0); __builtin_amdgcn_s_setprio(0); } while (0)
; #define PG8_WAIT_V(n) asm volatile("s_waitcnt vmcnt(" #n ")" ::: "memory")
; #define PG8_WAIT_L(n) asm volatile("s_waitcnt lgkmcnt(" #n ")" ::: "memory")
; #define PG8_BAR __builtin_amdgcn_s_barrier()
; #define PG8_SCHED __builtin_amdgcn_sched_barrier(0)
; template <class Epi>
; __device__ __forceinline__ void gemm_phase(LAS unsigned char* lds, const int wid, const Gemm g, const Epi& E) {
;     ...
;             PG8_LDA(At, 1, 1); PG8_STAGE(PG8_SB(1, 0), b3, voffB); PG8_STAGE(PG8_SB(1, 1), b3 + hstepB, voffB); PG8_STAGE(PG8_SA(1, 0), a3, voffA);
;             PG8_WAIT_V(8); PG8_WAIT_L(0); PG8_BAR; PG8_MMA(1, 0, At, B0); PG8_MMA(1, 1, At, B1); PG8_BAR; PG8_SCHED;
;         }
	s_mov_b64 s[42:43], s[44:45]
	s_add_i32 s73, s73, s23
	ds_read_b128 v[180:183], v147 offset:49152
	ds_read_b128 v[184:187], v147 offset:50176
	ds_read_b128 v[188:191], v147 offset:51200
	ds_read_b128 v[192:195], v147 offset:52224
	ds_read_b128 v[196:199], v147 offset:53248
	ds_read_b128 v[200:203], v147 offset:54272
	ds_read_b128 v[206:209], v147 offset:55296
	ds_read_b128 v[210:213], v147 offset:56320
	s_mov_b32 m0, s73
	v_lshl_add_u64 v[140:141], s[42:43], 0, v[132:133]
	global_load_lds_dwordx4 v[140:141], off
	s_add_i32 m0, s73, 0x2000
	v_lshl_add_u64 v[140:141], s[42:43], 0, v[128:129]
	s_add_u32 s42, s44, 0x40000
	s_addc_u32 s43, s45, 0
	s_add_i32 s44, s74, s23
	global_load_lds_dwordx4 v[140:141], off
	s_mov_b32 m0, s44
	v_lshl_add_u64 v[140:141], s[42:43], 0, v[132:133]
	global_load_lds_dwordx4 v[140:141], off
	v_lshl_add_u64 v[140:141], s[42:43], 0, v[128:129]
	s_add_i32 m0, s44, 0x2000
	s_nop 0
	global_load_lds_dwordx4 v[140:141], off
	s_mov_b32 m0, s57
	v_lshl_add_u64 v[140:141], s[40:41], 0, v[134:135]
	global_load_lds_dwordx4 v[140:141], off
	v_lshl_add_u64 v[140:141], s[40:41], 0, v[130:131]
	s_mov_b32 m0, s58
	s_nop 0
	global_load_lds_dwordx4 v[140:141], off
	s_waitcnt vmcnt(8)
	s_waitcnt lgkmcnt(0)
	s_barrier
	s_waitcnt lgkmcnt(0)
	v_mfma_f32_16x16x32_bf16 v[60:63], v[148:151], v[180:183], v[60:63]
	v_mfma_f32_16x16x32_bf16 v[56:59], v[156:159], v[180:183], v[56:59]
	v_mfma_f32_16x16x32_bf16 v[44:47], v[148:151], v[188:191], v[44:47]
	v_mfma_f32_16x16x32_bf16 v[40:43], v[156:159], v[188:191], v[40:43]
	v_mfma_f32_16x16x32_bf16 v[28:31], v[148:151], v[196:199], v[28:31]
	v_mfma_f32_16x16x32_bf16 v[24:27], v[156:159], v[196:199], v[24:27]
	v_mfma_f32_16x16x32_bf16 v[12:15], v[148:151], v[206:209], v[12:15]
	v_mfma_f32_16x16x32_bf16 v[8:11], v[156:159], v[206:209], v[8:11]
	v_mfma_f32_16x16x32_bf16 v[60:63], v[152:155], v[184:187], v[60:63]
	v_mfma_f32_16x16x32_bf16 v[56:59], v[160:163], v[184:187], v[56:59]
	v_mfma_f32_16x16x32_bf16 v[44:47], v[152:155], v[192:195], v[44:47]
	v_mfma_f32_16x16x32_bf16 v[40:43], v[160:163], v[192:195], v[40:43]
	v_mfma_f32_16x16x32_bf16 v[28:31], v[152:155], v[200:203], v[28:31]
	v_mfma_f32_16x16x32_bf16 v[24:27], v[160:163], v[200:203], v[24:27]
	v_mfma_f32_16x16x32_bf16 v[12:15], v[152:155], v[210:213], v[12:15]
	v_mfma_f32_16x16x32_bf16 v[8:11], v[160:163], v[210:213], v[8:11]
	v_mfma_f32_16x16x32_bf16 v[52:55], v[164:167], v[180:183], v[52:55]
	v_mfma_f32_16x16x32_bf16 v[48:51], v[172:175], v[180:183], v[48:51]
	v_mfma_f32_16x16x32_bf16 v[36:39], v[164:167], v[188:191], v[36:39]
	v_mfma_f32_16x16x32_bf16 v[32:35], v[172:175], v[188:191], v[32:35]
	v_mfma_f32_16x16x32_bf16 v[20:23], v[164:167], v[196:199], v[20:23]
	v_mfma_f32_16x16x32_bf16 v[16:19], v[172:175], v[196:199], v[16:19]
	v_mfma_f32_16x16x32_bf16 v[4:7], v[164:167], v[206:209], v[4:7]
	v_mfma_f32_16x16x32_bf16 v[0:3], v[172:175], v[206:209], v[0:3]
	v_mfma_f32_16x16x32_bf16 v[52:55], v[168:171], v[184:187], v[52:55]
	v_mfma_f32_16x16x32_bf16 v[48:51], v[176:179], v[184:187], v[48:51]
	v_mfma_f32_16x16x32_bf16 v[36:39], v[168:171], v[192:195], v[36:39]
	v_mfma_f32_16x16x32_bf16 v[32:35], v[176:179], v[192:195], v[32:35]
	v_mfma_f32_16x16x32_bf16 v[20:23], v[168:171], v[200:203], v[20:23]
	v_mfma_f32_16x16x32_bf16 v[16:19], v[176:179], v[200:203], v[16:19]
	v_mfma_f32_16x16x32_bf16 v[4:7], v[168:171], v[210:213], v[4:7]
	v_mfma_f32_16x16x32_bf16 v[0:3], v[176:179], v[210:213], v[0:3]
	s_barrier
	s_add_i32 s72, s72, 2
	s_add_u32 s70, s70, 0x100
	s_addc_u32 s71, s71, 0
	s_add_u32 s38, s38, 0x100
	s_addc_u32 s39, s39, 0
	s_cmp_gt_u32 s72, 13
	s_cbranch_scc0 .LBB0_349
	s_and_b64 vcc, exec, s[10:11]
	s_cbranch_vccz .LBB0_352
	s_barrier

; #define PG8_STAGE(bufoff, gbase, voff) do { const char* _gb = (const char*)(gbase); asm volatile("" : "+s"(_gb));     \
;         _Pragma("unroll") for (int _i = 0; _i < 2; ++_i) \
;         __builtin_amdgcn_global_load_lds((const unsigned*)(_gb + (voff)[_i]), (LAS unsigned*)(lds + (bufoff) + ldsw + _i * 8192), 16, 0, 0); } while (0)
; #define PG8_LDA(dst, b, h) do { _Pragma("unroll") for (int m = 0; m < 4; ++m) _Pragma("unroll") for (int k = 0; k < 2; ++k) dst[m][k] = *(const LAS bf16x8*)(lds + PG8_SA(b, h) + aoff + m * 2048 + k * 1024); } while (0)
; #define PG8_LDB(dst, b, h) do { _Pragma("unroll") for (int n = 0; n < 2; ++n) _Pragma("unroll") for (int k = 0; k < 2; ++k) dst[n][k] = *(const LAS bf16x8*)(lds + PG8_SB(b, h) + boff + n * 2048 + k * 1024); } while (0)
; #define PG8_MMA(ai, bj, At, Bt) do { __builtin_amdgcn_s_setprio(1); _Pragma("unroll") for (int m = 0; m < 4; ++m) _Pragma("unroll") for (int n = 0; n < 2; ++n) _Pragma("unroll") for (int k = 0; k < 2; ++k) \
;         acc[ai][bj][m][n] = __builtin_amdgcn_mfma_f32_16x16x32_bf16(Bt[n][k], At[m][k], acc[ai][bj][m][n], 0, 0, 0); __builtin_amdgcn_s_setprio(0); } while (0)
; #define PG8_WAIT_V(n) asm volatile("s_waitcnt vmcnt(" #n ")" ::: "memory")
; #define PG8_WAIT_L(n) asm volatile("s_waitcnt lgkmcnt(" #n ")" ::: "memory")
; #define PG8_BAR __builtin_amdgcn_s_barrier()
; #define PG8_SCHED __builtin_amdgcn_sched_barrier(0)
; template <class Epi>
; __device__ __forceinline__ void gemm_phase(LAS unsigned char* lds, const int wid, const Gemm g, const Epi& E) {
;     ...
;             PG8_LDB(B0, 0, 0); PG8_LDB(B1, 0, 1); PG8_SCHED; PG8_LDA(At, 0, 0); PG8_STAGE(PG8_SA(1, 1), a1 + hstepA, voffA);
;             PG8_WAIT_V(8); PG8_WAIT_L(0); PG8_BAR; PG8_MMA(0, 0, At, B0); PG8_MMA(0, 1, At, B1); PG8_BAR; PG8_SCHED;
;             PG8_LDA(At, 0, 1); PG8_STAGE(PG8_SB(0, 0), b2, voffB); PG8_STAGE(PG8_SB(0, 1), b2 + hstepB, voffB); PG8_STAGE(PG8_SA(0, 0), a2, voffA);
;             PG8_WAIT_V(8); PG8_WAIT_L(0); PG8_BAR; PG8_MMA(1, 0, At, B0); PG8_MMA(1, 1, At, B1); PG8_BAR; PG8_SCHED;
.LBB0_481:
	ds_read_b128 v[146:149], v143
	ds_read_b128 v[150:153], v143 offset:1024
	ds_read_b128 v[154:157], v143 offset:2048
	ds_read_b128 v[158:161], v143 offset:3072
	ds_read_b128 v[162:165], v144
	ds_read_b128 v[166:169], v144 offset:1024
	ds_read_b128 v[170:173], v144 offset:2048
	ds_read_b128 v[174:177], v144 offset:3072
	s_add_u32 s26, s24, 0xfffc0080
	s_addc_u32 s27, s25, -1
	s_add_u32 s30, s62, 0xffffff80
	s_addc_u32 s31, s63, -1
	s_add_u32 s65, s24, 0xfffc0100
	s_addc_u32 s68, s25, -1
	s_add_i32 s70, s52, s23
	s_add_i32 m0, s21, 0xc000
	s_add_i32 s69, s21, 0xe000
	s_add_i32 s71, s70, 0x2000
	s_cmp_eq_u32 s64, 12
	s_cselect_b32 s29, s15, s27
	s_cselect_b32 s28, s56, s26
	s_cselect_b32 s67, s13, s31
	s_cselect_b32 s66, s57, s30
	s_cselect_b32 s27, s59, s68
	s_cselect_b32 s26, s58, s65
	s_mov_b64 s[30:31], s[24:25]
	ds_read_b128 v[178:181], v145
	ds_read_b128 v[182:185], v145 offset:1024
	ds_read_b128 v[186:189], v145 offset:2048
	ds_read_b128 v[190:193], v145 offset:3072
	ds_read_b128 v[194:197], v145 offset:4096
	ds_read_b128 v[198:201], v145 offset:5120
	ds_read_b128 v[206:209], v145 offset:6144
	ds_read_b128 v[210:213], v145 offset:7168
	s_nop 0
	v_lshl_add_u64 v[202:203], s[30:31], 0, v[134:135]
	global_load_lds_dwordx4 v[202:203], off
	v_lshl_add_u64 v[202:203], s[30:31], 0, v[130:131]
	s_mov_b32 m0, s69
	s_nop 0
	global_load_lds_dwordx4 v[202:203], off
	s_waitcnt vmcnt(8)
	s_waitcnt lgkmcnt(0)
	s_barrier
	s_waitcnt lgkmcnt(0)
	v_mfma_f32_16x16x32_bf16 v[124:127], v[146:149], v[178:181], v[124:127]
	v_mfma_f32_16x16x32_bf16 v[120:123], v[154:157], v[178:181], v[120:123]
	v_mfma_f32_16x16x32_bf16 v[108:111], v[146:149], v[186:189], v[108:111]
	v_mfma_f32_16x16x32_bf16 v[104:107], v[154:157], v[186:189], v[104:107]
	v_mfma_f32_16x16x32_bf16 v[92:95], v[146:149], v[194:197], v[92:95]
	v_mfma_f32_16x16x32_bf16 v[88:91], v[154:157], v[194:197], v[88:91]
	v_mfma_f32_16x16x32_bf16 v[76:79], v[146:149], v[206:209], v[76:79]
	v_mfma_f32_16x16x32_bf16 v[72:75], v[154:157], v[206:209], v[72:75]
	v_mfma_f32_16x16x32_bf16 v[124:127], v[150:153], v[182:185], v[124:127]
	v_mfma_f32_16x16x32_bf16 v[120:123], v[158:161], v[182:185], v[120:123]
	v_mfma_f32_16x16x32_bf16 v[108:111], v[150:153], v[190:193], v[108:111]
	v_mfma_f32_16x16x32_bf16 v[104:107], v[158:161], v[190:193], v[104:107]
	v_mfma_f32_16x16x32_bf16 v[92:95], v[150:153], v[198:201], v[92:95]
	v_mfma_f32_16x16x32_bf16 v[88:91], v[158:161], v[198:201], v[88:91]
	v_mfma_f32_16x16x32_bf16 v[76:79], v[150:153], v[210:213], v[76:79]
	v_mfma_f32_16x16x32_bf16 v[72:75], v[158:161], v[210:213], v[72:75]
	v_mfma_f32_16x16x32_bf16 v[116:119], v[162:165], v[178:181], v[116:119]
	v_mfma_f32_16x16x32_bf16 v[112:115], v[170:173], v[178:181], v[112:115]
	v_mfma_f32_16x16x32_bf16 v[100:103], v[162:165], v[186:189], v[100:103]
	v_mfma_f32_16x16x32_bf16 v[96:99], v[170:173], v[186:189], v[96:99]
	v_mfma_f32_16x16x32_bf16 v[84:87], v[162:165], v[194:197], v[84:87]
	v_mfma_f32_16x16x32_bf16 v[80:83], v[170:173], v[194:197], v[80:83]
	v_mfma_f32_16x16x32_bf16 v[68:71], v[162:165], v[206:209], v[68:71]
	v_mfma_f32_16x16x32_bf16 v[64:67], v[170:173], v[206:209], v[64:67]
	v_mfma_f32_16x16x32_bf16 v[116:119], v[166:169], v[182:185], v[116:119]
	v_mfma_f32_16x16x32_bf16 v[112:115], v[174:177], v[182:185], v[112:115]
	v_mfma_f32_16x16x32_bf16 v[100:103], v[166:169], v[190:193], v[100:103]
	v_mfma_f32_16x16x32_bf16 v[96:99], v[174:177], v[190:193], v[96:99]
	v_mfma_f32_16x16x32_bf16 v[84:87], v[166:169], v[198:201], v[84:87]
	v_mfma_f32_16x16x32_bf16 v[80:83], v[174:177], v[198:201], v[80:83]
	v_mfma_f32_16x16x32_bf16 v[68:71], v[166:169], v[210:213], v[68:71]
	v_mfma_f32_16x16x32_bf16 v[64:67], v[174:177], v[210:213], v[64:67]
	s_barrier
	s_mov_b64 s[30:31], s[66:67]
	s_mov_b32 m0, s70
	ds_read_b128 v[178:181], v145 offset:16384
	ds_read_b128 v[182:185], v145 offset:17408
	ds_read_b128 v[186:189], v145 offset:18432
	ds_read_b128 v[190:193], v145 offset:19456
	ds_read_b128 v[194:197], v145 offset:20480
	ds_read_b128 v[198:201], v145 offset:21504
	ds_read_b128 v[206:209], v145 offset:22528
	ds_read_b128 v[210:213], v145 offset:23552
	s_nop 0
	v_lshl_add_u64 v[202:203], s[30:31], 0, v[132:133]
	global_load_lds_dwordx4 v[202:203], off
	v_lshl_add_u64 v[202:203], s[30:31], 0, v[128:129]
	s_cselect_b32 s31, s61, s63
	s_cselect_b32 s30, s60, s62
	s_add_u32 s66, s66, 0x40000
	s_mov_b32 m0, s71
	s_addc_u32 s67, s67, 0
	s_add_i32 s65, s53, s23
	global_load_lds_dwordx4 v[202:203], off
	s_mov_b32 m0, s65
	v_lshl_add_u64 v[202:203], s[66:67], 0, v[132:133]
	global_load_lds_dwordx4 v[202:203], off
	v_lshl_add_u64 v[202:203], s[66:67], 0, v[128:129]
	s_add_i32 m0, s65, 0x2000
	s_mov_b64 s[66:67], s[28:29]
	global_load_lds_dwordx4 v[202:203], off
	s_mov_b32 m0, s21
	v_lshl_add_u64 v[202:203], s[66:67], 0, v[134:135]
	global_load_lds_dwordx4 v[202:203], off
	v_lshl_add_u64 v[202:203], s[66:67], 0, v[130:131]
	s_mov_b32 m0, s42
	s_nop 0
	global_load_lds_dwordx4 v[202:203], off
	s_waitcnt vmcnt(8)
	s_waitcnt lgkmcnt(0)
	s_barrier
; #define PG8_STAGE(bufoff, gbase, voff) do { const char* _gb = (const char*)(gbase); asm volatile("" : "+s"(_gb));     \
;         _Pragma("unroll") for (int _i = 0; _i < 2; ++_i) \
;         __builtin_amdgcn_global_load_lds((const unsigned*)(_gb + (voff)[_i]), (LAS unsigned*)(lds + (bufoff) + ldsw + _i * 8192), 16, 0, 0); } while (0)
; #define PG8_LDA(dst, b, h) do { _Pragma("unroll") for (int m = 0; m < 4; ++m) _Pragma("unroll") for (int k = 0; k < 2; ++k) dst[m][k] = *(const LAS bf16x8*)(lds + PG8_SA(b, h) + aoff + m * 2048 + k * 1024); } while (0)
; #define PG8_LDB(dst, b, h) do { _Pragma("unroll") for (int n = 0; n < 2; ++n) _Pragma("unroll") for (int k = 0; k < 2; ++k) dst[n][k] = *(const LAS bf16x8*)(lds + PG8_SB(b, h) + boff + n * 2048 + k * 1024); } while (0)
; #define PG8_MMA(ai, bj, At, Bt) do { __builtin_amdgcn_s_setprio(1); _Pragma("unroll") for (int m = 0; m < 4; ++m) _Pragma("unroll") for (int n = 0; n < 2; ++n) _Pragma("unroll") for (int k = 0; k < 2; ++k) \
;         acc[ai][bj][m][n] = __builtin_amdgcn_mfma_f32_16x16x32_bf16(Bt[n][k], At[m][k], acc[ai][bj][m][n], 0, 0, 0); __builtin_amdgcn_s_setprio(0); } while (0)
; #define PG8_WAIT_V(n) asm volatile("s_waitcnt vmcnt(" #n ")" ::: "memory")
; #define PG8_WAIT_L(n) asm volatile("s_waitcnt lgkmcnt(" #n ")" ::: "memory")
; #define PG8_BAR __builtin_amdgcn_s_barrier()
; #define PG8_SCHED __builtin_amdgcn_sched_barrier(0)
; template <class Epi>
; __device__ __forceinline__ void gemm_phase(LAS unsigned char* lds, const int wid, const Gemm g, const Epi& E) {
;     ...
;             PG8_WAIT_V(8); PG8_WAIT_L(0); PG8_BAR; PG8_MMA(1, 0, At, B0); PG8_MMA(1, 1, At, B1); PG8_BAR; PG8_SCHED;
;             PG8_LDB(B0, 1, 0); PG8_LDB(B1, 1, 1); PG8_SCHED; PG8_LDA(At, 1, 0); PG8_STAGE(PG8_SA(0, 1), a2 + hstepA, voffA);
;             PG8_WAIT_V(8); PG8_WAIT_L(0); PG8_BAR; PG8_MMA(0, 0, At, B0); PG8_MMA(0, 1, At, B1); PG8_BAR; PG8_SCHED;
	s_waitcnt lgkmcnt(0)
	v_mfma_f32_16x16x32_bf16 v[60:63], v[146:149], v[178:181], v[60:63]
	v_mfma_f32_16x16x32_bf16 v[56:59], v[154:157], v[178:181], v[56:59]
	v_mfma_f32_16x16x32_bf16 v[44:47], v[146:149], v[186:189], v[44:47]
	v_mfma_f32_16x16x32_bf16 v[40:43], v[154:157], v[186:189], v[40:43]
	v_mfma_f32_16x16x32_bf16 v[28:31], v[146:149], v[194:197], v[28:31]
	v_mfma_f32_16x16x32_bf16 v[24:27], v[154:157], v[194:197], v[24:27]
	v_mfma_f32_16x16x32_bf16 v[12:15], v[146:149], v[206:209], v[12:15]
	v_mfma_f32_16x16x32_bf16 v[8:11], v[154:157], v[206:209], v[8:11]
	v_mfma_f32_16x16x32_bf16 v[60:63], v[150:153], v[182:185], v[60:63]
	v_mfma_f32_16x16x32_bf16 v[56:59], v[158:161], v[182:185], v[56:59]
	v_mfma_f32_16x16x32_bf16 v[44:47], v[150:153], v[190:193], v[44:47]
	v_mfma_f32_16x16x32_bf16 v[40:43], v[158:161], v[190:193], v[40:43]
	v_mfma_f32_16x16x32_bf16 v[28:31], v[150:153], v[198:201], v[28:31]
	v_mfma_f32_16x16x32_bf16 v[24:27], v[158:161], v[198:201], v[24:27]
	v_mfma_f32_16x16x32_bf16 v[12:15], v[150:153], v[210:213], v[12:15]
	v_mfma_f32_16x16x32_bf16 v[8:11], v[158:161], v[210:213], v[8:11]
	v_mfma_f32_16x16x32_bf16 v[52:55], v[162:165], v[178:181], v[52:55]
	v_mfma_f32_16x16x32_bf16 v[48:51], v[170:173], v[178:181], v[48:51]
	v_mfma_f32_16x16x32_bf16 v[36:39], v[162:165], v[186:189], v[36:39]
	v_mfma_f32_16x16x32_bf16 v[32:35], v[170:173], v[186:189], v[32:35]
	v_mfma_f32_16x16x32_bf16 v[20:23], v[162:165], v[194:197], v[20:23]
	v_mfma_f32_16x16x32_bf16 v[16:19], v[170:173], v[194:197], v[16:19]
	v_mfma_f32_16x16x32_bf16 v[4:7], v[162:165], v[206:209], v[4:7]
	v_mfma_f32_16x16x32_bf16 v[0:3], v[170:173], v[206:209], v[0:3]
	v_mfma_f32_16x16x32_bf16 v[52:55], v[166:169], v[182:185], v[52:55]
	v_mfma_f32_16x16x32_bf16 v[48:51], v[174:177], v[182:185], v[48:51]
	v_mfma_f32_16x16x32_bf16 v[36:39], v[166:169], v[190:193], v[36:39]
	v_mfma_f32_16x16x32_bf16 v[32:35], v[174:177], v[190:193], v[32:35]
	v_mfma_f32_16x16x32_bf16 v[20:23], v[166:169], v[198:201], v[20:23]
	v_mfma_f32_16x16x32_bf16 v[16:19], v[174:177], v[198:201], v[16:19]
	v_mfma_f32_16x16x32_bf16 v[4:7], v[166:169], v[210:213], v[4:7]
	v_mfma_f32_16x16x32_bf16 v[0:3], v[174:177], v[210:213], v[0:3]
	s_barrier
	s_add_i32 s65, 0, 0x18000
	s_add_i32 s66, 0, 0x1c000
	v_add_u32_e32 v158, s65, v142
	v_add_u32_e32 v174, s66, v142
	ds_read_b128 v[146:149], v158
	ds_read_b128 v[150:153], v158 offset:1024
	ds_read_b128 v[154:157], v158 offset:2048
	ds_read_b128 v[158:161], v158 offset:3072
	ds_read_b128 v[162:165], v174
	ds_read_b128 v[166:169], v174 offset:1024
	ds_read_b128 v[170:173], v174 offset:2048
	ds_read_b128 v[174:177], v174 offset:3072
	s_add_u32 s28, s28, 0x40000
	s_addc_u32 s29, s29, 0
	s_mov_b32 m0, s43
	ds_read_b128 v[178:181], v145 offset:32768
	ds_read_b128 v[182:185], v145 offset:33792
	ds_read_b128 v[186:189], v145 offset:34816
	ds_read_b128 v[190:193], v145 offset:35840
	ds_read_b128 v[194:197], v145 offset:36864
	ds_read_b128 v[198:201], v145 offset:37888
	ds_read_b128 v[206:209], v145 offset:38912
	ds_read_b128 v[210:213], v145 offset:39936
	s_nop 0
	v_lshl_add_u64 v[202:203], s[28:29], 0, v[134:135]
	global_load_lds_dwordx4 v[202:203], off
	v_lshl_add_u64 v[202:203], s[28:29], 0, v[130:131]
	s_mov_b32 m0, s44
	s_nop 0
	global_load_lds_dwordx4 v[202:203], off
	s_waitcnt vmcnt(8)
	s_waitcnt lgkmcnt(0)
	s_barrier
	s_waitcnt lgkmcnt(0)
	v_mfma_f32_16x16x32_bf16 v[124:127], v[146:149], v[178:181], v[124:127]
	v_mfma_f32_16x16x32_bf16 v[120:123], v[154:157], v[178:181], v[120:123]
	v_mfma_f32_16x16x32_bf16 v[108:111], v[146:149], v[186:189], v[108:111]
	v_mfma_f32_16x16x32_bf16 v[104:107], v[154:157], v[186:189], v[104:107]
	v_mfma_f32_16x16x32_bf16 v[92:95], v[146:149], v[194:197], v[92:95]
	v_mfma_f32_16x16x32_bf16 v[88:91], v[154:157], v[194:197], v[88:91]
	v_mfma_f32_16x16x32_bf16 v[76:79], v[146:149], v[206:209], v[76:79]
	v_mfma_f32_16x16x32_bf16 v[72:75], v[154:157], v[206:209], v[72:75]
	v_mfma_f32_16x16x32_bf16 v[124:127], v[150:153], v[182:185], v[124:127]
	v_mfma_f32_16x16x32_bf16 v[120:123], v[158:161], v[182:185], v[120:123]
	v_mfma_f32_16x16x32_bf16 v[108:111], v[150:153], v[190:193], v[108:111]
	v_mfma_f32_16x16x32_bf16 v[104:107], v[158:161], v[190:193], v[104:107]
	v_mfma_f32_16x16x32_bf16 v[92:95], v[150:153], v[198:201], v[92:95]
	v_mfma_f32_16x16x32_bf16 v[88:91], v[158:161], v[198:201], v[88:91]
	v_mfma_f32_16x16x32_bf16 v[76:79], v[150:153], v[210:213], v[76:79]
	v_mfma_f32_16x16x32_bf16 v[72:75], v[158:161], v[210:213], v[72:75]
	v_mfma_f32_16x16x32_bf16 v[116:119], v[162:165], v[178:181], v[116:119]
	v_mfma_f32_16x16x32_bf16 v[112:115], v[170:173], v[178:181], v[112:115]
	v_mfma_f32_16x16x32_bf16 v[100:103], v[162:165], v[186:189], v[100:103]
	v_mfma_f32_16x16x32_bf16 v[96:99], v[170:173], v[186:189], v[96:99]
	v_mfma_f32_16x16x32_bf16 v[84:87], v[162:165], v[194:197], v[84:87]
	v_mfma_f32_16x16x32_bf16 v[80:83], v[170:173], v[194:197], v[80:83]
	v_mfma_f32_16x16x32_bf16 v[68:71], v[162:165], v[206:209], v[68:71]
	v_mfma_f32_16x16x32_bf16 v[64:67], v[170:173], v[206:209], v[64:67]
	v_mfma_f32_16x16x32_bf16 v[116:119], v[166:169], v[182:185], v[116:119]
	v_mfma_f32_16x16x32_bf16 v[112:115], v[174:177], v[182:185], v[112:115]
	v_mfma_f32_16x16x32_bf16 v[100:103], v[166:169], v[190:193], v[100:103]
	v_mfma_f32_16x16x32_bf16 v[96:99], v[174:177], v[190:193], v[96:99]
	v_mfma_f32_16x16x32_bf16 v[84:87], v[166:169], v[198:201], v[84:87]
	v_mfma_f32_16x16x32_bf16 v[80:83], v[174:177], v[198:201], v[80:83]
	v_mfma_f32_16x16x32_bf16 v[68:71], v[166:169], v[210:213], v[68:71]
	v_mfma_f32_16x16x32_bf16 v[64:67], v[174:177], v[210:213], v[64:67]
	s_barrier
; #define PG8_STAGE(bufoff, gbase, voff) do { const char* _gb = (const char*)(gbase); asm volatile("" : "+s"(_gb));     \
;         _Pragma("unroll") for (int _i = 0; _i < 2; ++_i) \
;         __builtin_amdgcn_global_load_lds((const unsigned*)(_gb + (voff)[_i]), (LAS unsigned*)(lds + (bufoff) + ldsw + _i * 8192), 16, 0, 0); } while (0)
; #define PG8_LDA(dst, b, h) do { _Pragma("unroll") for (int m = 0; m < 4; ++m) _Pragma("unroll") for (int k = 0; k < 2; ++k) dst[m][k] = *(const LAS bf16x8*)(lds + PG8_SA(b, h) + aoff + m * 2048 + k * 1024); } while (0)
; #define PG8_MMA(ai, bj, At, Bt) do { __builtin_amdgcn_s_setprio(1); _Pragma("unroll") for (int m = 0; m < 4; ++m) _Pragma("unroll") for (int n = 0; n < 2; ++n) _Pragma("unroll") for (int k = 0; k < 2; ++k) \
;         acc[ai][bj][m][n] = __builtin_amdgcn_mfma_f32_16x16x32_bf16(Bt[n][k], At[m][k], acc[ai][bj][m][n], 0, 0, 0); __builtin_amdgcn_s_setprio(0); } while (0)
; #define PG8_WAIT_V(n) asm volatile("s_waitcnt vmcnt(" #n ")" ::: "memory")
; #define PG8_WAIT_L(n) asm volatile("s_waitcnt lgkmcnt(" #n ")" ::: "memory")
; #define PG8_BAR __builtin_amdgcn_s_barrier()
; #define PG8_SCHED __builtin_amdgcn_sched_barrier(0)
; template <class Epi>
; __device__ __forceinline__ void gemm_phase(LAS unsigned char* lds, const int wid, const Gemm g, const Epi& E) {
;     ...
;             PG8_LDA(At, 1, 1); PG8_STAGE(PG8_SB(1, 0), b3, voffB); PG8_STAGE(PG8_SB(1, 1), b3 + hstepB, voffB); PG8_STAGE(PG8_SA(1, 0), a3, voffA);
;             PG8_WAIT_V(8); PG8_WAIT_L(0); PG8_BAR; PG8_MMA(1, 0, At, B0); PG8_MMA(1, 1, At, B1); PG8_BAR; PG8_SCHED;
;         }
;         if (wr == 0) PG8_BAR;
	s_mov_b64 s[28:29], s[30:31]
	s_add_i32 s65, s65, s23
	ds_read_b128 v[178:181], v145 offset:49152
	ds_read_b128 v[182:185], v145 offset:50176
	ds_read_b128 v[186:189], v145 offset:51200
	ds_read_b128 v[190:193], v145 offset:52224
	ds_read_b128 v[194:197], v145 offset:53248
	ds_read_b128 v[198:201], v145 offset:54272
	ds_read_b128 v[206:209], v145 offset:55296
	ds_read_b128 v[210:213], v145 offset:56320
	s_mov_b32 m0, s65
	v_lshl_add_u64 v[202:203], s[28:29], 0, v[132:133]
	global_load_lds_dwordx4 v[202:203], off
	s_add_i32 m0, s65, 0x2000
	v_lshl_add_u64 v[202:203], s[28:29], 0, v[128:129]
	s_add_u32 s28, s30, 0x40000
	s_addc_u32 s29, s31, 0
	s_add_i32 s30, s66, s23
	global_load_lds_dwordx4 v[202:203], off
	s_mov_b32 m0, s30
	v_lshl_add_u64 v[202:203], s[28:29], 0, v[132:133]
	global_load_lds_dwordx4 v[202:203], off
	v_lshl_add_u64 v[202:203], s[28:29], 0, v[128:129]
	s_add_i32 m0, s30, 0x2000
	s_nop 0
	global_load_lds_dwordx4 v[202:203], off
	s_mov_b32 m0, s48
	v_lshl_add_u64 v[202:203], s[26:27], 0, v[134:135]
	global_load_lds_dwordx4 v[202:203], off
	v_lshl_add_u64 v[202:203], s[26:27], 0, v[130:131]
	s_mov_b32 m0, s49
	s_nop 0
	global_load_lds_dwordx4 v[202:203], off
	s_waitcnt vmcnt(8)
	s_waitcnt lgkmcnt(0)
	s_barrier
	s_waitcnt lgkmcnt(0)
	v_mfma_f32_16x16x32_bf16 v[60:63], v[146:149], v[178:181], v[60:63]
	v_mfma_f32_16x16x32_bf16 v[56:59], v[154:157], v[178:181], v[56:59]
	v_mfma_f32_16x16x32_bf16 v[44:47], v[146:149], v[186:189], v[44:47]
	v_mfma_f32_16x16x32_bf16 v[40:43], v[154:157], v[186:189], v[40:43]
	v_mfma_f32_16x16x32_bf16 v[28:31], v[146:149], v[194:197], v[28:31]
	v_mfma_f32_16x16x32_bf16 v[24:27], v[154:157], v[194:197], v[24:27]
	v_mfma_f32_16x16x32_bf16 v[12:15], v[146:149], v[206:209], v[12:15]
	v_mfma_f32_16x16x32_bf16 v[8:11], v[154:157], v[206:209], v[8:11]
	v_mfma_f32_16x16x32_bf16 v[60:63], v[150:153], v[182:185], v[60:63]
	v_mfma_f32_16x16x32_bf16 v[56:59], v[158:161], v[182:185], v[56:59]
	v_mfma_f32_16x16x32_bf16 v[44:47], v[150:153], v[190:193], v[44:47]
	v_mfma_f32_16x16x32_bf16 v[40:43], v[158:161], v[190:193], v[40:43]
	v_mfma_f32_16x16x32_bf16 v[28:31], v[150:153], v[198:201], v[28:31]
	v_mfma_f32_16x16x32_bf16 v[24:27], v[158:161], v[198:201], v[24:27]
	v_mfma_f32_16x16x32_bf16 v[12:15], v[150:153], v[210:213], v[12:15]
	v_mfma_f32_16x16x32_bf16 v[8:11], v[158:161], v[210:213], v[8:11]
	v_mfma_f32_16x16x32_bf16 v[52:55], v[162:165], v[178:181], v[52:55]
	v_mfma_f32_16x16x32_bf16 v[48:51], v[170:173], v[178:181], v[48:51]
	v_mfma_f32_16x16x32_bf16 v[36:39], v[162:165], v[186:189], v[36:39]
	v_mfma_f32_16x16x32_bf16 v[32:35], v[170:173], v[186:189], v[32:35]
	v_mfma_f32_16x16x32_bf16 v[20:23], v[162:165], v[194:197], v[20:23]
	v_mfma_f32_16x16x32_bf16 v[16:19], v[170:173], v[194:197], v[16:19]
	v_mfma_f32_16x16x32_bf16 v[4:7], v[162:165], v[206:209], v[4:7]
	v_mfma_f32_16x16x32_bf16 v[0:3], v[170:173], v[206:209], v[0:3]
	v_mfma_f32_16x16x32_bf16 v[52:55], v[166:169], v[182:185], v[52:55]
	v_mfma_f32_16x16x32_bf16 v[48:51], v[174:177], v[182:185], v[48:51]
	v_mfma_f32_16x16x32_bf16 v[36:39], v[166:169], v[190:193], v[36:39]
	v_mfma_f32_16x16x32_bf16 v[32:35], v[174:177], v[190:193], v[32:35]
	v_mfma_f32_16x16x32_bf16 v[20:23], v[166:169], v[198:201], v[20:23]
	v_mfma_f32_16x16x32_bf16 v[16:19], v[174:177], v[198:201], v[16:19]
	v_mfma_f32_16x16x32_bf16 v[4:7], v[166:169], v[210:213], v[4:7]
	v_mfma_f32_16x16x32_bf16 v[0:3], v[174:177], v[210:213], v[0:3]
	s_barrier
	s_add_i32 s64, s64, 2
	s_add_u32 s62, s62, 0x100
	s_addc_u32 s63, s63, 0
	s_add_u32 s24, s24, 0x100
	s_addc_u32 s25, s25, 0
	s_cmp_gt_u32 s64, 13
	s_cbranch_scc0 .LBB0_481
	s_and_b64 vcc, exec, s[8:9]
	s_cbranch_vccz .LBB0_484
	s_barrier

; #define PG8_STAGE(bufoff, gbase, voff) do { const char* _gb = (const char*)(gbase); asm volatile("" : "+s"(_gb));     \
;         _Pragma("unroll") for (int _i = 0; _i < 2; ++_i) \
;         __builtin_amdgcn_global_load_lds((const unsigned*)(_gb + (voff)[_i]), (LAS unsigned*)(lds + (bufoff) + ldsw + _i * 8192), 16, 0, 0); } while (0)
; #define PG8_LDA(dst, b, h) do { _Pragma("unroll") for (int m = 0; m < 4; ++m) _Pragma("unroll") for (int k = 0; k < 2; ++k) dst[m][k] = *(const LAS bf16x8*)(lds + PG8_SA(b, h) + aoff + m * 2048 + k * 1024); } while (0)
; #define PG8_LDB(dst, b, h) do { _Pragma("unroll") for (int n = 0; n < 2; ++n) _Pragma("unroll") for (int k = 0; k < 2; ++k) dst[n][k] = *(const LAS bf16x8*)(lds + PG8_SB(b, h) + boff + n * 2048 + k * 1024); } while (0)
; #define PG8_MMA(ai, bj, At, Bt) do { __builtin_amdgcn_s_setprio(1); _Pragma("unroll") for (int m = 0; m < 4; ++m) _Pragma("unroll") for (int n = 0; n < 2; ++n) _Pragma("unroll") for (int k = 0; k < 2; ++k) \
;         acc[ai][bj][m][n] = __builtin_amdgcn_mfma_f32_16x16x32_bf16(Bt[n][k], At[m][k], acc[ai][bj][m][n], 0, 0, 0); __builtin_amdgcn_s_setprio(0); } while (0)
; #define PG8_WAIT_V(n) asm volatile("s_waitcnt vmcnt(" #n ")" ::: "memory")
; #define PG8_WAIT_L(n) asm volatile("s_waitcnt lgkmcnt(" #n ")" ::: "memory")
; #define PG8_BAR __builtin_amdgcn_s_barrier()
; #define PG8_SCHED __builtin_amdgcn_sched_barrier(0)
; template <class Epi>
; __device__ __forceinline__ void gemm_phase(LAS unsigned char* lds, const int wid, const Gemm g, const Epi& E) {
;     ...
;         for (int t = 0; t < nt; t += 2) {
;             const bool last = (t == nt - 2);
;             const char* a1 = PG8_AP(cA, t + 1);
;             const char* a2 = last ? PG8_AP(nA, 0) : PG8_AP(cA, t + 2); const char* b2 = last ? PG8_BP(nB, 0) : PG8_BP(cB, t + 2);
;             const char* a3 = last ? PG8_AP(nA, 1) : PG8_AP(cA, t + 3); const char* b3 = last ? PG8_BP(nB, 1) : PG8_BP(cB, t + 3);
;             PG8_LDB(B0, 0, 0); PG8_LDB(B1, 0, 1); PG8_SCHED; PG8_LDA(At, 0, 0); PG8_STAGE(PG8_SA(1, 1), a1 + hstepA, voffA);
;             PG8_WAIT_V(8); PG8_WAIT_L(0); PG8_BAR; PG8_MMA(0, 0, At, B0); PG8_MMA(0, 1, At, B1); PG8_BAR; PG8_SCHED;
;             PG8_LDA(At, 0, 1); PG8_STAGE(PG8_SB(0, 0), b2, voffB); PG8_STAGE(PG8_SB(0, 1), b2 + hstepB, voffB); PG8_STAGE(PG8_SA(0, 0), a2, voffA);
.LBB0_555:
	ds_read_b128 v[140:143], v149
	ds_read_b128 v[152:155], v149 offset:1024
	ds_read_b128 v[156:159], v149 offset:2048
	ds_read_b128 v[160:163], v149 offset:3072
	ds_read_b128 v[164:167], v150
	ds_read_b128 v[168:171], v150 offset:1024
	ds_read_b128 v[172:175], v150 offset:2048
	ds_read_b128 v[176:179], v150 offset:3072
	s_add_u32 s30, s28, 0xfff50080
	s_addc_u32 s31, s29, -1
	s_add_u32 s38, s66, 0xffffff80
	s_addc_u32 s39, s67, -1
	s_add_u32 s69, s28, 0xfff50100
	s_addc_u32 s72, s29, -1
	s_add_i32 s74, s56, s23
	s_add_i32 m0, s45, 0xc000
	s_add_i32 s73, s45, 0xe000
	s_add_i32 s75, s74, 0x2000
	s_cmp_eq_u32 s68, 40
	s_cselect_b32 s35, s5, s31
	s_cselect_b32 s34, s4, s30
	s_cselect_b32 s71, s27, s39
	s_cselect_b32 s70, s26, s38
	s_cselect_b32 s31, s63, s72
	s_cselect_b32 s30, s62, s69
	s_mov_b64 s[38:39], s[28:29]
	ds_read_b128 v[180:183], v151
	ds_read_b128 v[184:187], v151 offset:1024
	ds_read_b128 v[188:191], v151 offset:2048
	ds_read_b128 v[192:195], v151 offset:3072
	ds_read_b128 v[196:199], v151 offset:4096
	ds_read_b128 v[200:203], v151 offset:5120
	ds_read_b128 v[206:209], v151 offset:6144
	ds_read_b128 v[210:213], v151 offset:7168
	s_nop 0
	v_lshl_add_u64 v[144:145], s[38:39], 0, v[134:135]
	global_load_lds_dwordx4 v[144:145], off
	v_lshl_add_u64 v[144:145], s[38:39], 0, v[130:131]
	s_mov_b32 m0, s73
	s_nop 0
	global_load_lds_dwordx4 v[144:145], off
	s_waitcnt vmcnt(8)
	s_waitcnt lgkmcnt(0)
	s_barrier
	s_waitcnt lgkmcnt(0)
	v_mfma_f32_16x16x32_bf16 v[124:127], v[140:143], v[180:183], v[124:127]
	v_mfma_f32_16x16x32_bf16 v[120:123], v[156:159], v[180:183], v[120:123]
	v_mfma_f32_16x16x32_bf16 v[108:111], v[140:143], v[188:191], v[108:111]
	v_mfma_f32_16x16x32_bf16 v[104:107], v[156:159], v[188:191], v[104:107]
	v_mfma_f32_16x16x32_bf16 v[92:95], v[140:143], v[196:199], v[92:95]
	v_mfma_f32_16x16x32_bf16 v[88:91], v[156:159], v[196:199], v[88:91]
	v_mfma_f32_16x16x32_bf16 v[76:79], v[140:143], v[206:209], v[76:79]
	v_mfma_f32_16x16x32_bf16 v[72:75], v[156:159], v[206:209], v[72:75]
	v_mfma_f32_16x16x32_bf16 v[124:127], v[152:155], v[184:187], v[124:127]
	v_mfma_f32_16x16x32_bf16 v[120:123], v[160:163], v[184:187], v[120:123]
	v_mfma_f32_16x16x32_bf16 v[108:111], v[152:155], v[192:195], v[108:111]
	v_mfma_f32_16x16x32_bf16 v[104:107], v[160:163], v[192:195], v[104:107]
	v_mfma_f32_16x16x32_bf16 v[92:95], v[152:155], v[200:203], v[92:95]
	v_mfma_f32_16x16x32_bf16 v[88:91], v[160:163], v[200:203], v[88:91]
	v_mfma_f32_16x16x32_bf16 v[76:79], v[152:155], v[210:213], v[76:79]
	v_mfma_f32_16x16x32_bf16 v[72:75], v[160:163], v[210:213], v[72:75]
	v_mfma_f32_16x16x32_bf16 v[116:119], v[164:167], v[180:183], v[116:119]
	v_mfma_f32_16x16x32_bf16 v[112:115], v[172:175], v[180:183], v[112:115]
	v_mfma_f32_16x16x32_bf16 v[100:103], v[164:167], v[188:191], v[100:103]
	v_mfma_f32_16x16x32_bf16 v[96:99], v[172:175], v[188:191], v[96:99]
	v_mfma_f32_16x16x32_bf16 v[84:87], v[164:167], v[196:199], v[84:87]
	v_mfma_f32_16x16x32_bf16 v[80:83], v[172:175], v[196:199], v[80:83]
	v_mfma_f32_16x16x32_bf16 v[68:71], v[164:167], v[206:209], v[68:71]
	v_mfma_f32_16x16x32_bf16 v[64:67], v[172:175], v[206:209], v[64:67]
	v_mfma_f32_16x16x32_bf16 v[116:119], v[168:171], v[184:187], v[116:119]
	v_mfma_f32_16x16x32_bf16 v[112:115], v[176:179], v[184:187], v[112:115]
	v_mfma_f32_16x16x32_bf16 v[100:103], v[168:171], v[192:195], v[100:103]
	v_mfma_f32_16x16x32_bf16 v[96:99], v[176:179], v[192:195], v[96:99]
	v_mfma_f32_16x16x32_bf16 v[84:87], v[168:171], v[200:203], v[84:87]
	v_mfma_f32_16x16x32_bf16 v[80:83], v[176:179], v[200:203], v[80:83]
	v_mfma_f32_16x16x32_bf16 v[68:71], v[168:171], v[210:213], v[68:71]
	v_mfma_f32_16x16x32_bf16 v[64:67], v[176:179], v[210:213], v[64:67]
	s_barrier
	s_mov_b64 s[38:39], s[70:71]
	s_mov_b32 m0, s74
	ds_read_b128 v[180:183], v151 offset:16384
	ds_read_b128 v[184:187], v151 offset:17408
	ds_read_b128 v[188:191], v151 offset:18432
	ds_read_b128 v[192:195], v151 offset:19456
	ds_read_b128 v[196:199], v151 offset:20480
	ds_read_b128 v[200:203], v151 offset:21504
	ds_read_b128 v[206:209], v151 offset:22528
	ds_read_b128 v[210:213], v151 offset:23552
	s_nop 0
	v_lshl_add_u64 v[144:145], s[38:39], 0, v[132:133]
	global_load_lds_dwordx4 v[144:145], off
	v_lshl_add_u64 v[144:145], s[38:39], 0, v[128:129]
	s_cselect_b32 s39, s65, s67
	s_cselect_b32 s38, s64, s66
	s_add_u32 s70, s70, 0xb0000
	s_mov_b32 m0, s75
	s_addc_u32 s71, s71, 0
	s_add_i32 s69, s57, s23
	global_load_lds_dwordx4 v[144:145], off
	s_mov_b32 m0, s69
	v_lshl_add_u64 v[144:145], s[70:71], 0, v[132:133]
	global_load_lds_dwordx4 v[144:145], off
	v_lshl_add_u64 v[144:145], s[70:71], 0, v[128:129]
	s_add_i32 m0, s69, 0x2000
	s_mov_b64 s[70:71], s[34:35]
	global_load_lds_dwordx4 v[144:145], off
	s_mov_b32 m0, s45
	v_lshl_add_u64 v[144:145], s[70:71], 0, v[134:135]
	global_load_lds_dwordx4 v[144:145], off
	v_lshl_add_u64 v[144:145], s[70:71], 0, v[130:131]
	s_mov_b32 m0, s46
	s_nop 0
	global_load_lds_dwordx4 v[144:145], off
	s_waitcnt vmcnt(8)
	s_waitcnt lgkmcnt(0)
	s_barrier
; #define PG8_STAGE(bufoff, gbase, voff) do { const char* _gb = (const char*)(gbase); asm volatile("" : "+s"(_gb));     \
;         _Pragma("unroll") for (int _i = 0; _i < 2; ++_i) \
;         __builtin_amdgcn_global_load_lds((const unsigned*)(_gb + (voff)[_i]), (LAS unsigned*)(lds + (bufoff) + ldsw + _i * 8192), 16, 0, 0); } while (0)
; #define PG8_LDA(dst, b, h) do { _Pragma("unroll") for (int m = 0; m < 4; ++m) _Pragma("unroll") for (int k = 0; k < 2; ++k) dst[m][k] = *(const LAS bf16x8*)(lds + PG8_SA(b, h) + aoff + m * 2048 + k * 1024); } while (0)
; #define PG8_LDB(dst, b, h) do { _Pragma("unroll") for (int n = 0; n < 2; ++n) _Pragma("unroll") for (int k = 0; k < 2; ++k) dst[n][k] = *(const LAS bf16x8*)(lds + PG8_SB(b, h) + boff + n * 2048 + k * 1024); } while (0)
; #define PG8_MMA(ai, bj, At, Bt) do { __builtin_amdgcn_s_setprio(1); _Pragma("unroll") for (int m = 0; m < 4; ++m) _Pragma("unroll") for (int n = 0; n < 2; ++n) _Pragma("unroll") for (int k = 0; k < 2; ++k) \
;         acc[ai][bj][m][n] = __builtin_amdgcn_mfma_f32_16x16x32_bf16(Bt[n][k], At[m][k], acc[ai][bj][m][n], 0, 0, 0); __builtin_amdgcn_s_setprio(0); } while (0)
; #define PG8_WAIT_V(n) asm volatile("s_waitcnt vmcnt(" #n ")" ::: "memory")
; #define PG8_WAIT_L(n) asm volatile("s_waitcnt lgkmcnt(" #n ")" ::: "memory")
; #define PG8_BAR __builtin_amdgcn_s_barrier()
; #define PG8_SCHED __builtin_amdgcn_sched_barrier(0)
; template <class Epi>
; __device__ __forceinline__ void gemm_phase(LAS unsigned char* lds, const int wid, const Gemm g, const Epi& E) {
;     ...
;             PG8_WAIT_V(8); PG8_WAIT_L(0); PG8_BAR; PG8_MMA(1, 0, At, B0); PG8_MMA(1, 1, At, B1); PG8_BAR; PG8_SCHED;
;             PG8_LDB(B0, 1, 0); PG8_LDB(B1, 1, 1); PG8_SCHED; PG8_LDA(At, 1, 0); PG8_STAGE(PG8_SA(0, 1), a2 + hstepA, voffA);
;             PG8_WAIT_V(8); PG8_WAIT_L(0); PG8_BAR; PG8_MMA(0, 0, At, B0); PG8_MMA(0, 1, At, B1); PG8_BAR; PG8_SCHED;
	s_waitcnt lgkmcnt(0)
	v_mfma_f32_16x16x32_bf16 v[60:63], v[140:143], v[180:183], v[60:63]
	v_mfma_f32_16x16x32_bf16 v[56:59], v[156:159], v[180:183], v[56:59]
	v_mfma_f32_16x16x32_bf16 v[44:47], v[140:143], v[188:191], v[44:47]
	v_mfma_f32_16x16x32_bf16 v[40:43], v[156:159], v[188:191], v[40:43]
	v_mfma_f32_16x16x32_bf16 v[28:31], v[140:143], v[196:199], v[28:31]
	v_mfma_f32_16x16x32_bf16 v[24:27], v[156:159], v[196:199], v[24:27]
	v_mfma_f32_16x16x32_bf16 v[12:15], v[140:143], v[206:209], v[12:15]
	v_mfma_f32_16x16x32_bf16 v[8:11], v[156:159], v[206:209], v[8:11]
	v_mfma_f32_16x16x32_bf16 v[60:63], v[152:155], v[184:187], v[60:63]
	v_mfma_f32_16x16x32_bf16 v[56:59], v[160:163], v[184:187], v[56:59]
	v_mfma_f32_16x16x32_bf16 v[44:47], v[152:155], v[192:195], v[44:47]
	v_mfma_f32_16x16x32_bf16 v[40:43], v[160:163], v[192:195], v[40:43]
	v_mfma_f32_16x16x32_bf16 v[28:31], v[152:155], v[200:203], v[28:31]
	v_mfma_f32_16x16x32_bf16 v[24:27], v[160:163], v[200:203], v[24:27]
	v_mfma_f32_16x16x32_bf16 v[12:15], v[152:155], v[210:213], v[12:15]
	v_mfma_f32_16x16x32_bf16 v[8:11], v[160:163], v[210:213], v[8:11]
	v_mfma_f32_16x16x32_bf16 v[52:55], v[164:167], v[180:183], v[52:55]
	v_mfma_f32_16x16x32_bf16 v[48:51], v[172:175], v[180:183], v[48:51]
	v_mfma_f32_16x16x32_bf16 v[36:39], v[164:167], v[188:191], v[36:39]
	v_mfma_f32_16x16x32_bf16 v[32:35], v[172:175], v[188:191], v[32:35]
	v_mfma_f32_16x16x32_bf16 v[20:23], v[164:167], v[196:199], v[20:23]
	v_mfma_f32_16x16x32_bf16 v[16:19], v[172:175], v[196:199], v[16:19]
	v_mfma_f32_16x16x32_bf16 v[4:7], v[164:167], v[206:209], v[4:7]
	v_mfma_f32_16x16x32_bf16 v[0:3], v[172:175], v[206:209], v[0:3]
	v_mfma_f32_16x16x32_bf16 v[52:55], v[168:171], v[184:187], v[52:55]
	v_mfma_f32_16x16x32_bf16 v[48:51], v[176:179], v[184:187], v[48:51]
	v_mfma_f32_16x16x32_bf16 v[36:39], v[168:171], v[192:195], v[36:39]
	v_mfma_f32_16x16x32_bf16 v[32:35], v[176:179], v[192:195], v[32:35]
	v_mfma_f32_16x16x32_bf16 v[20:23], v[168:171], v[200:203], v[20:23]
	v_mfma_f32_16x16x32_bf16 v[16:19], v[176:179], v[200:203], v[16:19]
	v_mfma_f32_16x16x32_bf16 v[4:7], v[168:171], v[210:213], v[4:7]
	v_mfma_f32_16x16x32_bf16 v[0:3], v[176:179], v[210:213], v[0:3]
	s_barrier
	s_add_i32 s69, 0, 0x18000
	v_add_u32_e32 v144, s69, v148
	s_add_i32 s70, 0, 0x1c000
	ds_read_b128 v[140:143], v144
	ds_read_b128 v[152:155], v144 offset:1024
	ds_read_b128 v[156:159], v144 offset:2048
	ds_read_b128 v[160:163], v144 offset:3072
	v_add_u32_e32 v144, s70, v148
	ds_read_b128 v[164:167], v144
	ds_read_b128 v[168:171], v144 offset:1024
	ds_read_b128 v[172:175], v144 offset:2048
	ds_read_b128 v[176:179], v144 offset:3072
	s_add_u32 s34, s34, 0xb0000
	s_addc_u32 s35, s35, 0
	s_mov_b32 m0, s47
	ds_read_b128 v[180:183], v151 offset:32768
	ds_read_b128 v[184:187], v151 offset:33792
	ds_read_b128 v[188:191], v151 offset:34816
	ds_read_b128 v[192:195], v151 offset:35840
	ds_read_b128 v[196:199], v151 offset:36864
	ds_read_b128 v[200:203], v151 offset:37888
	ds_read_b128 v[206:209], v151 offset:38912
	ds_read_b128 v[210:213], v151 offset:39936
	s_nop 0
	v_lshl_add_u64 v[144:145], s[34:35], 0, v[134:135]
	global_load_lds_dwordx4 v[144:145], off
	v_lshl_add_u64 v[144:145], s[34:35], 0, v[130:131]
	s_mov_b32 m0, s48
	s_nop 0
	global_load_lds_dwordx4 v[144:145], off
	s_waitcnt vmcnt(8)
	s_waitcnt lgkmcnt(0)
	s_barrier
	s_waitcnt lgkmcnt(0)
	v_mfma_f32_16x16x32_bf16 v[124:127], v[140:143], v[180:183], v[124:127]
	v_mfma_f32_16x16x32_bf16 v[120:123], v[156:159], v[180:183], v[120:123]
	v_mfma_f32_16x16x32_bf16 v[108:111], v[140:143], v[188:191], v[108:111]
	v_mfma_f32_16x16x32_bf16 v[104:107], v[156:159], v[188:191], v[104:107]
	v_mfma_f32_16x16x32_bf16 v[92:95], v[140:143], v[196:199], v[92:95]
	v_mfma_f32_16x16x32_bf16 v[88:91], v[156:159], v[196:199], v[88:91]
	v_mfma_f32_16x16x32_bf16 v[76:79], v[140:143], v[206:209], v[76:79]
	v_mfma_f32_16x16x32_bf16 v[72:75], v[156:159], v[206:209], v[72:75]
	v_mfma_f32_16x16x32_bf16 v[124:127], v[152:155], v[184:187], v[124:127]
	v_mfma_f32_16x16x32_bf16 v[120:123], v[160:163], v[184:187], v[120:123]
	v_mfma_f32_16x16x32_bf16 v[108:111], v[152:155], v[192:195], v[108:111]
	v_mfma_f32_16x16x32_bf16 v[104:107], v[160:163], v[192:195], v[104:107]
	v_mfma_f32_16x16x32_bf16 v[92:95], v[152:155], v[200:203], v[92:95]
	v_mfma_f32_16x16x32_bf16 v[88:91], v[160:163], v[200:203], v[88:91]
	v_mfma_f32_16x16x32_bf16 v[76:79], v[152:155], v[210:213], v[76:79]
	v_mfma_f32_16x16x32_bf16 v[72:75], v[160:163], v[210:213], v[72:75]
	v_mfma_f32_16x16x32_bf16 v[116:119], v[164:167], v[180:183], v[116:119]
	v_mfma_f32_16x16x32_bf16 v[112:115], v[172:175], v[180:183], v[112:115]
	v_mfma_f32_16x16x32_bf16 v[100:103], v[164:167], v[188:191], v[100:103]
	v_mfma_f32_16x16x32_bf16 v[96:99], v[172:175], v[188:191], v[96:99]
	v_mfma_f32_16x16x32_bf16 v[84:87], v[164:167], v[196:199], v[84:87]
	v_mfma_f32_16x16x32_bf16 v[80:83], v[172:175], v[196:199], v[80:83]
	v_mfma_f32_16x16x32_bf16 v[68:71], v[164:167], v[206:209], v[68:71]
	v_mfma_f32_16x16x32_bf16 v[64:67], v[172:175], v[206:209], v[64:67]
	v_mfma_f32_16x16x32_bf16 v[116:119], v[168:171], v[184:187], v[116:119]
	v_mfma_f32_16x16x32_bf16 v[112:115], v[176:179], v[184:187], v[112:115]
	v_mfma_f32_16x16x32_bf16 v[100:103], v[168:171], v[192:195], v[100:103]
	v_mfma_f32_16x16x32_bf16 v[96:99], v[176:179], v[192:195], v[96:99]
	v_mfma_f32_16x16x32_bf16 v[84:87], v[168:171], v[200:203], v[84:87]
	v_mfma_f32_16x16x32_bf16 v[80:83], v[176:179], v[200:203], v[80:83]
	v_mfma_f32_16x16x32_bf16 v[68:71], v[168:171], v[210:213], v[68:71]
	v_mfma_f32_16x16x32_bf16 v[64:67], v[176:179], v[210:213], v[64:67]
	s_barrier
; #define PG8_STAGE(bufoff, gbase, voff) do { const char* _gb = (const char*)(gbase); asm volatile("" : "+s"(_gb));     \
;         _Pragma("unroll") for (int _i = 0; _i < 2; ++_i) \
;         __builtin_amdgcn_global_load_lds((const unsigned*)(_gb + (voff)[_i]), (LAS unsigned*)(lds + (bufoff) + ldsw + _i * 8192), 16, 0, 0); } while (0)
; #define PG8_LDA(dst, b, h) do { _Pragma("unroll") for (int m = 0; m < 4; ++m) _Pragma("unroll") for (int k = 0; k < 2; ++k) dst[m][k] = *(const LAS bf16x8*)(lds + PG8_SA(b, h) + aoff + m * 2048 + k * 1024); } while (0)
; #define PG8_MMA(ai, bj, At, Bt) do { __builtin_amdgcn_s_setprio(1); _Pragma("unroll") for (int m = 0; m < 4; ++m) _Pragma("unroll") for (int n = 0; n < 2; ++n) _Pragma("unroll") for (int k = 0; k < 2; ++k) \
;         acc[ai][bj][m][n] = __builtin_amdgcn_mfma_f32_16x16x32_bf16(Bt[n][k], At[m][k], acc[ai][bj][m][n], 0, 0, 0); __builtin_amdgcn_s_setprio(0); } while (0)
; #define PG8_WAIT_V(n) asm volatile("s_waitcnt vmcnt(" #n ")" ::: "memory")
; #define PG8_WAIT_L(n) asm volatile("s_waitcnt lgkmcnt(" #n ")" ::: "memory")
; #define PG8_BAR __builtin_amdgcn_s_barrier()
; #define PG8_SCHED __builtin_amdgcn_sched_barrier(0)
; template <class Epi>
; __device__ __forceinline__ void gemm_phase(LAS unsigned char* lds, const int wid, const Gemm g, const Epi& E) {
;     ...
;             PG8_LDA(At, 1, 1); PG8_STAGE(PG8_SB(1, 0), b3, voffB); PG8_STAGE(PG8_SB(1, 1), b3 + hstepB, voffB); PG8_STAGE(PG8_SA(1, 0), a3, voffA);
;             PG8_WAIT_V(8); PG8_WAIT_L(0); PG8_BAR; PG8_MMA(1, 0, At, B0); PG8_MMA(1, 1, At, B1); PG8_BAR; PG8_SCHED;
;         }
;         if (wr == 0) PG8_BAR;
	s_mov_b64 s[34:35], s[38:39]
	s_add_i32 s69, s69, s23
	ds_read_b128 v[180:183], v151 offset:49152
	ds_read_b128 v[184:187], v151 offset:50176
	ds_read_b128 v[188:191], v151 offset:51200
	ds_read_b128 v[192:195], v151 offset:52224
	ds_read_b128 v[196:199], v151 offset:53248
	ds_read_b128 v[200:203], v151 offset:54272
	ds_read_b128 v[206:209], v151 offset:55296
	ds_read_b128 v[210:213], v151 offset:56320
	s_mov_b32 m0, s69
	v_lshl_add_u64 v[144:145], s[34:35], 0, v[132:133]
	global_load_lds_dwordx4 v[144:145], off
	s_add_i32 m0, s69, 0x2000
	v_lshl_add_u64 v[144:145], s[34:35], 0, v[128:129]
	s_add_u32 s34, s38, 0xb0000
	s_addc_u32 s35, s39, 0
	s_add_i32 s38, s70, s23
	global_load_lds_dwordx4 v[144:145], off
	s_mov_b32 m0, s38
	v_lshl_add_u64 v[144:145], s[34:35], 0, v[132:133]
	global_load_lds_dwordx4 v[144:145], off
	v_lshl_add_u64 v[144:145], s[34:35], 0, v[128:129]
	s_add_i32 m0, s38, 0x2000
	s_nop 0
	global_load_lds_dwordx4 v[144:145], off
	s_mov_b32 m0, s52
	v_lshl_add_u64 v[144:145], s[30:31], 0, v[134:135]
	global_load_lds_dwordx4 v[144:145], off
	v_lshl_add_u64 v[144:145], s[30:31], 0, v[130:131]
	s_mov_b32 m0, s53
	s_nop 0
	global_load_lds_dwordx4 v[144:145], off
	s_waitcnt vmcnt(8)
	s_waitcnt lgkmcnt(0)
	s_barrier
	s_waitcnt lgkmcnt(0)
	v_mfma_f32_16x16x32_bf16 v[60:63], v[140:143], v[180:183], v[60:63]
	v_mfma_f32_16x16x32_bf16 v[56:59], v[156:159], v[180:183], v[56:59]
	v_mfma_f32_16x16x32_bf16 v[44:47], v[140:143], v[188:191], v[44:47]
	v_mfma_f32_16x16x32_bf16 v[40:43], v[156:159], v[188:191], v[40:43]
	v_mfma_f32_16x16x32_bf16 v[28:31], v[140:143], v[196:199], v[28:31]
	v_mfma_f32_16x16x32_bf16 v[24:27], v[156:159], v[196:199], v[24:27]
	v_mfma_f32_16x16x32_bf16 v[12:15], v[140:143], v[206:209], v[12:15]
	v_mfma_f32_16x16x32_bf16 v[8:11], v[156:159], v[206:209], v[8:11]
	v_mfma_f32_16x16x32_bf16 v[60:63], v[152:155], v[184:187], v[60:63]
	v_mfma_f32_16x16x32_bf16 v[56:59], v[160:163], v[184:187], v[56:59]
	v_mfma_f32_16x16x32_bf16 v[44:47], v[152:155], v[192:195], v[44:47]
	v_mfma_f32_16x16x32_bf16 v[40:43], v[160:163], v[192:195], v[40:43]
	v_mfma_f32_16x16x32_bf16 v[28:31], v[152:155], v[200:203], v[28:31]
	v_mfma_f32_16x16x32_bf16 v[24:27], v[160:163], v[200:203], v[24:27]
	v_mfma_f32_16x16x32_bf16 v[12:15], v[152:155], v[210:213], v[12:15]
	v_mfma_f32_16x16x32_bf16 v[8:11], v[160:163], v[210:213], v[8:11]
	v_mfma_f32_16x16x32_bf16 v[52:55], v[164:167], v[180:183], v[52:55]
	v_mfma_f32_16x16x32_bf16 v[48:51], v[172:175], v[180:183], v[48:51]
	v_mfma_f32_16x16x32_bf16 v[36:39], v[164:167], v[188:191], v[36:39]
	v_mfma_f32_16x16x32_bf16 v[32:35], v[172:175], v[188:191], v[32:35]
	v_mfma_f32_16x16x32_bf16 v[20:23], v[164:167], v[196:199], v[20:23]
	v_mfma_f32_16x16x32_bf16 v[16:19], v[172:175], v[196:199], v[16:19]
	v_mfma_f32_16x16x32_bf16 v[4:7], v[164:167], v[206:209], v[4:7]
	v_mfma_f32_16x16x32_bf16 v[0:3], v[172:175], v[206:209], v[0:3]
	v_mfma_f32_16x16x32_bf16 v[52:55], v[168:171], v[184:187], v[52:55]
	v_mfma_f32_16x16x32_bf16 v[48:51], v[176:179], v[184:187], v[48:51]
	v_mfma_f32_16x16x32_bf16 v[36:39], v[168:171], v[192:195], v[36:39]
	v_mfma_f32_16x16x32_bf16 v[32:35], v[176:179], v[192:195], v[32:35]
	v_mfma_f32_16x16x32_bf16 v[20:23], v[168:171], v[200:203], v[20:23]
	v_mfma_f32_16x16x32_bf16 v[16:19], v[176:179], v[200:203], v[16:19]
	v_mfma_f32_16x16x32_bf16 v[4:7], v[168:171], v[210:213], v[4:7]
	v_mfma_f32_16x16x32_bf16 v[0:3], v[176:179], v[210:213], v[0:3]
	s_barrier
	s_add_i32 s68, s68, 2
	s_add_u32 s66, s66, 0x100
	s_addc_u32 s67, s67, 0
	s_add_u32 s28, s28, 0x100
	s_addc_u32 s29, s29, 0
	s_cmp_gt_u32 s68, 41
	s_cbranch_scc0 .LBB0_555
	s_and_b64 vcc, exec, s[10:11]
	s_cbranch_vccz .LBB0_558
	s_barrier

; #define PG8_STAGE(bufoff, gbase, voff) do { const char* _gb = (const char*)(gbase); asm volatile("" : "+s"(_gb));     \
;         _Pragma("unroll") for (int _i = 0; _i < 2; ++_i) \
;         __builtin_amdgcn_global_load_lds((const unsigned*)(_gb + (voff)[_i]), (LAS unsigned*)(lds + (bufoff) + ldsw + _i * 8192), 16, 0, 0); } while (0)
; #define PG8_LDA(dst, b, h) do { _Pragma("unroll") for (int m = 0; m < 4; ++m) _Pragma("unroll") for (int k = 0; k < 2; ++k) dst[m][k] = *(const LAS bf16x8*)(lds + PG8_SA(b, h) + aoff + m * 2048 + k * 1024); } while (0)
; #define PG8_LDB(dst, b, h) do { _Pragma("unroll") for (int n = 0; n < 2; ++n) _Pragma("unroll") for (int k = 0; k < 2; ++k) dst[n][k] = *(const LAS bf16x8*)(lds + PG8_SB(b, h) + boff + n * 2048 + k * 1024); } while (0)
; #define PG8_MMA(ai, bj, At, Bt) do { __builtin_amdgcn_s_setprio(1); _Pragma("unroll") for (int m = 0; m < 4; ++m) _Pragma("unroll") for (int n = 0; n < 2; ++n) _Pragma("unroll") for (int k = 0; k < 2; ++k) \
;         acc[ai][bj][m][n] = __builtin_amdgcn_mfma_f32_16x16x32_bf16(Bt[n][k], At[m][k], acc[ai][bj][m][n], 0, 0, 0); __builtin_amdgcn_s_setprio(0); } while (0)
; #define PG8_WAIT_V(n) asm volatile("s_waitcnt vmcnt(" #n ")" ::: "memory")
; #define PG8_WAIT_L(n) asm volatile("s_waitcnt lgkmcnt(" #n ")" ::: "memory")
; #define PG8_BAR __builtin_amdgcn_s_barrier()
; #define PG8_SCHED __builtin_amdgcn_sched_barrier(0)
; template <class Epi>
; __device__ __forceinline__ void gemm_phase(LAS unsigned char* lds, const int wid, const Gemm g, const Epi& E) {
;     ...
;         for (int t = 0; t < nt; t += 2) {
;             const bool last = (t == nt - 2);
;             const char* a1 = PG8_AP(cA, t + 1);
;             const char* a2 = last ? PG8_AP(nA, 0) : PG8_AP(cA, t + 2); const char* b2 = last ? PG8_BP(nB, 0) : PG8_BP(cB, t + 2);
;             const char* a3 = last ? PG8_AP(nA, 1) : PG8_AP(cA, t + 3); const char* b3 = last ? PG8_BP(nB, 1) : PG8_BP(cB, t + 3);
;             PG8_LDB(B0, 0, 0); PG8_LDB(B1, 0, 1); PG8_SCHED; PG8_LDA(At, 0, 0); PG8_STAGE(PG8_SA(1, 1), a1 + hstepA, voffA);
;             PG8_WAIT_V(8); PG8_WAIT_L(0); PG8_BAR; PG8_MMA(0, 0, At, B0); PG8_MMA(0, 1, At, B1); PG8_BAR; PG8_SCHED;
;             PG8_LDA(At, 0, 1); PG8_STAGE(PG8_SB(0, 0), b2, voffB); PG8_STAGE(PG8_SB(0, 1), b2 + hstepB, voffB); PG8_STAGE(PG8_SA(0, 0), a2, voffA);
.LBB0_831:
	ds_read_b128 v[140:143], v157
	ds_read_b128 v[144:147], v157 offset:1024
	ds_read_b128 v[148:151], v157 offset:2048
	ds_read_b128 v[160:163], v157 offset:3072
	ds_read_b128 v[164:167], v158
	ds_read_b128 v[168:171], v158 offset:1024
	ds_read_b128 v[172:175], v158 offset:2048
	ds_read_b128 v[176:179], v158 offset:3072
	s_add_u32 s50, s6, 0xfffc0080
	s_addc_u32 s51, s7, -1
	s_add_u32 s54, s88, 0xffffff80
	s_addc_u32 s55, s89, -1
	s_add_u32 s91, s6, 0xfffc0100
	s_addc_u32 s94, s7, -1
	s_add_i32 s96, s78, s61
	s_add_i32 m0, s21, 0xc000
	s_add_i32 s95, s21, 0xe000
	s_add_i32 s97, s96, 0x2000
	s_cmp_eq_u32 s90, 12
	s_cselect_b32 s53, s47, s51
	s_cselect_b32 s52, s46, s50
	s_cselect_b32 s93, s9, s55
	s_cselect_b32 s92, s43, s54
	s_cselect_b32 s51, s85, s94
	s_cselect_b32 s50, s45, s91
	s_mov_b64 s[54:55], s[6:7]
	ds_read_b128 v[180:183], v159
	ds_read_b128 v[184:187], v159 offset:1024
	ds_read_b128 v[188:191], v159 offset:2048
	ds_read_b128 v[192:195], v159 offset:3072
	ds_read_b128 v[196:199], v159 offset:4096
	ds_read_b128 v[200:203], v159 offset:5120
	ds_read_b128 v[206:209], v159 offset:6144
	ds_read_b128 v[210:213], v159 offset:7168
	s_nop 0
	v_lshl_add_u64 v[152:153], s[54:55], 0, v[128:129]
	global_load_lds_dwordx4 v[152:153], off
	v_lshl_add_u64 v[152:153], s[54:55], 0, v[132:133]
	s_mov_b32 m0, s95
	s_nop 0
	global_load_lds_dwordx4 v[152:153], off
	s_waitcnt vmcnt(8)
	s_waitcnt lgkmcnt(0)
	s_barrier
	s_waitcnt lgkmcnt(0)
	v_mfma_f32_16x16x32_bf16 v[124:127], v[140:143], v[180:183], v[124:127]
	v_mfma_f32_16x16x32_bf16 v[120:123], v[148:151], v[180:183], v[120:123]
	v_mfma_f32_16x16x32_bf16 v[116:119], v[140:143], v[188:191], v[116:119]
	v_mfma_f32_16x16x32_bf16 v[112:115], v[148:151], v[188:191], v[112:115]
	v_mfma_f32_16x16x32_bf16 v[100:103], v[140:143], v[196:199], v[100:103]
	v_mfma_f32_16x16x32_bf16 v[96:99], v[148:151], v[196:199], v[96:99]
	v_mfma_f32_16x16x32_bf16 v[84:87], v[140:143], v[206:209], v[84:87]
	v_mfma_f32_16x16x32_bf16 v[80:83], v[148:151], v[206:209], v[80:83]
	v_mfma_f32_16x16x32_bf16 v[124:127], v[144:147], v[184:187], v[124:127]
	v_mfma_f32_16x16x32_bf16 v[120:123], v[160:163], v[184:187], v[120:123]
	v_mfma_f32_16x16x32_bf16 v[116:119], v[144:147], v[192:195], v[116:119]
	v_mfma_f32_16x16x32_bf16 v[112:115], v[160:163], v[192:195], v[112:115]
	v_mfma_f32_16x16x32_bf16 v[100:103], v[144:147], v[200:203], v[100:103]
	v_mfma_f32_16x16x32_bf16 v[96:99], v[160:163], v[200:203], v[96:99]
	v_mfma_f32_16x16x32_bf16 v[84:87], v[144:147], v[210:213], v[84:87]
	v_mfma_f32_16x16x32_bf16 v[80:83], v[160:163], v[210:213], v[80:83]
	v_mfma_f32_16x16x32_bf16 v[108:111], v[164:167], v[180:183], v[108:111]
	v_mfma_f32_16x16x32_bf16 v[104:107], v[172:175], v[180:183], v[104:107]
	v_mfma_f32_16x16x32_bf16 v[92:95], v[164:167], v[188:191], v[92:95]
	v_mfma_f32_16x16x32_bf16 v[88:91], v[172:175], v[188:191], v[88:91]
	v_mfma_f32_16x16x32_bf16 v[76:79], v[164:167], v[196:199], v[76:79]
	v_mfma_f32_16x16x32_bf16 v[72:75], v[172:175], v[196:199], v[72:75]
	v_mfma_f32_16x16x32_bf16 v[68:71], v[164:167], v[206:209], v[68:71]
	v_mfma_f32_16x16x32_bf16 v[64:67], v[172:175], v[206:209], v[64:67]
	v_mfma_f32_16x16x32_bf16 v[108:111], v[168:171], v[184:187], v[108:111]
	v_mfma_f32_16x16x32_bf16 v[104:107], v[176:179], v[184:187], v[104:107]
	v_mfma_f32_16x16x32_bf16 v[92:95], v[168:171], v[192:195], v[92:95]
	v_mfma_f32_16x16x32_bf16 v[88:91], v[176:179], v[192:195], v[88:91]
	v_mfma_f32_16x16x32_bf16 v[76:79], v[168:171], v[200:203], v[76:79]
	v_mfma_f32_16x16x32_bf16 v[72:75], v[176:179], v[200:203], v[72:75]
	v_mfma_f32_16x16x32_bf16 v[68:71], v[168:171], v[210:213], v[68:71]
	v_mfma_f32_16x16x32_bf16 v[64:67], v[176:179], v[210:213], v[64:67]
	s_barrier
	s_mov_b64 s[54:55], s[92:93]
	s_mov_b32 m0, s96
	ds_read_b128 v[180:183], v159 offset:16384
	ds_read_b128 v[184:187], v159 offset:17408
	ds_read_b128 v[188:191], v159 offset:18432
	ds_read_b128 v[192:195], v159 offset:19456
	ds_read_b128 v[196:199], v159 offset:20480
	ds_read_b128 v[200:203], v159 offset:21504
	ds_read_b128 v[206:209], v159 offset:22528
	ds_read_b128 v[210:213], v159 offset:23552
	s_nop 0
	v_lshl_add_u64 v[152:153], s[54:55], 0, v[130:131]
	global_load_lds_dwordx4 v[152:153], off
	v_lshl_add_u64 v[152:153], s[54:55], 0, v[134:135]
	s_cselect_b32 s55, s87, s89
	s_cselect_b32 s54, s86, s88
	s_add_u32 s92, s92, 0x40000
	s_mov_b32 m0, s97
	s_addc_u32 s93, s93, 0
	s_add_i32 s91, s79, s61
	global_load_lds_dwordx4 v[152:153], off
	s_mov_b32 m0, s91
	v_lshl_add_u64 v[152:153], s[92:93], 0, v[130:131]
	global_load_lds_dwordx4 v[152:153], off
	v_lshl_add_u64 v[152:153], s[92:93], 0, v[134:135]
	s_add_i32 m0, s91, 0x2000
	s_mov_b64 s[92:93], s[52:53]
	global_load_lds_dwordx4 v[152:153], off
	s_mov_b32 m0, s21
	v_lshl_add_u64 v[152:153], s[92:93], 0, v[128:129]
	global_load_lds_dwordx4 v[152:153], off
	v_lshl_add_u64 v[152:153], s[92:93], 0, v[132:133]
	s_mov_b32 m0, s69
	s_nop 0
	global_load_lds_dwordx4 v[152:153], off
	s_waitcnt vmcnt(8)
	s_waitcnt lgkmcnt(0)
	s_barrier
; #define PG8_STAGE(bufoff, gbase, voff) do { const char* _gb = (const char*)(gbase); asm volatile("" : "+s"(_gb));     \
;         _Pragma("unroll") for (int _i = 0; _i < 2; ++_i) \
;         __builtin_amdgcn_global_load_lds((const unsigned*)(_gb + (voff)[_i]), (LAS unsigned*)(lds + (bufoff) + ldsw + _i * 8192), 16, 0, 0); } while (0)
; #define PG8_LDA(dst, b, h) do { _Pragma("unroll") for (int m = 0; m < 4; ++m) _Pragma("unroll") for (int k = 0; k < 2; ++k) dst[m][k] = *(const LAS bf16x8*)(lds + PG8_SA(b, h) + aoff + m * 2048 + k * 1024); } while (0)
; #define PG8_LDB(dst, b, h) do { _Pragma("unroll") for (int n = 0; n < 2; ++n) _Pragma("unroll") for (int k = 0; k < 2; ++k) dst[n][k] = *(const LAS bf16x8*)(lds + PG8_SB(b, h) + boff + n * 2048 + k * 1024); } while (0)
; #define PG8_MMA(ai, bj, At, Bt) do { __builtin_amdgcn_s_setprio(1); _Pragma("unroll") for (int m = 0; m < 4; ++m) _Pragma("unroll") for (int n = 0; n < 2; ++n) _Pragma("unroll") for (int k = 0; k < 2; ++k) \
;         acc[ai][bj][m][n] = __builtin_amdgcn_mfma_f32_16x16x32_bf16(Bt[n][k], At[m][k], acc[ai][bj][m][n], 0, 0, 0); __builtin_amdgcn_s_setprio(0); } while (0)
; #define PG8_WAIT_V(n) asm volatile("s_waitcnt vmcnt(" #n ")" ::: "memory")
; #define PG8_WAIT_L(n) asm volatile("s_waitcnt lgkmcnt(" #n ")" ::: "memory")
; #define PG8_BAR __builtin_amdgcn_s_barrier()
; #define PG8_SCHED __builtin_amdgcn_sched_barrier(0)
; template <class Epi>
; __device__ __forceinline__ void gemm_phase(LAS unsigned char* lds, const int wid, const Gemm g, const Epi& E) {
;     ...
;             PG8_WAIT_V(8); PG8_WAIT_L(0); PG8_BAR; PG8_MMA(1, 0, At, B0); PG8_MMA(1, 1, At, B1); PG8_BAR; PG8_SCHED;
;             PG8_LDB(B0, 1, 0); PG8_LDB(B1, 1, 1); PG8_SCHED; PG8_LDA(At, 1, 0); PG8_STAGE(PG8_SA(0, 1), a2 + hstepA, voffA);
;             PG8_WAIT_V(8); PG8_WAIT_L(0); PG8_BAR; PG8_MMA(0, 0, At, B0); PG8_MMA(0, 1, At, B1); PG8_BAR; PG8_SCHED;
	s_waitcnt lgkmcnt(0)
	v_mfma_f32_16x16x32_bf16 v[60:63], v[140:143], v[180:183], v[60:63]
	v_mfma_f32_16x16x32_bf16 v[56:59], v[148:151], v[180:183], v[56:59]
	v_mfma_f32_16x16x32_bf16 v[52:55], v[140:143], v[188:191], v[52:55]
	v_mfma_f32_16x16x32_bf16 v[48:51], v[148:151], v[188:191], v[48:51]
	v_mfma_f32_16x16x32_bf16 v[36:39], v[140:143], v[196:199], v[36:39]
	v_mfma_f32_16x16x32_bf16 v[32:35], v[148:151], v[196:199], v[32:35]
	v_mfma_f32_16x16x32_bf16 v[20:23], v[140:143], v[206:209], v[20:23]
	v_mfma_f32_16x16x32_bf16 v[16:19], v[148:151], v[206:209], v[16:19]
	v_mfma_f32_16x16x32_bf16 v[60:63], v[144:147], v[184:187], v[60:63]
	v_mfma_f32_16x16x32_bf16 v[56:59], v[160:163], v[184:187], v[56:59]
	v_mfma_f32_16x16x32_bf16 v[52:55], v[144:147], v[192:195], v[52:55]
	v_mfma_f32_16x16x32_bf16 v[48:51], v[160:163], v[192:195], v[48:51]
	v_mfma_f32_16x16x32_bf16 v[36:39], v[144:147], v[200:203], v[36:39]
	v_mfma_f32_16x16x32_bf16 v[32:35], v[160:163], v[200:203], v[32:35]
	v_mfma_f32_16x16x32_bf16 v[20:23], v[144:147], v[210:213], v[20:23]
	v_mfma_f32_16x16x32_bf16 v[16:19], v[160:163], v[210:213], v[16:19]
	v_mfma_f32_16x16x32_bf16 v[44:47], v[164:167], v[180:183], v[44:47]
	v_mfma_f32_16x16x32_bf16 v[40:43], v[172:175], v[180:183], v[40:43]
	v_mfma_f32_16x16x32_bf16 v[28:31], v[164:167], v[188:191], v[28:31]
	v_mfma_f32_16x16x32_bf16 v[24:27], v[172:175], v[188:191], v[24:27]
	v_mfma_f32_16x16x32_bf16 v[12:15], v[164:167], v[196:199], v[12:15]
	v_mfma_f32_16x16x32_bf16 v[8:11], v[172:175], v[196:199], v[8:11]
	v_mfma_f32_16x16x32_bf16 v[4:7], v[164:167], v[206:209], v[4:7]
	v_mfma_f32_16x16x32_bf16 v[0:3], v[172:175], v[206:209], v[0:3]
	v_mfma_f32_16x16x32_bf16 v[44:47], v[168:171], v[184:187], v[44:47]
	v_mfma_f32_16x16x32_bf16 v[40:43], v[176:179], v[184:187], v[40:43]
	v_mfma_f32_16x16x32_bf16 v[28:31], v[168:171], v[192:195], v[28:31]
	v_mfma_f32_16x16x32_bf16 v[24:27], v[176:179], v[192:195], v[24:27]
	v_mfma_f32_16x16x32_bf16 v[12:15], v[168:171], v[200:203], v[12:15]
	v_mfma_f32_16x16x32_bf16 v[8:11], v[176:179], v[200:203], v[8:11]
	v_mfma_f32_16x16x32_bf16 v[4:7], v[168:171], v[210:213], v[4:7]
	v_mfma_f32_16x16x32_bf16 v[0:3], v[176:179], v[210:213], v[0:3]
	s_barrier
	s_add_i32 s91, 0, 0x18000
	v_add_u32_e32 v152, s91, v156
	s_add_i32 s92, 0, 0x1c000
	ds_read_b128 v[140:143], v152
	ds_read_b128 v[144:147], v152 offset:1024
	ds_read_b128 v[148:151], v152 offset:2048
	ds_read_b128 v[160:163], v152 offset:3072
	v_add_u32_e32 v152, s92, v156
	ds_read_b128 v[164:167], v152
	ds_read_b128 v[168:171], v152 offset:1024
	ds_read_b128 v[172:175], v152 offset:2048
	ds_read_b128 v[176:179], v152 offset:3072
	s_add_u32 s52, s52, 0x40000
	s_addc_u32 s53, s53, 0
	s_mov_b32 m0, s70
	ds_read_b128 v[180:183], v159 offset:32768
	ds_read_b128 v[184:187], v159 offset:33792
	ds_read_b128 v[188:191], v159 offset:34816
	ds_read_b128 v[192:195], v159 offset:35840
	ds_read_b128 v[196:199], v159 offset:36864
	ds_read_b128 v[200:203], v159 offset:37888
	ds_read_b128 v[206:209], v159 offset:38912
	ds_read_b128 v[210:213], v159 offset:39936
	s_nop 0
	v_lshl_add_u64 v[152:153], s[52:53], 0, v[128:129]
	global_load_lds_dwordx4 v[152:153], off
	v_lshl_add_u64 v[152:153], s[52:53], 0, v[132:133]
	s_mov_b32 m0, s71
	s_nop 0
	global_load_lds_dwordx4 v[152:153], off
	s_waitcnt vmcnt(8)
	s_waitcnt lgkmcnt(0)
	s_barrier
	s_waitcnt lgkmcnt(0)
	v_mfma_f32_16x16x32_bf16 v[124:127], v[140:143], v[180:183], v[124:127]
	v_mfma_f32_16x16x32_bf16 v[120:123], v[148:151], v[180:183], v[120:123]
	v_mfma_f32_16x16x32_bf16 v[116:119], v[140:143], v[188:191], v[116:119]
	v_mfma_f32_16x16x32_bf16 v[112:115], v[148:151], v[188:191], v[112:115]
	v_mfma_f32_16x16x32_bf16 v[100:103], v[140:143], v[196:199], v[100:103]
	v_mfma_f32_16x16x32_bf16 v[96:99], v[148:151], v[196:199], v[96:99]
	v_mfma_f32_16x16x32_bf16 v[84:87], v[140:143], v[206:209], v[84:87]
	v_mfma_f32_16x16x32_bf16 v[80:83], v[148:151], v[206:209], v[80:83]
	v_mfma_f32_16x16x32_bf16 v[124:127], v[144:147], v[184:187], v[124:127]
	v_mfma_f32_16x16x32_bf16 v[120:123], v[160:163], v[184:187], v[120:123]
	v_mfma_f32_16x16x32_bf16 v[116:119], v[144:147], v[192:195], v[116:119]
	v_mfma_f32_16x16x32_bf16 v[112:115], v[160:163], v[192:195], v[112:115]
	v_mfma_f32_16x16x32_bf16 v[100:103], v[144:147], v[200:203], v[100:103]
	v_mfma_f32_16x16x32_bf16 v[96:99], v[160:163], v[200:203], v[96:99]
	v_mfma_f32_16x16x32_bf16 v[84:87], v[144:147], v[210:213], v[84:87]
	v_mfma_f32_16x16x32_bf16 v[80:83], v[160:163], v[210:213], v[80:83]
	v_mfma_f32_16x16x32_bf16 v[108:111], v[164:167], v[180:183], v[108:111]
	v_mfma_f32_16x16x32_bf16 v[104:107], v[172:175], v[180:183], v[104:107]
	v_mfma_f32_16x16x32_bf16 v[92:95], v[164:167], v[188:191], v[92:95]
	v_mfma_f32_16x16x32_bf16 v[88:91], v[172:175], v[188:191], v[88:91]
	v_mfma_f32_16x16x32_bf16 v[76:79], v[164:167], v[196:199], v[76:79]
	v_mfma_f32_16x16x32_bf16 v[72:75], v[172:175], v[196:199], v[72:75]
	v_mfma_f32_16x16x32_bf16 v[68:71], v[164:167], v[206:209], v[68:71]
	v_mfma_f32_16x16x32_bf16 v[64:67], v[172:175], v[206:209], v[64:67]
	v_mfma_f32_16x16x32_bf16 v[108:111], v[168:171], v[184:187], v[108:111]
	v_mfma_f32_16x16x32_bf16 v[104:107], v[176:179], v[184:187], v[104:107]
	v_mfma_f32_16x16x32_bf16 v[92:95], v[168:171], v[192:195], v[92:95]
	v_mfma_f32_16x16x32_bf16 v[88:91], v[176:179], v[192:195], v[88:91]
	v_mfma_f32_16x16x32_bf16 v[76:79], v[168:171], v[200:203], v[76:79]
	v_mfma_f32_16x16x32_bf16 v[72:75], v[176:179], v[200:203], v[72:75]
	v_mfma_f32_16x16x32_bf16 v[68:71], v[168:171], v[210:213], v[68:71]
	v_mfma_f32_16x16x32_bf16 v[64:67], v[176:179], v[210:213], v[64:67]
	s_barrier
; #define PG8_STAGE(bufoff, gbase, voff) do { const char* _gb = (const char*)(gbase); asm volatile("" : "+s"(_gb));     \
;         _Pragma("unroll") for (int _i = 0; _i < 2; ++_i) \
;         __builtin_amdgcn_global_load_lds((const unsigned*)(_gb + (voff)[_i]), (LAS unsigned*)(lds + (bufoff) + ldsw + _i * 8192), 16, 0, 0); } while (0)
; #define PG8_LDA(dst, b, h) do { _Pragma("unroll") for (int m = 0; m < 4; ++m) _Pragma("unroll") for (int k = 0; k < 2; ++k) dst[m][k] = *(const LAS bf16x8*)(lds + PG8_SA(b, h) + aoff + m * 2048 + k * 1024); } while (0)
; #define PG8_MMA(ai, bj, At, Bt) do { __builtin_amdgcn_s_setprio(1); _Pragma("unroll") for (int m = 0; m < 4; ++m) _Pragma("unroll") for (int n = 0; n < 2; ++n) _Pragma("unroll") for (int k = 0; k < 2; ++k) \
;         acc[ai][bj][m][n] = __builtin_amdgcn_mfma_f32_16x16x32_bf16(Bt[n][k], At[m][k], acc[ai][bj][m][n], 0, 0, 0); __builtin_amdgcn_s_setprio(0); } while (0)
; #define PG8_WAIT_V(n) asm volatile("s_waitcnt vmcnt(" #n ")" ::: "memory")
; #define PG8_WAIT_L(n) asm volatile("s_waitcnt lgkmcnt(" #n ")" ::: "memory")
; #define PG8_BAR __builtin_amdgcn_s_barrier()
; #define PG8_SCHED __builtin_amdgcn_sched_barrier(0)
; template <class Epi>
; __device__ __forceinline__ void gemm_phase(LAS unsigned char* lds, const int wid, const Gemm g, const Epi& E) {
;     ...
;             PG8_LDA(At, 1, 1); PG8_STAGE(PG8_SB(1, 0), b3, voffB); PG8_STAGE(PG8_SB(1, 1), b3 + hstepB, voffB); PG8_STAGE(PG8_SA(1, 0), a3, voffA);
;             PG8_WAIT_V(8); PG8_WAIT_L(0); PG8_BAR; PG8_MMA(1, 0, At, B0); PG8_MMA(1, 1, At, B1); PG8_BAR; PG8_SCHED;
;         }
;         if (wr == 0) PG8_BAR;
	s_mov_b64 s[52:53], s[54:55]
	s_add_i32 s91, s91, s61
	ds_read_b128 v[180:183], v159 offset:49152
	ds_read_b128 v[184:187], v159 offset:50176
	ds_read_b128 v[188:191], v159 offset:51200
	ds_read_b128 v[192:195], v159 offset:52224
	ds_read_b128 v[196:199], v159 offset:53248
	ds_read_b128 v[200:203], v159 offset:54272
	ds_read_b128 v[206:209], v159 offset:55296
	ds_read_b128 v[210:213], v159 offset:56320
	s_mov_b32 m0, s91
	v_lshl_add_u64 v[152:153], s[52:53], 0, v[130:131]
	global_load_lds_dwordx4 v[152:153], off
	s_add_i32 m0, s91, 0x2000
	v_lshl_add_u64 v[152:153], s[52:53], 0, v[134:135]
	s_add_u32 s52, s54, 0x40000
	s_addc_u32 s53, s55, 0
	s_add_i32 s54, s92, s61
	global_load_lds_dwordx4 v[152:153], off
	s_mov_b32 m0, s54
	v_lshl_add_u64 v[152:153], s[52:53], 0, v[130:131]
	global_load_lds_dwordx4 v[152:153], off
	v_lshl_add_u64 v[152:153], s[52:53], 0, v[134:135]
	s_add_i32 m0, s54, 0x2000
	s_nop 0
	global_load_lds_dwordx4 v[152:153], off
	s_mov_b32 m0, s75
	v_lshl_add_u64 v[152:153], s[50:51], 0, v[128:129]
	global_load_lds_dwordx4 v[152:153], off
	v_lshl_add_u64 v[152:153], s[50:51], 0, v[132:133]
	s_mov_b32 m0, s76
	s_nop 0
	global_load_lds_dwordx4 v[152:153], off
	s_waitcnt vmcnt(8)
	s_waitcnt lgkmcnt(0)
	s_barrier
	s_waitcnt lgkmcnt(0)
	v_mfma_f32_16x16x32_bf16 v[60:63], v[140:143], v[180:183], v[60:63]
	v_mfma_f32_16x16x32_bf16 v[56:59], v[148:151], v[180:183], v[56:59]
	v_mfma_f32_16x16x32_bf16 v[52:55], v[140:143], v[188:191], v[52:55]
	v_mfma_f32_16x16x32_bf16 v[48:51], v[148:151], v[188:191], v[48:51]
	v_mfma_f32_16x16x32_bf16 v[36:39], v[140:143], v[196:199], v[36:39]
	v_mfma_f32_16x16x32_bf16 v[32:35], v[148:151], v[196:199], v[32:35]
	v_mfma_f32_16x16x32_bf16 v[20:23], v[140:143], v[206:209], v[20:23]
	v_mfma_f32_16x16x32_bf16 v[16:19], v[148:151], v[206:209], v[16:19]
	v_mfma_f32_16x16x32_bf16 v[60:63], v[144:147], v[184:187], v[60:63]
	v_mfma_f32_16x16x32_bf16 v[56:59], v[160:163], v[184:187], v[56:59]
	v_mfma_f32_16x16x32_bf16 v[52:55], v[144:147], v[192:195], v[52:55]
	v_mfma_f32_16x16x32_bf16 v[48:51], v[160:163], v[192:195], v[48:51]
	v_mfma_f32_16x16x32_bf16 v[36:39], v[144:147], v[200:203], v[36:39]
	v_mfma_f32_16x16x32_bf16 v[32:35], v[160:163], v[200:203], v[32:35]
	v_mfma_f32_16x16x32_bf16 v[20:23], v[144:147], v[210:213], v[20:23]
	v_mfma_f32_16x16x32_bf16 v[16:19], v[160:163], v[210:213], v[16:19]
	v_mfma_f32_16x16x32_bf16 v[44:47], v[164:167], v[180:183], v[44:47]
	v_mfma_f32_16x16x32_bf16 v[40:43], v[172:175], v[180:183], v[40:43]
	v_mfma_f32_16x16x32_bf16 v[28:31], v[164:167], v[188:191], v[28:31]
	v_mfma_f32_16x16x32_bf16 v[24:27], v[172:175], v[188:191], v[24:27]
	v_mfma_f32_16x16x32_bf16 v[12:15], v[164:167], v[196:199], v[12:15]
	v_mfma_f32_16x16x32_bf16 v[8:11], v[172:175], v[196:199], v[8:11]
	v_mfma_f32_16x16x32_bf16 v[4:7], v[164:167], v[206:209], v[4:7]
	v_mfma_f32_16x16x32_bf16 v[0:3], v[172:175], v[206:209], v[0:3]
	v_mfma_f32_16x16x32_bf16 v[44:47], v[168:171], v[184:187], v[44:47]
	v_mfma_f32_16x16x32_bf16 v[40:43], v[176:179], v[184:187], v[40:43]
	v_mfma_f32_16x16x32_bf16 v[28:31], v[168:171], v[192:195], v[28:31]
	v_mfma_f32_16x16x32_bf16 v[24:27], v[176:179], v[192:195], v[24:27]
	v_mfma_f32_16x16x32_bf16 v[12:15], v[168:171], v[200:203], v[12:15]
	v_mfma_f32_16x16x32_bf16 v[8:11], v[176:179], v[200:203], v[8:11]
	v_mfma_f32_16x16x32_bf16 v[4:7], v[168:171], v[210:213], v[4:7]
	v_mfma_f32_16x16x32_bf16 v[0:3], v[176:179], v[210:213], v[0:3]
	s_barrier
	s_add_i32 s90, s90, 2
	s_add_u32 s88, s88, 0x100
	s_addc_u32 s89, s89, 0
	s_add_u32 s6, s6, 0x100
	s_addc_u32 s7, s7, 0
	s_cmp_gt_u32 s90, 13
	s_cbranch_scc0 .LBB0_831
	s_and_b64 vcc, exec, s[12:13]
	s_cbranch_vccz .LBB0_834
	s_barrier

; #define PG8_STAGE(bufoff, gbase, voff) do { const char* _gb = (const char*)(gbase); asm volatile("" : "+s"(_gb));     \
;         _Pragma("unroll") for (int _i = 0; _i < 2; ++_i) \
;         __builtin_amdgcn_global_load_lds((const unsigned*)(_gb + (voff)[_i]), (LAS unsigned*)(lds + (bufoff) + ldsw + _i * 8192), 16, 0, 0); } while (0)
; #define PG8_LDA(dst, b, h) do { _Pragma("unroll") for (int m = 0; m < 4; ++m) _Pragma("unroll") for (int k = 0; k < 2; ++k) dst[m][k] = *(const LAS bf16x8*)(lds + PG8_SA(b, h) + aoff + m * 2048 + k * 1024); } while (0)
; #define PG8_LDB(dst, b, h) do { _Pragma("unroll") for (int n = 0; n < 2; ++n) _Pragma("unroll") for (int k = 0; k < 2; ++k) dst[n][k] = *(const LAS bf16x8*)(lds + PG8_SB(b, h) + boff + n * 2048 + k * 1024); } while (0)
; #define PG8_MMA(ai, bj, At, Bt) do { __builtin_amdgcn_s_setprio(1); _Pragma("unroll") for (int m = 0; m < 4; ++m) _Pragma("unroll") for (int n = 0; n < 2; ++n) _Pragma("unroll") for (int k = 0; k < 2; ++k) \
;         acc[ai][bj][m][n] = __builtin_amdgcn_mfma_f32_16x16x32_bf16(Bt[n][k], At[m][k], acc[ai][bj][m][n], 0, 0, 0); __builtin_amdgcn_s_setprio(0); } while (0)
; #define PG8_WAIT_V(n) asm volatile("s_waitcnt vmcnt(" #n ")" ::: "memory")
; #define PG8_WAIT_L(n) asm volatile("s_waitcnt lgkmcnt(" #n ")" ::: "memory")
; #define PG8_BAR __builtin_amdgcn_s_barrier()
; #define PG8_SCHED __builtin_amdgcn_sched_barrier(0)
; template <class Epi>
; __device__ __forceinline__ void gemm_phase(LAS unsigned char* lds, const int wid, const Gemm g, const Epi& E) {
;     ...
;         for (int t = 0; t < nt; t += 2) {
;             const bool last = (t == nt - 2);
;             const char* a1 = PG8_AP(cA, t + 1);
;             const char* a2 = last ? PG8_AP(nA, 0) : PG8_AP(cA, t + 2); const char* b2 = last ? PG8_BP(nB, 0) : PG8_BP(cB, t + 2);
;             const char* a3 = last ? PG8_AP(nA, 1) : PG8_AP(cA, t + 3); const char* b3 = last ? PG8_BP(nB, 1) : PG8_BP(cB, t + 3);
;             PG8_LDB(B0, 0, 0); PG8_LDB(B1, 0, 1); PG8_SCHED; PG8_LDA(At, 0, 0); PG8_STAGE(PG8_SA(1, 1), a1 + hstepA, voffA);
;             PG8_WAIT_V(8); PG8_WAIT_L(0); PG8_BAR; PG8_MMA(0, 0, At, B0); PG8_MMA(0, 1, At, B1); PG8_BAR; PG8_SCHED;
;             PG8_LDA(At, 0, 1); PG8_STAGE(PG8_SB(0, 0), b2, voffB); PG8_STAGE(PG8_SB(0, 1), b2 + hstepB, voffB); PG8_STAGE(PG8_SA(0, 0), a2, voffA);
.LBB0_952:
	s_add_i32 s92, s92, 2
	s_cmp_lt_u32 s92, 16
	s_cselect_b32 s54, 0, -1
	s_cselect_b32 s55, s79, 0xfffff800
	s_cmp_lt_u32 s92, 14
	s_cselect_b32 s57, s79, 0xfffff800
	s_cselect_b32 s56, 0, -1
	s_add_u32 s57, s57, s6
	s_addc_u32 s56, s56, s7
	s_add_u32 s57, s52, s57
	s_addc_u32 s56, s53, s56
	s_add_u32 s93, s57, 0x100
	s_addc_u32 s56, s56, 0
	s_add_u32 s57, s50, s6
	s_addc_u32 s58, s51, s7
	s_add_u32 s94, s57, 0x100
	s_addc_u32 s95, s58, 0
	s_cmp_lt_u32 s92, 13
	s_cselect_b32 s96, s79, 0xfffff800
	s_cselect_b32 s59, 0, -1
	s_add_u32 s96, s96, s6
	s_addc_u32 s59, s59, s7
	s_add_u32 s96, s52, s96
	s_addc_u32 s59, s53, s59
	s_add_u32 s96, s96, 0x180
	s_addc_u32 s97, s59, 0
	ds_read_b128 v[140:143], v157
	ds_read_b128 v[144:147], v157 offset:1024
	ds_read_b128 v[148:151], v157 offset:2048
	ds_read_b128 v[160:163], v157 offset:3072
	ds_read_b128 v[164:167], v158
	ds_read_b128 v[168:171], v158 offset:1024
	ds_read_b128 v[172:175], v158 offset:2048
	ds_read_b128 v[176:179], v158 offset:3072
	s_add_u32 vcc_lo, s57, 0x180
	s_addc_u32 vcc_hi, s58, 0
	s_add_u32 s55, s55, s6
	s_addc_u32 s54, s54, s7
	s_add_u32 s55, s52, s55
	s_addc_u32 s54, s53, s54
	s_add_u32 s58, s55, 0x40080
	s_addc_u32 s59, s54, 0
	s_add_i32 s11, s80, s61
	s_add_i32 m0, s10, 0xc000
	s_add_i32 s19, s10, 0xe000
	s_add_i32 s78, s11, 0x2000
	s_cmpk_eq_i32 s6, 0xf00
	s_cselect_b32 s57, s87, s56
	s_cselect_b32 s56, s45, s93
	s_cselect_b32 s95, s9, s95
	s_cselect_b32 s94, s43, s94
	s_cselect_b32 s55, s89, s97
	s_cselect_b32 s54, s88, s96
	ds_read_b128 v[180:183], v159
	ds_read_b128 v[184:187], v159 offset:1024
	ds_read_b128 v[188:191], v159 offset:2048
	ds_read_b128 v[192:195], v159 offset:3072
	ds_read_b128 v[196:199], v159 offset:4096
	ds_read_b128 v[200:203], v159 offset:5120
	ds_read_b128 v[206:209], v159 offset:6144
	ds_read_b128 v[210:213], v159 offset:7168
	s_nop 0
	v_lshl_add_u64 v[152:153], s[58:59], 0, v[128:129]
	global_load_lds_dwordx4 v[152:153], off
	v_lshl_add_u64 v[152:153], s[58:59], 0, v[132:133]
	s_mov_b32 m0, s19
	s_nop 0
	global_load_lds_dwordx4 v[152:153], off
	s_waitcnt vmcnt(8)
	s_waitcnt lgkmcnt(0)
	s_barrier
	s_waitcnt lgkmcnt(0)
	v_mfma_f32_16x16x32_bf16 v[124:127], v[140:143], v[180:183], v[124:127]
	v_mfma_f32_16x16x32_bf16 v[120:123], v[148:151], v[180:183], v[120:123]
	v_mfma_f32_16x16x32_bf16 v[116:119], v[140:143], v[188:191], v[116:119]
	v_mfma_f32_16x16x32_bf16 v[112:115], v[148:151], v[188:191], v[112:115]
	v_mfma_f32_16x16x32_bf16 v[100:103], v[140:143], v[196:199], v[100:103]
	v_mfma_f32_16x16x32_bf16 v[96:99], v[148:151], v[196:199], v[96:99]
	v_mfma_f32_16x16x32_bf16 v[84:87], v[140:143], v[206:209], v[84:87]
	v_mfma_f32_16x16x32_bf16 v[80:83], v[148:151], v[206:209], v[80:83]
	v_mfma_f32_16x16x32_bf16 v[124:127], v[144:147], v[184:187], v[124:127]
	v_mfma_f32_16x16x32_bf16 v[120:123], v[160:163], v[184:187], v[120:123]
	v_mfma_f32_16x16x32_bf16 v[116:119], v[144:147], v[192:195], v[116:119]
	v_mfma_f32_16x16x32_bf16 v[112:115], v[160:163], v[192:195], v[112:115]
	v_mfma_f32_16x16x32_bf16 v[100:103], v[144:147], v[200:203], v[100:103]
	v_mfma_f32_16x16x32_bf16 v[96:99], v[160:163], v[200:203], v[96:99]
	v_mfma_f32_16x16x32_bf16 v[84:87], v[144:147], v[210:213], v[84:87]
	v_mfma_f32_16x16x32_bf16 v[80:83], v[160:163], v[210:213], v[80:83]
	v_mfma_f32_16x16x32_bf16 v[108:111], v[164:167], v[180:183], v[108:111]
	v_mfma_f32_16x16x32_bf16 v[104:107], v[172:175], v[180:183], v[104:107]
	v_mfma_f32_16x16x32_bf16 v[92:95], v[164:167], v[188:191], v[92:95]
	v_mfma_f32_16x16x32_bf16 v[88:91], v[172:175], v[188:191], v[88:91]
	v_mfma_f32_16x16x32_bf16 v[76:79], v[164:167], v[196:199], v[76:79]
	v_mfma_f32_16x16x32_bf16 v[72:75], v[172:175], v[196:199], v[72:75]
	v_mfma_f32_16x16x32_bf16 v[68:71], v[164:167], v[206:209], v[68:71]
	v_mfma_f32_16x16x32_bf16 v[64:67], v[172:175], v[206:209], v[64:67]
	v_mfma_f32_16x16x32_bf16 v[108:111], v[168:171], v[184:187], v[108:111]
	v_mfma_f32_16x16x32_bf16 v[104:107], v[176:179], v[184:187], v[104:107]
	v_mfma_f32_16x16x32_bf16 v[92:95], v[168:171], v[192:195], v[92:95]
	v_mfma_f32_16x16x32_bf16 v[88:91], v[176:179], v[192:195], v[88:91]
	v_mfma_f32_16x16x32_bf16 v[76:79], v[168:171], v[200:203], v[76:79]
	v_mfma_f32_16x16x32_bf16 v[72:75], v[176:179], v[200:203], v[72:75]
	v_mfma_f32_16x16x32_bf16 v[68:71], v[168:171], v[210:213], v[68:71]
	v_mfma_f32_16x16x32_bf16 v[64:67], v[176:179], v[210:213], v[64:67]
	s_barrier
	s_mov_b64 s[58:59], s[94:95]
	s_mov_b32 m0, s11
	ds_read_b128 v[180:183], v159 offset:16384
	ds_read_b128 v[184:187], v159 offset:17408
	ds_read_b128 v[188:191], v159 offset:18432
	ds_read_b128 v[192:195], v159 offset:19456
	ds_read_b128 v[196:199], v159 offset:20480
	ds_read_b128 v[200:203], v159 offset:21504
	ds_read_b128 v[206:209], v159 offset:22528
	ds_read_b128 v[210:213], v159 offset:23552
	s_nop 0
	v_lshl_add_u64 v[152:153], s[58:59], 0, v[130:131]
	global_load_lds_dwordx4 v[152:153], off
	v_lshl_add_u64 v[152:153], s[58:59], 0, v[134:135]
	s_cselect_b32 s59, s91, vcc_hi
	s_cselect_b32 s58, s90, vcc_lo
	s_add_u32 s94, s94, 0x80000
	s_mov_b32 m0, s78
	s_addc_u32 s95, s95, 0
	s_add_i32 s1, s81, s61
	global_load_lds_dwordx4 v[152:153], off
	s_mov_b32 m0, s1
	v_lshl_add_u64 v[152:153], s[94:95], 0, v[130:131]
	global_load_lds_dwordx4 v[152:153], off
	v_lshl_add_u64 v[152:153], s[94:95], 0, v[134:135]
	s_add_i32 m0, s1, 0x2000
	s_mov_b64 s[94:95], s[56:57]
	global_load_lds_dwordx4 v[152:153], off
	s_mov_b32 m0, s10
	v_lshl_add_u64 v[152:153], s[94:95], 0, v[128:129]
	global_load_lds_dwordx4 v[152:153], off
	v_lshl_add_u64 v[152:153], s[94:95], 0, v[132:133]
	s_mov_b32 m0, s69
	s_nop 0
	global_load_lds_dwordx4 v[152:153], off
	s_waitcnt vmcnt(8)
	s_waitcnt lgkmcnt(0)
	s_barrier
; #define PG8_STAGE(bufoff, gbase, voff) do { const char* _gb = (const char*)(gbase); asm volatile("" : "+s"(_gb));     \
;         _Pragma("unroll") for (int _i = 0; _i < 2; ++_i) \
;         __builtin_amdgcn_global_load_lds((const unsigned*)(_gb + (voff)[_i]), (LAS unsigned*)(lds + (bufoff) + ldsw + _i * 8192), 16, 0, 0); } while (0)
; #define PG8_LDA(dst, b, h) do { _Pragma("unroll") for (int m = 0; m < 4; ++m) _Pragma("unroll") for (int k = 0; k < 2; ++k) dst[m][k] = *(const LAS bf16x8*)(lds + PG8_SA(b, h) + aoff + m * 2048 + k * 1024); } while (0)
; #define PG8_LDB(dst, b, h) do { _Pragma("unroll") for (int n = 0; n < 2; ++n) _Pragma("unroll") for (int k = 0; k < 2; ++k) dst[n][k] = *(const LAS bf16x8*)(lds + PG8_SB(b, h) + boff + n * 2048 + k * 1024); } while (0)
; #define PG8_MMA(ai, bj, At, Bt) do { __builtin_amdgcn_s_setprio(1); _Pragma("unroll") for (int m = 0; m < 4; ++m) _Pragma("unroll") for (int n = 0; n < 2; ++n) _Pragma("unroll") for (int k = 0; k < 2; ++k) \
;         acc[ai][bj][m][n] = __builtin_amdgcn_mfma_f32_16x16x32_bf16(Bt[n][k], At[m][k], acc[ai][bj][m][n], 0, 0, 0); __builtin_amdgcn_s_setprio(0); } while (0)
; #define PG8_WAIT_V(n) asm volatile("s_waitcnt vmcnt(" #n ")" ::: "memory")
; #define PG8_WAIT_L(n) asm volatile("s_waitcnt lgkmcnt(" #n ")" ::: "memory")
; #define PG8_BAR __builtin_amdgcn_s_barrier()
; #define PG8_SCHED __builtin_amdgcn_sched_barrier(0)
; template <class Epi>
; __device__ __forceinline__ void gemm_phase(LAS unsigned char* lds, const int wid, const Gemm g, const Epi& E) {
;     ...
;             PG8_WAIT_V(8); PG8_WAIT_L(0); PG8_BAR; PG8_MMA(1, 0, At, B0); PG8_MMA(1, 1, At, B1); PG8_BAR; PG8_SCHED;
;             PG8_LDB(B0, 1, 0); PG8_LDB(B1, 1, 1); PG8_SCHED; PG8_LDA(At, 1, 0); PG8_STAGE(PG8_SA(0, 1), a2 + hstepA, voffA);
;             PG8_WAIT_V(8); PG8_WAIT_L(0); PG8_BAR; PG8_MMA(0, 0, At, B0); PG8_MMA(0, 1, At, B1); PG8_BAR; PG8_SCHED;
	s_waitcnt lgkmcnt(0)
	v_mfma_f32_16x16x32_bf16 v[60:63], v[140:143], v[180:183], v[60:63]
	v_mfma_f32_16x16x32_bf16 v[56:59], v[148:151], v[180:183], v[56:59]
	v_mfma_f32_16x16x32_bf16 v[52:55], v[140:143], v[188:191], v[52:55]
	v_mfma_f32_16x16x32_bf16 v[48:51], v[148:151], v[188:191], v[48:51]
	v_mfma_f32_16x16x32_bf16 v[36:39], v[140:143], v[196:199], v[36:39]
	v_mfma_f32_16x16x32_bf16 v[32:35], v[148:151], v[196:199], v[32:35]
	v_mfma_f32_16x16x32_bf16 v[20:23], v[140:143], v[206:209], v[20:23]
	v_mfma_f32_16x16x32_bf16 v[16:19], v[148:151], v[206:209], v[16:19]
	v_mfma_f32_16x16x32_bf16 v[60:63], v[144:147], v[184:187], v[60:63]
	v_mfma_f32_16x16x32_bf16 v[56:59], v[160:163], v[184:187], v[56:59]
	v_mfma_f32_16x16x32_bf16 v[52:55], v[144:147], v[192:195], v[52:55]
	v_mfma_f32_16x16x32_bf16 v[48:51], v[160:163], v[192:195], v[48:51]
	v_mfma_f32_16x16x32_bf16 v[36:39], v[144:147], v[200:203], v[36:39]
	v_mfma_f32_16x16x32_bf16 v[32:35], v[160:163], v[200:203], v[32:35]
	v_mfma_f32_16x16x32_bf16 v[20:23], v[144:147], v[210:213], v[20:23]
	v_mfma_f32_16x16x32_bf16 v[16:19], v[160:163], v[210:213], v[16:19]
	v_mfma_f32_16x16x32_bf16 v[44:47], v[164:167], v[180:183], v[44:47]
	v_mfma_f32_16x16x32_bf16 v[40:43], v[172:175], v[180:183], v[40:43]
	v_mfma_f32_16x16x32_bf16 v[28:31], v[164:167], v[188:191], v[28:31]
	v_mfma_f32_16x16x32_bf16 v[24:27], v[172:175], v[188:191], v[24:27]
	v_mfma_f32_16x16x32_bf16 v[12:15], v[164:167], v[196:199], v[12:15]
	v_mfma_f32_16x16x32_bf16 v[8:11], v[172:175], v[196:199], v[8:11]
	v_mfma_f32_16x16x32_bf16 v[4:7], v[164:167], v[206:209], v[4:7]
	v_mfma_f32_16x16x32_bf16 v[0:3], v[172:175], v[206:209], v[0:3]
	v_mfma_f32_16x16x32_bf16 v[44:47], v[168:171], v[184:187], v[44:47]
	v_mfma_f32_16x16x32_bf16 v[40:43], v[176:179], v[184:187], v[40:43]
	v_mfma_f32_16x16x32_bf16 v[28:31], v[168:171], v[192:195], v[28:31]
	v_mfma_f32_16x16x32_bf16 v[24:27], v[176:179], v[192:195], v[24:27]
	v_mfma_f32_16x16x32_bf16 v[12:15], v[168:171], v[200:203], v[12:15]
	v_mfma_f32_16x16x32_bf16 v[8:11], v[176:179], v[200:203], v[8:11]
	v_mfma_f32_16x16x32_bf16 v[4:7], v[168:171], v[210:213], v[4:7]
	v_mfma_f32_16x16x32_bf16 v[0:3], v[176:179], v[210:213], v[0:3]
	s_barrier
	s_add_i32 s1, 0, 0x18000
	v_add_u32_e32 v152, s1, v156
	s_add_i32 s11, 0, 0x1c000
	ds_read_b128 v[140:143], v152
	ds_read_b128 v[144:147], v152 offset:1024
	ds_read_b128 v[148:151], v152 offset:2048
	ds_read_b128 v[160:163], v152 offset:3072
	v_add_u32_e32 v152, s11, v156
	ds_read_b128 v[164:167], v152
	ds_read_b128 v[168:171], v152 offset:1024
	ds_read_b128 v[172:175], v152 offset:2048
	ds_read_b128 v[176:179], v152 offset:3072
	s_add_u32 s56, s56, 0x40000
	s_addc_u32 s57, s57, 0
	s_mov_b32 m0, s70
	ds_read_b128 v[180:183], v159 offset:32768
	ds_read_b128 v[184:187], v159 offset:33792
	ds_read_b128 v[188:191], v159 offset:34816
	ds_read_b128 v[192:195], v159 offset:35840
	ds_read_b128 v[196:199], v159 offset:36864
	ds_read_b128 v[200:203], v159 offset:37888
	ds_read_b128 v[206:209], v159 offset:38912
	ds_read_b128 v[210:213], v159 offset:39936
	s_nop 0
	v_lshl_add_u64 v[152:153], s[56:57], 0, v[128:129]
	global_load_lds_dwordx4 v[152:153], off
	v_lshl_add_u64 v[152:153], s[56:57], 0, v[132:133]
	s_mov_b32 m0, s71
	s_nop 0
	global_load_lds_dwordx4 v[152:153], off
	s_waitcnt vmcnt(8)
	s_waitcnt lgkmcnt(0)
	s_barrier
	s_waitcnt lgkmcnt(0)
	v_mfma_f32_16x16x32_bf16 v[124:127], v[140:143], v[180:183], v[124:127]
	v_mfma_f32_16x16x32_bf16 v[120:123], v[148:151], v[180:183], v[120:123]
	v_mfma_f32_16x16x32_bf16 v[116:119], v[140:143], v[188:191], v[116:119]
	v_mfma_f32_16x16x32_bf16 v[112:115], v[148:151], v[188:191], v[112:115]
	v_mfma_f32_16x16x32_bf16 v[100:103], v[140:143], v[196:199], v[100:103]
	v_mfma_f32_16x16x32_bf16 v[96:99], v[148:151], v[196:199], v[96:99]
	v_mfma_f32_16x16x32_bf16 v[84:87], v[140:143], v[206:209], v[84:87]
	v_mfma_f32_16x16x32_bf16 v[80:83], v[148:151], v[206:209], v[80:83]
	v_mfma_f32_16x16x32_bf16 v[124:127], v[144:147], v[184:187], v[124:127]
	v_mfma_f32_16x16x32_bf16 v[120:123], v[160:163], v[184:187], v[120:123]
	v_mfma_f32_16x16x32_bf16 v[116:119], v[144:147], v[192:195], v[116:119]
	v_mfma_f32_16x16x32_bf16 v[112:115], v[160:163], v[192:195], v[112:115]
	v_mfma_f32_16x16x32_bf16 v[100:103], v[144:147], v[200:203], v[100:103]
	v_mfma_f32_16x16x32_bf16 v[96:99], v[160:163], v[200:203], v[96:99]
	v_mfma_f32_16x16x32_bf16 v[84:87], v[144:147], v[210:213], v[84:87]
	v_mfma_f32_16x16x32_bf16 v[80:83], v[160:163], v[210:213], v[80:83]
	v_mfma_f32_16x16x32_bf16 v[108:111], v[164:167], v[180:183], v[108:111]
	v_mfma_f32_16x16x32_bf16 v[104:107], v[172:175], v[180:183], v[104:107]
	v_mfma_f32_16x16x32_bf16 v[92:95], v[164:167], v[188:191], v[92:95]
	v_mfma_f32_16x16x32_bf16 v[88:91], v[172:175], v[188:191], v[88:91]
	v_mfma_f32_16x16x32_bf16 v[76:79], v[164:167], v[196:199], v[76:79]
	v_mfma_f32_16x16x32_bf16 v[72:75], v[172:175], v[196:199], v[72:75]
	v_mfma_f32_16x16x32_bf16 v[68:71], v[164:167], v[206:209], v[68:71]
	v_mfma_f32_16x16x32_bf16 v[64:67], v[172:175], v[206:209], v[64:67]
	v_mfma_f32_16x16x32_bf16 v[108:111], v[168:171], v[184:187], v[108:111]
	v_mfma_f32_16x16x32_bf16 v[104:107], v[176:179], v[184:187], v[104:107]
	v_mfma_f32_16x16x32_bf16 v[92:95], v[168:171], v[192:195], v[92:95]
	v_mfma_f32_16x16x32_bf16 v[88:91], v[176:179], v[192:195], v[88:91]
	v_mfma_f32_16x16x32_bf16 v[76:79], v[168:171], v[200:203], v[76:79]
	v_mfma_f32_16x16x32_bf16 v[72:75], v[176:179], v[200:203], v[72:75]
	v_mfma_f32_16x16x32_bf16 v[68:71], v[168:171], v[210:213], v[68:71]
	v_mfma_f32_16x16x32_bf16 v[64:67], v[176:179], v[210:213], v[64:67]
	s_barrier
; #define PG8_STAGE(bufoff, gbase, voff) do { const char* _gb = (const char*)(gbase); asm volatile("" : "+s"(_gb));     \
;         _Pragma("unroll") for (int _i = 0; _i < 2; ++_i) \
;         __builtin_amdgcn_global_load_lds((const unsigned*)(_gb + (voff)[_i]), (LAS unsigned*)(lds + (bufoff) + ldsw + _i * 8192), 16, 0, 0); } while (0)
; #define PG8_LDA(dst, b, h) do { _Pragma("unroll") for (int m = 0; m < 4; ++m) _Pragma("unroll") for (int k = 0; k < 2; ++k) dst[m][k] = *(const LAS bf16x8*)(lds + PG8_SA(b, h) + aoff + m * 2048 + k * 1024); } while (0)
; #define PG8_MMA(ai, bj, At, Bt) do { __builtin_amdgcn_s_setprio(1); _Pragma("unroll") for (int m = 0; m < 4; ++m) _Pragma("unroll") for (int n = 0; n < 2; ++n) _Pragma("unroll") for (int k = 0; k < 2; ++k) \
;         acc[ai][bj][m][n] = __builtin_amdgcn_mfma_f32_16x16x32_bf16(Bt[n][k], At[m][k], acc[ai][bj][m][n], 0, 0, 0); __builtin_amdgcn_s_setprio(0); } while (0)
; #define PG8_WAIT_V(n) asm volatile("s_waitcnt vmcnt(" #n ")" ::: "memory")
; #define PG8_WAIT_L(n) asm volatile("s_waitcnt lgkmcnt(" #n ")" ::: "memory")
; #define PG8_BAR __builtin_amdgcn_s_barrier()
; #define PG8_SCHED __builtin_amdgcn_sched_barrier(0)
; template <class Epi>
; __device__ __forceinline__ void gemm_phase(LAS unsigned char* lds, const int wid, const Gemm g, const Epi& E) {
;     ...
;             PG8_LDA(At, 1, 1); PG8_STAGE(PG8_SB(1, 0), b3, voffB); PG8_STAGE(PG8_SB(1, 1), b3 + hstepB, voffB); PG8_STAGE(PG8_SA(1, 0), a3, voffA);
;             PG8_WAIT_V(8); PG8_WAIT_L(0); PG8_BAR; PG8_MMA(1, 0, At, B0); PG8_MMA(1, 1, At, B1); PG8_BAR; PG8_SCHED;
;         }
;         if (wr == 0) PG8_BAR;
	s_mov_b64 s[56:57], s[58:59]
	s_add_i32 s1, s1, s61
	ds_read_b128 v[180:183], v159 offset:49152
	ds_read_b128 v[184:187], v159 offset:50176
	ds_read_b128 v[188:191], v159 offset:51200
	ds_read_b128 v[192:195], v159 offset:52224
	ds_read_b128 v[196:199], v159 offset:53248
	ds_read_b128 v[200:203], v159 offset:54272
	ds_read_b128 v[206:209], v159 offset:55296
	ds_read_b128 v[210:213], v159 offset:56320
	s_mov_b32 m0, s1
	v_lshl_add_u64 v[152:153], s[56:57], 0, v[130:131]
	global_load_lds_dwordx4 v[152:153], off
	s_add_i32 m0, s1, 0x2000
	v_lshl_add_u64 v[152:153], s[56:57], 0, v[134:135]
	s_add_u32 s56, s58, 0x80000
	s_addc_u32 s57, s59, 0
	s_add_i32 s1, s11, s61
	global_load_lds_dwordx4 v[152:153], off
	s_mov_b32 m0, s1
	v_lshl_add_u64 v[152:153], s[56:57], 0, v[130:131]
	global_load_lds_dwordx4 v[152:153], off
	v_lshl_add_u64 v[152:153], s[56:57], 0, v[134:135]
	s_add_i32 m0, s1, 0x2000
	s_nop 0
	global_load_lds_dwordx4 v[152:153], off
	s_mov_b32 m0, s75
	v_lshl_add_u64 v[152:153], s[54:55], 0, v[128:129]
	global_load_lds_dwordx4 v[152:153], off
	v_lshl_add_u64 v[152:153], s[54:55], 0, v[132:133]
	s_mov_b32 m0, s76
	s_nop 0
	global_load_lds_dwordx4 v[152:153], off
	s_waitcnt vmcnt(8)
	s_waitcnt lgkmcnt(0)
	s_barrier
	s_waitcnt lgkmcnt(0)
	v_mfma_f32_16x16x32_bf16 v[60:63], v[140:143], v[180:183], v[60:63]
	v_mfma_f32_16x16x32_bf16 v[56:59], v[148:151], v[180:183], v[56:59]
	v_mfma_f32_16x16x32_bf16 v[52:55], v[140:143], v[188:191], v[52:55]
	v_mfma_f32_16x16x32_bf16 v[48:51], v[148:151], v[188:191], v[48:51]
	v_mfma_f32_16x16x32_bf16 v[36:39], v[140:143], v[196:199], v[36:39]
	v_mfma_f32_16x16x32_bf16 v[32:35], v[148:151], v[196:199], v[32:35]
	v_mfma_f32_16x16x32_bf16 v[20:23], v[140:143], v[206:209], v[20:23]
	v_mfma_f32_16x16x32_bf16 v[16:19], v[148:151], v[206:209], v[16:19]
	v_mfma_f32_16x16x32_bf16 v[60:63], v[144:147], v[184:187], v[60:63]
	v_mfma_f32_16x16x32_bf16 v[56:59], v[160:163], v[184:187], v[56:59]
	v_mfma_f32_16x16x32_bf16 v[52:55], v[144:147], v[192:195], v[52:55]
	v_mfma_f32_16x16x32_bf16 v[48:51], v[160:163], v[192:195], v[48:51]
	v_mfma_f32_16x16x32_bf16 v[36:39], v[144:147], v[200:203], v[36:39]
	v_mfma_f32_16x16x32_bf16 v[32:35], v[160:163], v[200:203], v[32:35]
	v_mfma_f32_16x16x32_bf16 v[20:23], v[144:147], v[210:213], v[20:23]
	v_mfma_f32_16x16x32_bf16 v[16:19], v[160:163], v[210:213], v[16:19]
	v_mfma_f32_16x16x32_bf16 v[44:47], v[164:167], v[180:183], v[44:47]
	v_mfma_f32_16x16x32_bf16 v[40:43], v[172:175], v[180:183], v[40:43]
	v_mfma_f32_16x16x32_bf16 v[28:31], v[164:167], v[188:191], v[28:31]
	v_mfma_f32_16x16x32_bf16 v[24:27], v[172:175], v[188:191], v[24:27]
	v_mfma_f32_16x16x32_bf16 v[12:15], v[164:167], v[196:199], v[12:15]
	v_mfma_f32_16x16x32_bf16 v[8:11], v[172:175], v[196:199], v[8:11]
	v_mfma_f32_16x16x32_bf16 v[4:7], v[164:167], v[206:209], v[4:7]
	v_mfma_f32_16x16x32_bf16 v[0:3], v[172:175], v[206:209], v[0:3]
	v_mfma_f32_16x16x32_bf16 v[44:47], v[168:171], v[184:187], v[44:47]
	v_mfma_f32_16x16x32_bf16 v[40:43], v[176:179], v[184:187], v[40:43]
	v_mfma_f32_16x16x32_bf16 v[28:31], v[168:171], v[192:195], v[28:31]
	v_mfma_f32_16x16x32_bf16 v[24:27], v[176:179], v[192:195], v[24:27]
	v_mfma_f32_16x16x32_bf16 v[12:15], v[168:171], v[200:203], v[12:15]
	v_mfma_f32_16x16x32_bf16 v[8:11], v[176:179], v[200:203], v[8:11]
	v_mfma_f32_16x16x32_bf16 v[4:7], v[168:171], v[210:213], v[4:7]
	v_mfma_f32_16x16x32_bf16 v[0:3], v[176:179], v[210:213], v[0:3]
	s_barrier
	s_add_u32 s6, s6, 0x100
	s_addc_u32 s7, s7, 0
	s_cmp_gt_u32 s92, 29
	s_cbranch_scc0 .LBB0_952
	s_and_b64 vcc, exec, s[12:13]
	s_cbranch_vccz .LBB0_955
	s_barrier

; #define PG8_STAGE(bufoff, gbase, voff) do { const char* _gb = (const char*)(gbase); asm volatile("" : "+s"(_gb));     \
;         _Pragma("unroll") for (int _i = 0; _i < 2; ++_i) \
;         __builtin_amdgcn_global_load_lds((const unsigned*)(_gb + (voff)[_i]), (LAS unsigned*)(lds + (bufoff) + ldsw + _i * 8192), 16, 0, 0); } while (0)
; #define PG8_LDA(dst, b, h) do { _Pragma("unroll") for (int m = 0; m < 4; ++m) _Pragma("unroll") for (int k = 0; k < 2; ++k) dst[m][k] = *(const LAS bf16x8*)(lds + PG8_SA(b, h) + aoff + m * 2048 + k * 1024); } while (0)
; #define PG8_LDB(dst, b, h) do { _Pragma("unroll") for (int n = 0; n < 2; ++n) _Pragma("unroll") for (int k = 0; k < 2; ++k) dst[n][k] = *(const LAS bf16x8*)(lds + PG8_SB(b, h) + boff + n * 2048 + k * 1024); } while (0)
; #define PG8_MMA(ai, bj, At, Bt) do { __builtin_amdgcn_s_setprio(1); _Pragma("unroll") for (int m = 0; m < 4; ++m) _Pragma("unroll") for (int n = 0; n < 2; ++n) _Pragma("unroll") for (int k = 0; k < 2; ++k) \
;         acc[ai][bj][m][n] = __builtin_amdgcn_mfma_f32_16x16x32_bf16(Bt[n][k], At[m][k], acc[ai][bj][m][n], 0, 0, 0); __builtin_amdgcn_s_setprio(0); } while (0)
; #define PG8_WAIT_V(n) asm volatile("s_waitcnt vmcnt(" #n ")" ::: "memory")
; #define PG8_WAIT_L(n) asm volatile("s_waitcnt lgkmcnt(" #n ")" ::: "memory")
; #define PG8_BAR __builtin_amdgcn_s_barrier()
; #define PG8_SCHED __builtin_amdgcn_sched_barrier(0)
; template <class Epi>
; __device__ __forceinline__ void gemm_phase(LAS unsigned char* lds, const int wid, const Gemm g, const Epi& E) {
;     ...
;         for (int t = 0; t < nt; t += 2) {
;             const bool last = (t == nt - 2);
;             const char* a1 = PG8_AP(cA, t + 1);
;             const char* a2 = last ? PG8_AP(nA, 0) : PG8_AP(cA, t + 2); const char* b2 = last ? PG8_BP(nB, 0) : PG8_BP(cB, t + 2);
;             const char* a3 = last ? PG8_AP(nA, 1) : PG8_AP(cA, t + 3); const char* b3 = last ? PG8_BP(nB, 1) : PG8_BP(cB, t + 3);
;             PG8_LDB(B0, 0, 0); PG8_LDB(B1, 0, 1); PG8_SCHED; PG8_LDA(At, 0, 0); PG8_STAGE(PG8_SA(1, 1), a1 + hstepA, voffA);
;             PG8_WAIT_V(8); PG8_WAIT_L(0); PG8_BAR; PG8_MMA(0, 0, At, B0); PG8_MMA(0, 1, At, B1); PG8_BAR; PG8_SCHED;
;             PG8_LDA(At, 0, 1); PG8_STAGE(PG8_SB(0, 0), b2, voffB); PG8_STAGE(PG8_SB(0, 1), b2 + hstepB, voffB); PG8_STAGE(PG8_SA(0, 0), a2, voffA);
.LBB0_1125:
	ds_read_b128 v[104:107], v163
	ds_read_b128 v[108:111], v163 offset:1024
	ds_read_b128 v[148:151], v163 offset:2048
	ds_read_b128 v[152:155], v163 offset:3072
	ds_read_b128 v[156:159], v164
	ds_read_b128 v[168:171], v164 offset:1024
	ds_read_b128 v[172:175], v164 offset:2048
	ds_read_b128 v[176:179], v164 offset:3072
	s_add_u32 s0, s4, 0xfffe0080
	s_addc_u32 s1, s5, -1
	s_add_u32 s40, s74, 0xffffff80
	s_addc_u32 s41, s75, -1
	s_add_u32 s44, s4, 0xfffe0100
	s_addc_u32 s45, s5, -1
	s_add_i32 s80, s64, s47
	s_add_i32 m0, s52, 0xc000
	s_add_i32 s77, s52, 0xe000
	s_add_i32 s81, s80, 0x2000
	s_cmp_eq_u32 s76, 2
	s_cselect_b32 s43, s29, s1
	s_cselect_b32 s42, s39, s0
	s_cselect_b32 s79, s31, s41
	s_cselect_b32 s78, s30, s40
	s_cselect_b32 s41, s71, s45
	s_cselect_b32 s40, s70, s44
	s_mov_b64 s[44:45], s[4:5]
	ds_read_b128 v[180:183], v165
	ds_read_b128 v[184:187], v165 offset:1024
	ds_read_b128 v[188:191], v165 offset:2048
	ds_read_b128 v[192:195], v165 offset:3072
	ds_read_b128 v[196:199], v165 offset:4096
	ds_read_b128 v[200:203], v165 offset:5120
	ds_read_b128 v[206:209], v165 offset:6144
	ds_read_b128 v[210:213], v165 offset:7168
	s_nop 0
	v_lshl_add_u64 v[204:205], s[44:45], 0, v[136:137]
	global_load_lds_dwordx4 v[204:205], off
	v_lshl_add_u64 v[204:205], s[44:45], 0, v[140:141]
	s_mov_b32 m0, s77
	s_nop 0
	global_load_lds_dwordx4 v[204:205], off
	s_waitcnt vmcnt(8)
	s_waitcnt lgkmcnt(0)
	s_barrier
	s_waitcnt lgkmcnt(0)
	v_mfma_f32_16x16x32_bf16 v[132:135], v[104:107], v[180:183], v[132:135]
	v_mfma_f32_16x16x32_bf16 v[128:131], v[148:151], v[180:183], v[128:131]
	v_mfma_f32_16x16x32_bf16 v[124:127], v[104:107], v[188:191], v[124:127]
	v_mfma_f32_16x16x32_bf16 v[120:123], v[148:151], v[188:191], v[120:123]
	v_mfma_f32_16x16x32_bf16 v[116:119], v[104:107], v[196:199], v[116:119]
	v_mfma_f32_16x16x32_bf16 v[112:115], v[148:151], v[196:199], v[112:115]
	v_mfma_f32_16x16x32_bf16 v[100:103], v[104:107], v[206:209], v[100:103]
	v_mfma_f32_16x16x32_bf16 v[96:99], v[148:151], v[206:209], v[96:99]
	v_mfma_f32_16x16x32_bf16 v[132:135], v[108:111], v[184:187], v[132:135]
	v_mfma_f32_16x16x32_bf16 v[128:131], v[152:155], v[184:187], v[128:131]
	v_mfma_f32_16x16x32_bf16 v[124:127], v[108:111], v[192:195], v[124:127]
	v_mfma_f32_16x16x32_bf16 v[120:123], v[152:155], v[192:195], v[120:123]
	v_mfma_f32_16x16x32_bf16 v[116:119], v[108:111], v[200:203], v[116:119]
	v_mfma_f32_16x16x32_bf16 v[112:115], v[152:155], v[200:203], v[112:115]
	v_mfma_f32_16x16x32_bf16 v[100:103], v[108:111], v[210:213], v[100:103]
	v_mfma_f32_16x16x32_bf16 v[96:99], v[152:155], v[210:213], v[96:99]
	v_mfma_f32_16x16x32_bf16 v[60:63], v[156:159], v[180:183], v[60:63]
	v_mfma_f32_16x16x32_bf16 v[56:59], v[172:175], v[180:183], v[56:59]
	v_mfma_f32_16x16x32_bf16 v[52:55], v[156:159], v[188:191], v[52:55]
	v_mfma_f32_16x16x32_bf16 v[48:51], v[172:175], v[188:191], v[48:51]
	v_mfma_f32_16x16x32_bf16 v[44:47], v[156:159], v[196:199], v[44:47]
	v_mfma_f32_16x16x32_bf16 v[40:43], v[172:175], v[196:199], v[40:43]
	v_mfma_f32_16x16x32_bf16 v[36:39], v[156:159], v[206:209], v[36:39]
	v_mfma_f32_16x16x32_bf16 v[32:35], v[172:175], v[206:209], v[32:35]
	v_mfma_f32_16x16x32_bf16 v[60:63], v[168:171], v[184:187], v[60:63]
	v_mfma_f32_16x16x32_bf16 v[56:59], v[176:179], v[184:187], v[56:59]
	v_mfma_f32_16x16x32_bf16 v[52:55], v[168:171], v[192:195], v[52:55]
	v_mfma_f32_16x16x32_bf16 v[48:51], v[176:179], v[192:195], v[48:51]
	v_mfma_f32_16x16x32_bf16 v[44:47], v[168:171], v[200:203], v[44:47]
	v_mfma_f32_16x16x32_bf16 v[40:43], v[176:179], v[200:203], v[40:43]
	v_mfma_f32_16x16x32_bf16 v[36:39], v[168:171], v[210:213], v[36:39]
	v_mfma_f32_16x16x32_bf16 v[32:35], v[176:179], v[210:213], v[32:35]
	s_barrier
	s_mov_b64 s[44:45], s[78:79]
	s_mov_b32 m0, s80
	ds_read_b128 v[180:183], v165 offset:16384
	ds_read_b128 v[184:187], v165 offset:17408
	ds_read_b128 v[188:191], v165 offset:18432
	ds_read_b128 v[192:195], v165 offset:19456
	ds_read_b128 v[196:199], v165 offset:20480
	ds_read_b128 v[200:203], v165 offset:21504
	ds_read_b128 v[206:209], v165 offset:22528
	ds_read_b128 v[210:213], v165 offset:23552
	s_nop 0
	v_lshl_add_u64 v[204:205], s[44:45], 0, v[138:139]
	global_load_lds_dwordx4 v[204:205], off
	v_lshl_add_u64 v[204:205], s[44:45], 0, v[142:143]
	s_cselect_b32 s45, s73, s75
	s_cselect_b32 s44, s72, s74
	s_add_u32 s78, s78, 0x18000
	s_mov_b32 m0, s81
	s_addc_u32 s79, s79, 0
	s_add_i32 s0, s65, s47
	global_load_lds_dwordx4 v[204:205], off
	s_mov_b32 m0, s0
	v_lshl_add_u64 v[204:205], s[78:79], 0, v[138:139]
	global_load_lds_dwordx4 v[204:205], off
	v_lshl_add_u64 v[204:205], s[78:79], 0, v[142:143]
	s_add_i32 m0, s0, 0x2000
	s_mov_b64 s[78:79], s[42:43]
	global_load_lds_dwordx4 v[204:205], off
	s_mov_b32 m0, s52
	v_lshl_add_u64 v[204:205], s[78:79], 0, v[136:137]
	global_load_lds_dwordx4 v[204:205], off
	v_lshl_add_u64 v[204:205], s[78:79], 0, v[140:141]
	s_mov_b32 m0, s53
	s_nop 0
	global_load_lds_dwordx4 v[204:205], off
	s_waitcnt vmcnt(8)
	s_waitcnt lgkmcnt(0)
	s_barrier
; #define PG8_STAGE(bufoff, gbase, voff) do { const char* _gb = (const char*)(gbase); asm volatile("" : "+s"(_gb));     \
;         _Pragma("unroll") for (int _i = 0; _i < 2; ++_i) \
;         __builtin_amdgcn_global_load_lds((const unsigned*)(_gb + (voff)[_i]), (LAS unsigned*)(lds + (bufoff) + ldsw + _i * 8192), 16, 0, 0); } while (0)
; #define PG8_LDA(dst, b, h) do { _Pragma("unroll") for (int m = 0; m < 4; ++m) _Pragma("unroll") for (int k = 0; k < 2; ++k) dst[m][k] = *(const LAS bf16x8*)(lds + PG8_SA(b, h) + aoff + m * 2048 + k * 1024); } while (0)
; #define PG8_LDB(dst, b, h) do { _Pragma("unroll") for (int n = 0; n < 2; ++n) _Pragma("unroll") for (int k = 0; k < 2; ++k) dst[n][k] = *(const LAS bf16x8*)(lds + PG8_SB(b, h) + boff + n * 2048 + k * 1024); } while (0)
; #define PG8_MMA(ai, bj, At, Bt) do { __builtin_amdgcn_s_setprio(1); _Pragma("unroll") for (int m = 0; m < 4; ++m) _Pragma("unroll") for (int n = 0; n < 2; ++n) _Pragma("unroll") for (int k = 0; k < 2; ++k) \
;         acc[ai][bj][m][n] = __builtin_amdgcn_mfma_f32_16x16x32_bf16(Bt[n][k], At[m][k], acc[ai][bj][m][n], 0, 0, 0); __builtin_amdgcn_s_setprio(0); } while (0)
; #define PG8_WAIT_V(n) asm volatile("s_waitcnt vmcnt(" #n ")" ::: "memory")
; #define PG8_WAIT_L(n) asm volatile("s_waitcnt lgkmcnt(" #n ")" ::: "memory")
; #define PG8_BAR __builtin_amdgcn_s_barrier()
; #define PG8_SCHED __builtin_amdgcn_sched_barrier(0)
; template <class Epi>
; __device__ __forceinline__ void gemm_phase(LAS unsigned char* lds, const int wid, const Gemm g, const Epi& E) {
;     ...
;             PG8_WAIT_V(8); PG8_WAIT_L(0); PG8_BAR; PG8_MMA(1, 0, At, B0); PG8_MMA(1, 1, At, B1); PG8_BAR; PG8_SCHED;
;             PG8_LDB(B0, 1, 0); PG8_LDB(B1, 1, 1); PG8_SCHED; PG8_LDA(At, 1, 0); PG8_STAGE(PG8_SA(0, 1), a2 + hstepA, voffA);
;             PG8_WAIT_V(8); PG8_WAIT_L(0); PG8_BAR; PG8_MMA(0, 0, At, B0); PG8_MMA(0, 1, At, B1); PG8_BAR; PG8_SCHED;
	s_waitcnt lgkmcnt(0)
	v_mfma_f32_16x16x32_bf16 v[92:95], v[104:107], v[180:183], v[92:95]
	v_mfma_f32_16x16x32_bf16 v[88:91], v[148:151], v[180:183], v[88:91]
	v_mfma_f32_16x16x32_bf16 v[84:87], v[104:107], v[188:191], v[84:87]
	v_mfma_f32_16x16x32_bf16 v[80:83], v[148:151], v[188:191], v[80:83]
	v_mfma_f32_16x16x32_bf16 v[76:79], v[104:107], v[196:199], v[76:79]
	v_mfma_f32_16x16x32_bf16 v[72:75], v[148:151], v[196:199], v[72:75]
	v_mfma_f32_16x16x32_bf16 v[68:71], v[104:107], v[206:209], v[68:71]
	v_mfma_f32_16x16x32_bf16 v[64:67], v[148:151], v[206:209], v[64:67]
	v_mfma_f32_16x16x32_bf16 v[92:95], v[108:111], v[184:187], v[92:95]
	v_mfma_f32_16x16x32_bf16 v[88:91], v[152:155], v[184:187], v[88:91]
	v_mfma_f32_16x16x32_bf16 v[84:87], v[108:111], v[192:195], v[84:87]
	v_mfma_f32_16x16x32_bf16 v[80:83], v[152:155], v[192:195], v[80:83]
	v_mfma_f32_16x16x32_bf16 v[76:79], v[108:111], v[200:203], v[76:79]
	v_mfma_f32_16x16x32_bf16 v[72:75], v[152:155], v[200:203], v[72:75]
	v_mfma_f32_16x16x32_bf16 v[68:71], v[108:111], v[210:213], v[68:71]
	v_mfma_f32_16x16x32_bf16 v[64:67], v[152:155], v[210:213], v[64:67]
	v_mfma_f32_16x16x32_bf16 v[28:31], v[156:159], v[180:183], v[28:31]
	v_mfma_f32_16x16x32_bf16 v[24:27], v[172:175], v[180:183], v[24:27]
	v_mfma_f32_16x16x32_bf16 v[20:23], v[156:159], v[188:191], v[20:23]
	v_mfma_f32_16x16x32_bf16 v[16:19], v[172:175], v[188:191], v[16:19]
	v_mfma_f32_16x16x32_bf16 v[12:15], v[156:159], v[196:199], v[12:15]
	v_mfma_f32_16x16x32_bf16 v[8:11], v[172:175], v[196:199], v[8:11]
	v_mfma_f32_16x16x32_bf16 v[4:7], v[156:159], v[206:209], v[4:7]
	v_mfma_f32_16x16x32_bf16 v[0:3], v[172:175], v[206:209], v[0:3]
	v_mfma_f32_16x16x32_bf16 v[28:31], v[168:171], v[184:187], v[28:31]
	v_mfma_f32_16x16x32_bf16 v[24:27], v[176:179], v[184:187], v[24:27]
	v_mfma_f32_16x16x32_bf16 v[20:23], v[168:171], v[192:195], v[20:23]
	v_mfma_f32_16x16x32_bf16 v[16:19], v[176:179], v[192:195], v[16:19]
	v_mfma_f32_16x16x32_bf16 v[12:15], v[168:171], v[200:203], v[12:15]
	v_mfma_f32_16x16x32_bf16 v[8:11], v[176:179], v[200:203], v[8:11]
	v_mfma_f32_16x16x32_bf16 v[4:7], v[168:171], v[210:213], v[4:7]
	v_mfma_f32_16x16x32_bf16 v[0:3], v[176:179], v[210:213], v[0:3]
	s_barrier
	s_add_i32 s0, 0, 0x18000
	s_add_i32 s1, 0, 0x1c000
	v_add_u32_e32 v152, s0, v162
	v_add_u32_e32 v167, s1, v162
	ds_read_b128 v[104:107], v152
	ds_read_b128 v[108:111], v152 offset:1024
	ds_read_b128 v[148:151], v152 offset:2048
	ds_read_b128 v[152:155], v152 offset:3072
	ds_read_b128 v[156:159], v167
	ds_read_b128 v[168:171], v167 offset:1024
	ds_read_b128 v[172:175], v167 offset:2048
	ds_read_b128 v[176:179], v167 offset:3072
	s_add_u32 s42, s42, 0x20000
	s_addc_u32 s43, s43, 0
	s_mov_b32 m0, s54
	ds_read_b128 v[180:183], v165 offset:32768
	ds_read_b128 v[184:187], v165 offset:33792
	ds_read_b128 v[188:191], v165 offset:34816
	ds_read_b128 v[192:195], v165 offset:35840
	ds_read_b128 v[196:199], v165 offset:36864
	ds_read_b128 v[200:203], v165 offset:37888
	ds_read_b128 v[206:209], v165 offset:38912
	ds_read_b128 v[210:213], v165 offset:39936
	s_nop 0
	v_lshl_add_u64 v[204:205], s[42:43], 0, v[136:137]
	global_load_lds_dwordx4 v[204:205], off
	v_lshl_add_u64 v[204:205], s[42:43], 0, v[140:141]
	s_mov_b32 m0, s55
	s_nop 0
	global_load_lds_dwordx4 v[204:205], off
	s_waitcnt vmcnt(8)
	s_waitcnt lgkmcnt(0)
	s_barrier
	s_waitcnt lgkmcnt(0)
	v_mfma_f32_16x16x32_bf16 v[132:135], v[104:107], v[180:183], v[132:135]
	v_mfma_f32_16x16x32_bf16 v[128:131], v[148:151], v[180:183], v[128:131]
	v_mfma_f32_16x16x32_bf16 v[124:127], v[104:107], v[188:191], v[124:127]
	v_mfma_f32_16x16x32_bf16 v[120:123], v[148:151], v[188:191], v[120:123]
	v_mfma_f32_16x16x32_bf16 v[116:119], v[104:107], v[196:199], v[116:119]
	v_mfma_f32_16x16x32_bf16 v[112:115], v[148:151], v[196:199], v[112:115]
	v_mfma_f32_16x16x32_bf16 v[100:103], v[104:107], v[206:209], v[100:103]
	v_mfma_f32_16x16x32_bf16 v[96:99], v[148:151], v[206:209], v[96:99]
	v_mfma_f32_16x16x32_bf16 v[132:135], v[108:111], v[184:187], v[132:135]
	v_mfma_f32_16x16x32_bf16 v[128:131], v[152:155], v[184:187], v[128:131]
	v_mfma_f32_16x16x32_bf16 v[124:127], v[108:111], v[192:195], v[124:127]
	v_mfma_f32_16x16x32_bf16 v[120:123], v[152:155], v[192:195], v[120:123]
	v_mfma_f32_16x16x32_bf16 v[116:119], v[108:111], v[200:203], v[116:119]
	v_mfma_f32_16x16x32_bf16 v[112:115], v[152:155], v[200:203], v[112:115]
	v_mfma_f32_16x16x32_bf16 v[100:103], v[108:111], v[210:213], v[100:103]
	v_mfma_f32_16x16x32_bf16 v[96:99], v[152:155], v[210:213], v[96:99]
	v_mfma_f32_16x16x32_bf16 v[60:63], v[156:159], v[180:183], v[60:63]
	v_mfma_f32_16x16x32_bf16 v[56:59], v[172:175], v[180:183], v[56:59]
	v_mfma_f32_16x16x32_bf16 v[52:55], v[156:159], v[188:191], v[52:55]
	v_mfma_f32_16x16x32_bf16 v[48:51], v[172:175], v[188:191], v[48:51]
	v_mfma_f32_16x16x32_bf16 v[44:47], v[156:159], v[196:199], v[44:47]
	v_mfma_f32_16x16x32_bf16 v[40:43], v[172:175], v[196:199], v[40:43]
	v_mfma_f32_16x16x32_bf16 v[36:39], v[156:159], v[206:209], v[36:39]
	v_mfma_f32_16x16x32_bf16 v[32:35], v[172:175], v[206:209], v[32:35]
	v_mfma_f32_16x16x32_bf16 v[60:63], v[168:171], v[184:187], v[60:63]
	v_mfma_f32_16x16x32_bf16 v[56:59], v[176:179], v[184:187], v[56:59]
	v_mfma_f32_16x16x32_bf16 v[52:55], v[168:171], v[192:195], v[52:55]
	v_mfma_f32_16x16x32_bf16 v[48:51], v[176:179], v[192:195], v[48:51]
	v_mfma_f32_16x16x32_bf16 v[44:47], v[168:171], v[200:203], v[44:47]
	v_mfma_f32_16x16x32_bf16 v[40:43], v[176:179], v[200:203], v[40:43]
	v_mfma_f32_16x16x32_bf16 v[36:39], v[168:171], v[210:213], v[36:39]
	v_mfma_f32_16x16x32_bf16 v[32:35], v[176:179], v[210:213], v[32:35]
	s_barrier
; #define PG8_STAGE(bufoff, gbase, voff) do { const char* _gb = (const char*)(gbase); asm volatile("" : "+s"(_gb));     \
;         _Pragma("unroll") for (int _i = 0; _i < 2; ++_i) \
;         __builtin_amdgcn_global_load_lds((const unsigned*)(_gb + (voff)[_i]), (LAS unsigned*)(lds + (bufoff) + ldsw + _i * 8192), 16, 0, 0); } while (0)
; #define PG8_LDA(dst, b, h) do { _Pragma("unroll") for (int m = 0; m < 4; ++m) _Pragma("unroll") for (int k = 0; k < 2; ++k) dst[m][k] = *(const LAS bf16x8*)(lds + PG8_SA(b, h) + aoff + m * 2048 + k * 1024); } while (0)
; #define PG8_MMA(ai, bj, At, Bt) do { __builtin_amdgcn_s_setprio(1); _Pragma("unroll") for (int m = 0; m < 4; ++m) _Pragma("unroll") for (int n = 0; n < 2; ++n) _Pragma("unroll") for (int k = 0; k < 2; ++k) \
;         acc[ai][bj][m][n] = __builtin_amdgcn_mfma_f32_16x16x32_bf16(Bt[n][k], At[m][k], acc[ai][bj][m][n], 0, 0, 0); __builtin_amdgcn_s_setprio(0); } while (0)
; #define PG8_WAIT_V(n) asm volatile("s_waitcnt vmcnt(" #n ")" ::: "memory")
; #define PG8_WAIT_L(n) asm volatile("s_waitcnt lgkmcnt(" #n ")" ::: "memory")
; #define PG8_BAR __builtin_amdgcn_s_barrier()
; #define PG8_SCHED __builtin_amdgcn_sched_barrier(0)
; template <class Epi>
; __device__ __forceinline__ void gemm_phase(LAS unsigned char* lds, const int wid, const Gemm g, const Epi& E) {
;     ...
;             PG8_LDA(At, 1, 1); PG8_STAGE(PG8_SB(1, 0), b3, voffB); PG8_STAGE(PG8_SB(1, 1), b3 + hstepB, voffB); PG8_STAGE(PG8_SA(1, 0), a3, voffA);
;             PG8_WAIT_V(8); PG8_WAIT_L(0); PG8_BAR; PG8_MMA(1, 0, At, B0); PG8_MMA(1, 1, At, B1); PG8_BAR; PG8_SCHED;
;         }
;         if (wr == 0) PG8_BAR;
	s_mov_b64 s[42:43], s[44:45]
	s_add_i32 s0, s0, s47
	ds_read_b128 v[180:183], v165 offset:49152
	ds_read_b128 v[184:187], v165 offset:50176
	ds_read_b128 v[188:191], v165 offset:51200
	ds_read_b128 v[192:195], v165 offset:52224
	ds_read_b128 v[196:199], v165 offset:53248
	ds_read_b128 v[200:203], v165 offset:54272
	ds_read_b128 v[206:209], v165 offset:55296
	ds_read_b128 v[210:213], v165 offset:56320
	s_mov_b32 m0, s0
	v_lshl_add_u64 v[204:205], s[42:43], 0, v[138:139]
	global_load_lds_dwordx4 v[204:205], off
	s_add_i32 m0, s0, 0x2000
	v_lshl_add_u64 v[204:205], s[42:43], 0, v[142:143]
	s_add_u32 s42, s44, 0x18000
	s_addc_u32 s43, s45, 0
	s_add_i32 s0, s1, s47
	global_load_lds_dwordx4 v[204:205], off
	s_mov_b32 m0, s0
	v_lshl_add_u64 v[204:205], s[42:43], 0, v[138:139]
	global_load_lds_dwordx4 v[204:205], off
	v_lshl_add_u64 v[204:205], s[42:43], 0, v[142:143]
	s_add_i32 m0, s0, 0x2000
	s_nop 0
	global_load_lds_dwordx4 v[204:205], off
	s_mov_b32 m0, s61
	v_lshl_add_u64 v[204:205], s[40:41], 0, v[136:137]
	global_load_lds_dwordx4 v[204:205], off
	v_lshl_add_u64 v[204:205], s[40:41], 0, v[140:141]
	s_mov_b32 m0, s62
	s_nop 0
	global_load_lds_dwordx4 v[204:205], off
	s_waitcnt vmcnt(8)
	s_waitcnt lgkmcnt(0)
	s_barrier
	s_waitcnt lgkmcnt(0)
	v_mfma_f32_16x16x32_bf16 v[92:95], v[104:107], v[180:183], v[92:95]
	v_mfma_f32_16x16x32_bf16 v[88:91], v[148:151], v[180:183], v[88:91]
	v_mfma_f32_16x16x32_bf16 v[84:87], v[104:107], v[188:191], v[84:87]
	v_mfma_f32_16x16x32_bf16 v[80:83], v[148:151], v[188:191], v[80:83]
	v_mfma_f32_16x16x32_bf16 v[76:79], v[104:107], v[196:199], v[76:79]
	v_mfma_f32_16x16x32_bf16 v[72:75], v[148:151], v[196:199], v[72:75]
	v_mfma_f32_16x16x32_bf16 v[68:71], v[104:107], v[206:209], v[68:71]
	v_mfma_f32_16x16x32_bf16 v[64:67], v[148:151], v[206:209], v[64:67]
	v_mfma_f32_16x16x32_bf16 v[92:95], v[108:111], v[184:187], v[92:95]
	v_mfma_f32_16x16x32_bf16 v[88:91], v[152:155], v[184:187], v[88:91]
	v_mfma_f32_16x16x32_bf16 v[84:87], v[108:111], v[192:195], v[84:87]
	v_mfma_f32_16x16x32_bf16 v[80:83], v[152:155], v[192:195], v[80:83]
	v_mfma_f32_16x16x32_bf16 v[76:79], v[108:111], v[200:203], v[76:79]
	v_mfma_f32_16x16x32_bf16 v[72:75], v[152:155], v[200:203], v[72:75]
	v_mfma_f32_16x16x32_bf16 v[68:71], v[108:111], v[210:213], v[68:71]
	v_mfma_f32_16x16x32_bf16 v[64:67], v[152:155], v[210:213], v[64:67]
	v_mfma_f32_16x16x32_bf16 v[28:31], v[156:159], v[180:183], v[28:31]
	v_mfma_f32_16x16x32_bf16 v[24:27], v[172:175], v[180:183], v[24:27]
	v_mfma_f32_16x16x32_bf16 v[20:23], v[156:159], v[188:191], v[20:23]
	v_mfma_f32_16x16x32_bf16 v[16:19], v[172:175], v[188:191], v[16:19]
	v_mfma_f32_16x16x32_bf16 v[12:15], v[156:159], v[196:199], v[12:15]
	v_mfma_f32_16x16x32_bf16 v[8:11], v[172:175], v[196:199], v[8:11]
	v_mfma_f32_16x16x32_bf16 v[4:7], v[156:159], v[206:209], v[4:7]
	v_mfma_f32_16x16x32_bf16 v[0:3], v[172:175], v[206:209], v[0:3]
	v_mfma_f32_16x16x32_bf16 v[28:31], v[168:171], v[184:187], v[28:31]
	v_mfma_f32_16x16x32_bf16 v[24:27], v[176:179], v[184:187], v[24:27]
	v_mfma_f32_16x16x32_bf16 v[20:23], v[168:171], v[192:195], v[20:23]
	v_mfma_f32_16x16x32_bf16 v[16:19], v[176:179], v[192:195], v[16:19]
	v_mfma_f32_16x16x32_bf16 v[12:15], v[168:171], v[200:203], v[12:15]
	v_mfma_f32_16x16x32_bf16 v[8:11], v[176:179], v[200:203], v[8:11]
	v_mfma_f32_16x16x32_bf16 v[4:7], v[168:171], v[210:213], v[4:7]
	v_mfma_f32_16x16x32_bf16 v[0:3], v[176:179], v[210:213], v[0:3]
	s_barrier
	s_add_i32 s76, s76, 2
	s_add_u32 s74, s74, 0x100
	s_addc_u32 s75, s75, 0
	s_add_u32 s4, s4, 0x100
	s_addc_u32 s5, s5, 0
	s_cmp_gt_u32 s76, 3
	s_cbranch_scc0 .LBB0_1125
	s_and_b64 vcc, exec, s[14:15]
	s_cbranch_vccz .LBB0_1128
	s_barrier

; #define PG8_STAGE(bufoff, gbase, voff) do { const char* _gb = (const char*)(gbase); asm volatile("" : "+s"(_gb));     \
;         _Pragma("unroll") for (int _i = 0; _i < 2; ++_i) \
;         __builtin_amdgcn_global_load_lds((const unsigned*)(_gb + (voff)[_i]), (LAS unsigned*)(lds + (bufoff) + ldsw + _i * 8192), 16, 0, 0); } while (0)
; #define PG8_LDA(dst, b, h) do { _Pragma("unroll") for (int m = 0; m < 4; ++m) _Pragma("unroll") for (int k = 0; k < 2; ++k) dst[m][k] = *(const LAS bf16x8*)(lds + PG8_SA(b, h) + aoff + m * 2048 + k * 1024); } while (0)
; #define PG8_LDB(dst, b, h) do { _Pragma("unroll") for (int n = 0; n < 2; ++n) _Pragma("unroll") for (int k = 0; k < 2; ++k) dst[n][k] = *(const LAS bf16x8*)(lds + PG8_SB(b, h) + boff + n * 2048 + k * 1024); } while (0)
; #define PG8_MMA(ai, bj, At, Bt) do { __builtin_amdgcn_s_setprio(1); _Pragma("unroll") for (int m = 0; m < 4; ++m) _Pragma("unroll") for (int n = 0; n < 2; ++n) _Pragma("unroll") for (int k = 0; k < 2; ++k) \
;         acc[ai][bj][m][n] = __builtin_amdgcn_mfma_f32_16x16x32_bf16(Bt[n][k], At[m][k], acc[ai][bj][m][n], 0, 0, 0); __builtin_amdgcn_s_setprio(0); } while (0)
; #define PG8_WAIT_V(n) asm volatile("s_waitcnt vmcnt(" #n ")" ::: "memory")
; #define PG8_WAIT_L(n) asm volatile("s_waitcnt lgkmcnt(" #n ")" ::: "memory")
; #define PG8_BAR __builtin_amdgcn_s_barrier()
; #define PG8_SCHED __builtin_amdgcn_sched_barrier(0)
; template <class Epi>
; __device__ __forceinline__ void gemm_phase(LAS unsigned char* lds, const int wid, const Gemm g, const Epi& E) {
;     ...
;         for (int t = 0; t < nt; t += 2) {
;             const bool last = (t == nt - 2);
;             const char* a1 = PG8_AP(cA, t + 1);
;             const char* a2 = last ? PG8_AP(nA, 0) : PG8_AP(cA, t + 2); const char* b2 = last ? PG8_BP(nB, 0) : PG8_BP(cB, t + 2);
;             const char* a3 = last ? PG8_AP(nA, 1) : PG8_AP(cA, t + 3); const char* b3 = last ? PG8_BP(nB, 1) : PG8_BP(cB, t + 3);
;             PG8_LDB(B0, 0, 0); PG8_LDB(B1, 0, 1); PG8_SCHED; PG8_LDA(At, 0, 0); PG8_STAGE(PG8_SA(1, 1), a1 + hstepA, voffA);
;             PG8_WAIT_V(8); PG8_WAIT_L(0); PG8_BAR; PG8_MMA(0, 0, At, B0); PG8_MMA(0, 1, At, B1); PG8_BAR; PG8_SCHED;
;             PG8_LDA(At, 0, 1); PG8_STAGE(PG8_SB(0, 0), b2, voffB); PG8_STAGE(PG8_SB(0, 1), b2 + hstepB, voffB); PG8_STAGE(PG8_SA(0, 0), a2, voffA);
.LBB0_1328:
	s_add_u32 s0, s40, s46
	s_addc_u32 s1, s41, 0
	s_add_u32 s47, s0, 0x100
	s_addc_u32 s50, s1, 0
	s_and_b64 s[48:49], s[44:45], exec
	s_cselect_b32 s53, s27, s50
	s_cselect_b32 s52, s79, s47
	s_add_u32 s48, s38, s46
	s_addc_u32 s49, s39, 0
	s_add_u32 s50, s48, 0x100
	s_addc_u32 s51, s49, 0
	s_and_b64 s[46:47], s[44:45], exec
	s_cselect_b32 s55, s25, s51
	s_cselect_b32 s54, s80, s50
	s_add_u32 s50, s0, 0x180
	s_addc_u32 s51, s1, 0
	s_and_b64 s[46:47], s[44:45], exec
	s_cselect_b32 s46, s81, s50
	s_cselect_b32 s47, s82, s51
	s_add_u32 s48, s48, 0x180
	s_addc_u32 s49, s49, 0
	s_add_u32 s58, s0, 0x20080
	s_addc_u32 s59, s1, 0
	s_add_i32 s94, s76, s23
	s_add_i32 m0, s65, 0xc000
	s_add_i32 s0, s65, 0xe000
	s_add_i32 s91, s94, 0x2000
	ds_read_b128 v[140:143], v157
	ds_read_b128 v[144:147], v157 offset:1024
	ds_read_b128 v[148:151], v157 offset:2048
	ds_read_b128 v[162:165], v157 offset:3072
	ds_read_b128 v[166:169], v158
	ds_read_b128 v[170:173], v158 offset:1024
	ds_read_b128 v[174:177], v158 offset:2048
	ds_read_b128 v[178:181], v158 offset:3072
	s_add_u32 s56, s54, 0x10000
	s_addc_u32 s57, s55, 0
	s_add_i32 s90, s77, s23
	s_add_i32 s89, s90, 0x2000
	s_add_i32 s88, 0, 0x18000
	s_add_i32 s87, 0, 0x1c000
	s_add_u32 s50, s52, 0x20000
	s_addc_u32 s51, s53, 0
	s_and_b64 s[44:45], s[44:45], exec
	s_cselect_b32 s49, s84, s49
	s_cselect_b32 s48, s83, s48
	s_add_i32 s86, s88, s23
	s_add_i32 s85, s86, 0x2000
	s_add_u32 s44, s48, 0x10000
	s_addc_u32 s45, s49, 0
	s_add_i32 s93, s87, s23
	s_add_i32 s92, s93, 0x2000
	ds_read_b128 v[182:185], v159
	ds_read_b128 v[186:189], v159 offset:1024
	ds_read_b128 v[190:193], v159 offset:2048
	ds_read_b128 v[194:197], v159 offset:3072
	ds_read_b128 v[198:201], v159 offset:4096
	ds_read_b128 v[206:209], v159 offset:5120
	ds_read_b128 v[210:213], v159 offset:6144
	ds_read_b128 v[214:217], v159 offset:7168
	s_nop 0
	v_lshl_add_u64 v[202:203], s[58:59], 0, v[134:135]
	global_load_lds_dwordx4 v[202:203], off
	v_lshl_add_u64 v[202:203], s[58:59], 0, v[130:131]
	s_mov_b32 m0, s0
	s_nop 0
	global_load_lds_dwordx4 v[202:203], off
	s_waitcnt vmcnt(8)
	s_waitcnt lgkmcnt(0)
	s_barrier
	s_waitcnt lgkmcnt(0)
	v_mfma_f32_16x16x32_bf16 v[124:127], v[140:143], v[182:185], v[124:127]
	v_mfma_f32_16x16x32_bf16 v[120:123], v[148:151], v[182:185], v[120:123]
	v_mfma_f32_16x16x32_bf16 v[108:111], v[140:143], v[190:193], v[108:111]
	v_mfma_f32_16x16x32_bf16 v[104:107], v[148:151], v[190:193], v[104:107]
	v_mfma_f32_16x16x32_bf16 v[92:95], v[140:143], v[198:201], v[92:95]
	v_mfma_f32_16x16x32_bf16 v[88:91], v[148:151], v[198:201], v[88:91]
	v_mfma_f32_16x16x32_bf16 v[76:79], v[140:143], v[210:213], v[76:79]
	v_mfma_f32_16x16x32_bf16 v[72:75], v[148:151], v[210:213], v[72:75]
	v_mfma_f32_16x16x32_bf16 v[124:127], v[144:147], v[186:189], v[124:127]
	v_mfma_f32_16x16x32_bf16 v[120:123], v[162:165], v[186:189], v[120:123]
	v_mfma_f32_16x16x32_bf16 v[108:111], v[144:147], v[194:197], v[108:111]
	v_mfma_f32_16x16x32_bf16 v[104:107], v[162:165], v[194:197], v[104:107]
	v_mfma_f32_16x16x32_bf16 v[92:95], v[144:147], v[206:209], v[92:95]
	v_mfma_f32_16x16x32_bf16 v[88:91], v[162:165], v[206:209], v[88:91]
	v_mfma_f32_16x16x32_bf16 v[76:79], v[144:147], v[214:217], v[76:79]
	v_mfma_f32_16x16x32_bf16 v[72:75], v[162:165], v[214:217], v[72:75]
	v_mfma_f32_16x16x32_bf16 v[116:119], v[166:169], v[182:185], v[116:119]
	v_mfma_f32_16x16x32_bf16 v[112:115], v[174:177], v[182:185], v[112:115]
	v_mfma_f32_16x16x32_bf16 v[100:103], v[166:169], v[190:193], v[100:103]
	v_mfma_f32_16x16x32_bf16 v[96:99], v[174:177], v[190:193], v[96:99]
	v_mfma_f32_16x16x32_bf16 v[84:87], v[166:169], v[198:201], v[84:87]
	v_mfma_f32_16x16x32_bf16 v[80:83], v[174:177], v[198:201], v[80:83]
	v_mfma_f32_16x16x32_bf16 v[68:71], v[166:169], v[210:213], v[68:71]
	v_mfma_f32_16x16x32_bf16 v[64:67], v[174:177], v[210:213], v[64:67]
	v_mfma_f32_16x16x32_bf16 v[116:119], v[170:173], v[186:189], v[116:119]
	v_mfma_f32_16x16x32_bf16 v[112:115], v[178:181], v[186:189], v[112:115]
	v_mfma_f32_16x16x32_bf16 v[100:103], v[170:173], v[194:197], v[100:103]
	v_mfma_f32_16x16x32_bf16 v[96:99], v[178:181], v[194:197], v[96:99]
	v_mfma_f32_16x16x32_bf16 v[84:87], v[170:173], v[206:209], v[84:87]
	v_mfma_f32_16x16x32_bf16 v[80:83], v[178:181], v[206:209], v[80:83]
	v_mfma_f32_16x16x32_bf16 v[68:71], v[170:173], v[214:217], v[68:71]
	v_mfma_f32_16x16x32_bf16 v[64:67], v[178:181], v[214:217], v[64:67]
	s_barrier
	s_mov_b32 m0, s94
	ds_read_b128 v[182:185], v159 offset:16384
	ds_read_b128 v[186:189], v159 offset:17408
	ds_read_b128 v[190:193], v159 offset:18432
	ds_read_b128 v[194:197], v159 offset:19456
	ds_read_b128 v[198:201], v159 offset:20480
	ds_read_b128 v[206:209], v159 offset:21504
	ds_read_b128 v[210:213], v159 offset:22528
	ds_read_b128 v[214:217], v159 offset:23552
	s_nop 0
	v_lshl_add_u64 v[202:203], s[54:55], 0, v[132:133]
	global_load_lds_dwordx4 v[202:203], off
	v_lshl_add_u64 v[202:203], s[54:55], 0, v[128:129]
	s_mov_b32 m0, s91
	s_nop 0
	global_load_lds_dwordx4 v[202:203], off
	s_mov_b32 m0, s90
	v_lshl_add_u64 v[202:203], s[56:57], 0, v[132:133]
	global_load_lds_dwordx4 v[202:203], off
	v_lshl_add_u64 v[202:203], s[56:57], 0, v[128:129]
	s_mov_b32 m0, s89
	s_nop 0
	global_load_lds_dwordx4 v[202:203], off
	s_mov_b32 m0, s65
	v_lshl_add_u64 v[202:203], s[52:53], 0, v[134:135]
	global_load_lds_dwordx4 v[202:203], off
	v_lshl_add_u64 v[202:203], s[52:53], 0, v[130:131]
	s_mov_b32 m0, s66
	s_nop 0
	global_load_lds_dwordx4 v[202:203], off
	s_waitcnt vmcnt(8)
	s_waitcnt lgkmcnt(0)
	s_barrier
; #define PG8_STAGE(bufoff, gbase, voff) do { const char* _gb = (const char*)(gbase); asm volatile("" : "+s"(_gb));     \
;         _Pragma("unroll") for (int _i = 0; _i < 2; ++_i) \
;         __builtin_amdgcn_global_load_lds((const unsigned*)(_gb + (voff)[_i]), (LAS unsigned*)(lds + (bufoff) + ldsw + _i * 8192), 16, 0, 0); } while (0)
; #define PG8_LDA(dst, b, h) do { _Pragma("unroll") for (int m = 0; m < 4; ++m) _Pragma("unroll") for (int k = 0; k < 2; ++k) dst[m][k] = *(const LAS bf16x8*)(lds + PG8_SA(b, h) + aoff + m * 2048 + k * 1024); } while (0)
; #define PG8_LDB(dst, b, h) do { _Pragma("unroll") for (int n = 0; n < 2; ++n) _Pragma("unroll") for (int k = 0; k < 2; ++k) dst[n][k] = *(const LAS bf16x8*)(lds + PG8_SB(b, h) + boff + n * 2048 + k * 1024); } while (0)
; #define PG8_MMA(ai, bj, At, Bt) do { __builtin_amdgcn_s_setprio(1); _Pragma("unroll") for (int m = 0; m < 4; ++m) _Pragma("unroll") for (int n = 0; n < 2; ++n) _Pragma("unroll") for (int k = 0; k < 2; ++k) \
;         acc[ai][bj][m][n] = __builtin_amdgcn_mfma_f32_16x16x32_bf16(Bt[n][k], At[m][k], acc[ai][bj][m][n], 0, 0, 0); __builtin_amdgcn_s_setprio(0); } while (0)
; #define PG8_WAIT_V(n) asm volatile("s_waitcnt vmcnt(" #n ")" ::: "memory")
; #define PG8_WAIT_L(n) asm volatile("s_waitcnt lgkmcnt(" #n ")" ::: "memory")
; #define PG8_BAR __builtin_amdgcn_s_barrier()
; #define PG8_SCHED __builtin_amdgcn_sched_barrier(0)
; template <class Epi>
; __device__ __forceinline__ void gemm_phase(LAS unsigned char* lds, const int wid, const Gemm g, const Epi& E) {
;     ...
;             PG8_WAIT_V(8); PG8_WAIT_L(0); PG8_BAR; PG8_MMA(1, 0, At, B0); PG8_MMA(1, 1, At, B1); PG8_BAR; PG8_SCHED;
;             PG8_LDB(B0, 1, 0); PG8_LDB(B1, 1, 1); PG8_SCHED; PG8_LDA(At, 1, 0); PG8_STAGE(PG8_SA(0, 1), a2 + hstepA, voffA);
;             PG8_WAIT_V(8); PG8_WAIT_L(0); PG8_BAR; PG8_MMA(0, 0, At, B0); PG8_MMA(0, 1, At, B1); PG8_BAR; PG8_SCHED;
	s_waitcnt lgkmcnt(0)
	v_mfma_f32_16x16x32_bf16 v[60:63], v[140:143], v[182:185], v[60:63]
	v_mfma_f32_16x16x32_bf16 v[56:59], v[148:151], v[182:185], v[56:59]
	v_mfma_f32_16x16x32_bf16 v[44:47], v[140:143], v[190:193], v[44:47]
	v_mfma_f32_16x16x32_bf16 v[40:43], v[148:151], v[190:193], v[40:43]
	v_mfma_f32_16x16x32_bf16 v[28:31], v[140:143], v[198:201], v[28:31]
	v_mfma_f32_16x16x32_bf16 v[24:27], v[148:151], v[198:201], v[24:27]
	v_mfma_f32_16x16x32_bf16 v[12:15], v[140:143], v[210:213], v[12:15]
	v_mfma_f32_16x16x32_bf16 v[8:11], v[148:151], v[210:213], v[8:11]
	v_mfma_f32_16x16x32_bf16 v[60:63], v[144:147], v[186:189], v[60:63]
	v_mfma_f32_16x16x32_bf16 v[56:59], v[162:165], v[186:189], v[56:59]
	v_mfma_f32_16x16x32_bf16 v[44:47], v[144:147], v[194:197], v[44:47]
	v_mfma_f32_16x16x32_bf16 v[40:43], v[162:165], v[194:197], v[40:43]
	v_mfma_f32_16x16x32_bf16 v[28:31], v[144:147], v[206:209], v[28:31]
	v_mfma_f32_16x16x32_bf16 v[24:27], v[162:165], v[206:209], v[24:27]
	v_mfma_f32_16x16x32_bf16 v[12:15], v[144:147], v[214:217], v[12:15]
	v_mfma_f32_16x16x32_bf16 v[8:11], v[162:165], v[214:217], v[8:11]
	v_mfma_f32_16x16x32_bf16 v[52:55], v[166:169], v[182:185], v[52:55]
	v_mfma_f32_16x16x32_bf16 v[48:51], v[174:177], v[182:185], v[48:51]
	v_mfma_f32_16x16x32_bf16 v[36:39], v[166:169], v[190:193], v[36:39]
	v_mfma_f32_16x16x32_bf16 v[32:35], v[174:177], v[190:193], v[32:35]
	v_mfma_f32_16x16x32_bf16 v[20:23], v[166:169], v[198:201], v[20:23]
	v_mfma_f32_16x16x32_bf16 v[16:19], v[174:177], v[198:201], v[16:19]
	v_mfma_f32_16x16x32_bf16 v[4:7], v[166:169], v[210:213], v[4:7]
	v_mfma_f32_16x16x32_bf16 v[0:3], v[174:177], v[210:213], v[0:3]
	v_mfma_f32_16x16x32_bf16 v[52:55], v[170:173], v[186:189], v[52:55]
	v_mfma_f32_16x16x32_bf16 v[48:51], v[178:181], v[186:189], v[48:51]
	v_mfma_f32_16x16x32_bf16 v[36:39], v[170:173], v[194:197], v[36:39]
	v_mfma_f32_16x16x32_bf16 v[32:35], v[178:181], v[194:197], v[32:35]
	v_mfma_f32_16x16x32_bf16 v[20:23], v[170:173], v[206:209], v[20:23]
	v_mfma_f32_16x16x32_bf16 v[16:19], v[178:181], v[206:209], v[16:19]
	v_mfma_f32_16x16x32_bf16 v[4:7], v[170:173], v[214:217], v[4:7]
	v_mfma_f32_16x16x32_bf16 v[0:3], v[178:181], v[214:217], v[0:3]
	s_barrier
	v_add_u32_e32 v161, s88, v156
	ds_read_b128 v[140:143], v161
	ds_read_b128 v[144:147], v161 offset:1024
	ds_read_b128 v[148:151], v161 offset:2048
	ds_read_b128 v[162:165], v161 offset:3072
	v_add_u32_e32 v161, s87, v156
	ds_read_b128 v[166:169], v161
	ds_read_b128 v[170:173], v161 offset:1024
	ds_read_b128 v[174:177], v161 offset:2048
	ds_read_b128 v[178:181], v161 offset:3072
	s_mov_b32 m0, s67
	ds_read_b128 v[182:185], v159 offset:32768
	ds_read_b128 v[186:189], v159 offset:33792
	ds_read_b128 v[190:193], v159 offset:34816
	ds_read_b128 v[194:197], v159 offset:35840
	ds_read_b128 v[198:201], v159 offset:36864
	ds_read_b128 v[206:209], v159 offset:37888
	ds_read_b128 v[210:213], v159 offset:38912
	ds_read_b128 v[214:217], v159 offset:39936
	s_nop 0
	v_lshl_add_u64 v[202:203], s[50:51], 0, v[134:135]
	global_load_lds_dwordx4 v[202:203], off
	v_lshl_add_u64 v[202:203], s[50:51], 0, v[130:131]
	s_mov_b32 m0, s68
	s_nop 0
	global_load_lds_dwordx4 v[202:203], off
	s_waitcnt vmcnt(8)
	s_waitcnt lgkmcnt(0)
	s_barrier
	s_waitcnt lgkmcnt(0)
	v_mfma_f32_16x16x32_bf16 v[124:127], v[140:143], v[182:185], v[124:127]
	v_mfma_f32_16x16x32_bf16 v[120:123], v[148:151], v[182:185], v[120:123]
	v_mfma_f32_16x16x32_bf16 v[108:111], v[140:143], v[190:193], v[108:111]
	v_mfma_f32_16x16x32_bf16 v[104:107], v[148:151], v[190:193], v[104:107]
	v_mfma_f32_16x16x32_bf16 v[92:95], v[140:143], v[198:201], v[92:95]
	v_mfma_f32_16x16x32_bf16 v[88:91], v[148:151], v[198:201], v[88:91]
	v_mfma_f32_16x16x32_bf16 v[76:79], v[140:143], v[210:213], v[76:79]
	v_mfma_f32_16x16x32_bf16 v[72:75], v[148:151], v[210:213], v[72:75]
	v_mfma_f32_16x16x32_bf16 v[124:127], v[144:147], v[186:189], v[124:127]
	v_mfma_f32_16x16x32_bf16 v[120:123], v[162:165], v[186:189], v[120:123]
	v_mfma_f32_16x16x32_bf16 v[108:111], v[144:147], v[194:197], v[108:111]
	v_mfma_f32_16x16x32_bf16 v[104:107], v[162:165], v[194:197], v[104:107]
	v_mfma_f32_16x16x32_bf16 v[92:95], v[144:147], v[206:209], v[92:95]
	v_mfma_f32_16x16x32_bf16 v[88:91], v[162:165], v[206:209], v[88:91]
	v_mfma_f32_16x16x32_bf16 v[76:79], v[144:147], v[214:217], v[76:79]
	v_mfma_f32_16x16x32_bf16 v[72:75], v[162:165], v[214:217], v[72:75]
	v_mfma_f32_16x16x32_bf16 v[116:119], v[166:169], v[182:185], v[116:119]
	v_mfma_f32_16x16x32_bf16 v[112:115], v[174:177], v[182:185], v[112:115]
	v_mfma_f32_16x16x32_bf16 v[100:103], v[166:169], v[190:193], v[100:103]
	v_mfma_f32_16x16x32_bf16 v[96:99], v[174:177], v[190:193], v[96:99]
	v_mfma_f32_16x16x32_bf16 v[84:87], v[166:169], v[198:201], v[84:87]
	v_mfma_f32_16x16x32_bf16 v[80:83], v[174:177], v[198:201], v[80:83]
	v_mfma_f32_16x16x32_bf16 v[68:71], v[166:169], v[210:213], v[68:71]
	v_mfma_f32_16x16x32_bf16 v[64:67], v[174:177], v[210:213], v[64:67]
	v_mfma_f32_16x16x32_bf16 v[116:119], v[170:173], v[186:189], v[116:119]
	v_mfma_f32_16x16x32_bf16 v[112:115], v[178:181], v[186:189], v[112:115]
	v_mfma_f32_16x16x32_bf16 v[100:103], v[170:173], v[194:197], v[100:103]
	v_mfma_f32_16x16x32_bf16 v[96:99], v[178:181], v[194:197], v[96:99]
	v_mfma_f32_16x16x32_bf16 v[84:87], v[170:173], v[206:209], v[84:87]
	v_mfma_f32_16x16x32_bf16 v[80:83], v[178:181], v[206:209], v[80:83]
	v_mfma_f32_16x16x32_bf16 v[68:71], v[170:173], v[214:217], v[68:71]
	v_mfma_f32_16x16x32_bf16 v[64:67], v[178:181], v[214:217], v[64:67]
	s_barrier
; #define PG8_STAGE(bufoff, gbase, voff) do { const char* _gb = (const char*)(gbase); asm volatile("" : "+s"(_gb));     \
;         _Pragma("unroll") for (int _i = 0; _i < 2; ++_i) \
;         __builtin_amdgcn_global_load_lds((const unsigned*)(_gb + (voff)[_i]), (LAS unsigned*)(lds + (bufoff) + ldsw + _i * 8192), 16, 0, 0); } while (0)
; #define PG8_LDA(dst, b, h) do { _Pragma("unroll") for (int m = 0; m < 4; ++m) _Pragma("unroll") for (int k = 0; k < 2; ++k) dst[m][k] = *(const LAS bf16x8*)(lds + PG8_SA(b, h) + aoff + m * 2048 + k * 1024); } while (0)
; #define PG8_MMA(ai, bj, At, Bt) do { __builtin_amdgcn_s_setprio(1); _Pragma("unroll") for (int m = 0; m < 4; ++m) _Pragma("unroll") for (int n = 0; n < 2; ++n) _Pragma("unroll") for (int k = 0; k < 2; ++k) \
;         acc[ai][bj][m][n] = __builtin_amdgcn_mfma_f32_16x16x32_bf16(Bt[n][k], At[m][k], acc[ai][bj][m][n], 0, 0, 0); __builtin_amdgcn_s_setprio(0); } while (0)
; #define PG8_WAIT_V(n) asm volatile("s_waitcnt vmcnt(" #n ")" ::: "memory")
; #define PG8_WAIT_L(n) asm volatile("s_waitcnt lgkmcnt(" #n ")" ::: "memory")
; #define PG8_BAR __builtin_amdgcn_s_barrier()
; #define PG8_SCHED __builtin_amdgcn_sched_barrier(0)
; template <class Epi>
; __device__ __forceinline__ void gemm_phase(LAS unsigned char* lds, const int wid, const Gemm g, const Epi& E) {
;     ...
;             PG8_LDA(At, 1, 1); PG8_STAGE(PG8_SB(1, 0), b3, voffB); PG8_STAGE(PG8_SB(1, 1), b3 + hstepB, voffB); PG8_STAGE(PG8_SA(1, 0), a3, voffA);
;             PG8_WAIT_V(8); PG8_WAIT_L(0); PG8_BAR; PG8_MMA(1, 0, At, B0); PG8_MMA(1, 1, At, B1); PG8_BAR; PG8_SCHED;
;         }
;         if (wr == 0) PG8_BAR;
	s_mov_b32 m0, s86
	ds_read_b128 v[182:185], v159 offset:49152
	ds_read_b128 v[186:189], v159 offset:50176
	ds_read_b128 v[190:193], v159 offset:51200
	ds_read_b128 v[194:197], v159 offset:52224
	ds_read_b128 v[198:201], v159 offset:53248
	ds_read_b128 v[206:209], v159 offset:54272
	ds_read_b128 v[210:213], v159 offset:55296
	ds_read_b128 v[214:217], v159 offset:56320
	s_nop 0
	v_lshl_add_u64 v[202:203], s[48:49], 0, v[132:133]
	global_load_lds_dwordx4 v[202:203], off
	v_lshl_add_u64 v[202:203], s[48:49], 0, v[128:129]
	s_mov_b32 m0, s85
	s_nop 0
	global_load_lds_dwordx4 v[202:203], off
	s_mov_b32 m0, s93
	v_lshl_add_u64 v[202:203], s[44:45], 0, v[132:133]
	global_load_lds_dwordx4 v[202:203], off
	v_lshl_add_u64 v[202:203], s[44:45], 0, v[128:129]
	s_mov_b32 m0, s92
	s_nop 0
	global_load_lds_dwordx4 v[202:203], off
	s_mov_b32 m0, s72
	v_lshl_add_u64 v[202:203], s[46:47], 0, v[134:135]
	global_load_lds_dwordx4 v[202:203], off
	v_lshl_add_u64 v[202:203], s[46:47], 0, v[130:131]
	s_mov_b32 m0, s73
	s_nop 0
	global_load_lds_dwordx4 v[202:203], off
	s_waitcnt vmcnt(8)
	s_waitcnt lgkmcnt(0)
	s_barrier
	s_waitcnt lgkmcnt(0)
	v_mfma_f32_16x16x32_bf16 v[60:63], v[140:143], v[182:185], v[60:63]
	v_mfma_f32_16x16x32_bf16 v[56:59], v[148:151], v[182:185], v[56:59]
	v_mfma_f32_16x16x32_bf16 v[44:47], v[140:143], v[190:193], v[44:47]
	v_mfma_f32_16x16x32_bf16 v[40:43], v[148:151], v[190:193], v[40:43]
	v_mfma_f32_16x16x32_bf16 v[28:31], v[140:143], v[198:201], v[28:31]
	v_mfma_f32_16x16x32_bf16 v[24:27], v[148:151], v[198:201], v[24:27]
	v_mfma_f32_16x16x32_bf16 v[12:15], v[140:143], v[210:213], v[12:15]
	v_mfma_f32_16x16x32_bf16 v[8:11], v[148:151], v[210:213], v[8:11]
	v_mfma_f32_16x16x32_bf16 v[60:63], v[144:147], v[186:189], v[60:63]
	v_mfma_f32_16x16x32_bf16 v[56:59], v[162:165], v[186:189], v[56:59]
	v_mfma_f32_16x16x32_bf16 v[44:47], v[144:147], v[194:197], v[44:47]
	v_mfma_f32_16x16x32_bf16 v[40:43], v[162:165], v[194:197], v[40:43]
	v_mfma_f32_16x16x32_bf16 v[28:31], v[144:147], v[206:209], v[28:31]
	v_mfma_f32_16x16x32_bf16 v[24:27], v[162:165], v[206:209], v[24:27]
	v_mfma_f32_16x16x32_bf16 v[12:15], v[144:147], v[214:217], v[12:15]
	v_mfma_f32_16x16x32_bf16 v[8:11], v[162:165], v[214:217], v[8:11]
	v_mfma_f32_16x16x32_bf16 v[52:55], v[166:169], v[182:185], v[52:55]
	v_mfma_f32_16x16x32_bf16 v[48:51], v[174:177], v[182:185], v[48:51]
	v_mfma_f32_16x16x32_bf16 v[36:39], v[166:169], v[190:193], v[36:39]
	v_mfma_f32_16x16x32_bf16 v[32:35], v[174:177], v[190:193], v[32:35]
	v_mfma_f32_16x16x32_bf16 v[20:23], v[166:169], v[198:201], v[20:23]
	v_mfma_f32_16x16x32_bf16 v[16:19], v[174:177], v[198:201], v[16:19]
	v_mfma_f32_16x16x32_bf16 v[4:7], v[166:169], v[210:213], v[4:7]
	v_mfma_f32_16x16x32_bf16 v[0:3], v[174:177], v[210:213], v[0:3]
	v_mfma_f32_16x16x32_bf16 v[52:55], v[170:173], v[186:189], v[52:55]
	v_mfma_f32_16x16x32_bf16 v[48:51], v[178:181], v[186:189], v[48:51]
	v_mfma_f32_16x16x32_bf16 v[36:39], v[170:173], v[194:197], v[36:39]
	v_mfma_f32_16x16x32_bf16 v[32:35], v[178:181], v[194:197], v[32:35]
	v_mfma_f32_16x16x32_bf16 v[20:23], v[170:173], v[206:209], v[20:23]
	v_mfma_f32_16x16x32_bf16 v[16:19], v[178:181], v[206:209], v[16:19]
	v_mfma_f32_16x16x32_bf16 v[4:7], v[170:173], v[214:217], v[4:7]
	v_mfma_f32_16x16x32_bf16 v[0:3], v[178:181], v[214:217], v[0:3]
	s_barrier
	s_movk_i32 s46, 0x100
	s_andn2_b64 vcc, exec, s[42:43]
	s_mov_b64 s[44:45], -1
	s_mov_b64 s[42:43], 0
	s_cbranch_vccz .LBB0_1328
	s_and_b64 vcc, exec, s[14:15]
	s_cbranch_vccz .LBB0_1331
	s_barrier

; #define PG8_STAGE(bufoff, gbase, voff) do { const char* _gb = (const char*)(gbase); asm volatile("" : "+s"(_gb));     \
;         _Pragma("unroll") for (int _i = 0; _i < 2; ++_i) \
;         __builtin_amdgcn_global_load_lds((const unsigned*)(_gb + (voff)[_i]), (LAS unsigned*)(lds + (bufoff) + ldsw + _i * 8192), 16, 0, 0); } while (0)
; #define PG8_LDA(dst, b, h) do { _Pragma("unroll") for (int m = 0; m < 4; ++m) _Pragma("unroll") for (int k = 0; k < 2; ++k) dst[m][k] = *(const LAS bf16x8*)(lds + PG8_SA(b, h) + aoff + m * 2048 + k * 1024); } while (0)
; #define PG8_LDB(dst, b, h) do { _Pragma("unroll") for (int n = 0; n < 2; ++n) _Pragma("unroll") for (int k = 0; k < 2; ++k) dst[n][k] = *(const LAS bf16x8*)(lds + PG8_SB(b, h) + boff + n * 2048 + k * 1024); } while (0)
; #define PG8_MMA(ai, bj, At, Bt) do { __builtin_amdgcn_s_setprio(1); _Pragma("unroll") for (int m = 0; m < 4; ++m) _Pragma("unroll") for (int n = 0; n < 2; ++n) _Pragma("unroll") for (int k = 0; k < 2; ++k) \
;         acc[ai][bj][m][n] = __builtin_amdgcn_mfma_f32_16x16x32_bf16(Bt[n][k], At[m][k], acc[ai][bj][m][n], 0, 0, 0); __builtin_amdgcn_s_setprio(0); } while (0)
; #define PG8_WAIT_V(n) asm volatile("s_waitcnt vmcnt(" #n ")" ::: "memory")
; #define PG8_WAIT_L(n) asm volatile("s_waitcnt lgkmcnt(" #n ")" ::: "memory")
; #define PG8_BAR __builtin_amdgcn_s_barrier()
; #define PG8_SCHED __builtin_amdgcn_sched_barrier(0)
; template <class Epi>
; __device__ __forceinline__ void gemm_phase(LAS unsigned char* lds, const int wid, const Gemm g, const Epi& E) {
;     ...
;         for (int t = 0; t < nt; t += 2) {
;             const bool last = (t == nt - 2);
;             const char* a1 = PG8_AP(cA, t + 1);
;             const char* a2 = last ? PG8_AP(nA, 0) : PG8_AP(cA, t + 2); const char* b2 = last ? PG8_BP(nB, 0) : PG8_BP(cB, t + 2);
;             const char* a3 = last ? PG8_AP(nA, 1) : PG8_AP(cA, t + 3); const char* b3 = last ? PG8_BP(nB, 1) : PG8_BP(cB, t + 3);
;             PG8_LDB(B0, 0, 0); PG8_LDB(B1, 0, 1); PG8_SCHED; PG8_LDA(At, 0, 0); PG8_STAGE(PG8_SA(1, 1), a1 + hstepA, voffA);
;             PG8_WAIT_V(8); PG8_WAIT_L(0); PG8_BAR; PG8_MMA(0, 0, At, B0); PG8_MMA(0, 1, At, B1); PG8_BAR; PG8_SCHED;
;             PG8_LDA(At, 0, 1); PG8_STAGE(PG8_SB(0, 0), b2, voffB); PG8_STAGE(PG8_SB(0, 1), b2 + hstepB, voffB); PG8_STAGE(PG8_SA(0, 0), a2, voffA);
.LBB0_1398:
	ds_read_b128 v[140:143], v149
	ds_read_b128 v[152:155], v149 offset:1024
	ds_read_b128 v[156:159], v149 offset:2048
	ds_read_b128 v[160:163], v149 offset:3072
	ds_read_b128 v[164:167], v150
	ds_read_b128 v[168:171], v150 offset:1024
	ds_read_b128 v[172:175], v150 offset:2048
	ds_read_b128 v[176:179], v150 offset:3072
	s_add_u32 s0, s38, 0xfffc0080
	s_addc_u32 s1, s39, -1
	s_add_u32 s40, s70, 0xffffff80
	s_addc_u32 s41, s71, -1
	s_add_u32 s44, s38, 0xfffc0100
	s_addc_u32 s45, s39, -1
	s_add_i32 s76, s61, s23
	s_add_i32 m0, s35, 0xc000
	s_add_i32 s73, s35, 0xe000
	s_add_i32 s77, s76, 0x2000
	s_cmp_eq_u32 s72, 12
	s_cselect_b32 s43, s27, s1
	s_cselect_b32 s42, s64, s0
	s_cselect_b32 s75, s25, s41
	s_cselect_b32 s74, s65, s40
	s_cselect_b32 s41, s67, s45
	s_cselect_b32 s40, s66, s44
	s_mov_b64 s[44:45], s[38:39]
	ds_read_b128 v[180:183], v151
	ds_read_b128 v[184:187], v151 offset:1024
	ds_read_b128 v[188:191], v151 offset:2048
	ds_read_b128 v[192:195], v151 offset:3072
	ds_read_b128 v[196:199], v151 offset:4096
	ds_read_b128 v[200:203], v151 offset:5120
	ds_read_b128 v[206:209], v151 offset:6144
	ds_read_b128 v[210:213], v151 offset:7168
	s_nop 0
	v_lshl_add_u64 v[144:145], s[44:45], 0, v[134:135]
	global_load_lds_dwordx4 v[144:145], off
	v_lshl_add_u64 v[144:145], s[44:45], 0, v[130:131]
	s_mov_b32 m0, s73
	s_nop 0
	global_load_lds_dwordx4 v[144:145], off
	s_waitcnt vmcnt(8)
	s_waitcnt lgkmcnt(0)
	s_barrier
	s_waitcnt lgkmcnt(0)
	v_mfma_f32_16x16x32_bf16 v[124:127], v[140:143], v[180:183], v[124:127]
	v_mfma_f32_16x16x32_bf16 v[120:123], v[156:159], v[180:183], v[120:123]
	v_mfma_f32_16x16x32_bf16 v[108:111], v[140:143], v[188:191], v[108:111]
	v_mfma_f32_16x16x32_bf16 v[104:107], v[156:159], v[188:191], v[104:107]
	v_mfma_f32_16x16x32_bf16 v[92:95], v[140:143], v[196:199], v[92:95]
	v_mfma_f32_16x16x32_bf16 v[88:91], v[156:159], v[196:199], v[88:91]
	v_mfma_f32_16x16x32_bf16 v[76:79], v[140:143], v[206:209], v[76:79]
	v_mfma_f32_16x16x32_bf16 v[72:75], v[156:159], v[206:209], v[72:75]
	v_mfma_f32_16x16x32_bf16 v[124:127], v[152:155], v[184:187], v[124:127]
	v_mfma_f32_16x16x32_bf16 v[120:123], v[160:163], v[184:187], v[120:123]
	v_mfma_f32_16x16x32_bf16 v[108:111], v[152:155], v[192:195], v[108:111]
	v_mfma_f32_16x16x32_bf16 v[104:107], v[160:163], v[192:195], v[104:107]
	v_mfma_f32_16x16x32_bf16 v[92:95], v[152:155], v[200:203], v[92:95]
	v_mfma_f32_16x16x32_bf16 v[88:91], v[160:163], v[200:203], v[88:91]
	v_mfma_f32_16x16x32_bf16 v[76:79], v[152:155], v[210:213], v[76:79]
	v_mfma_f32_16x16x32_bf16 v[72:75], v[160:163], v[210:213], v[72:75]
	v_mfma_f32_16x16x32_bf16 v[116:119], v[164:167], v[180:183], v[116:119]
	v_mfma_f32_16x16x32_bf16 v[112:115], v[172:175], v[180:183], v[112:115]
	v_mfma_f32_16x16x32_bf16 v[100:103], v[164:167], v[188:191], v[100:103]
	v_mfma_f32_16x16x32_bf16 v[96:99], v[172:175], v[188:191], v[96:99]
	v_mfma_f32_16x16x32_bf16 v[84:87], v[164:167], v[196:199], v[84:87]
	v_mfma_f32_16x16x32_bf16 v[80:83], v[172:175], v[196:199], v[80:83]
	v_mfma_f32_16x16x32_bf16 v[68:71], v[164:167], v[206:209], v[68:71]
	v_mfma_f32_16x16x32_bf16 v[64:67], v[172:175], v[206:209], v[64:67]
	v_mfma_f32_16x16x32_bf16 v[116:119], v[168:171], v[184:187], v[116:119]
	v_mfma_f32_16x16x32_bf16 v[112:115], v[176:179], v[184:187], v[112:115]
	v_mfma_f32_16x16x32_bf16 v[100:103], v[168:171], v[192:195], v[100:103]
	v_mfma_f32_16x16x32_bf16 v[96:99], v[176:179], v[192:195], v[96:99]
	v_mfma_f32_16x16x32_bf16 v[84:87], v[168:171], v[200:203], v[84:87]
	v_mfma_f32_16x16x32_bf16 v[80:83], v[176:179], v[200:203], v[80:83]
	v_mfma_f32_16x16x32_bf16 v[68:71], v[168:171], v[210:213], v[68:71]
	v_mfma_f32_16x16x32_bf16 v[64:67], v[176:179], v[210:213], v[64:67]
	s_barrier
	s_mov_b64 s[44:45], s[74:75]
	s_mov_b32 m0, s76
	ds_read_b128 v[180:183], v151 offset:16384
	ds_read_b128 v[184:187], v151 offset:17408
	ds_read_b128 v[188:191], v151 offset:18432
	ds_read_b128 v[192:195], v151 offset:19456
	ds_read_b128 v[196:199], v151 offset:20480
	ds_read_b128 v[200:203], v151 offset:21504
	ds_read_b128 v[206:209], v151 offset:22528
	ds_read_b128 v[210:213], v151 offset:23552
	s_nop 0
	v_lshl_add_u64 v[144:145], s[44:45], 0, v[132:133]
	global_load_lds_dwordx4 v[144:145], off
	v_lshl_add_u64 v[144:145], s[44:45], 0, v[128:129]
	s_cselect_b32 s45, s69, s71
	s_cselect_b32 s44, s68, s70
	s_add_u32 s74, s74, 0x40000
	s_mov_b32 m0, s77
	s_addc_u32 s75, s75, 0
	s_add_i32 s0, s62, s23
	global_load_lds_dwordx4 v[144:145], off
	s_mov_b32 m0, s0
	v_lshl_add_u64 v[144:145], s[74:75], 0, v[132:133]
	global_load_lds_dwordx4 v[144:145], off
	v_lshl_add_u64 v[144:145], s[74:75], 0, v[128:129]
	s_add_i32 m0, s0, 0x2000
	s_mov_b64 s[74:75], s[42:43]
	global_load_lds_dwordx4 v[144:145], off
	s_mov_b32 m0, s35
	v_lshl_add_u64 v[144:145], s[74:75], 0, v[134:135]
	global_load_lds_dwordx4 v[144:145], off
	v_lshl_add_u64 v[144:145], s[74:75], 0, v[130:131]
	s_mov_b32 m0, s51
	s_nop 0
	global_load_lds_dwordx4 v[144:145], off
	s_waitcnt vmcnt(8)
	s_waitcnt lgkmcnt(0)
	s_barrier
; #define PG8_STAGE(bufoff, gbase, voff) do { const char* _gb = (const char*)(gbase); asm volatile("" : "+s"(_gb));     \
;         _Pragma("unroll") for (int _i = 0; _i < 2; ++_i) \
;         __builtin_amdgcn_global_load_lds((const unsigned*)(_gb + (voff)[_i]), (LAS unsigned*)(lds + (bufoff) + ldsw + _i * 8192), 16, 0, 0); } while (0)
; #define PG8_LDA(dst, b, h) do { _Pragma("unroll") for (int m = 0; m < 4; ++m) _Pragma("unroll") for (int k = 0; k < 2; ++k) dst[m][k] = *(const LAS bf16x8*)(lds + PG8_SA(b, h) + aoff + m * 2048 + k * 1024); } while (0)
; #define PG8_LDB(dst, b, h) do { _Pragma("unroll") for (int n = 0; n < 2; ++n) _Pragma("unroll") for (int k = 0; k < 2; ++k) dst[n][k] = *(const LAS bf16x8*)(lds + PG8_SB(b, h) + boff + n * 2048 + k * 1024); } while (0)
; #define PG8_MMA(ai, bj, At, Bt) do { __builtin_amdgcn_s_setprio(1); _Pragma("unroll") for (int m = 0; m < 4; ++m) _Pragma("unroll") for (int n = 0; n < 2; ++n) _Pragma("unroll") for (int k = 0; k < 2; ++k) \
;         acc[ai][bj][m][n] = __builtin_amdgcn_mfma_f32_16x16x32_bf16(Bt[n][k], At[m][k], acc[ai][bj][m][n], 0, 0, 0); __builtin_amdgcn_s_setprio(0); } while (0)
; #define PG8_WAIT_V(n) asm volatile("s_waitcnt vmcnt(" #n ")" ::: "memory")
; #define PG8_WAIT_L(n) asm volatile("s_waitcnt lgkmcnt(" #n ")" ::: "memory")
; #define PG8_BAR __builtin_amdgcn_s_barrier()
; #define PG8_SCHED __builtin_amdgcn_sched_barrier(0)
; template <class Epi>
; __device__ __forceinline__ void gemm_phase(LAS unsigned char* lds, const int wid, const Gemm g, const Epi& E) {
;     ...
;             PG8_WAIT_V(8); PG8_WAIT_L(0); PG8_BAR; PG8_MMA(1, 0, At, B0); PG8_MMA(1, 1, At, B1); PG8_BAR; PG8_SCHED;
;             PG8_LDB(B0, 1, 0); PG8_LDB(B1, 1, 1); PG8_SCHED; PG8_LDA(At, 1, 0); PG8_STAGE(PG8_SA(0, 1), a2 + hstepA, voffA);
;             PG8_WAIT_V(8); PG8_WAIT_L(0); PG8_BAR; PG8_MMA(0, 0, At, B0); PG8_MMA(0, 1, At, B1); PG8_BAR; PG8_SCHED;
	s_waitcnt lgkmcnt(0)
	v_mfma_f32_16x16x32_bf16 v[60:63], v[140:143], v[180:183], v[60:63]
	v_mfma_f32_16x16x32_bf16 v[56:59], v[156:159], v[180:183], v[56:59]
	v_mfma_f32_16x16x32_bf16 v[44:47], v[140:143], v[188:191], v[44:47]
	v_mfma_f32_16x16x32_bf16 v[40:43], v[156:159], v[188:191], v[40:43]
	v_mfma_f32_16x16x32_bf16 v[28:31], v[140:143], v[196:199], v[28:31]
	v_mfma_f32_16x16x32_bf16 v[24:27], v[156:159], v[196:199], v[24:27]
	v_mfma_f32_16x16x32_bf16 v[12:15], v[140:143], v[206:209], v[12:15]
	v_mfma_f32_16x16x32_bf16 v[8:11], v[156:159], v[206:209], v[8:11]
	v_mfma_f32_16x16x32_bf16 v[60:63], v[152:155], v[184:187], v[60:63]
	v_mfma_f32_16x16x32_bf16 v[56:59], v[160:163], v[184:187], v[56:59]
	v_mfma_f32_16x16x32_bf16 v[44:47], v[152:155], v[192:195], v[44:47]
	v_mfma_f32_16x16x32_bf16 v[40:43], v[160:163], v[192:195], v[40:43]
	v_mfma_f32_16x16x32_bf16 v[28:31], v[152:155], v[200:203], v[28:31]
	v_mfma_f32_16x16x32_bf16 v[24:27], v[160:163], v[200:203], v[24:27]
	v_mfma_f32_16x16x32_bf16 v[12:15], v[152:155], v[210:213], v[12:15]
	v_mfma_f32_16x16x32_bf16 v[8:11], v[160:163], v[210:213], v[8:11]
	v_mfma_f32_16x16x32_bf16 v[52:55], v[164:167], v[180:183], v[52:55]
	v_mfma_f32_16x16x32_bf16 v[48:51], v[172:175], v[180:183], v[48:51]
	v_mfma_f32_16x16x32_bf16 v[36:39], v[164:167], v[188:191], v[36:39]
	v_mfma_f32_16x16x32_bf16 v[32:35], v[172:175], v[188:191], v[32:35]
	v_mfma_f32_16x16x32_bf16 v[20:23], v[164:167], v[196:199], v[20:23]
	v_mfma_f32_16x16x32_bf16 v[16:19], v[172:175], v[196:199], v[16:19]
	v_mfma_f32_16x16x32_bf16 v[4:7], v[164:167], v[206:209], v[4:7]
	v_mfma_f32_16x16x32_bf16 v[0:3], v[172:175], v[206:209], v[0:3]
	v_mfma_f32_16x16x32_bf16 v[52:55], v[168:171], v[184:187], v[52:55]
	v_mfma_f32_16x16x32_bf16 v[48:51], v[176:179], v[184:187], v[48:51]
	v_mfma_f32_16x16x32_bf16 v[36:39], v[168:171], v[192:195], v[36:39]
	v_mfma_f32_16x16x32_bf16 v[32:35], v[176:179], v[192:195], v[32:35]
	v_mfma_f32_16x16x32_bf16 v[20:23], v[168:171], v[200:203], v[20:23]
	v_mfma_f32_16x16x32_bf16 v[16:19], v[176:179], v[200:203], v[16:19]
	v_mfma_f32_16x16x32_bf16 v[4:7], v[168:171], v[210:213], v[4:7]
	v_mfma_f32_16x16x32_bf16 v[0:3], v[176:179], v[210:213], v[0:3]
	s_barrier
	s_add_i32 s0, 0, 0x18000
	v_add_u32_e32 v144, s0, v148
	s_add_i32 s1, 0, 0x1c000
	ds_read_b128 v[140:143], v144
	ds_read_b128 v[152:155], v144 offset:1024
	ds_read_b128 v[156:159], v144 offset:2048
	ds_read_b128 v[160:163], v144 offset:3072
	v_add_u32_e32 v144, s1, v148
	ds_read_b128 v[164:167], v144
	ds_read_b128 v[168:171], v144 offset:1024
	ds_read_b128 v[172:175], v144 offset:2048
	ds_read_b128 v[176:179], v144 offset:3072
	s_add_u32 s42, s42, 0x40000
	s_addc_u32 s43, s43, 0
	s_mov_b32 m0, s52
	ds_read_b128 v[180:183], v151 offset:32768
	ds_read_b128 v[184:187], v151 offset:33792
	ds_read_b128 v[188:191], v151 offset:34816
	ds_read_b128 v[192:195], v151 offset:35840
	ds_read_b128 v[196:199], v151 offset:36864
	ds_read_b128 v[200:203], v151 offset:37888
	ds_read_b128 v[206:209], v151 offset:38912
	ds_read_b128 v[210:213], v151 offset:39936
	s_nop 0
	v_lshl_add_u64 v[144:145], s[42:43], 0, v[134:135]
	global_load_lds_dwordx4 v[144:145], off
	v_lshl_add_u64 v[144:145], s[42:43], 0, v[130:131]
	s_mov_b32 m0, s53
	s_nop 0
	global_load_lds_dwordx4 v[144:145], off
	s_waitcnt vmcnt(8)
	s_waitcnt lgkmcnt(0)
	s_barrier
	s_waitcnt lgkmcnt(0)
	v_mfma_f32_16x16x32_bf16 v[124:127], v[140:143], v[180:183], v[124:127]
	v_mfma_f32_16x16x32_bf16 v[120:123], v[156:159], v[180:183], v[120:123]
	v_mfma_f32_16x16x32_bf16 v[108:111], v[140:143], v[188:191], v[108:111]
	v_mfma_f32_16x16x32_bf16 v[104:107], v[156:159], v[188:191], v[104:107]
	v_mfma_f32_16x16x32_bf16 v[92:95], v[140:143], v[196:199], v[92:95]
	v_mfma_f32_16x16x32_bf16 v[88:91], v[156:159], v[196:199], v[88:91]
	v_mfma_f32_16x16x32_bf16 v[76:79], v[140:143], v[206:209], v[76:79]
	v_mfma_f32_16x16x32_bf16 v[72:75], v[156:159], v[206:209], v[72:75]
	v_mfma_f32_16x16x32_bf16 v[124:127], v[152:155], v[184:187], v[124:127]
	v_mfma_f32_16x16x32_bf16 v[120:123], v[160:163], v[184:187], v[120:123]
	v_mfma_f32_16x16x32_bf16 v[108:111], v[152:155], v[192:195], v[108:111]
	v_mfma_f32_16x16x32_bf16 v[104:107], v[160:163], v[192:195], v[104:107]
	v_mfma_f32_16x16x32_bf16 v[92:95], v[152:155], v[200:203], v[92:95]
	v_mfma_f32_16x16x32_bf16 v[88:91], v[160:163], v[200:203], v[88:91]
	v_mfma_f32_16x16x32_bf16 v[76:79], v[152:155], v[210:213], v[76:79]
	v_mfma_f32_16x16x32_bf16 v[72:75], v[160:163], v[210:213], v[72:75]
	v_mfma_f32_16x16x32_bf16 v[116:119], v[164:167], v[180:183], v[116:119]
	v_mfma_f32_16x16x32_bf16 v[112:115], v[172:175], v[180:183], v[112:115]
	v_mfma_f32_16x16x32_bf16 v[100:103], v[164:167], v[188:191], v[100:103]
	v_mfma_f32_16x16x32_bf16 v[96:99], v[172:175], v[188:191], v[96:99]
	v_mfma_f32_16x16x32_bf16 v[84:87], v[164:167], v[196:199], v[84:87]
	v_mfma_f32_16x16x32_bf16 v[80:83], v[172:175], v[196:199], v[80:83]
	v_mfma_f32_16x16x32_bf16 v[68:71], v[164:167], v[206:209], v[68:71]
	v_mfma_f32_16x16x32_bf16 v[64:67], v[172:175], v[206:209], v[64:67]
	v_mfma_f32_16x16x32_bf16 v[116:119], v[168:171], v[184:187], v[116:119]
	v_mfma_f32_16x16x32_bf16 v[112:115], v[176:179], v[184:187], v[112:115]
	v_mfma_f32_16x16x32_bf16 v[100:103], v[168:171], v[192:195], v[100:103]
	v_mfma_f32_16x16x32_bf16 v[96:99], v[176:179], v[192:195], v[96:99]
	v_mfma_f32_16x16x32_bf16 v[84:87], v[168:171], v[200:203], v[84:87]
	v_mfma_f32_16x16x32_bf16 v[80:83], v[176:179], v[200:203], v[80:83]
	v_mfma_f32_16x16x32_bf16 v[68:71], v[168:171], v[210:213], v[68:71]
	v_mfma_f32_16x16x32_bf16 v[64:67], v[176:179], v[210:213], v[64:67]
	s_barrier
; #define PG8_STAGE(bufoff, gbase, voff) do { const char* _gb = (const char*)(gbase); asm volatile("" : "+s"(_gb));     \
;         _Pragma("unroll") for (int _i = 0; _i < 2; ++_i) \
;         __builtin_amdgcn_global_load_lds((const unsigned*)(_gb + (voff)[_i]), (LAS unsigned*)(lds + (bufoff) + ldsw + _i * 8192), 16, 0, 0); } while (0)
; #define PG8_LDA(dst, b, h) do { _Pragma("unroll") for (int m = 0; m < 4; ++m) _Pragma("unroll") for (int k = 0; k < 2; ++k) dst[m][k] = *(const LAS bf16x8*)(lds + PG8_SA(b, h) + aoff + m * 2048 + k * 1024); } while (0)
; #define PG8_MMA(ai, bj, At, Bt) do { __builtin_amdgcn_s_setprio(1); _Pragma("unroll") for (int m = 0; m < 4; ++m) _Pragma("unroll") for (int n = 0; n < 2; ++n) _Pragma("unroll") for (int k = 0; k < 2; ++k) \
;         acc[ai][bj][m][n] = __builtin_amdgcn_mfma_f32_16x16x32_bf16(Bt[n][k], At[m][k], acc[ai][bj][m][n], 0, 0, 0); __builtin_amdgcn_s_setprio(0); } while (0)
; #define PG8_WAIT_V(n) asm volatile("s_waitcnt vmcnt(" #n ")" ::: "memory")
; #define PG8_WAIT_L(n) asm volatile("s_waitcnt lgkmcnt(" #n ")" ::: "memory")
; #define PG8_BAR __builtin_amdgcn_s_barrier()
; #define PG8_SCHED __builtin_amdgcn_sched_barrier(0)
; template <class Epi>
; __device__ __forceinline__ void gemm_phase(LAS unsigned char* lds, const int wid, const Gemm g, const Epi& E) {
;     ...
;             PG8_LDA(At, 1, 1); PG8_STAGE(PG8_SB(1, 0), b3, voffB); PG8_STAGE(PG8_SB(1, 1), b3 + hstepB, voffB); PG8_STAGE(PG8_SA(1, 0), a3, voffA);
;             PG8_WAIT_V(8); PG8_WAIT_L(0); PG8_BAR; PG8_MMA(1, 0, At, B0); PG8_MMA(1, 1, At, B1); PG8_BAR; PG8_SCHED;
;         }
;         if (wr == 0) PG8_BAR;
	s_mov_b64 s[42:43], s[44:45]
	s_add_i32 s0, s0, s23
	ds_read_b128 v[180:183], v151 offset:49152
	ds_read_b128 v[184:187], v151 offset:50176
	ds_read_b128 v[188:191], v151 offset:51200
	ds_read_b128 v[192:195], v151 offset:52224
	ds_read_b128 v[196:199], v151 offset:53248
	ds_read_b128 v[200:203], v151 offset:54272
	ds_read_b128 v[206:209], v151 offset:55296
	ds_read_b128 v[210:213], v151 offset:56320
	s_mov_b32 m0, s0
	v_lshl_add_u64 v[144:145], s[42:43], 0, v[132:133]
	global_load_lds_dwordx4 v[144:145], off
	s_add_i32 m0, s0, 0x2000
	v_lshl_add_u64 v[144:145], s[42:43], 0, v[128:129]
	s_add_u32 s42, s44, 0x40000
	s_addc_u32 s43, s45, 0
	s_add_i32 s0, s1, s23
	global_load_lds_dwordx4 v[144:145], off
	s_mov_b32 m0, s0
	v_lshl_add_u64 v[144:145], s[42:43], 0, v[132:133]
	global_load_lds_dwordx4 v[144:145], off
	v_lshl_add_u64 v[144:145], s[42:43], 0, v[128:129]
	s_add_i32 m0, s0, 0x2000
	s_nop 0
	global_load_lds_dwordx4 v[144:145], off
	s_mov_b32 m0, s57
	v_lshl_add_u64 v[144:145], s[40:41], 0, v[134:135]
	global_load_lds_dwordx4 v[144:145], off
	v_lshl_add_u64 v[144:145], s[40:41], 0, v[130:131]
	s_mov_b32 m0, s58
	s_nop 0
	global_load_lds_dwordx4 v[144:145], off
	s_waitcnt vmcnt(8)
	s_waitcnt lgkmcnt(0)
	s_barrier
	s_waitcnt lgkmcnt(0)
	v_mfma_f32_16x16x32_bf16 v[60:63], v[140:143], v[180:183], v[60:63]
	v_mfma_f32_16x16x32_bf16 v[56:59], v[156:159], v[180:183], v[56:59]
	v_mfma_f32_16x16x32_bf16 v[44:47], v[140:143], v[188:191], v[44:47]
	v_mfma_f32_16x16x32_bf16 v[40:43], v[156:159], v[188:191], v[40:43]
	v_mfma_f32_16x16x32_bf16 v[28:31], v[140:143], v[196:199], v[28:31]
	v_mfma_f32_16x16x32_bf16 v[24:27], v[156:159], v[196:199], v[24:27]
	v_mfma_f32_16x16x32_bf16 v[12:15], v[140:143], v[206:209], v[12:15]
	v_mfma_f32_16x16x32_bf16 v[8:11], v[156:159], v[206:209], v[8:11]
	v_mfma_f32_16x16x32_bf16 v[60:63], v[152:155], v[184:187], v[60:63]
	v_mfma_f32_16x16x32_bf16 v[56:59], v[160:163], v[184:187], v[56:59]
	v_mfma_f32_16x16x32_bf16 v[44:47], v[152:155], v[192:195], v[44:47]
	v_mfma_f32_16x16x32_bf16 v[40:43], v[160:163], v[192:195], v[40:43]
	v_mfma_f32_16x16x32_bf16 v[28:31], v[152:155], v[200:203], v[28:31]
	v_mfma_f32_16x16x32_bf16 v[24:27], v[160:163], v[200:203], v[24:27]
	v_mfma_f32_16x16x32_bf16 v[12:15], v[152:155], v[210:213], v[12:15]
	v_mfma_f32_16x16x32_bf16 v[8:11], v[160:163], v[210:213], v[8:11]
	v_mfma_f32_16x16x32_bf16 v[52:55], v[164:167], v[180:183], v[52:55]
	v_mfma_f32_16x16x32_bf16 v[48:51], v[172:175], v[180:183], v[48:51]
	v_mfma_f32_16x16x32_bf16 v[36:39], v[164:167], v[188:191], v[36:39]
	v_mfma_f32_16x16x32_bf16 v[32:35], v[172:175], v[188:191], v[32:35]
	v_mfma_f32_16x16x32_bf16 v[20:23], v[164:167], v[196:199], v[20:23]
	v_mfma_f32_16x16x32_bf16 v[16:19], v[172:175], v[196:199], v[16:19]
	v_mfma_f32_16x16x32_bf16 v[4:7], v[164:167], v[206:209], v[4:7]
	v_mfma_f32_16x16x32_bf16 v[0:3], v[172:175], v[206:209], v[0:3]
	v_mfma_f32_16x16x32_bf16 v[52:55], v[168:171], v[184:187], v[52:55]
	v_mfma_f32_16x16x32_bf16 v[48:51], v[176:179], v[184:187], v[48:51]
	v_mfma_f32_16x16x32_bf16 v[36:39], v[168:171], v[192:195], v[36:39]
	v_mfma_f32_16x16x32_bf16 v[32:35], v[176:179], v[192:195], v[32:35]
	v_mfma_f32_16x16x32_bf16 v[20:23], v[168:171], v[200:203], v[20:23]
	v_mfma_f32_16x16x32_bf16 v[16:19], v[176:179], v[200:203], v[16:19]
	v_mfma_f32_16x16x32_bf16 v[4:7], v[168:171], v[210:213], v[4:7]
	v_mfma_f32_16x16x32_bf16 v[0:3], v[176:179], v[210:213], v[0:3]
	s_barrier
	s_add_i32 s72, s72, 2
	s_add_u32 s70, s70, 0x100
	s_addc_u32 s71, s71, 0
	s_add_u32 s38, s38, 0x100
	s_addc_u32 s39, s39, 0
	s_cmp_gt_u32 s72, 13
	s_cbranch_scc0 .LBB0_1398
	s_and_b64 vcc, exec, s[10:11]
	s_cbranch_vccz .LBB0_1401
	s_barrier

; #define PG8_STAGE(bufoff, gbase, voff) do { const char* _gb = (const char*)(gbase); asm volatile("" : "+s"(_gb));     \
;         _Pragma("unroll") for (int _i = 0; _i < 2; ++_i) \
;         __builtin_amdgcn_global_load_lds((const unsigned*)(_gb + (voff)[_i]), (LAS unsigned*)(lds + (bufoff) + ldsw + _i * 8192), 16, 0, 0); } while (0)
; #define PG8_LDA(dst, b, h) do { _Pragma("unroll") for (int m = 0; m < 4; ++m) _Pragma("unroll") for (int k = 0; k < 2; ++k) dst[m][k] = *(const LAS bf16x8*)(lds + PG8_SA(b, h) + aoff + m * 2048 + k * 1024); } while (0)
; #define PG8_LDB(dst, b, h) do { _Pragma("unroll") for (int n = 0; n < 2; ++n) _Pragma("unroll") for (int k = 0; k < 2; ++k) dst[n][k] = *(const LAS bf16x8*)(lds + PG8_SB(b, h) + boff + n * 2048 + k * 1024); } while (0)
; #define PG8_MMA(ai, bj, At, Bt) do { __builtin_amdgcn_s_setprio(1); _Pragma("unroll") for (int m = 0; m < 4; ++m) _Pragma("unroll") for (int n = 0; n < 2; ++n) _Pragma("unroll") for (int k = 0; k < 2; ++k) \
;         acc[ai][bj][m][n] = __builtin_amdgcn_mfma_f32_16x16x32_bf16(Bt[n][k], At[m][k], acc[ai][bj][m][n], 0, 0, 0); __builtin_amdgcn_s_setprio(0); } while (0)
; #define PG8_WAIT_V(n) asm volatile("s_waitcnt vmcnt(" #n ")" ::: "memory")
; #define PG8_WAIT_L(n) asm volatile("s_waitcnt lgkmcnt(" #n ")" ::: "memory")
; #define PG8_BAR __builtin_amdgcn_s_barrier()
; #define PG8_SCHED __builtin_amdgcn_sched_barrier(0)
; template <class Epi>
; __device__ __forceinline__ void gemm_phase(LAS unsigned char* lds, const int wid, const Gemm g, const Epi& E) {
;     ...
;         for (int t = 0; t < nt; t += 2) {
;             const bool last = (t == nt - 2);
;             const char* a1 = PG8_AP(cA, t + 1);
;             const char* a2 = last ? PG8_AP(nA, 0) : PG8_AP(cA, t + 2); const char* b2 = last ? PG8_BP(nB, 0) : PG8_BP(cB, t + 2);
;             const char* a3 = last ? PG8_AP(nA, 1) : PG8_AP(cA, t + 3); const char* b3 = last ? PG8_BP(nB, 1) : PG8_BP(cB, t + 3);
;             PG8_LDB(B0, 0, 0); PG8_LDB(B1, 0, 1); PG8_SCHED; PG8_LDA(At, 0, 0); PG8_STAGE(PG8_SA(1, 1), a1 + hstepA, voffA);
;             PG8_WAIT_V(8); PG8_WAIT_L(0); PG8_BAR; PG8_MMA(0, 0, At, B0); PG8_MMA(0, 1, At, B1); PG8_BAR; PG8_SCHED;
;             PG8_LDA(At, 0, 1); PG8_STAGE(PG8_SB(0, 0), b2, voffB); PG8_STAGE(PG8_SB(0, 1), b2 + hstepB, voffB); PG8_STAGE(PG8_SA(0, 0), a2, voffA);
.LBB0_1530:
	ds_read_b128 v[146:149], v143
	ds_read_b128 v[150:153], v143 offset:1024
	ds_read_b128 v[154:157], v143 offset:2048
	ds_read_b128 v[158:161], v143 offset:3072
	ds_read_b128 v[162:165], v144
	ds_read_b128 v[166:169], v144 offset:1024
	ds_read_b128 v[170:173], v144 offset:2048
	ds_read_b128 v[174:177], v144 offset:3072
	s_add_u32 s0, s24, 0xfffc0080
	s_addc_u32 s1, s25, -1
	s_add_u32 s26, s62, 0xffffff80
	s_addc_u32 s27, s63, -1
	s_add_u32 s30, s24, 0xfffc0100
	s_addc_u32 s31, s25, -1
	s_add_i32 s68, s52, s23
	s_add_i32 m0, s21, 0xc000
	s_add_i32 s65, s21, 0xe000
	s_add_i32 s69, s68, 0x2000
	s_cmp_eq_u32 s64, 12
	s_cselect_b32 s29, s15, s1
	s_cselect_b32 s28, s56, s0
	s_cselect_b32 s67, s13, s27
	s_cselect_b32 s66, s57, s26
	s_cselect_b32 s27, s59, s31
	s_cselect_b32 s26, s58, s30
	s_mov_b64 s[30:31], s[24:25]
	ds_read_b128 v[178:181], v145
	ds_read_b128 v[182:185], v145 offset:1024
	ds_read_b128 v[186:189], v145 offset:2048
	ds_read_b128 v[190:193], v145 offset:3072
	ds_read_b128 v[194:197], v145 offset:4096
	ds_read_b128 v[198:201], v145 offset:5120
	ds_read_b128 v[206:209], v145 offset:6144
	ds_read_b128 v[210:213], v145 offset:7168
	s_nop 0
	v_lshl_add_u64 v[202:203], s[30:31], 0, v[134:135]
	global_load_lds_dwordx4 v[202:203], off
	v_lshl_add_u64 v[202:203], s[30:31], 0, v[130:131]
	s_mov_b32 m0, s65
	s_nop 0
	global_load_lds_dwordx4 v[202:203], off
	s_waitcnt vmcnt(8)
	s_waitcnt lgkmcnt(0)
	s_barrier
	s_waitcnt lgkmcnt(0)
	v_mfma_f32_16x16x32_bf16 v[124:127], v[146:149], v[178:181], v[124:127]
	v_mfma_f32_16x16x32_bf16 v[120:123], v[154:157], v[178:181], v[120:123]
	v_mfma_f32_16x16x32_bf16 v[108:111], v[146:149], v[186:189], v[108:111]
	v_mfma_f32_16x16x32_bf16 v[104:107], v[154:157], v[186:189], v[104:107]
	v_mfma_f32_16x16x32_bf16 v[92:95], v[146:149], v[194:197], v[92:95]
	v_mfma_f32_16x16x32_bf16 v[88:91], v[154:157], v[194:197], v[88:91]
	v_mfma_f32_16x16x32_bf16 v[76:79], v[146:149], v[206:209], v[76:79]
	v_mfma_f32_16x16x32_bf16 v[72:75], v[154:157], v[206:209], v[72:75]
	v_mfma_f32_16x16x32_bf16 v[124:127], v[150:153], v[182:185], v[124:127]
	v_mfma_f32_16x16x32_bf16 v[120:123], v[158:161], v[182:185], v[120:123]
	v_mfma_f32_16x16x32_bf16 v[108:111], v[150:153], v[190:193], v[108:111]
	v_mfma_f32_16x16x32_bf16 v[104:107], v[158:161], v[190:193], v[104:107]
	v_mfma_f32_16x16x32_bf16 v[92:95], v[150:153], v[198:201], v[92:95]
	v_mfma_f32_16x16x32_bf16 v[88:91], v[158:161], v[198:201], v[88:91]
	v_mfma_f32_16x16x32_bf16 v[76:79], v[150:153], v[210:213], v[76:79]
	v_mfma_f32_16x16x32_bf16 v[72:75], v[158:161], v[210:213], v[72:75]
	v_mfma_f32_16x16x32_bf16 v[116:119], v[162:165], v[178:181], v[116:119]
	v_mfma_f32_16x16x32_bf16 v[112:115], v[170:173], v[178:181], v[112:115]
	v_mfma_f32_16x16x32_bf16 v[100:103], v[162:165], v[186:189], v[100:103]
	v_mfma_f32_16x16x32_bf16 v[96:99], v[170:173], v[186:189], v[96:99]
	v_mfma_f32_16x16x32_bf16 v[84:87], v[162:165], v[194:197], v[84:87]
	v_mfma_f32_16x16x32_bf16 v[80:83], v[170:173], v[194:197], v[80:83]
	v_mfma_f32_16x16x32_bf16 v[68:71], v[162:165], v[206:209], v[68:71]
	v_mfma_f32_16x16x32_bf16 v[64:67], v[170:173], v[206:209], v[64:67]
	v_mfma_f32_16x16x32_bf16 v[116:119], v[166:169], v[182:185], v[116:119]
	v_mfma_f32_16x16x32_bf16 v[112:115], v[174:177], v[182:185], v[112:115]
	v_mfma_f32_16x16x32_bf16 v[100:103], v[166:169], v[190:193], v[100:103]
	v_mfma_f32_16x16x32_bf16 v[96:99], v[174:177], v[190:193], v[96:99]
	v_mfma_f32_16x16x32_bf16 v[84:87], v[166:169], v[198:201], v[84:87]
	v_mfma_f32_16x16x32_bf16 v[80:83], v[174:177], v[198:201], v[80:83]
	v_mfma_f32_16x16x32_bf16 v[68:71], v[166:169], v[210:213], v[68:71]
	v_mfma_f32_16x16x32_bf16 v[64:67], v[174:177], v[210:213], v[64:67]
	s_barrier
	s_mov_b64 s[30:31], s[66:67]
	s_mov_b32 m0, s68
	ds_read_b128 v[178:181], v145 offset:16384
	ds_read_b128 v[182:185], v145 offset:17408
	ds_read_b128 v[186:189], v145 offset:18432
	ds_read_b128 v[190:193], v145 offset:19456
	ds_read_b128 v[194:197], v145 offset:20480
	ds_read_b128 v[198:201], v145 offset:21504
	ds_read_b128 v[206:209], v145 offset:22528
	ds_read_b128 v[210:213], v145 offset:23552
	s_nop 0
	v_lshl_add_u64 v[202:203], s[30:31], 0, v[132:133]
	global_load_lds_dwordx4 v[202:203], off
	v_lshl_add_u64 v[202:203], s[30:31], 0, v[128:129]
	s_cselect_b32 s31, s61, s63
	s_cselect_b32 s30, s60, s62
	s_add_u32 s66, s66, 0x40000
	s_mov_b32 m0, s69
	s_addc_u32 s67, s67, 0
	s_add_i32 s0, s53, s23
	global_load_lds_dwordx4 v[202:203], off
	s_mov_b32 m0, s0
	v_lshl_add_u64 v[202:203], s[66:67], 0, v[132:133]
	global_load_lds_dwordx4 v[202:203], off
	v_lshl_add_u64 v[202:203], s[66:67], 0, v[128:129]
	s_add_i32 m0, s0, 0x2000
	s_mov_b64 s[66:67], s[28:29]
	global_load_lds_dwordx4 v[202:203], off
	s_mov_b32 m0, s21
	v_lshl_add_u64 v[202:203], s[66:67], 0, v[134:135]
	global_load_lds_dwordx4 v[202:203], off
	v_lshl_add_u64 v[202:203], s[66:67], 0, v[130:131]
	s_mov_b32 m0, s42
	s_nop 0
	global_load_lds_dwordx4 v[202:203], off
	s_waitcnt vmcnt(8)
	s_waitcnt lgkmcnt(0)
	s_barrier
; #define PG8_STAGE(bufoff, gbase, voff) do { const char* _gb = (const char*)(gbase); asm volatile("" : "+s"(_gb));     \
;         _Pragma("unroll") for (int _i = 0; _i < 2; ++_i) \
;         __builtin_amdgcn_global_load_lds((const unsigned*)(_gb + (voff)[_i]), (LAS unsigned*)(lds + (bufoff) + ldsw + _i * 8192), 16, 0, 0); } while (0)
; #define PG8_LDA(dst, b, h) do { _Pragma("unroll") for (int m = 0; m < 4; ++m) _Pragma("unroll") for (int k = 0; k < 2; ++k) dst[m][k] = *(const LAS bf16x8*)(lds + PG8_SA(b, h) + aoff + m * 2048 + k * 1024); } while (0)
; #define PG8_LDB(dst, b, h) do { _Pragma("unroll") for (int n = 0; n < 2; ++n) _Pragma("unroll") for (int k = 0; k < 2; ++k) dst[n][k] = *(const LAS bf16x8*)(lds + PG8_SB(b, h) + boff + n * 2048 + k * 1024); } while (0)
; #define PG8_MMA(ai, bj, At, Bt) do { __builtin_amdgcn_s_setprio(1); _Pragma("unroll") for (int m = 0; m < 4; ++m) _Pragma("unroll") for (int n = 0; n < 2; ++n) _Pragma("unroll") for (int k = 0; k < 2; ++k) \
;         acc[ai][bj][m][n] = __builtin_amdgcn_mfma_f32_16x16x32_bf16(Bt[n][k], At[m][k], acc[ai][bj][m][n], 0, 0, 0); __builtin_amdgcn_s_setprio(0); } while (0)
; #define PG8_WAIT_V(n) asm volatile("s_waitcnt vmcnt(" #n ")" ::: "memory")
; #define PG8_WAIT_L(n) asm volatile("s_waitcnt lgkmcnt(" #n ")" ::: "memory")
; #define PG8_BAR __builtin_amdgcn_s_barrier()
; #define PG8_SCHED __builtin_amdgcn_sched_barrier(0)
; template <class Epi>
; __device__ __forceinline__ void gemm_phase(LAS unsigned char* lds, const int wid, const Gemm g, const Epi& E) {
;     ...
;             PG8_WAIT_V(8); PG8_WAIT_L(0); PG8_BAR; PG8_MMA(1, 0, At, B0); PG8_MMA(1, 1, At, B1); PG8_BAR; PG8_SCHED;
;             PG8_LDB(B0, 1, 0); PG8_LDB(B1, 1, 1); PG8_SCHED; PG8_LDA(At, 1, 0); PG8_STAGE(PG8_SA(0, 1), a2 + hstepA, voffA);
;             PG8_WAIT_V(8); PG8_WAIT_L(0); PG8_BAR; PG8_MMA(0, 0, At, B0); PG8_MMA(0, 1, At, B1); PG8_BAR; PG8_SCHED;
	s_waitcnt lgkmcnt(0)
	v_mfma_f32_16x16x32_bf16 v[60:63], v[146:149], v[178:181], v[60:63]
	v_mfma_f32_16x16x32_bf16 v[56:59], v[154:157], v[178:181], v[56:59]
	v_mfma_f32_16x16x32_bf16 v[44:47], v[146:149], v[186:189], v[44:47]
	v_mfma_f32_16x16x32_bf16 v[40:43], v[154:157], v[186:189], v[40:43]
	v_mfma_f32_16x16x32_bf16 v[28:31], v[146:149], v[194:197], v[28:31]
	v_mfma_f32_16x16x32_bf16 v[24:27], v[154:157], v[194:197], v[24:27]
	v_mfma_f32_16x16x32_bf16 v[12:15], v[146:149], v[206:209], v[12:15]
	v_mfma_f32_16x16x32_bf16 v[8:11], v[154:157], v[206:209], v[8:11]
	v_mfma_f32_16x16x32_bf16 v[60:63], v[150:153], v[182:185], v[60:63]
	v_mfma_f32_16x16x32_bf16 v[56:59], v[158:161], v[182:185], v[56:59]
	v_mfma_f32_16x16x32_bf16 v[44:47], v[150:153], v[190:193], v[44:47]
	v_mfma_f32_16x16x32_bf16 v[40:43], v[158:161], v[190:193], v[40:43]
	v_mfma_f32_16x16x32_bf16 v[28:31], v[150:153], v[198:201], v[28:31]
	v_mfma_f32_16x16x32_bf16 v[24:27], v[158:161], v[198:201], v[24:27]
	v_mfma_f32_16x16x32_bf16 v[12:15], v[150:153], v[210:213], v[12:15]
	v_mfma_f32_16x16x32_bf16 v[8:11], v[158:161], v[210:213], v[8:11]
	v_mfma_f32_16x16x32_bf16 v[52:55], v[162:165], v[178:181], v[52:55]
	v_mfma_f32_16x16x32_bf16 v[48:51], v[170:173], v[178:181], v[48:51]
	v_mfma_f32_16x16x32_bf16 v[36:39], v[162:165], v[186:189], v[36:39]
	v_mfma_f32_16x16x32_bf16 v[32:35], v[170:173], v[186:189], v[32:35]
	v_mfma_f32_16x16x32_bf16 v[20:23], v[162:165], v[194:197], v[20:23]
	v_mfma_f32_16x16x32_bf16 v[16:19], v[170:173], v[194:197], v[16:19]
	v_mfma_f32_16x16x32_bf16 v[4:7], v[162:165], v[206:209], v[4:7]
	v_mfma_f32_16x16x32_bf16 v[0:3], v[170:173], v[206:209], v[0:3]
	v_mfma_f32_16x16x32_bf16 v[52:55], v[166:169], v[182:185], v[52:55]
	v_mfma_f32_16x16x32_bf16 v[48:51], v[174:177], v[182:185], v[48:51]
	v_mfma_f32_16x16x32_bf16 v[36:39], v[166:169], v[190:193], v[36:39]
	v_mfma_f32_16x16x32_bf16 v[32:35], v[174:177], v[190:193], v[32:35]
	v_mfma_f32_16x16x32_bf16 v[20:23], v[166:169], v[198:201], v[20:23]
	v_mfma_f32_16x16x32_bf16 v[16:19], v[174:177], v[198:201], v[16:19]
	v_mfma_f32_16x16x32_bf16 v[4:7], v[166:169], v[210:213], v[4:7]
	v_mfma_f32_16x16x32_bf16 v[0:3], v[174:177], v[210:213], v[0:3]
	s_barrier
	s_add_i32 s0, 0, 0x18000
	s_add_i32 s1, 0, 0x1c000
	v_add_u32_e32 v158, s0, v142
	v_add_u32_e32 v174, s1, v142
	ds_read_b128 v[146:149], v158
	ds_read_b128 v[150:153], v158 offset:1024
	ds_read_b128 v[154:157], v158 offset:2048
	ds_read_b128 v[158:161], v158 offset:3072
	ds_read_b128 v[162:165], v174
	ds_read_b128 v[166:169], v174 offset:1024
	ds_read_b128 v[170:173], v174 offset:2048
	ds_read_b128 v[174:177], v174 offset:3072
	s_add_u32 s28, s28, 0x40000
	s_addc_u32 s29, s29, 0
	s_mov_b32 m0, s43
	ds_read_b128 v[178:181], v145 offset:32768
	ds_read_b128 v[182:185], v145 offset:33792
	ds_read_b128 v[186:189], v145 offset:34816
	ds_read_b128 v[190:193], v145 offset:35840
	ds_read_b128 v[194:197], v145 offset:36864
	ds_read_b128 v[198:201], v145 offset:37888
	ds_read_b128 v[206:209], v145 offset:38912
	ds_read_b128 v[210:213], v145 offset:39936
	s_nop 0
	v_lshl_add_u64 v[202:203], s[28:29], 0, v[134:135]
	global_load_lds_dwordx4 v[202:203], off
	v_lshl_add_u64 v[202:203], s[28:29], 0, v[130:131]
	s_mov_b32 m0, s44
	s_nop 0
	global_load_lds_dwordx4 v[202:203], off
	s_waitcnt vmcnt(8)
	s_waitcnt lgkmcnt(0)
	s_barrier
	s_waitcnt lgkmcnt(0)
	v_mfma_f32_16x16x32_bf16 v[124:127], v[146:149], v[178:181], v[124:127]
	v_mfma_f32_16x16x32_bf16 v[120:123], v[154:157], v[178:181], v[120:123]
	v_mfma_f32_16x16x32_bf16 v[108:111], v[146:149], v[186:189], v[108:111]
	v_mfma_f32_16x16x32_bf16 v[104:107], v[154:157], v[186:189], v[104:107]
	v_mfma_f32_16x16x32_bf16 v[92:95], v[146:149], v[194:197], v[92:95]
	v_mfma_f32_16x16x32_bf16 v[88:91], v[154:157], v[194:197], v[88:91]
	v_mfma_f32_16x16x32_bf16 v[76:79], v[146:149], v[206:209], v[76:79]
	v_mfma_f32_16x16x32_bf16 v[72:75], v[154:157], v[206:209], v[72:75]
	v_mfma_f32_16x16x32_bf16 v[124:127], v[150:153], v[182:185], v[124:127]
	v_mfma_f32_16x16x32_bf16 v[120:123], v[158:161], v[182:185], v[120:123]
	v_mfma_f32_16x16x32_bf16 v[108:111], v[150:153], v[190:193], v[108:111]
	v_mfma_f32_16x16x32_bf16 v[104:107], v[158:161], v[190:193], v[104:107]
	v_mfma_f32_16x16x32_bf16 v[92:95], v[150:153], v[198:201], v[92:95]
	v_mfma_f32_16x16x32_bf16 v[88:91], v[158:161], v[198:201], v[88:91]
	v_mfma_f32_16x16x32_bf16 v[76:79], v[150:153], v[210:213], v[76:79]
	v_mfma_f32_16x16x32_bf16 v[72:75], v[158:161], v[210:213], v[72:75]
	v_mfma_f32_16x16x32_bf16 v[116:119], v[162:165], v[178:181], v[116:119]
	v_mfma_f32_16x16x32_bf16 v[112:115], v[170:173], v[178:181], v[112:115]
	v_mfma_f32_16x16x32_bf16 v[100:103], v[162:165], v[186:189], v[100:103]
	v_mfma_f32_16x16x32_bf16 v[96:99], v[170:173], v[186:189], v[96:99]
	v_mfma_f32_16x16x32_bf16 v[84:87], v[162:165], v[194:197], v[84:87]
	v_mfma_f32_16x16x32_bf16 v[80:83], v[170:173], v[194:197], v[80:83]
	v_mfma_f32_16x16x32_bf16 v[68:71], v[162:165], v[206:209], v[68:71]
	v_mfma_f32_16x16x32_bf16 v[64:67], v[170:173], v[206:209], v[64:67]
	v_mfma_f32_16x16x32_bf16 v[116:119], v[166:169], v[182:185], v[116:119]
	v_mfma_f32_16x16x32_bf16 v[112:115], v[174:177], v[182:185], v[112:115]
	v_mfma_f32_16x16x32_bf16 v[100:103], v[166:169], v[190:193], v[100:103]
	v_mfma_f32_16x16x32_bf16 v[96:99], v[174:177], v[190:193], v[96:99]
	v_mfma_f32_16x16x32_bf16 v[84:87], v[166:169], v[198:201], v[84:87]
	v_mfma_f32_16x16x32_bf16 v[80:83], v[174:177], v[198:201], v[80:83]
	v_mfma_f32_16x16x32_bf16 v[68:71], v[166:169], v[210:213], v[68:71]
	v_mfma_f32_16x16x32_bf16 v[64:67], v[174:177], v[210:213], v[64:67]
	s_barrier
; #define PG8_STAGE(bufoff, gbase, voff) do { const char* _gb = (const char*)(gbase); asm volatile("" : "+s"(_gb));     \
;         _Pragma("unroll") for (int _i = 0; _i < 2; ++_i) \
;         __builtin_amdgcn_global_load_lds((const unsigned*)(_gb + (voff)[_i]), (LAS unsigned*)(lds + (bufoff) + ldsw + _i * 8192), 16, 0, 0); } while (0)
; #define PG8_LDA(dst, b, h) do { _Pragma("unroll") for (int m = 0; m < 4; ++m) _Pragma("unroll") for (int k = 0; k < 2; ++k) dst[m][k] = *(const LAS bf16x8*)(lds + PG8_SA(b, h) + aoff + m * 2048 + k * 1024); } while (0)
; #define PG8_MMA(ai, bj, At, Bt) do { __builtin_amdgcn_s_setprio(1); _Pragma("unroll") for (int m = 0; m < 4; ++m) _Pragma("unroll") for (int n = 0; n < 2; ++n) _Pragma("unroll") for (int k = 0; k < 2; ++k) \
;         acc[ai][bj][m][n] = __builtin_amdgcn_mfma_f32_16x16x32_bf16(Bt[n][k], At[m][k], acc[ai][bj][m][n], 0, 0, 0); __builtin_amdgcn_s_setprio(0); } while (0)
; #define PG8_WAIT_V(n) asm volatile("s_waitcnt vmcnt(" #n ")" ::: "memory")
; #define PG8_WAIT_L(n) asm volatile("s_waitcnt lgkmcnt(" #n ")" ::: "memory")
; #define PG8_BAR __builtin_amdgcn_s_barrier()
; #define PG8_SCHED __builtin_amdgcn_sched_barrier(0)
; template <class Epi>
; __device__ __forceinline__ void gemm_phase(LAS unsigned char* lds, const int wid, const Gemm g, const Epi& E) {
;     ...
;             PG8_LDA(At, 1, 1); PG8_STAGE(PG8_SB(1, 0), b3, voffB); PG8_STAGE(PG8_SB(1, 1), b3 + hstepB, voffB); PG8_STAGE(PG8_SA(1, 0), a3, voffA);
;             PG8_WAIT_V(8); PG8_WAIT_L(0); PG8_BAR; PG8_MMA(1, 0, At, B0); PG8_MMA(1, 1, At, B1); PG8_BAR; PG8_SCHED;
;         }
;         if (wr == 0) PG8_BAR;
	s_mov_b64 s[28:29], s[30:31]
	s_add_i32 s0, s0, s23
	ds_read_b128 v[178:181], v145 offset:49152
	ds_read_b128 v[182:185], v145 offset:50176
	ds_read_b128 v[186:189], v145 offset:51200
	ds_read_b128 v[190:193], v145 offset:52224
	ds_read_b128 v[194:197], v145 offset:53248
	ds_read_b128 v[198:201], v145 offset:54272
	ds_read_b128 v[206:209], v145 offset:55296
	ds_read_b128 v[210:213], v145 offset:56320
	s_mov_b32 m0, s0
	v_lshl_add_u64 v[202:203], s[28:29], 0, v[132:133]
	global_load_lds_dwordx4 v[202:203], off
	s_add_i32 m0, s0, 0x2000
	v_lshl_add_u64 v[202:203], s[28:29], 0, v[128:129]
	s_add_u32 s28, s30, 0x40000
	s_addc_u32 s29, s31, 0
	s_add_i32 s0, s1, s23
	global_load_lds_dwordx4 v[202:203], off
	s_mov_b32 m0, s0
	v_lshl_add_u64 v[202:203], s[28:29], 0, v[132:133]
	global_load_lds_dwordx4 v[202:203], off
	v_lshl_add_u64 v[202:203], s[28:29], 0, v[128:129]
	s_add_i32 m0, s0, 0x2000
	s_nop 0
	global_load_lds_dwordx4 v[202:203], off
	s_mov_b32 m0, s48
	v_lshl_add_u64 v[202:203], s[26:27], 0, v[134:135]
	global_load_lds_dwordx4 v[202:203], off
	v_lshl_add_u64 v[202:203], s[26:27], 0, v[130:131]
	s_mov_b32 m0, s49
	s_nop 0
	global_load_lds_dwordx4 v[202:203], off
	s_waitcnt vmcnt(8)
	s_waitcnt lgkmcnt(0)
	s_barrier
	s_waitcnt lgkmcnt(0)
	v_mfma_f32_16x16x32_bf16 v[60:63], v[146:149], v[178:181], v[60:63]
	v_mfma_f32_16x16x32_bf16 v[56:59], v[154:157], v[178:181], v[56:59]
	v_mfma_f32_16x16x32_bf16 v[44:47], v[146:149], v[186:189], v[44:47]
	v_mfma_f32_16x16x32_bf16 v[40:43], v[154:157], v[186:189], v[40:43]
	v_mfma_f32_16x16x32_bf16 v[28:31], v[146:149], v[194:197], v[28:31]
	v_mfma_f32_16x16x32_bf16 v[24:27], v[154:157], v[194:197], v[24:27]
	v_mfma_f32_16x16x32_bf16 v[12:15], v[146:149], v[206:209], v[12:15]
	v_mfma_f32_16x16x32_bf16 v[8:11], v[154:157], v[206:209], v[8:11]
	v_mfma_f32_16x16x32_bf16 v[60:63], v[150:153], v[182:185], v[60:63]
	v_mfma_f32_16x16x32_bf16 v[56:59], v[158:161], v[182:185], v[56:59]
	v_mfma_f32_16x16x32_bf16 v[44:47], v[150:153], v[190:193], v[44:47]
	v_mfma_f32_16x16x32_bf16 v[40:43], v[158:161], v[190:193], v[40:43]
	v_mfma_f32_16x16x32_bf16 v[28:31], v[150:153], v[198:201], v[28:31]
	v_mfma_f32_16x16x32_bf16 v[24:27], v[158:161], v[198:201], v[24:27]
	v_mfma_f32_16x16x32_bf16 v[12:15], v[150:153], v[210:213], v[12:15]
	v_mfma_f32_16x16x32_bf16 v[8:11], v[158:161], v[210:213], v[8:11]
	v_mfma_f32_16x16x32_bf16 v[52:55], v[162:165], v[178:181], v[52:55]
	v_mfma_f32_16x16x32_bf16 v[48:51], v[170:173], v[178:181], v[48:51]
	v_mfma_f32_16x16x32_bf16 v[36:39], v[162:165], v[186:189], v[36:39]
	v_mfma_f32_16x16x32_bf16 v[32:35], v[170:173], v[186:189], v[32:35]
	v_mfma_f32_16x16x32_bf16 v[20:23], v[162:165], v[194:197], v[20:23]
	v_mfma_f32_16x16x32_bf16 v[16:19], v[170:173], v[194:197], v[16:19]
	v_mfma_f32_16x16x32_bf16 v[4:7], v[162:165], v[206:209], v[4:7]
	v_mfma_f32_16x16x32_bf16 v[0:3], v[170:173], v[206:209], v[0:3]
	v_mfma_f32_16x16x32_bf16 v[52:55], v[166:169], v[182:185], v[52:55]
	v_mfma_f32_16x16x32_bf16 v[48:51], v[174:177], v[182:185], v[48:51]
	v_mfma_f32_16x16x32_bf16 v[36:39], v[166:169], v[190:193], v[36:39]
	v_mfma_f32_16x16x32_bf16 v[32:35], v[174:177], v[190:193], v[32:35]
	v_mfma_f32_16x16x32_bf16 v[20:23], v[166:169], v[198:201], v[20:23]
	v_mfma_f32_16x16x32_bf16 v[16:19], v[174:177], v[198:201], v[16:19]
	v_mfma_f32_16x16x32_bf16 v[4:7], v[166:169], v[210:213], v[4:7]
	v_mfma_f32_16x16x32_bf16 v[0:3], v[174:177], v[210:213], v[0:3]
	s_barrier
	s_add_i32 s64, s64, 2
	s_add_u32 s62, s62, 0x100
	s_addc_u32 s63, s63, 0
	s_add_u32 s24, s24, 0x100
	s_addc_u32 s25, s25, 0
	s_cmp_gt_u32 s64, 13
	s_cbranch_scc0 .LBB0_1530
	s_and_b64 vcc, exec, s[8:9]
	s_cbranch_vccz .LBB0_1533
	s_barrier

; #define PG8_STAGE(bufoff, gbase, voff) do { const char* _gb = (const char*)(gbase); asm volatile("" : "+s"(_gb));     \
;         _Pragma("unroll") for (int _i = 0; _i < 2; ++_i) \
;         __builtin_amdgcn_global_load_lds((const unsigned*)(_gb + (voff)[_i]), (LAS unsigned*)(lds + (bufoff) + ldsw + _i * 8192), 16, 0, 0); } while (0)
; #define PG8_LDA(dst, b, h) do { _Pragma("unroll") for (int m = 0; m < 4; ++m) _Pragma("unroll") for (int k = 0; k < 2; ++k) dst[m][k] = *(const LAS bf16x8*)(lds + PG8_SA(b, h) + aoff + m * 2048 + k * 1024); } while (0)
; #define PG8_LDB(dst, b, h) do { _Pragma("unroll") for (int n = 0; n < 2; ++n) _Pragma("unroll") for (int k = 0; k < 2; ++k) dst[n][k] = *(const LAS bf16x8*)(lds + PG8_SB(b, h) + boff + n * 2048 + k * 1024); } while (0)
; #define PG8_MMA(ai, bj, At, Bt) do { __builtin_amdgcn_s_setprio(1); _Pragma("unroll") for (int m = 0; m < 4; ++m) _Pragma("unroll") for (int n = 0; n < 2; ++n) _Pragma("unroll") for (int k = 0; k < 2; ++k) \
;         acc[ai][bj][m][n] = __builtin_amdgcn_mfma_f32_16x16x32_bf16(Bt[n][k], At[m][k], acc[ai][bj][m][n], 0, 0, 0); __builtin_amdgcn_s_setprio(0); } while (0)
; #define PG8_WAIT_V(n) asm volatile("s_waitcnt vmcnt(" #n ")" ::: "memory")
; #define PG8_WAIT_L(n) asm volatile("s_waitcnt lgkmcnt(" #n ")" ::: "memory")
; #define PG8_BAR __builtin_amdgcn_s_barrier()
; #define PG8_SCHED __builtin_amdgcn_sched_barrier(0)
; template <class Epi>
; __device__ __forceinline__ void gemm_phase(LAS unsigned char* lds, const int wid, const Gemm g, const Epi& E) {
;     ...
;         for (int t = 0; t < nt; t += 2) {
;             const bool last = (t == nt - 2);
;             const char* a1 = PG8_AP(cA, t + 1);
;             const char* a2 = last ? PG8_AP(nA, 0) : PG8_AP(cA, t + 2); const char* b2 = last ? PG8_BP(nB, 0) : PG8_BP(cB, t + 2);
;             const char* a3 = last ? PG8_AP(nA, 1) : PG8_AP(cA, t + 3); const char* b3 = last ? PG8_BP(nB, 1) : PG8_BP(cB, t + 3);
;             PG8_LDB(B0, 0, 0); PG8_LDB(B1, 0, 1); PG8_SCHED; PG8_LDA(At, 0, 0); PG8_STAGE(PG8_SA(1, 1), a1 + hstepA, voffA);
;             PG8_WAIT_V(8); PG8_WAIT_L(0); PG8_BAR; PG8_MMA(0, 0, At, B0); PG8_MMA(0, 1, At, B1); PG8_BAR; PG8_SCHED;
;             PG8_LDA(At, 0, 1); PG8_STAGE(PG8_SB(0, 0), b2, voffB); PG8_STAGE(PG8_SB(0, 1), b2 + hstepB, voffB); PG8_STAGE(PG8_SA(0, 0), a2, voffA);
.LBB0_1604:
	ds_read_b128 v[140:143], v149
	ds_read_b128 v[152:155], v149 offset:1024
	ds_read_b128 v[156:159], v149 offset:2048
	ds_read_b128 v[160:163], v149 offset:3072
	ds_read_b128 v[164:167], v150
	ds_read_b128 v[168:171], v150 offset:1024
	ds_read_b128 v[172:175], v150 offset:2048
	ds_read_b128 v[176:179], v150 offset:3072
	s_add_u32 s0, s28, 0xfff50080
	s_addc_u32 s1, s29, -1
	s_add_u32 s30, s66, 0xffffff80
	s_addc_u32 s31, s67, -1
	s_add_u32 s38, s28, 0xfff50100
	s_addc_u32 s39, s29, -1
	s_add_i32 s72, s56, s23
	s_add_i32 m0, s45, 0xc000
	s_add_i32 s69, s45, 0xe000
	s_add_i32 s73, s72, 0x2000
	s_cmp_eq_u32 s68, 40
	s_cselect_b32 s35, s5, s1
	s_cselect_b32 s34, s4, s0
	s_cselect_b32 s71, s27, s31
	s_cselect_b32 s70, s26, s30
	s_cselect_b32 s31, s63, s39
	s_cselect_b32 s30, s62, s38
	s_mov_b64 s[38:39], s[28:29]
	ds_read_b128 v[180:183], v151
	ds_read_b128 v[184:187], v151 offset:1024
	ds_read_b128 v[188:191], v151 offset:2048
	ds_read_b128 v[192:195], v151 offset:3072
	ds_read_b128 v[196:199], v151 offset:4096
	ds_read_b128 v[200:203], v151 offset:5120
	ds_read_b128 v[206:209], v151 offset:6144
	ds_read_b128 v[210:213], v151 offset:7168
	s_nop 0
	v_lshl_add_u64 v[144:145], s[38:39], 0, v[134:135]
	global_load_lds_dwordx4 v[144:145], off
	v_lshl_add_u64 v[144:145], s[38:39], 0, v[130:131]
	s_mov_b32 m0, s69
	s_nop 0
	global_load_lds_dwordx4 v[144:145], off
	s_waitcnt vmcnt(8)
	s_waitcnt lgkmcnt(0)
	s_barrier
	s_waitcnt lgkmcnt(0)
	v_mfma_f32_16x16x32_bf16 v[124:127], v[140:143], v[180:183], v[124:127]
	v_mfma_f32_16x16x32_bf16 v[120:123], v[156:159], v[180:183], v[120:123]
	v_mfma_f32_16x16x32_bf16 v[108:111], v[140:143], v[188:191], v[108:111]
	v_mfma_f32_16x16x32_bf16 v[104:107], v[156:159], v[188:191], v[104:107]
	v_mfma_f32_16x16x32_bf16 v[92:95], v[140:143], v[196:199], v[92:95]
	v_mfma_f32_16x16x32_bf16 v[88:91], v[156:159], v[196:199], v[88:91]
	v_mfma_f32_16x16x32_bf16 v[76:79], v[140:143], v[206:209], v[76:79]
	v_mfma_f32_16x16x32_bf16 v[72:75], v[156:159], v[206:209], v[72:75]
	v_mfma_f32_16x16x32_bf16 v[124:127], v[152:155], v[184:187], v[124:127]
	v_mfma_f32_16x16x32_bf16 v[120:123], v[160:163], v[184:187], v[120:123]
	v_mfma_f32_16x16x32_bf16 v[108:111], v[152:155], v[192:195], v[108:111]
	v_mfma_f32_16x16x32_bf16 v[104:107], v[160:163], v[192:195], v[104:107]
	v_mfma_f32_16x16x32_bf16 v[92:95], v[152:155], v[200:203], v[92:95]
	v_mfma_f32_16x16x32_bf16 v[88:91], v[160:163], v[200:203], v[88:91]
	v_mfma_f32_16x16x32_bf16 v[76:79], v[152:155], v[210:213], v[76:79]
	v_mfma_f32_16x16x32_bf16 v[72:75], v[160:163], v[210:213], v[72:75]
	v_mfma_f32_16x16x32_bf16 v[116:119], v[164:167], v[180:183], v[116:119]
	v_mfma_f32_16x16x32_bf16 v[112:115], v[172:175], v[180:183], v[112:115]
	v_mfma_f32_16x16x32_bf16 v[100:103], v[164:167], v[188:191], v[100:103]
	v_mfma_f32_16x16x32_bf16 v[96:99], v[172:175], v[188:191], v[96:99]
	v_mfma_f32_16x16x32_bf16 v[84:87], v[164:167], v[196:199], v[84:87]
	v_mfma_f32_16x16x32_bf16 v[80:83], v[172:175], v[196:199], v[80:83]
	v_mfma_f32_16x16x32_bf16 v[68:71], v[164:167], v[206:209], v[68:71]
	v_mfma_f32_16x16x32_bf16 v[64:67], v[172:175], v[206:209], v[64:67]
	v_mfma_f32_16x16x32_bf16 v[116:119], v[168:171], v[184:187], v[116:119]
	v_mfma_f32_16x16x32_bf16 v[112:115], v[176:179], v[184:187], v[112:115]
	v_mfma_f32_16x16x32_bf16 v[100:103], v[168:171], v[192:195], v[100:103]
	v_mfma_f32_16x16x32_bf16 v[96:99], v[176:179], v[192:195], v[96:99]
	v_mfma_f32_16x16x32_bf16 v[84:87], v[168:171], v[200:203], v[84:87]
	v_mfma_f32_16x16x32_bf16 v[80:83], v[176:179], v[200:203], v[80:83]
	v_mfma_f32_16x16x32_bf16 v[68:71], v[168:171], v[210:213], v[68:71]
	v_mfma_f32_16x16x32_bf16 v[64:67], v[176:179], v[210:213], v[64:67]
	s_barrier
	s_mov_b64 s[38:39], s[70:71]
	s_mov_b32 m0, s72
	ds_read_b128 v[180:183], v151 offset:16384
	ds_read_b128 v[184:187], v151 offset:17408
	ds_read_b128 v[188:191], v151 offset:18432
	ds_read_b128 v[192:195], v151 offset:19456
	ds_read_b128 v[196:199], v151 offset:20480
	ds_read_b128 v[200:203], v151 offset:21504
	ds_read_b128 v[206:209], v151 offset:22528
	ds_read_b128 v[210:213], v151 offset:23552
	s_nop 0
	v_lshl_add_u64 v[144:145], s[38:39], 0, v[132:133]
	global_load_lds_dwordx4 v[144:145], off
	v_lshl_add_u64 v[144:145], s[38:39], 0, v[128:129]
	s_cselect_b32 s39, s65, s67
	s_cselect_b32 s38, s64, s66
	s_add_u32 s70, s70, 0xb0000
	s_mov_b32 m0, s73
	s_addc_u32 s71, s71, 0
	s_add_i32 s0, s57, s23
	global_load_lds_dwordx4 v[144:145], off
	s_mov_b32 m0, s0
	v_lshl_add_u64 v[144:145], s[70:71], 0, v[132:133]
	global_load_lds_dwordx4 v[144:145], off
	v_lshl_add_u64 v[144:145], s[70:71], 0, v[128:129]
	s_add_i32 m0, s0, 0x2000
	s_mov_b64 s[70:71], s[34:35]
	global_load_lds_dwordx4 v[144:145], off
	s_mov_b32 m0, s45
	v_lshl_add_u64 v[144:145], s[70:71], 0, v[134:135]
	global_load_lds_dwordx4 v[144:145], off
	v_lshl_add_u64 v[144:145], s[70:71], 0, v[130:131]
	s_mov_b32 m0, s46
	s_nop 0
	global_load_lds_dwordx4 v[144:145], off
	s_waitcnt vmcnt(8)
	s_waitcnt lgkmcnt(0)
	s_barrier
; #define PG8_STAGE(bufoff, gbase, voff) do { const char* _gb = (const char*)(gbase); asm volatile("" : "+s"(_gb));     \
;         _Pragma("unroll") for (int _i = 0; _i < 2; ++_i) \
;         __builtin_amdgcn_global_load_lds((const unsigned*)(_gb + (voff)[_i]), (LAS unsigned*)(lds + (bufoff) + ldsw + _i * 8192), 16, 0, 0); } while (0)
; #define PG8_LDA(dst, b, h) do { _Pragma("unroll") for (int m = 0; m < 4; ++m) _Pragma("unroll") for (int k = 0; k < 2; ++k) dst[m][k] = *(const LAS bf16x8*)(lds + PG8_SA(b, h) + aoff + m * 2048 + k * 1024); } while (0)
; #define PG8_LDB(dst, b, h) do { _Pragma("unroll") for (int n = 0; n < 2; ++n) _Pragma("unroll") for (int k = 0; k < 2; ++k) dst[n][k] = *(const LAS bf16x8*)(lds + PG8_SB(b, h) + boff + n * 2048 + k * 1024); } while (0)
; #define PG8_MMA(ai, bj, At, Bt) do { __builtin_amdgcn_s_setprio(1); _Pragma("unroll") for (int m = 0; m < 4; ++m) _Pragma("unroll") for (int n = 0; n < 2; ++n) _Pragma("unroll") for (int k = 0; k < 2; ++k) \
;         acc[ai][bj][m][n] = __builtin_amdgcn_mfma_f32_16x16x32_bf16(Bt[n][k], At[m][k], acc[ai][bj][m][n], 0, 0, 0); __builtin_amdgcn_s_setprio(0); } while (0)
; #define PG8_WAIT_V(n) asm volatile("s_waitcnt vmcnt(" #n ")" ::: "memory")
; #define PG8_WAIT_L(n) asm volatile("s_waitcnt lgkmcnt(" #n ")" ::: "memory")
; #define PG8_BAR __builtin_amdgcn_s_barrier()
; #define PG8_SCHED __builtin_amdgcn_sched_barrier(0)
; template <class Epi>
; __device__ __forceinline__ void gemm_phase(LAS unsigned char* lds, const int wid, const Gemm g, const Epi& E) {
;     ...
;             PG8_WAIT_V(8); PG8_WAIT_L(0); PG8_BAR; PG8_MMA(1, 0, At, B0); PG8_MMA(1, 1, At, B1); PG8_BAR; PG8_SCHED;
;             PG8_LDB(B0, 1, 0); PG8_LDB(B1, 1, 1); PG8_SCHED; PG8_LDA(At, 1, 0); PG8_STAGE(PG8_SA(0, 1), a2 + hstepA, voffA);
;             PG8_WAIT_V(8); PG8_WAIT_L(0); PG8_BAR; PG8_MMA(0, 0, At, B0); PG8_MMA(0, 1, At, B1); PG8_BAR; PG8_SCHED;
	s_waitcnt lgkmcnt(0)
	v_mfma_f32_16x16x32_bf16 v[60:63], v[140:143], v[180:183], v[60:63]
	v_mfma_f32_16x16x32_bf16 v[56:59], v[156:159], v[180:183], v[56:59]
	v_mfma_f32_16x16x32_bf16 v[44:47], v[140:143], v[188:191], v[44:47]
	v_mfma_f32_16x16x32_bf16 v[40:43], v[156:159], v[188:191], v[40:43]
	v_mfma_f32_16x16x32_bf16 v[28:31], v[140:143], v[196:199], v[28:31]
	v_mfma_f32_16x16x32_bf16 v[24:27], v[156:159], v[196:199], v[24:27]
	v_mfma_f32_16x16x32_bf16 v[12:15], v[140:143], v[206:209], v[12:15]
	v_mfma_f32_16x16x32_bf16 v[8:11], v[156:159], v[206:209], v[8:11]
	v_mfma_f32_16x16x32_bf16 v[60:63], v[152:155], v[184:187], v[60:63]
	v_mfma_f32_16x16x32_bf16 v[56:59], v[160:163], v[184:187], v[56:59]
	v_mfma_f32_16x16x32_bf16 v[44:47], v[152:155], v[192:195], v[44:47]
	v_mfma_f32_16x16x32_bf16 v[40:43], v[160:163], v[192:195], v[40:43]
	v_mfma_f32_16x16x32_bf16 v[28:31], v[152:155], v[200:203], v[28:31]
	v_mfma_f32_16x16x32_bf16 v[24:27], v[160:163], v[200:203], v[24:27]
	v_mfma_f32_16x16x32_bf16 v[12:15], v[152:155], v[210:213], v[12:15]
	v_mfma_f32_16x16x32_bf16 v[8:11], v[160:163], v[210:213], v[8:11]
	v_mfma_f32_16x16x32_bf16 v[52:55], v[164:167], v[180:183], v[52:55]
	v_mfma_f32_16x16x32_bf16 v[48:51], v[172:175], v[180:183], v[48:51]
	v_mfma_f32_16x16x32_bf16 v[36:39], v[164:167], v[188:191], v[36:39]
	v_mfma_f32_16x16x32_bf16 v[32:35], v[172:175], v[188:191], v[32:35]
	v_mfma_f32_16x16x32_bf16 v[20:23], v[164:167], v[196:199], v[20:23]
	v_mfma_f32_16x16x32_bf16 v[16:19], v[172:175], v[196:199], v[16:19]
	v_mfma_f32_16x16x32_bf16 v[4:7], v[164:167], v[206:209], v[4:7]
	v_mfma_f32_16x16x32_bf16 v[0:3], v[172:175], v[206:209], v[0:3]
	v_mfma_f32_16x16x32_bf16 v[52:55], v[168:171], v[184:187], v[52:55]
	v_mfma_f32_16x16x32_bf16 v[48:51], v[176:179], v[184:187], v[48:51]
	v_mfma_f32_16x16x32_bf16 v[36:39], v[168:171], v[192:195], v[36:39]
	v_mfma_f32_16x16x32_bf16 v[32:35], v[176:179], v[192:195], v[32:35]
	v_mfma_f32_16x16x32_bf16 v[20:23], v[168:171], v[200:203], v[20:23]
	v_mfma_f32_16x16x32_bf16 v[16:19], v[176:179], v[200:203], v[16:19]
	v_mfma_f32_16x16x32_bf16 v[4:7], v[168:171], v[210:213], v[4:7]
	v_mfma_f32_16x16x32_bf16 v[0:3], v[176:179], v[210:213], v[0:3]
	s_barrier
	s_add_i32 s0, 0, 0x18000
	v_add_u32_e32 v144, s0, v148
	s_add_i32 s1, 0, 0x1c000
	ds_read_b128 v[140:143], v144
	ds_read_b128 v[152:155], v144 offset:1024
	ds_read_b128 v[156:159], v144 offset:2048
	ds_read_b128 v[160:163], v144 offset:3072
	v_add_u32_e32 v144, s1, v148
	ds_read_b128 v[164:167], v144
	ds_read_b128 v[168:171], v144 offset:1024
	ds_read_b128 v[172:175], v144 offset:2048
	ds_read_b128 v[176:179], v144 offset:3072
	s_add_u32 s34, s34, 0xb0000
	s_addc_u32 s35, s35, 0
	s_mov_b32 m0, s47
	ds_read_b128 v[180:183], v151 offset:32768
	ds_read_b128 v[184:187], v151 offset:33792
	ds_read_b128 v[188:191], v151 offset:34816
	ds_read_b128 v[192:195], v151 offset:35840
	ds_read_b128 v[196:199], v151 offset:36864
	ds_read_b128 v[200:203], v151 offset:37888
	ds_read_b128 v[206:209], v151 offset:38912
	ds_read_b128 v[210:213], v151 offset:39936
	s_nop 0
	v_lshl_add_u64 v[144:145], s[34:35], 0, v[134:135]
	global_load_lds_dwordx4 v[144:145], off
	v_lshl_add_u64 v[144:145], s[34:35], 0, v[130:131]
	s_mov_b32 m0, s48
	s_nop 0
	global_load_lds_dwordx4 v[144:145], off
	s_waitcnt vmcnt(8)
	s_waitcnt lgkmcnt(0)
	s_barrier
	s_waitcnt lgkmcnt(0)
	v_mfma_f32_16x16x32_bf16 v[124:127], v[140:143], v[180:183], v[124:127]
	v_mfma_f32_16x16x32_bf16 v[120:123], v[156:159], v[180:183], v[120:123]
	v_mfma_f32_16x16x32_bf16 v[108:111], v[140:143], v[188:191], v[108:111]
	v_mfma_f32_16x16x32_bf16 v[104:107], v[156:159], v[188:191], v[104:107]
	v_mfma_f32_16x16x32_bf16 v[92:95], v[140:143], v[196:199], v[92:95]
	v_mfma_f32_16x16x32_bf16 v[88:91], v[156:159], v[196:199], v[88:91]
	v_mfma_f32_16x16x32_bf16 v[76:79], v[140:143], v[206:209], v[76:79]
	v_mfma_f32_16x16x32_bf16 v[72:75], v[156:159], v[206:209], v[72:75]
	v_mfma_f32_16x16x32_bf16 v[124:127], v[152:155], v[184:187], v[124:127]
	v_mfma_f32_16x16x32_bf16 v[120:123], v[160:163], v[184:187], v[120:123]
	v_mfma_f32_16x16x32_bf16 v[108:111], v[152:155], v[192:195], v[108:111]
	v_mfma_f32_16x16x32_bf16 v[104:107], v[160:163], v[192:195], v[104:107]
	v_mfma_f32_16x16x32_bf16 v[92:95], v[152:155], v[200:203], v[92:95]
	v_mfma_f32_16x16x32_bf16 v[88:91], v[160:163], v[200:203], v[88:91]
	v_mfma_f32_16x16x32_bf16 v[76:79], v[152:155], v[210:213], v[76:79]
	v_mfma_f32_16x16x32_bf16 v[72:75], v[160:163], v[210:213], v[72:75]
	v_mfma_f32_16x16x32_bf16 v[116:119], v[164:167], v[180:183], v[116:119]
	v_mfma_f32_16x16x32_bf16 v[112:115], v[172:175], v[180:183], v[112:115]
	v_mfma_f32_16x16x32_bf16 v[100:103], v[164:167], v[188:191], v[100:103]
	v_mfma_f32_16x16x32_bf16 v[96:99], v[172:175], v[188:191], v[96:99]
	v_mfma_f32_16x16x32_bf16 v[84:87], v[164:167], v[196:199], v[84:87]
	v_mfma_f32_16x16x32_bf16 v[80:83], v[172:175], v[196:199], v[80:83]
	v_mfma_f32_16x16x32_bf16 v[68:71], v[164:167], v[206:209], v[68:71]
	v_mfma_f32_16x16x32_bf16 v[64:67], v[172:175], v[206:209], v[64:67]
	v_mfma_f32_16x16x32_bf16 v[116:119], v[168:171], v[184:187], v[116:119]
	v_mfma_f32_16x16x32_bf16 v[112:115], v[176:179], v[184:187], v[112:115]
	v_mfma_f32_16x16x32_bf16 v[100:103], v[168:171], v[192:195], v[100:103]
	v_mfma_f32_16x16x32_bf16 v[96:99], v[176:179], v[192:195], v[96:99]
	v_mfma_f32_16x16x32_bf16 v[84:87], v[168:171], v[200:203], v[84:87]
	v_mfma_f32_16x16x32_bf16 v[80:83], v[176:179], v[200:203], v[80:83]
	v_mfma_f32_16x16x32_bf16 v[68:71], v[168:171], v[210:213], v[68:71]
	v_mfma_f32_16x16x32_bf16 v[64:67], v[176:179], v[210:213], v[64:67]
	s_barrier
; #define PG8_STAGE(bufoff, gbase, voff) do { const char* _gb = (const char*)(gbase); asm volatile("" : "+s"(_gb));     \
;         _Pragma("unroll") for (int _i = 0; _i < 2; ++_i) \
;         __builtin_amdgcn_global_load_lds((const unsigned*)(_gb + (voff)[_i]), (LAS unsigned*)(lds + (bufoff) + ldsw + _i * 8192), 16, 0, 0); } while (0)
; #define PG8_LDA(dst, b, h) do { _Pragma("unroll") for (int m = 0; m < 4; ++m) _Pragma("unroll") for (int k = 0; k < 2; ++k) dst[m][k] = *(const LAS bf16x8*)(lds + PG8_SA(b, h) + aoff + m * 2048 + k * 1024); } while (0)
; #define PG8_MMA(ai, bj, At, Bt) do { __builtin_amdgcn_s_setprio(1); _Pragma("unroll") for (int m = 0; m < 4; ++m) _Pragma("unroll") for (int n = 0; n < 2; ++n) _Pragma("unroll") for (int k = 0; k < 2; ++k) \
;         acc[ai][bj][m][n] = __builtin_amdgcn_mfma_f32_16x16x32_bf16(Bt[n][k], At[m][k], acc[ai][bj][m][n], 0, 0, 0); __builtin_amdgcn_s_setprio(0); } while (0)
; #define PG8_WAIT_V(n) asm volatile("s_waitcnt vmcnt(" #n ")" ::: "memory")
; #define PG8_WAIT_L(n) asm volatile("s_waitcnt lgkmcnt(" #n ")" ::: "memory")
; #define PG8_BAR __builtin_amdgcn_s_barrier()
; #define PG8_SCHED __builtin_amdgcn_sched_barrier(0)
; template <class Epi>
; __device__ __forceinline__ void gemm_phase(LAS unsigned char* lds, const int wid, const Gemm g, const Epi& E) {
;     ...
;             PG8_LDA(At, 1, 1); PG8_STAGE(PG8_SB(1, 0), b3, voffB); PG8_STAGE(PG8_SB(1, 1), b3 + hstepB, voffB); PG8_STAGE(PG8_SA(1, 0), a3, voffA);
;             PG8_WAIT_V(8); PG8_WAIT_L(0); PG8_BAR; PG8_MMA(1, 0, At, B0); PG8_MMA(1, 1, At, B1); PG8_BAR; PG8_SCHED;
;         }
;         if (wr == 0) PG8_BAR;
	s_mov_b64 s[34:35], s[38:39]
	s_add_i32 s0, s0, s23
	ds_read_b128 v[180:183], v151 offset:49152
	ds_read_b128 v[184:187], v151 offset:50176
	ds_read_b128 v[188:191], v151 offset:51200
	ds_read_b128 v[192:195], v151 offset:52224
	ds_read_b128 v[196:199], v151 offset:53248
	ds_read_b128 v[200:203], v151 offset:54272
	ds_read_b128 v[206:209], v151 offset:55296
	ds_read_b128 v[210:213], v151 offset:56320
	s_mov_b32 m0, s0
	v_lshl_add_u64 v[144:145], s[34:35], 0, v[132:133]
	global_load_lds_dwordx4 v[144:145], off
	s_add_i32 m0, s0, 0x2000
	v_lshl_add_u64 v[144:145], s[34:35], 0, v[128:129]
	s_add_u32 s34, s38, 0xb0000
	s_addc_u32 s35, s39, 0
	s_add_i32 s0, s1, s23
	global_load_lds_dwordx4 v[144:145], off
	s_mov_b32 m0, s0
	v_lshl_add_u64 v[144:145], s[34:35], 0, v[132:133]
	global_load_lds_dwordx4 v[144:145], off
	v_lshl_add_u64 v[144:145], s[34:35], 0, v[128:129]
	s_add_i32 m0, s0, 0x2000
	s_nop 0
	global_load_lds_dwordx4 v[144:145], off
	s_mov_b32 m0, s52
	v_lshl_add_u64 v[144:145], s[30:31], 0, v[134:135]
	global_load_lds_dwordx4 v[144:145], off
	v_lshl_add_u64 v[144:145], s[30:31], 0, v[130:131]
	s_mov_b32 m0, s53
	s_nop 0
	global_load_lds_dwordx4 v[144:145], off
	s_waitcnt vmcnt(8)
	s_waitcnt lgkmcnt(0)
	s_barrier
	s_waitcnt lgkmcnt(0)
	v_mfma_f32_16x16x32_bf16 v[60:63], v[140:143], v[180:183], v[60:63]
	v_mfma_f32_16x16x32_bf16 v[56:59], v[156:159], v[180:183], v[56:59]
	v_mfma_f32_16x16x32_bf16 v[44:47], v[140:143], v[188:191], v[44:47]
	v_mfma_f32_16x16x32_bf16 v[40:43], v[156:159], v[188:191], v[40:43]
	v_mfma_f32_16x16x32_bf16 v[28:31], v[140:143], v[196:199], v[28:31]
	v_mfma_f32_16x16x32_bf16 v[24:27], v[156:159], v[196:199], v[24:27]
	v_mfma_f32_16x16x32_bf16 v[12:15], v[140:143], v[206:209], v[12:15]
	v_mfma_f32_16x16x32_bf16 v[8:11], v[156:159], v[206:209], v[8:11]
	v_mfma_f32_16x16x32_bf16 v[60:63], v[152:155], v[184:187], v[60:63]
	v_mfma_f32_16x16x32_bf16 v[56:59], v[160:163], v[184:187], v[56:59]
	v_mfma_f32_16x16x32_bf16 v[44:47], v[152:155], v[192:195], v[44:47]
	v_mfma_f32_16x16x32_bf16 v[40:43], v[160:163], v[192:195], v[40:43]
	v_mfma_f32_16x16x32_bf16 v[28:31], v[152:155], v[200:203], v[28:31]
	v_mfma_f32_16x16x32_bf16 v[24:27], v[160:163], v[200:203], v[24:27]
	v_mfma_f32_16x16x32_bf16 v[12:15], v[152:155], v[210:213], v[12:15]
	v_mfma_f32_16x16x32_bf16 v[8:11], v[160:163], v[210:213], v[8:11]
	v_mfma_f32_16x16x32_bf16 v[52:55], v[164:167], v[180:183], v[52:55]
	v_mfma_f32_16x16x32_bf16 v[48:51], v[172:175], v[180:183], v[48:51]
	v_mfma_f32_16x16x32_bf16 v[36:39], v[164:167], v[188:191], v[36:39]
	v_mfma_f32_16x16x32_bf16 v[32:35], v[172:175], v[188:191], v[32:35]
	v_mfma_f32_16x16x32_bf16 v[20:23], v[164:167], v[196:199], v[20:23]
	v_mfma_f32_16x16x32_bf16 v[16:19], v[172:175], v[196:199], v[16:19]
	v_mfma_f32_16x16x32_bf16 v[4:7], v[164:167], v[206:209], v[4:7]
	v_mfma_f32_16x16x32_bf16 v[0:3], v[172:175], v[206:209], v[0:3]
	v_mfma_f32_16x16x32_bf16 v[52:55], v[168:171], v[184:187], v[52:55]
	v_mfma_f32_16x16x32_bf16 v[48:51], v[176:179], v[184:187], v[48:51]
	v_mfma_f32_16x16x32_bf16 v[36:39], v[168:171], v[192:195], v[36:39]
	v_mfma_f32_16x16x32_bf16 v[32:35], v[176:179], v[192:195], v[32:35]
	v_mfma_f32_16x16x32_bf16 v[20:23], v[168:171], v[200:203], v[20:23]
	v_mfma_f32_16x16x32_bf16 v[16:19], v[176:179], v[200:203], v[16:19]
	v_mfma_f32_16x16x32_bf16 v[4:7], v[168:171], v[210:213], v[4:7]
	v_mfma_f32_16x16x32_bf16 v[0:3], v[176:179], v[210:213], v[0:3]
	s_barrier
	s_add_i32 s68, s68, 2
	s_add_u32 s66, s66, 0x100
	s_addc_u32 s67, s67, 0
	s_add_u32 s28, s28, 0x100
	s_addc_u32 s29, s29, 0
	s_cmp_gt_u32 s68, 41
	s_cbranch_scc0 .LBB0_1604
	s_and_b64 vcc, exec, s[10:11]
	s_cbranch_vccz .LBB0_1607
	s_barrier

; #define PG8_STAGE(bufoff, gbase, voff) do { const char* _gb = (const char*)(gbase); asm volatile("" : "+s"(_gb));     \
;         _Pragma("unroll") for (int _i = 0; _i < 2; ++_i) \
;         __builtin_amdgcn_global_load_lds((const unsigned*)(_gb + (voff)[_i]), (LAS unsigned*)(lds + (bufoff) + ldsw + _i * 8192), 16, 0, 0); } while (0)
; #define PG8_LDA(dst, b, h) do { _Pragma("unroll") for (int m = 0; m < 4; ++m) _Pragma("unroll") for (int k = 0; k < 2; ++k) dst[m][k] = *(const LAS bf16x8*)(lds + PG8_SA(b, h) + aoff + m * 2048 + k * 1024); } while (0)
; #define PG8_LDB(dst, b, h) do { _Pragma("unroll") for (int n = 0; n < 2; ++n) _Pragma("unroll") for (int k = 0; k < 2; ++k) dst[n][k] = *(const LAS bf16x8*)(lds + PG8_SB(b, h) + boff + n * 2048 + k * 1024); } while (0)
; #define PG8_MMA(ai, bj, At, Bt) do { __builtin_amdgcn_s_setprio(1); _Pragma("unroll") for (int m = 0; m < 4; ++m) _Pragma("unroll") for (int n = 0; n < 2; ++n) _Pragma("unroll") for (int k = 0; k < 2; ++k) \
;         acc[ai][bj][m][n] = __builtin_amdgcn_mfma_f32_16x16x32_bf16(Bt[n][k], At[m][k], acc[ai][bj][m][n], 0, 0, 0); __builtin_amdgcn_s_setprio(0); } while (0)
; #define PG8_WAIT_V(n) asm volatile("s_waitcnt vmcnt(" #n ")" ::: "memory")
; #define PG8_WAIT_L(n) asm volatile("s_waitcnt lgkmcnt(" #n ")" ::: "memory")
; #define PG8_BAR __builtin_amdgcn_s_barrier()
; template <class Epi>
; __device__ __forceinline__ void gemm_phase(LAS unsigned char* lds, const int wid, const Gemm g, const Epi& E) {
;     ...
;             const bool last = (t == nt - 2);
;             const char* a1 = PG8_AP(cA, t + 1);
;             const char* a2 = last ? PG8_AP(nA, 0) : PG8_AP(cA, t + 2); const char* b2 = last ? PG8_BP(nB, 0) : PG8_BP(cB, t + 2);
;             const char* a3 = last ? PG8_AP(nA, 1) : PG8_AP(cA, t + 3); const char* b3 = last ? PG8_BP(nB, 1) : PG8_BP(cB, t + 3);
;             PG8_LDB(B0, 0, 0); PG8_LDB(B1, 0, 1); PG8_SCHED; PG8_LDA(At, 0, 0); PG8_STAGE(PG8_SA(1, 1), a1 + hstepA, voffA);
;             PG8_WAIT_V(8); PG8_WAIT_L(0); PG8_BAR; PG8_MMA(0, 0, At, B0); PG8_MMA(0, 1, At, B1); PG8_BAR; PG8_SCHED;
;             PG8_LDA(At, 0, 1); PG8_STAGE(PG8_SB(0, 0), b2, voffB); PG8_STAGE(PG8_SB(0, 1), b2 + hstepB, voffB); PG8_STAGE(PG8_SA(0, 0), a2, voffA);
;             PG8_WAIT_V(8); PG8_WAIT_L(0); PG8_BAR; PG8_MMA(1, 0, At, B0); PG8_MMA(1, 1, At, B1); PG8_BAR; PG8_SCHED;
.LBB0_1751:
	ds_read_b128 v[128:131], v167
	ds_read_b128 v[132:135], v167 offset:1024
	ds_read_b128 v[136:139], v167 offset:2048
	ds_read_b128 v[140:143], v167 offset:3072
	ds_read_b128 v[156:159], v168
	ds_read_b128 v[172:175], v168 offset:1024
	ds_read_b128 v[176:179], v168 offset:2048
	ds_read_b128 v[180:183], v168 offset:3072
	s_add_u32 s0, s34, 0xfffc0080
	s_addc_u32 s1, s35, -1
	s_add_u32 s38, s72, 0xffffff80
	s_addc_u32 s39, s73, -1
	s_add_u32 s42, s34, 0xfffc0100
	s_addc_u32 s43, s35, -1
	s_add_i32 s78, s63, s47
	s_add_i32 m0, s31, 0xc000
	s_add_i32 s75, s31, 0xe000
	s_add_i32 s79, s78, 0x2000
	s_cmp_eq_u32 s74, 12
	s_cselect_b32 s41, s5, s1
	s_cselect_b32 s40, s25, s0
	s_cselect_b32 s77, s21, s39
	s_cselect_b32 s76, s67, s38
	s_cselect_b32 s39, s69, s43
	s_cselect_b32 s38, s68, s42
	s_mov_b64 s[42:43], s[34:35]
	ds_read_b128 v[184:187], v169
	ds_read_b128 v[188:191], v169 offset:1024
	ds_read_b128 v[192:195], v169 offset:2048
	ds_read_b128 v[196:199], v169 offset:3072
	ds_read_b128 v[200:203], v169 offset:4096
	ds_read_b128 v[206:209], v169 offset:5120
	ds_read_b128 v[210:213], v169 offset:6144
	ds_read_b128 v[214:217], v169 offset:7168
	s_nop 0
	v_lshl_add_u64 v[160:161], s[42:43], 0, v[144:145]
	global_load_lds_dwordx4 v[160:161], off
	v_lshl_add_u64 v[160:161], s[42:43], 0, v[148:149]
	s_mov_b32 m0, s75
	s_nop 0
	global_load_lds_dwordx4 v[160:161], off
	s_waitcnt vmcnt(8)
	s_waitcnt lgkmcnt(0)
	s_barrier
	s_waitcnt lgkmcnt(0)
	v_mfma_f32_16x16x32_bf16 v[124:127], v[128:131], v[184:187], v[124:127]
	v_mfma_f32_16x16x32_bf16 v[120:123], v[136:139], v[184:187], v[120:123]
	v_mfma_f32_16x16x32_bf16 v[108:111], v[128:131], v[192:195], v[108:111]
	v_mfma_f32_16x16x32_bf16 v[104:107], v[136:139], v[192:195], v[104:107]
	v_mfma_f32_16x16x32_bf16 v[92:95], v[128:131], v[200:203], v[92:95]
	v_mfma_f32_16x16x32_bf16 v[88:91], v[136:139], v[200:203], v[88:91]
	v_mfma_f32_16x16x32_bf16 v[80:83], v[128:131], v[210:213], v[80:83]
	v_mfma_f32_16x16x32_bf16 v[72:75], v[136:139], v[210:213], v[72:75]
	v_mfma_f32_16x16x32_bf16 v[124:127], v[132:135], v[188:191], v[124:127]
	v_mfma_f32_16x16x32_bf16 v[120:123], v[140:143], v[188:191], v[120:123]
	v_mfma_f32_16x16x32_bf16 v[108:111], v[132:135], v[196:199], v[108:111]
	v_mfma_f32_16x16x32_bf16 v[104:107], v[140:143], v[196:199], v[104:107]
	v_mfma_f32_16x16x32_bf16 v[92:95], v[132:135], v[206:209], v[92:95]
	v_mfma_f32_16x16x32_bf16 v[88:91], v[140:143], v[206:209], v[88:91]
	v_mfma_f32_16x16x32_bf16 v[80:83], v[132:135], v[214:217], v[80:83]
	v_mfma_f32_16x16x32_bf16 v[72:75], v[140:143], v[214:217], v[72:75]
	v_mfma_f32_16x16x32_bf16 v[116:119], v[156:159], v[184:187], v[116:119]
	v_mfma_f32_16x16x32_bf16 v[112:115], v[176:179], v[184:187], v[112:115]
	v_mfma_f32_16x16x32_bf16 v[100:103], v[156:159], v[192:195], v[100:103]
	v_mfma_f32_16x16x32_bf16 v[96:99], v[176:179], v[192:195], v[96:99]
	v_mfma_f32_16x16x32_bf16 v[84:87], v[156:159], v[200:203], v[84:87]
	v_mfma_f32_16x16x32_bf16 v[76:79], v[176:179], v[200:203], v[76:79]
	v_mfma_f32_16x16x32_bf16 v[68:71], v[156:159], v[210:213], v[68:71]
	v_mfma_f32_16x16x32_bf16 v[64:67], v[176:179], v[210:213], v[64:67]
	v_mfma_f32_16x16x32_bf16 v[116:119], v[172:175], v[188:191], v[116:119]
	v_mfma_f32_16x16x32_bf16 v[112:115], v[180:183], v[188:191], v[112:115]
	v_mfma_f32_16x16x32_bf16 v[100:103], v[172:175], v[196:199], v[100:103]
	v_mfma_f32_16x16x32_bf16 v[96:99], v[180:183], v[196:199], v[96:99]
	v_mfma_f32_16x16x32_bf16 v[84:87], v[172:175], v[206:209], v[84:87]
	v_mfma_f32_16x16x32_bf16 v[76:79], v[180:183], v[206:209], v[76:79]
	v_mfma_f32_16x16x32_bf16 v[68:71], v[172:175], v[214:217], v[68:71]
	v_mfma_f32_16x16x32_bf16 v[64:67], v[180:183], v[214:217], v[64:67]
	s_barrier
	s_mov_b64 s[42:43], s[76:77]
	s_mov_b32 m0, s78
	ds_read_b128 v[184:187], v169 offset:16384
	ds_read_b128 v[188:191], v169 offset:17408
	ds_read_b128 v[192:195], v169 offset:18432
	ds_read_b128 v[196:199], v169 offset:19456
	ds_read_b128 v[200:203], v169 offset:20480
	ds_read_b128 v[206:209], v169 offset:21504
	ds_read_b128 v[210:213], v169 offset:22528
	ds_read_b128 v[214:217], v169 offset:23552
	s_nop 0
	v_lshl_add_u64 v[160:161], s[42:43], 0, v[146:147]
	global_load_lds_dwordx4 v[160:161], off
	v_lshl_add_u64 v[160:161], s[42:43], 0, v[150:151]
	s_cselect_b32 s43, s71, s73
	s_cselect_b32 s42, s70, s72
	s_add_u32 s76, s76, 0x40000
	s_mov_b32 m0, s79
	s_addc_u32 s77, s77, 0
	s_add_i32 s0, s64, s47
	global_load_lds_dwordx4 v[160:161], off
	s_mov_b32 m0, s0
	v_lshl_add_u64 v[160:161], s[76:77], 0, v[146:147]
	global_load_lds_dwordx4 v[160:161], off
	v_lshl_add_u64 v[160:161], s[76:77], 0, v[150:151]
	s_add_i32 m0, s0, 0x2000
	s_mov_b64 s[76:77], s[40:41]
	global_load_lds_dwordx4 v[160:161], off
	s_mov_b32 m0, s31
	v_lshl_add_u64 v[160:161], s[76:77], 0, v[144:145]
	global_load_lds_dwordx4 v[160:161], off
	v_lshl_add_u64 v[160:161], s[76:77], 0, v[148:149]
	s_mov_b32 m0, s52
	s_nop 0
	global_load_lds_dwordx4 v[160:161], off
	s_waitcnt vmcnt(8)
	s_waitcnt lgkmcnt(0)
	s_barrier
; #define PG8_STAGE(bufoff, gbase, voff) do { const char* _gb = (const char*)(gbase); asm volatile("" : "+s"(_gb));     \
;         _Pragma("unroll") for (int _i = 0; _i < 2; ++_i) \
;         __builtin_amdgcn_global_load_lds((const unsigned*)(_gb + (voff)[_i]), (LAS unsigned*)(lds + (bufoff) + ldsw + _i * 8192), 16, 0, 0); } while (0)
; #define PG8_LDA(dst, b, h) do { _Pragma("unroll") for (int m = 0; m < 4; ++m) _Pragma("unroll") for (int k = 0; k < 2; ++k) dst[m][k] = *(const LAS bf16x8*)(lds + PG8_SA(b, h) + aoff + m * 2048 + k * 1024); } while (0)
; #define PG8_LDB(dst, b, h) do { _Pragma("unroll") for (int n = 0; n < 2; ++n) _Pragma("unroll") for (int k = 0; k < 2; ++k) dst[n][k] = *(const LAS bf16x8*)(lds + PG8_SB(b, h) + boff + n * 2048 + k * 1024); } while (0)
; #define PG8_MMA(ai, bj, At, Bt) do { __builtin_amdgcn_s_setprio(1); _Pragma("unroll") for (int m = 0; m < 4; ++m) _Pragma("unroll") for (int n = 0; n < 2; ++n) _Pragma("unroll") for (int k = 0; k < 2; ++k) \
;         acc[ai][bj][m][n] = __builtin_amdgcn_mfma_f32_16x16x32_bf16(Bt[n][k], At[m][k], acc[ai][bj][m][n], 0, 0, 0); __builtin_amdgcn_s_setprio(0); } while (0)
; #define PG8_WAIT_V(n) asm volatile("s_waitcnt vmcnt(" #n ")" ::: "memory")
; #define PG8_WAIT_L(n) asm volatile("s_waitcnt lgkmcnt(" #n ")" ::: "memory")
; #define PG8_BAR __builtin_amdgcn_s_barrier()
; #define PG8_SCHED __builtin_amdgcn_sched_barrier(0)
; template <class Epi>
; __device__ __forceinline__ void gemm_phase(LAS unsigned char* lds, const int wid, const Gemm g, const Epi& E) {
;     ...
;             PG8_WAIT_V(8); PG8_WAIT_L(0); PG8_BAR; PG8_MMA(1, 0, At, B0); PG8_MMA(1, 1, At, B1); PG8_BAR; PG8_SCHED;
;             PG8_LDB(B0, 1, 0); PG8_LDB(B1, 1, 1); PG8_SCHED; PG8_LDA(At, 1, 0); PG8_STAGE(PG8_SA(0, 1), a2 + hstepA, voffA);
;             PG8_WAIT_V(8); PG8_WAIT_L(0); PG8_BAR; PG8_MMA(0, 0, At, B0); PG8_MMA(0, 1, At, B1); PG8_BAR; PG8_SCHED;
	s_waitcnt lgkmcnt(0)
	v_mfma_f32_16x16x32_bf16 v[60:63], v[128:131], v[184:187], v[60:63]
	v_mfma_f32_16x16x32_bf16 v[56:59], v[136:139], v[184:187], v[56:59]
	v_mfma_f32_16x16x32_bf16 v[48:51], v[128:131], v[192:195], v[48:51]
	v_mfma_f32_16x16x32_bf16 v[40:43], v[136:139], v[192:195], v[40:43]
	v_mfma_f32_16x16x32_bf16 v[28:31], v[128:131], v[200:203], v[28:31]
	v_mfma_f32_16x16x32_bf16 v[24:27], v[136:139], v[200:203], v[24:27]
	v_mfma_f32_16x16x32_bf16 v[16:19], v[128:131], v[210:213], v[16:19]
	v_mfma_f32_16x16x32_bf16 v[8:11], v[136:139], v[210:213], v[8:11]
	v_mfma_f32_16x16x32_bf16 v[60:63], v[132:135], v[188:191], v[60:63]
	v_mfma_f32_16x16x32_bf16 v[56:59], v[140:143], v[188:191], v[56:59]
	v_mfma_f32_16x16x32_bf16 v[48:51], v[132:135], v[196:199], v[48:51]
	v_mfma_f32_16x16x32_bf16 v[40:43], v[140:143], v[196:199], v[40:43]
	v_mfma_f32_16x16x32_bf16 v[28:31], v[132:135], v[206:209], v[28:31]
	v_mfma_f32_16x16x32_bf16 v[24:27], v[140:143], v[206:209], v[24:27]
	v_mfma_f32_16x16x32_bf16 v[16:19], v[132:135], v[214:217], v[16:19]
	v_mfma_f32_16x16x32_bf16 v[8:11], v[140:143], v[214:217], v[8:11]
	v_mfma_f32_16x16x32_bf16 v[52:55], v[156:159], v[184:187], v[52:55]
	v_mfma_f32_16x16x32_bf16 v[44:47], v[176:179], v[184:187], v[44:47]
	v_mfma_f32_16x16x32_bf16 v[36:39], v[156:159], v[192:195], v[36:39]
	v_mfma_f32_16x16x32_bf16 v[32:35], v[176:179], v[192:195], v[32:35]
	v_mfma_f32_16x16x32_bf16 v[20:23], v[156:159], v[200:203], v[20:23]
	v_mfma_f32_16x16x32_bf16 v[12:15], v[176:179], v[200:203], v[12:15]
	v_mfma_f32_16x16x32_bf16 v[4:7], v[156:159], v[210:213], v[4:7]
	v_mfma_f32_16x16x32_bf16 v[0:3], v[176:179], v[210:213], v[0:3]
	v_mfma_f32_16x16x32_bf16 v[52:55], v[172:175], v[188:191], v[52:55]
	v_mfma_f32_16x16x32_bf16 v[44:47], v[180:183], v[188:191], v[44:47]
	v_mfma_f32_16x16x32_bf16 v[36:39], v[172:175], v[196:199], v[36:39]
	v_mfma_f32_16x16x32_bf16 v[32:35], v[180:183], v[196:199], v[32:35]
	v_mfma_f32_16x16x32_bf16 v[20:23], v[172:175], v[206:209], v[20:23]
	v_mfma_f32_16x16x32_bf16 v[12:15], v[180:183], v[206:209], v[12:15]
	v_mfma_f32_16x16x32_bf16 v[4:7], v[172:175], v[214:217], v[4:7]
	v_mfma_f32_16x16x32_bf16 v[0:3], v[180:183], v[214:217], v[0:3]
	s_barrier
	s_add_i32 s0, 0, 0x18000
	s_add_i32 s1, 0, 0x1c000
	v_add_u32_e32 v140, s0, v166
	v_add_u32_e32 v160, s1, v166
	ds_read_b128 v[128:131], v140
	ds_read_b128 v[132:135], v140 offset:1024
	ds_read_b128 v[136:139], v140 offset:2048
	ds_read_b128 v[140:143], v140 offset:3072
	ds_read_b128 v[156:159], v160
	ds_read_b128 v[172:175], v160 offset:1024
	ds_read_b128 v[176:179], v160 offset:2048
	ds_read_b128 v[180:183], v160 offset:3072
	s_add_u32 s40, s40, 0x40000
	s_addc_u32 s41, s41, 0
	s_mov_b32 m0, s53
	ds_read_b128 v[184:187], v169 offset:32768
	ds_read_b128 v[188:191], v169 offset:33792
	ds_read_b128 v[192:195], v169 offset:34816
	ds_read_b128 v[196:199], v169 offset:35840
	ds_read_b128 v[200:203], v169 offset:36864
	ds_read_b128 v[206:209], v169 offset:37888
	ds_read_b128 v[210:213], v169 offset:38912
	ds_read_b128 v[214:217], v169 offset:39936
	s_nop 0
	v_lshl_add_u64 v[160:161], s[40:41], 0, v[144:145]
	global_load_lds_dwordx4 v[160:161], off
	v_lshl_add_u64 v[160:161], s[40:41], 0, v[148:149]
	s_mov_b32 m0, s54
	s_nop 0
	global_load_lds_dwordx4 v[160:161], off
	s_waitcnt vmcnt(8)
	s_waitcnt lgkmcnt(0)
	s_barrier
	s_waitcnt lgkmcnt(0)
	v_mfma_f32_16x16x32_bf16 v[124:127], v[128:131], v[184:187], v[124:127]
	v_mfma_f32_16x16x32_bf16 v[120:123], v[136:139], v[184:187], v[120:123]
	v_mfma_f32_16x16x32_bf16 v[108:111], v[128:131], v[192:195], v[108:111]
	v_mfma_f32_16x16x32_bf16 v[104:107], v[136:139], v[192:195], v[104:107]
	v_mfma_f32_16x16x32_bf16 v[92:95], v[128:131], v[200:203], v[92:95]
	v_mfma_f32_16x16x32_bf16 v[88:91], v[136:139], v[200:203], v[88:91]
	v_mfma_f32_16x16x32_bf16 v[80:83], v[128:131], v[210:213], v[80:83]
	v_mfma_f32_16x16x32_bf16 v[72:75], v[136:139], v[210:213], v[72:75]
	v_mfma_f32_16x16x32_bf16 v[124:127], v[132:135], v[188:191], v[124:127]
	v_mfma_f32_16x16x32_bf16 v[120:123], v[140:143], v[188:191], v[120:123]
	v_mfma_f32_16x16x32_bf16 v[108:111], v[132:135], v[196:199], v[108:111]
	v_mfma_f32_16x16x32_bf16 v[104:107], v[140:143], v[196:199], v[104:107]
	v_mfma_f32_16x16x32_bf16 v[92:95], v[132:135], v[206:209], v[92:95]
	v_mfma_f32_16x16x32_bf16 v[88:91], v[140:143], v[206:209], v[88:91]
	v_mfma_f32_16x16x32_bf16 v[80:83], v[132:135], v[214:217], v[80:83]
	v_mfma_f32_16x16x32_bf16 v[72:75], v[140:143], v[214:217], v[72:75]
	v_mfma_f32_16x16x32_bf16 v[116:119], v[156:159], v[184:187], v[116:119]
	v_mfma_f32_16x16x32_bf16 v[112:115], v[176:179], v[184:187], v[112:115]
	v_mfma_f32_16x16x32_bf16 v[100:103], v[156:159], v[192:195], v[100:103]
	v_mfma_f32_16x16x32_bf16 v[96:99], v[176:179], v[192:195], v[96:99]
	v_mfma_f32_16x16x32_bf16 v[84:87], v[156:159], v[200:203], v[84:87]
	v_mfma_f32_16x16x32_bf16 v[76:79], v[176:179], v[200:203], v[76:79]
	v_mfma_f32_16x16x32_bf16 v[68:71], v[156:159], v[210:213], v[68:71]
	v_mfma_f32_16x16x32_bf16 v[64:67], v[176:179], v[210:213], v[64:67]
	v_mfma_f32_16x16x32_bf16 v[116:119], v[172:175], v[188:191], v[116:119]
	v_mfma_f32_16x16x32_bf16 v[112:115], v[180:183], v[188:191], v[112:115]
	v_mfma_f32_16x16x32_bf16 v[100:103], v[172:175], v[196:199], v[100:103]
	v_mfma_f32_16x16x32_bf16 v[96:99], v[180:183], v[196:199], v[96:99]
	v_mfma_f32_16x16x32_bf16 v[84:87], v[172:175], v[206:209], v[84:87]
	v_mfma_f32_16x16x32_bf16 v[76:79], v[180:183], v[206:209], v[76:79]
	v_mfma_f32_16x16x32_bf16 v[68:71], v[172:175], v[214:217], v[68:71]
	v_mfma_f32_16x16x32_bf16 v[64:67], v[180:183], v[214:217], v[64:67]
	s_barrier
; #define PG8_STAGE(bufoff, gbase, voff) do { const char* _gb = (const char*)(gbase); asm volatile("" : "+s"(_gb));     \
;         _Pragma("unroll") for (int _i = 0; _i < 2; ++_i) \
;         __builtin_amdgcn_global_load_lds((const unsigned*)(_gb + (voff)[_i]), (LAS unsigned*)(lds + (bufoff) + ldsw + _i * 8192), 16, 0, 0); } while (0)
; #define PG8_LDA(dst, b, h) do { _Pragma("unroll") for (int m = 0; m < 4; ++m) _Pragma("unroll") for (int k = 0; k < 2; ++k) dst[m][k] = *(const LAS bf16x8*)(lds + PG8_SA(b, h) + aoff + m * 2048 + k * 1024); } while (0)
; #define PG8_MMA(ai, bj, At, Bt) do { __builtin_amdgcn_s_setprio(1); _Pragma("unroll") for (int m = 0; m < 4; ++m) _Pragma("unroll") for (int n = 0; n < 2; ++n) _Pragma("unroll") for (int k = 0; k < 2; ++k) \
;         acc[ai][bj][m][n] = __builtin_amdgcn_mfma_f32_16x16x32_bf16(Bt[n][k], At[m][k], acc[ai][bj][m][n], 0, 0, 0); __builtin_amdgcn_s_setprio(0); } while (0)
; #define PG8_WAIT_V(n) asm volatile("s_waitcnt vmcnt(" #n ")" ::: "memory")
; #define PG8_WAIT_L(n) asm volatile("s_waitcnt lgkmcnt(" #n ")" ::: "memory")
; #define PG8_BAR __builtin_amdgcn_s_barrier()
; #define PG8_SCHED __builtin_amdgcn_sched_barrier(0)
; template <class Epi>
; __device__ __forceinline__ void gemm_phase(LAS unsigned char* lds, const int wid, const Gemm g, const Epi& E) {
;     ...
;             PG8_LDA(At, 1, 1); PG8_STAGE(PG8_SB(1, 0), b3, voffB); PG8_STAGE(PG8_SB(1, 1), b3 + hstepB, voffB); PG8_STAGE(PG8_SA(1, 0), a3, voffA);
;             PG8_WAIT_V(8); PG8_WAIT_L(0); PG8_BAR; PG8_MMA(1, 0, At, B0); PG8_MMA(1, 1, At, B1); PG8_BAR; PG8_SCHED;
;         }
;         if (wr == 0) PG8_BAR;
	s_mov_b64 s[40:41], s[42:43]
	s_add_i32 s0, s0, s47
	ds_read_b128 v[184:187], v169 offset:49152
	ds_read_b128 v[188:191], v169 offset:50176
	ds_read_b128 v[192:195], v169 offset:51200
	ds_read_b128 v[196:199], v169 offset:52224
	ds_read_b128 v[200:203], v169 offset:53248
	ds_read_b128 v[206:209], v169 offset:54272
	ds_read_b128 v[210:213], v169 offset:55296
	ds_read_b128 v[214:217], v169 offset:56320
	s_mov_b32 m0, s0
	v_lshl_add_u64 v[160:161], s[40:41], 0, v[146:147]
	global_load_lds_dwordx4 v[160:161], off
	s_add_i32 m0, s0, 0x2000
	v_lshl_add_u64 v[160:161], s[40:41], 0, v[150:151]
	s_add_u32 s40, s42, 0x40000
	s_addc_u32 s41, s43, 0
	s_add_i32 s0, s1, s47
	global_load_lds_dwordx4 v[160:161], off
	s_mov_b32 m0, s0
	v_lshl_add_u64 v[160:161], s[40:41], 0, v[146:147]
	global_load_lds_dwordx4 v[160:161], off
	v_lshl_add_u64 v[160:161], s[40:41], 0, v[150:151]
	s_add_i32 m0, s0, 0x2000
	s_nop 0
	global_load_lds_dwordx4 v[160:161], off
	s_mov_b32 m0, s59
	v_lshl_add_u64 v[160:161], s[38:39], 0, v[144:145]
	global_load_lds_dwordx4 v[160:161], off
	v_lshl_add_u64 v[160:161], s[38:39], 0, v[148:149]
	s_mov_b32 m0, s60
	s_nop 0
	global_load_lds_dwordx4 v[160:161], off
	s_waitcnt vmcnt(8)
	s_waitcnt lgkmcnt(0)
	s_barrier
	s_waitcnt lgkmcnt(0)
	v_mfma_f32_16x16x32_bf16 v[60:63], v[128:131], v[184:187], v[60:63]
	v_mfma_f32_16x16x32_bf16 v[56:59], v[136:139], v[184:187], v[56:59]
	v_mfma_f32_16x16x32_bf16 v[48:51], v[128:131], v[192:195], v[48:51]
	v_mfma_f32_16x16x32_bf16 v[40:43], v[136:139], v[192:195], v[40:43]
	v_mfma_f32_16x16x32_bf16 v[28:31], v[128:131], v[200:203], v[28:31]
	v_mfma_f32_16x16x32_bf16 v[24:27], v[136:139], v[200:203], v[24:27]
	v_mfma_f32_16x16x32_bf16 v[16:19], v[128:131], v[210:213], v[16:19]
	v_mfma_f32_16x16x32_bf16 v[8:11], v[136:139], v[210:213], v[8:11]
	v_mfma_f32_16x16x32_bf16 v[60:63], v[132:135], v[188:191], v[60:63]
	v_mfma_f32_16x16x32_bf16 v[56:59], v[140:143], v[188:191], v[56:59]
	v_mfma_f32_16x16x32_bf16 v[48:51], v[132:135], v[196:199], v[48:51]
	v_mfma_f32_16x16x32_bf16 v[40:43], v[140:143], v[196:199], v[40:43]
	v_mfma_f32_16x16x32_bf16 v[28:31], v[132:135], v[206:209], v[28:31]
	v_mfma_f32_16x16x32_bf16 v[24:27], v[140:143], v[206:209], v[24:27]
	v_mfma_f32_16x16x32_bf16 v[16:19], v[132:135], v[214:217], v[16:19]
	v_mfma_f32_16x16x32_bf16 v[8:11], v[140:143], v[214:217], v[8:11]
	v_mfma_f32_16x16x32_bf16 v[52:55], v[156:159], v[184:187], v[52:55]
	v_mfma_f32_16x16x32_bf16 v[44:47], v[176:179], v[184:187], v[44:47]
	v_mfma_f32_16x16x32_bf16 v[36:39], v[156:159], v[192:195], v[36:39]
	v_mfma_f32_16x16x32_bf16 v[32:35], v[176:179], v[192:195], v[32:35]
	v_mfma_f32_16x16x32_bf16 v[20:23], v[156:159], v[200:203], v[20:23]
	v_mfma_f32_16x16x32_bf16 v[12:15], v[176:179], v[200:203], v[12:15]
	v_mfma_f32_16x16x32_bf16 v[4:7], v[156:159], v[210:213], v[4:7]
	v_mfma_f32_16x16x32_bf16 v[0:3], v[176:179], v[210:213], v[0:3]
	v_mfma_f32_16x16x32_bf16 v[52:55], v[172:175], v[188:191], v[52:55]
	v_mfma_f32_16x16x32_bf16 v[44:47], v[180:183], v[188:191], v[44:47]
	v_mfma_f32_16x16x32_bf16 v[36:39], v[172:175], v[196:199], v[36:39]
	v_mfma_f32_16x16x32_bf16 v[32:35], v[180:183], v[196:199], v[32:35]
	v_mfma_f32_16x16x32_bf16 v[20:23], v[172:175], v[206:209], v[20:23]
	v_mfma_f32_16x16x32_bf16 v[12:15], v[180:183], v[206:209], v[12:15]
	v_mfma_f32_16x16x32_bf16 v[4:7], v[172:175], v[214:217], v[4:7]
	v_mfma_f32_16x16x32_bf16 v[0:3], v[180:183], v[214:217], v[0:3]
	s_barrier
	s_add_i32 s74, s74, 2
	s_add_u32 s72, s72, 0x100
	s_addc_u32 s73, s73, 0
	s_add_u32 s34, s34, 0x100
	s_addc_u32 s35, s35, 0
	s_cmp_gt_u32 s74, 13
	s_cbranch_scc0 .LBB0_1751
	s_and_b64 vcc, exec, s[10:11]
	s_cbranch_vccz .LBB0_1754
	s_barrier

; #define PG8_STAGE(bufoff, gbase, voff) do { const char* _gb = (const char*)(gbase); asm volatile("" : "+s"(_gb));     \
;         _Pragma("unroll") for (int _i = 0; _i < 2; ++_i) \
;         __builtin_amdgcn_global_load_lds((const unsigned*)(_gb + (voff)[_i]), (LAS unsigned*)(lds + (bufoff) + ldsw + _i * 8192), 16, 0, 0); } while (0)
; #define PG8_LDA(dst, b, h) do { _Pragma("unroll") for (int m = 0; m < 4; ++m) _Pragma("unroll") for (int k = 0; k < 2; ++k) dst[m][k] = *(const LAS bf16x8*)(lds + PG8_SA(b, h) + aoff + m * 2048 + k * 1024); } while (0)
; #define PG8_LDB(dst, b, h) do { _Pragma("unroll") for (int n = 0; n < 2; ++n) _Pragma("unroll") for (int k = 0; k < 2; ++k) dst[n][k] = *(const LAS bf16x8*)(lds + PG8_SB(b, h) + boff + n * 2048 + k * 1024); } while (0)
; #define PG8_MMA(ai, bj, At, Bt) do { __builtin_amdgcn_s_setprio(1); _Pragma("unroll") for (int m = 0; m < 4; ++m) _Pragma("unroll") for (int n = 0; n < 2; ++n) _Pragma("unroll") for (int k = 0; k < 2; ++k) \
;         acc[ai][bj][m][n] = __builtin_amdgcn_mfma_f32_16x16x32_bf16(Bt[n][k], At[m][k], acc[ai][bj][m][n], 0, 0, 0); __builtin_amdgcn_s_setprio(0); } while (0)
; #define PG8_WAIT_V(n) asm volatile("s_waitcnt vmcnt(" #n ")" ::: "memory")
; #define PG8_WAIT_L(n) asm volatile("s_waitcnt lgkmcnt(" #n ")" ::: "memory")
; #define PG8_BAR __builtin_amdgcn_s_barrier()
; template <class Epi>
; __device__ __forceinline__ void gemm_phase(LAS unsigned char* lds, const int wid, const Gemm g, const Epi& E) {
;     ...
;             const bool last = (t == nt - 2);
;             const char* a1 = PG8_AP(cA, t + 1);
;             const char* a2 = last ? PG8_AP(nA, 0) : PG8_AP(cA, t + 2); const char* b2 = last ? PG8_BP(nB, 0) : PG8_BP(cB, t + 2);
;             const char* a3 = last ? PG8_AP(nA, 1) : PG8_AP(cA, t + 3); const char* b3 = last ? PG8_BP(nB, 1) : PG8_BP(cB, t + 3);
;             PG8_LDB(B0, 0, 0); PG8_LDB(B1, 0, 1); PG8_SCHED; PG8_LDA(At, 0, 0); PG8_STAGE(PG8_SA(1, 1), a1 + hstepA, voffA);
;             PG8_WAIT_V(8); PG8_WAIT_L(0); PG8_BAR; PG8_MMA(0, 0, At, B0); PG8_MMA(0, 1, At, B1); PG8_BAR; PG8_SCHED;
;             PG8_LDA(At, 0, 1); PG8_STAGE(PG8_SB(0, 0), b2, voffB); PG8_STAGE(PG8_SB(0, 1), b2 + hstepB, voffB); PG8_STAGE(PG8_SA(0, 0), a2, voffA);
;             PG8_WAIT_V(8); PG8_WAIT_L(0); PG8_BAR; PG8_MMA(1, 0, At, B0); PG8_MMA(1, 1, At, B1); PG8_BAR; PG8_SCHED;
.LBB0_2479:
	ds_read_b128 v[140:143], v157
	ds_read_b128 v[144:147], v157 offset:1024
	ds_read_b128 v[148:151], v157 offset:2048
	ds_read_b128 v[160:163], v157 offset:3072
	ds_read_b128 v[164:167], v158
	ds_read_b128 v[168:171], v158 offset:1024
	ds_read_b128 v[172:175], v158 offset:2048
	ds_read_b128 v[176:179], v158 offset:3072
	s_add_u32 s0, s6, 0xfffc0080
	s_addc_u32 s1, s7, -1
	s_add_u32 s50, s88, 0xffffff80
	s_addc_u32 s51, s89, -1
	s_add_u32 s54, s6, 0xfffc0100
	s_addc_u32 s55, s7, -1
	s_add_i32 s94, s78, s59
	s_add_i32 m0, s21, 0xc000
	s_add_i32 s91, s21, 0xe000
	s_add_i32 s95, s94, 0x2000
	s_cmp_eq_u32 s90, 12
	s_cselect_b32 s53, s47, s1
	s_cselect_b32 s52, s46, s0
	s_cselect_b32 s93, s9, s51
	s_cselect_b32 s92, s43, s50
	s_cselect_b32 s51, s85, s55
	s_cselect_b32 s50, s45, s54
	s_mov_b64 s[54:55], s[6:7]
	ds_read_b128 v[180:183], v159
	ds_read_b128 v[184:187], v159 offset:1024
	ds_read_b128 v[188:191], v159 offset:2048
	ds_read_b128 v[192:195], v159 offset:3072
	ds_read_b128 v[196:199], v159 offset:4096
	ds_read_b128 v[200:203], v159 offset:5120
	ds_read_b128 v[206:209], v159 offset:6144
	ds_read_b128 v[210:213], v159 offset:7168
	s_nop 0
	v_lshl_add_u64 v[152:153], s[54:55], 0, v[128:129]
	global_load_lds_dwordx4 v[152:153], off
	v_lshl_add_u64 v[152:153], s[54:55], 0, v[132:133]
	s_mov_b32 m0, s91
	s_nop 0
	global_load_lds_dwordx4 v[152:153], off
	s_waitcnt vmcnt(8)
	s_waitcnt lgkmcnt(0)
	s_barrier
	s_waitcnt lgkmcnt(0)
	v_mfma_f32_16x16x32_bf16 v[124:127], v[140:143], v[180:183], v[124:127]
	v_mfma_f32_16x16x32_bf16 v[120:123], v[148:151], v[180:183], v[120:123]
	v_mfma_f32_16x16x32_bf16 v[116:119], v[140:143], v[188:191], v[116:119]
	v_mfma_f32_16x16x32_bf16 v[112:115], v[148:151], v[188:191], v[112:115]
	v_mfma_f32_16x16x32_bf16 v[100:103], v[140:143], v[196:199], v[100:103]
	v_mfma_f32_16x16x32_bf16 v[96:99], v[148:151], v[196:199], v[96:99]
	v_mfma_f32_16x16x32_bf16 v[84:87], v[140:143], v[206:209], v[84:87]
	v_mfma_f32_16x16x32_bf16 v[80:83], v[148:151], v[206:209], v[80:83]
	v_mfma_f32_16x16x32_bf16 v[124:127], v[144:147], v[184:187], v[124:127]
	v_mfma_f32_16x16x32_bf16 v[120:123], v[160:163], v[184:187], v[120:123]
	v_mfma_f32_16x16x32_bf16 v[116:119], v[144:147], v[192:195], v[116:119]
	v_mfma_f32_16x16x32_bf16 v[112:115], v[160:163], v[192:195], v[112:115]
	v_mfma_f32_16x16x32_bf16 v[100:103], v[144:147], v[200:203], v[100:103]
	v_mfma_f32_16x16x32_bf16 v[96:99], v[160:163], v[200:203], v[96:99]
	v_mfma_f32_16x16x32_bf16 v[84:87], v[144:147], v[210:213], v[84:87]
	v_mfma_f32_16x16x32_bf16 v[80:83], v[160:163], v[210:213], v[80:83]
	v_mfma_f32_16x16x32_bf16 v[108:111], v[164:167], v[180:183], v[108:111]
	v_mfma_f32_16x16x32_bf16 v[104:107], v[172:175], v[180:183], v[104:107]
	v_mfma_f32_16x16x32_bf16 v[92:95], v[164:167], v[188:191], v[92:95]
	v_mfma_f32_16x16x32_bf16 v[88:91], v[172:175], v[188:191], v[88:91]
	v_mfma_f32_16x16x32_bf16 v[76:79], v[164:167], v[196:199], v[76:79]
	v_mfma_f32_16x16x32_bf16 v[72:75], v[172:175], v[196:199], v[72:75]
	v_mfma_f32_16x16x32_bf16 v[68:71], v[164:167], v[206:209], v[68:71]
	v_mfma_f32_16x16x32_bf16 v[64:67], v[172:175], v[206:209], v[64:67]
	v_mfma_f32_16x16x32_bf16 v[108:111], v[168:171], v[184:187], v[108:111]
	v_mfma_f32_16x16x32_bf16 v[104:107], v[176:179], v[184:187], v[104:107]
	v_mfma_f32_16x16x32_bf16 v[92:95], v[168:171], v[192:195], v[92:95]
	v_mfma_f32_16x16x32_bf16 v[88:91], v[176:179], v[192:195], v[88:91]
	v_mfma_f32_16x16x32_bf16 v[76:79], v[168:171], v[200:203], v[76:79]
	v_mfma_f32_16x16x32_bf16 v[72:75], v[176:179], v[200:203], v[72:75]
	v_mfma_f32_16x16x32_bf16 v[68:71], v[168:171], v[210:213], v[68:71]
	v_mfma_f32_16x16x32_bf16 v[64:67], v[176:179], v[210:213], v[64:67]
	s_barrier
	s_mov_b64 s[54:55], s[92:93]
	s_mov_b32 m0, s94
	ds_read_b128 v[180:183], v159 offset:16384
	ds_read_b128 v[184:187], v159 offset:17408
	ds_read_b128 v[188:191], v159 offset:18432
	ds_read_b128 v[192:195], v159 offset:19456
	ds_read_b128 v[196:199], v159 offset:20480
	ds_read_b128 v[200:203], v159 offset:21504
	ds_read_b128 v[206:209], v159 offset:22528
	ds_read_b128 v[210:213], v159 offset:23552
	s_nop 0
	v_lshl_add_u64 v[152:153], s[54:55], 0, v[130:131]
	global_load_lds_dwordx4 v[152:153], off
	v_lshl_add_u64 v[152:153], s[54:55], 0, v[134:135]
	s_cselect_b32 s55, s87, s89
	s_cselect_b32 s54, s86, s88
	s_add_u32 s92, s92, 0x40000
	s_mov_b32 m0, s95
	s_addc_u32 s93, s93, 0
	s_add_i32 s0, s79, s59
	global_load_lds_dwordx4 v[152:153], off
	s_mov_b32 m0, s0
	v_lshl_add_u64 v[152:153], s[92:93], 0, v[130:131]
	global_load_lds_dwordx4 v[152:153], off
	v_lshl_add_u64 v[152:153], s[92:93], 0, v[134:135]
	s_add_i32 m0, s0, 0x2000
	s_mov_b64 s[92:93], s[52:53]
	global_load_lds_dwordx4 v[152:153], off
	s_mov_b32 m0, s21
	v_lshl_add_u64 v[152:153], s[92:93], 0, v[128:129]
	global_load_lds_dwordx4 v[152:153], off
	v_lshl_add_u64 v[152:153], s[92:93], 0, v[132:133]
	s_mov_b32 m0, s69
	s_nop 0
	global_load_lds_dwordx4 v[152:153], off
	s_waitcnt vmcnt(8)
	s_waitcnt lgkmcnt(0)
	s_barrier
; #define PG8_STAGE(bufoff, gbase, voff) do { const char* _gb = (const char*)(gbase); asm volatile("" : "+s"(_gb));     \
;         _Pragma("unroll") for (int _i = 0; _i < 2; ++_i) \
;         __builtin_amdgcn_global_load_lds((const unsigned*)(_gb + (voff)[_i]), (LAS unsigned*)(lds + (bufoff) + ldsw + _i * 8192), 16, 0, 0); } while (0)
; #define PG8_LDA(dst, b, h) do { _Pragma("unroll") for (int m = 0; m < 4; ++m) _Pragma("unroll") for (int k = 0; k < 2; ++k) dst[m][k] = *(const LAS bf16x8*)(lds + PG8_SA(b, h) + aoff + m * 2048 + k * 1024); } while (0)
; #define PG8_LDB(dst, b, h) do { _Pragma("unroll") for (int n = 0; n < 2; ++n) _Pragma("unroll") for (int k = 0; k < 2; ++k) dst[n][k] = *(const LAS bf16x8*)(lds + PG8_SB(b, h) + boff + n * 2048 + k * 1024); } while (0)
; #define PG8_MMA(ai, bj, At, Bt) do { __builtin_amdgcn_s_setprio(1); _Pragma("unroll") for (int m = 0; m < 4; ++m) _Pragma("unroll") for (int n = 0; n < 2; ++n) _Pragma("unroll") for (int k = 0; k < 2; ++k) \
;         acc[ai][bj][m][n] = __builtin_amdgcn_mfma_f32_16x16x32_bf16(Bt[n][k], At[m][k], acc[ai][bj][m][n], 0, 0, 0); __builtin_amdgcn_s_setprio(0); } while (0)
; #define PG8_WAIT_V(n) asm volatile("s_waitcnt vmcnt(" #n ")" ::: "memory")
; #define PG8_WAIT_L(n) asm volatile("s_waitcnt lgkmcnt(" #n ")" ::: "memory")
; #define PG8_BAR __builtin_amdgcn_s_barrier()
; #define PG8_SCHED __builtin_amdgcn_sched_barrier(0)
; template <class Epi>
; __device__ __forceinline__ void gemm_phase(LAS unsigned char* lds, const int wid, const Gemm g, const Epi& E) {
;     ...
;             PG8_WAIT_V(8); PG8_WAIT_L(0); PG8_BAR; PG8_MMA(1, 0, At, B0); PG8_MMA(1, 1, At, B1); PG8_BAR; PG8_SCHED;
;             PG8_LDB(B0, 1, 0); PG8_LDB(B1, 1, 1); PG8_SCHED; PG8_LDA(At, 1, 0); PG8_STAGE(PG8_SA(0, 1), a2 + hstepA, voffA);
;             PG8_WAIT_V(8); PG8_WAIT_L(0); PG8_BAR; PG8_MMA(0, 0, At, B0); PG8_MMA(0, 1, At, B1); PG8_BAR; PG8_SCHED;
	s_waitcnt lgkmcnt(0)
	v_mfma_f32_16x16x32_bf16 v[60:63], v[140:143], v[180:183], v[60:63]
	v_mfma_f32_16x16x32_bf16 v[56:59], v[148:151], v[180:183], v[56:59]
	v_mfma_f32_16x16x32_bf16 v[52:55], v[140:143], v[188:191], v[52:55]
	v_mfma_f32_16x16x32_bf16 v[48:51], v[148:151], v[188:191], v[48:51]
	v_mfma_f32_16x16x32_bf16 v[36:39], v[140:143], v[196:199], v[36:39]
	v_mfma_f32_16x16x32_bf16 v[32:35], v[148:151], v[196:199], v[32:35]
	v_mfma_f32_16x16x32_bf16 v[20:23], v[140:143], v[206:209], v[20:23]
	v_mfma_f32_16x16x32_bf16 v[16:19], v[148:151], v[206:209], v[16:19]
	v_mfma_f32_16x16x32_bf16 v[60:63], v[144:147], v[184:187], v[60:63]
	v_mfma_f32_16x16x32_bf16 v[56:59], v[160:163], v[184:187], v[56:59]
	v_mfma_f32_16x16x32_bf16 v[52:55], v[144:147], v[192:195], v[52:55]
	v_mfma_f32_16x16x32_bf16 v[48:51], v[160:163], v[192:195], v[48:51]
	v_mfma_f32_16x16x32_bf16 v[36:39], v[144:147], v[200:203], v[36:39]
	v_mfma_f32_16x16x32_bf16 v[32:35], v[160:163], v[200:203], v[32:35]
	v_mfma_f32_16x16x32_bf16 v[20:23], v[144:147], v[210:213], v[20:23]
	v_mfma_f32_16x16x32_bf16 v[16:19], v[160:163], v[210:213], v[16:19]
	v_mfma_f32_16x16x32_bf16 v[44:47], v[164:167], v[180:183], v[44:47]
	v_mfma_f32_16x16x32_bf16 v[40:43], v[172:175], v[180:183], v[40:43]
	v_mfma_f32_16x16x32_bf16 v[28:31], v[164:167], v[188:191], v[28:31]
	v_mfma_f32_16x16x32_bf16 v[24:27], v[172:175], v[188:191], v[24:27]
	v_mfma_f32_16x16x32_bf16 v[12:15], v[164:167], v[196:199], v[12:15]
	v_mfma_f32_16x16x32_bf16 v[8:11], v[172:175], v[196:199], v[8:11]
	v_mfma_f32_16x16x32_bf16 v[4:7], v[164:167], v[206:209], v[4:7]
	v_mfma_f32_16x16x32_bf16 v[0:3], v[172:175], v[206:209], v[0:3]
	v_mfma_f32_16x16x32_bf16 v[44:47], v[168:171], v[184:187], v[44:47]
	v_mfma_f32_16x16x32_bf16 v[40:43], v[176:179], v[184:187], v[40:43]
	v_mfma_f32_16x16x32_bf16 v[28:31], v[168:171], v[192:195], v[28:31]
	v_mfma_f32_16x16x32_bf16 v[24:27], v[176:179], v[192:195], v[24:27]
	v_mfma_f32_16x16x32_bf16 v[12:15], v[168:171], v[200:203], v[12:15]
	v_mfma_f32_16x16x32_bf16 v[8:11], v[176:179], v[200:203], v[8:11]
	v_mfma_f32_16x16x32_bf16 v[4:7], v[168:171], v[210:213], v[4:7]
	v_mfma_f32_16x16x32_bf16 v[0:3], v[176:179], v[210:213], v[0:3]
	s_barrier
	s_add_i32 s0, 0, 0x18000
	v_add_u32_e32 v152, s0, v156
	s_add_i32 s1, 0, 0x1c000
	ds_read_b128 v[140:143], v152
	ds_read_b128 v[144:147], v152 offset:1024
	ds_read_b128 v[148:151], v152 offset:2048
	ds_read_b128 v[160:163], v152 offset:3072
	v_add_u32_e32 v152, s1, v156
	ds_read_b128 v[164:167], v152
	ds_read_b128 v[168:171], v152 offset:1024
	ds_read_b128 v[172:175], v152 offset:2048
	ds_read_b128 v[176:179], v152 offset:3072
	s_add_u32 s52, s52, 0x40000
	s_addc_u32 s53, s53, 0
	s_mov_b32 m0, s70
	ds_read_b128 v[180:183], v159 offset:32768
	ds_read_b128 v[184:187], v159 offset:33792
	ds_read_b128 v[188:191], v159 offset:34816
	ds_read_b128 v[192:195], v159 offset:35840
	ds_read_b128 v[196:199], v159 offset:36864
	ds_read_b128 v[200:203], v159 offset:37888
	ds_read_b128 v[206:209], v159 offset:38912
	ds_read_b128 v[210:213], v159 offset:39936
	s_nop 0
	v_lshl_add_u64 v[152:153], s[52:53], 0, v[128:129]
	global_load_lds_dwordx4 v[152:153], off
	v_lshl_add_u64 v[152:153], s[52:53], 0, v[132:133]
	s_mov_b32 m0, s71
	s_nop 0
	global_load_lds_dwordx4 v[152:153], off
	s_waitcnt vmcnt(8)
	s_waitcnt lgkmcnt(0)
	s_barrier
	s_waitcnt lgkmcnt(0)
	v_mfma_f32_16x16x32_bf16 v[124:127], v[140:143], v[180:183], v[124:127]
	v_mfma_f32_16x16x32_bf16 v[120:123], v[148:151], v[180:183], v[120:123]
	v_mfma_f32_16x16x32_bf16 v[116:119], v[140:143], v[188:191], v[116:119]
	v_mfma_f32_16x16x32_bf16 v[112:115], v[148:151], v[188:191], v[112:115]
	v_mfma_f32_16x16x32_bf16 v[100:103], v[140:143], v[196:199], v[100:103]
	v_mfma_f32_16x16x32_bf16 v[96:99], v[148:151], v[196:199], v[96:99]
	v_mfma_f32_16x16x32_bf16 v[84:87], v[140:143], v[206:209], v[84:87]
	v_mfma_f32_16x16x32_bf16 v[80:83], v[148:151], v[206:209], v[80:83]
	v_mfma_f32_16x16x32_bf16 v[124:127], v[144:147], v[184:187], v[124:127]
	v_mfma_f32_16x16x32_bf16 v[120:123], v[160:163], v[184:187], v[120:123]
	v_mfma_f32_16x16x32_bf16 v[116:119], v[144:147], v[192:195], v[116:119]
	v_mfma_f32_16x16x32_bf16 v[112:115], v[160:163], v[192:195], v[112:115]
	v_mfma_f32_16x16x32_bf16 v[100:103], v[144:147], v[200:203], v[100:103]
	v_mfma_f32_16x16x32_bf16 v[96:99], v[160:163], v[200:203], v[96:99]
	v_mfma_f32_16x16x32_bf16 v[84:87], v[144:147], v[210:213], v[84:87]
	v_mfma_f32_16x16x32_bf16 v[80:83], v[160:163], v[210:213], v[80:83]
	v_mfma_f32_16x16x32_bf16 v[108:111], v[164:167], v[180:183], v[108:111]
	v_mfma_f32_16x16x32_bf16 v[104:107], v[172:175], v[180:183], v[104:107]
	v_mfma_f32_16x16x32_bf16 v[92:95], v[164:167], v[188:191], v[92:95]
	v_mfma_f32_16x16x32_bf16 v[88:91], v[172:175], v[188:191], v[88:91]
	v_mfma_f32_16x16x32_bf16 v[76:79], v[164:167], v[196:199], v[76:79]
	v_mfma_f32_16x16x32_bf16 v[72:75], v[172:175], v[196:199], v[72:75]
	v_mfma_f32_16x16x32_bf16 v[68:71], v[164:167], v[206:209], v[68:71]
	v_mfma_f32_16x16x32_bf16 v[64:67], v[172:175], v[206:209], v[64:67]
	v_mfma_f32_16x16x32_bf16 v[108:111], v[168:171], v[184:187], v[108:111]
	v_mfma_f32_16x16x32_bf16 v[104:107], v[176:179], v[184:187], v[104:107]
	v_mfma_f32_16x16x32_bf16 v[92:95], v[168:171], v[192:195], v[92:95]
	v_mfma_f32_16x16x32_bf16 v[88:91], v[176:179], v[192:195], v[88:91]
	v_mfma_f32_16x16x32_bf16 v[76:79], v[168:171], v[200:203], v[76:79]
	v_mfma_f32_16x16x32_bf16 v[72:75], v[176:179], v[200:203], v[72:75]
	v_mfma_f32_16x16x32_bf16 v[68:71], v[168:171], v[210:213], v[68:71]
	v_mfma_f32_16x16x32_bf16 v[64:67], v[176:179], v[210:213], v[64:67]
	s_barrier
; #define PG8_STAGE(bufoff, gbase, voff) do { const char* _gb = (const char*)(gbase); asm volatile("" : "+s"(_gb));     \
;         _Pragma("unroll") for (int _i = 0; _i < 2; ++_i) \
;         __builtin_amdgcn_global_load_lds((const unsigned*)(_gb + (voff)[_i]), (LAS unsigned*)(lds + (bufoff) + ldsw + _i * 8192), 16, 0, 0); } while (0)
; #define PG8_LDA(dst, b, h) do { _Pragma("unroll") for (int m = 0; m < 4; ++m) _Pragma("unroll") for (int k = 0; k < 2; ++k) dst[m][k] = *(const LAS bf16x8*)(lds + PG8_SA(b, h) + aoff + m * 2048 + k * 1024); } while (0)
; #define PG8_MMA(ai, bj, At, Bt) do { __builtin_amdgcn_s_setprio(1); _Pragma("unroll") for (int m = 0; m < 4; ++m) _Pragma("unroll") for (int n = 0; n < 2; ++n) _Pragma("unroll") for (int k = 0; k < 2; ++k) \
;         acc[ai][bj][m][n] = __builtin_amdgcn_mfma_f32_16x16x32_bf16(Bt[n][k], At[m][k], acc[ai][bj][m][n], 0, 0, 0); __builtin_amdgcn_s_setprio(0); } while (0)
; #define PG8_WAIT_V(n) asm volatile("s_waitcnt vmcnt(" #n ")" ::: "memory")
; #define PG8_WAIT_L(n) asm volatile("s_waitcnt lgkmcnt(" #n ")" ::: "memory")
; #define PG8_BAR __builtin_amdgcn_s_barrier()
; #define PG8_SCHED __builtin_amdgcn_sched_barrier(0)
; template <class Epi>
; __device__ __forceinline__ void gemm_phase(LAS unsigned char* lds, const int wid, const Gemm g, const Epi& E) {
;     ...
;             PG8_LDA(At, 1, 1); PG8_STAGE(PG8_SB(1, 0), b3, voffB); PG8_STAGE(PG8_SB(1, 1), b3 + hstepB, voffB); PG8_STAGE(PG8_SA(1, 0), a3, voffA);
;             PG8_WAIT_V(8); PG8_WAIT_L(0); PG8_BAR; PG8_MMA(1, 0, At, B0); PG8_MMA(1, 1, At, B1); PG8_BAR; PG8_SCHED;
;         }
;         if (wr == 0) PG8_BAR;
	s_mov_b64 s[52:53], s[54:55]
	s_add_i32 s0, s0, s59
	ds_read_b128 v[180:183], v159 offset:49152
	ds_read_b128 v[184:187], v159 offset:50176
	ds_read_b128 v[188:191], v159 offset:51200
	ds_read_b128 v[192:195], v159 offset:52224
	ds_read_b128 v[196:199], v159 offset:53248
	ds_read_b128 v[200:203], v159 offset:54272
	ds_read_b128 v[206:209], v159 offset:55296
	ds_read_b128 v[210:213], v159 offset:56320
	s_mov_b32 m0, s0
	v_lshl_add_u64 v[152:153], s[52:53], 0, v[130:131]
	global_load_lds_dwordx4 v[152:153], off
	s_add_i32 m0, s0, 0x2000
	v_lshl_add_u64 v[152:153], s[52:53], 0, v[134:135]
	s_add_u32 s52, s54, 0x40000
	s_addc_u32 s53, s55, 0
	s_add_i32 s0, s1, s59
	global_load_lds_dwordx4 v[152:153], off
	s_mov_b32 m0, s0
	v_lshl_add_u64 v[152:153], s[52:53], 0, v[130:131]
	global_load_lds_dwordx4 v[152:153], off
	v_lshl_add_u64 v[152:153], s[52:53], 0, v[134:135]
	s_add_i32 m0, s0, 0x2000
	s_nop 0
	global_load_lds_dwordx4 v[152:153], off
	s_mov_b32 m0, s75
	v_lshl_add_u64 v[152:153], s[50:51], 0, v[128:129]
	global_load_lds_dwordx4 v[152:153], off
	v_lshl_add_u64 v[152:153], s[50:51], 0, v[132:133]
	s_mov_b32 m0, s76
	s_nop 0
	global_load_lds_dwordx4 v[152:153], off
	s_waitcnt vmcnt(8)
	s_waitcnt lgkmcnt(0)
	s_barrier
	s_waitcnt lgkmcnt(0)
	v_mfma_f32_16x16x32_bf16 v[60:63], v[140:143], v[180:183], v[60:63]
	v_mfma_f32_16x16x32_bf16 v[56:59], v[148:151], v[180:183], v[56:59]
	v_mfma_f32_16x16x32_bf16 v[52:55], v[140:143], v[188:191], v[52:55]
	v_mfma_f32_16x16x32_bf16 v[48:51], v[148:151], v[188:191], v[48:51]
	v_mfma_f32_16x16x32_bf16 v[36:39], v[140:143], v[196:199], v[36:39]
	v_mfma_f32_16x16x32_bf16 v[32:35], v[148:151], v[196:199], v[32:35]
	v_mfma_f32_16x16x32_bf16 v[20:23], v[140:143], v[206:209], v[20:23]
	v_mfma_f32_16x16x32_bf16 v[16:19], v[148:151], v[206:209], v[16:19]
	v_mfma_f32_16x16x32_bf16 v[60:63], v[144:147], v[184:187], v[60:63]
	v_mfma_f32_16x16x32_bf16 v[56:59], v[160:163], v[184:187], v[56:59]
	v_mfma_f32_16x16x32_bf16 v[52:55], v[144:147], v[192:195], v[52:55]
	v_mfma_f32_16x16x32_bf16 v[48:51], v[160:163], v[192:195], v[48:51]
	v_mfma_f32_16x16x32_bf16 v[36:39], v[144:147], v[200:203], v[36:39]
	v_mfma_f32_16x16x32_bf16 v[32:35], v[160:163], v[200:203], v[32:35]
	v_mfma_f32_16x16x32_bf16 v[20:23], v[144:147], v[210:213], v[20:23]
	v_mfma_f32_16x16x32_bf16 v[16:19], v[160:163], v[210:213], v[16:19]
	v_mfma_f32_16x16x32_bf16 v[44:47], v[164:167], v[180:183], v[44:47]
	v_mfma_f32_16x16x32_bf16 v[40:43], v[172:175], v[180:183], v[40:43]
	v_mfma_f32_16x16x32_bf16 v[28:31], v[164:167], v[188:191], v[28:31]
	v_mfma_f32_16x16x32_bf16 v[24:27], v[172:175], v[188:191], v[24:27]
	v_mfma_f32_16x16x32_bf16 v[12:15], v[164:167], v[196:199], v[12:15]
	v_mfma_f32_16x16x32_bf16 v[8:11], v[172:175], v[196:199], v[8:11]
	v_mfma_f32_16x16x32_bf16 v[4:7], v[164:167], v[206:209], v[4:7]
	v_mfma_f32_16x16x32_bf16 v[0:3], v[172:175], v[206:209], v[0:3]
	v_mfma_f32_16x16x32_bf16 v[44:47], v[168:171], v[184:187], v[44:47]
	v_mfma_f32_16x16x32_bf16 v[40:43], v[176:179], v[184:187], v[40:43]
	v_mfma_f32_16x16x32_bf16 v[28:31], v[168:171], v[192:195], v[28:31]
	v_mfma_f32_16x16x32_bf16 v[24:27], v[176:179], v[192:195], v[24:27]
	v_mfma_f32_16x16x32_bf16 v[12:15], v[168:171], v[200:203], v[12:15]
	v_mfma_f32_16x16x32_bf16 v[8:11], v[176:179], v[200:203], v[8:11]
	v_mfma_f32_16x16x32_bf16 v[4:7], v[168:171], v[210:213], v[4:7]
	v_mfma_f32_16x16x32_bf16 v[0:3], v[176:179], v[210:213], v[0:3]
	s_barrier
	s_add_i32 s90, s90, 2
	s_add_u32 s88, s88, 0x100
	s_addc_u32 s89, s89, 0
	s_add_u32 s6, s6, 0x100
	s_addc_u32 s7, s7, 0
	s_cmp_gt_u32 s90, 13
	s_cbranch_scc0 .LBB0_2479
	s_and_b64 vcc, exec, s[12:13]
	s_cbranch_vccz .LBB0_2482
	s_barrier

; #define PG8_STAGE(bufoff, gbase, voff) do { const char* _gb = (const char*)(gbase); asm volatile("" : "+s"(_gb));     \
;         _Pragma("unroll") for (int _i = 0; _i < 2; ++_i) \
;         __builtin_amdgcn_global_load_lds((const unsigned*)(_gb + (voff)[_i]), (LAS unsigned*)(lds + (bufoff) + ldsw + _i * 8192), 16, 0, 0); } while (0)
; #define PG8_LDA(dst, b, h) do { _Pragma("unroll") for (int m = 0; m < 4; ++m) _Pragma("unroll") for (int k = 0; k < 2; ++k) dst[m][k] = *(const LAS bf16x8*)(lds + PG8_SA(b, h) + aoff + m * 2048 + k * 1024); } while (0)
; #define PG8_LDB(dst, b, h) do { _Pragma("unroll") for (int n = 0; n < 2; ++n) _Pragma("unroll") for (int k = 0; k < 2; ++k) dst[n][k] = *(const LAS bf16x8*)(lds + PG8_SB(b, h) + boff + n * 2048 + k * 1024); } while (0)
; #define PG8_MMA(ai, bj, At, Bt) do { __builtin_amdgcn_s_setprio(1); _Pragma("unroll") for (int m = 0; m < 4; ++m) _Pragma("unroll") for (int n = 0; n < 2; ++n) _Pragma("unroll") for (int k = 0; k < 2; ++k) \
;         acc[ai][bj][m][n] = __builtin_amdgcn_mfma_f32_16x16x32_bf16(Bt[n][k], At[m][k], acc[ai][bj][m][n], 0, 0, 0); __builtin_amdgcn_s_setprio(0); } while (0)
; #define PG8_WAIT_V(n) asm volatile("s_waitcnt vmcnt(" #n ")" ::: "memory")
; #define PG8_WAIT_L(n) asm volatile("s_waitcnt lgkmcnt(" #n ")" ::: "memory")
; #define PG8_BAR __builtin_amdgcn_s_barrier()
; template <class Epi>
; __device__ __forceinline__ void gemm_phase(LAS unsigned char* lds, const int wid, const Gemm g, const Epi& E) {
;     ...
;             const bool last = (t == nt - 2);
;             const char* a1 = PG8_AP(cA, t + 1);
;             const char* a2 = last ? PG8_AP(nA, 0) : PG8_AP(cA, t + 2); const char* b2 = last ? PG8_BP(nB, 0) : PG8_BP(cB, t + 2);
;             const char* a3 = last ? PG8_AP(nA, 1) : PG8_AP(cA, t + 3); const char* b3 = last ? PG8_BP(nB, 1) : PG8_BP(cB, t + 3);
;             PG8_LDB(B0, 0, 0); PG8_LDB(B1, 0, 1); PG8_SCHED; PG8_LDA(At, 0, 0); PG8_STAGE(PG8_SA(1, 1), a1 + hstepA, voffA);
;             PG8_WAIT_V(8); PG8_WAIT_L(0); PG8_BAR; PG8_MMA(0, 0, At, B0); PG8_MMA(0, 1, At, B1); PG8_BAR; PG8_SCHED;
;             PG8_LDA(At, 0, 1); PG8_STAGE(PG8_SB(0, 0), b2, voffB); PG8_STAGE(PG8_SB(0, 1), b2 + hstepB, voffB); PG8_STAGE(PG8_SA(0, 0), a2, voffA);
;             PG8_WAIT_V(8); PG8_WAIT_L(0); PG8_BAR; PG8_MMA(1, 0, At, B0); PG8_MMA(1, 1, At, B1); PG8_BAR; PG8_SCHED;
.LBB0_2599:
	s_add_i32 s91, s91, 2
	s_cmp_lt_u32 s91, 16
	s_cselect_b32 s0, 0, -1
	s_cselect_b32 s1, s77, 0xfffff800
	s_cmp_lt_u32 s91, 14
	s_cselect_b32 s53, s77, 0xfffff800
	s_cselect_b32 s52, 0, -1
	s_add_u32 s53, s53, s6
	s_addc_u32 s52, s52, s7
	s_add_u32 s53, s50, s53
	s_addc_u32 s52, s51, s52
	s_add_u32 s53, s53, 0x100
	s_addc_u32 s52, s52, 0
	s_add_u32 s54, s48, s6
	s_addc_u32 s55, s49, s7
	s_add_u32 s92, s54, 0x100
	s_addc_u32 s93, s55, 0
	s_cmp_lt_u32 s91, 13
	s_cselect_b32 s57, s77, 0xfffff800
	s_cselect_b32 s56, 0, -1
	s_add_u32 s57, s57, s6
	s_addc_u32 s56, s56, s7
	s_add_u32 s57, s50, s57
	s_addc_u32 s56, s51, s56
	s_add_u32 s94, s57, 0x180
	s_addc_u32 s95, s56, 0
	ds_read_b128 v[140:143], v157
	ds_read_b128 v[144:147], v157 offset:1024
	ds_read_b128 v[148:151], v157 offset:2048
	ds_read_b128 v[160:163], v157 offset:3072
	ds_read_b128 v[164:167], v158
	ds_read_b128 v[168:171], v158 offset:1024
	ds_read_b128 v[172:175], v158 offset:2048
	ds_read_b128 v[176:179], v158 offset:3072
	s_add_u32 s96, s54, 0x180
	s_addc_u32 s97, s55, 0
	s_add_u32 s1, s1, s6
	s_addc_u32 s0, s0, s7
	s_add_u32 s1, s50, s1
	s_addc_u32 s0, s51, s0
	s_add_u32 s56, s1, 0x40080
	s_addc_u32 s57, s0, 0
	s_add_i32 s1, s78, s59
	s_add_i32 m0, s17, 0xc000
	s_add_i32 s0, s17, 0xe000
	s_add_i32 vcc_lo, s1, 0x2000
	s_cmpk_eq_i32 s6, 0xf00
	s_cselect_b32 s55, s86, s52
	s_cselect_b32 s54, s43, s53
	s_cselect_b32 s93, s9, s93
	s_cselect_b32 s92, s41, s92
	s_cselect_b32 s53, s88, s95
	s_cselect_b32 s52, s87, s94
	ds_read_b128 v[180:183], v159
	ds_read_b128 v[184:187], v159 offset:1024
	ds_read_b128 v[188:191], v159 offset:2048
	ds_read_b128 v[192:195], v159 offset:3072
	ds_read_b128 v[196:199], v159 offset:4096
	ds_read_b128 v[200:203], v159 offset:5120
	ds_read_b128 v[206:209], v159 offset:6144
	ds_read_b128 v[210:213], v159 offset:7168
	s_nop 0
	v_lshl_add_u64 v[152:153], s[56:57], 0, v[128:129]
	global_load_lds_dwordx4 v[152:153], off
	v_lshl_add_u64 v[152:153], s[56:57], 0, v[132:133]
	s_mov_b32 m0, s0
	s_nop 0
	global_load_lds_dwordx4 v[152:153], off
	s_waitcnt vmcnt(8)
	s_waitcnt lgkmcnt(0)
	s_barrier
	s_waitcnt lgkmcnt(0)
	v_mfma_f32_16x16x32_bf16 v[124:127], v[140:143], v[180:183], v[124:127]
	v_mfma_f32_16x16x32_bf16 v[120:123], v[148:151], v[180:183], v[120:123]
	v_mfma_f32_16x16x32_bf16 v[116:119], v[140:143], v[188:191], v[116:119]
	v_mfma_f32_16x16x32_bf16 v[112:115], v[148:151], v[188:191], v[112:115]
	v_mfma_f32_16x16x32_bf16 v[100:103], v[140:143], v[196:199], v[100:103]
	v_mfma_f32_16x16x32_bf16 v[96:99], v[148:151], v[196:199], v[96:99]
	v_mfma_f32_16x16x32_bf16 v[84:87], v[140:143], v[206:209], v[84:87]
	v_mfma_f32_16x16x32_bf16 v[80:83], v[148:151], v[206:209], v[80:83]
	v_mfma_f32_16x16x32_bf16 v[124:127], v[144:147], v[184:187], v[124:127]
	v_mfma_f32_16x16x32_bf16 v[120:123], v[160:163], v[184:187], v[120:123]
	v_mfma_f32_16x16x32_bf16 v[116:119], v[144:147], v[192:195], v[116:119]
	v_mfma_f32_16x16x32_bf16 v[112:115], v[160:163], v[192:195], v[112:115]
	v_mfma_f32_16x16x32_bf16 v[100:103], v[144:147], v[200:203], v[100:103]
	v_mfma_f32_16x16x32_bf16 v[96:99], v[160:163], v[200:203], v[96:99]
	v_mfma_f32_16x16x32_bf16 v[84:87], v[144:147], v[210:213], v[84:87]
	v_mfma_f32_16x16x32_bf16 v[80:83], v[160:163], v[210:213], v[80:83]
	v_mfma_f32_16x16x32_bf16 v[108:111], v[164:167], v[180:183], v[108:111]
	v_mfma_f32_16x16x32_bf16 v[104:107], v[172:175], v[180:183], v[104:107]
	v_mfma_f32_16x16x32_bf16 v[92:95], v[164:167], v[188:191], v[92:95]
	v_mfma_f32_16x16x32_bf16 v[88:91], v[172:175], v[188:191], v[88:91]
	v_mfma_f32_16x16x32_bf16 v[76:79], v[164:167], v[196:199], v[76:79]
	v_mfma_f32_16x16x32_bf16 v[72:75], v[172:175], v[196:199], v[72:75]
	v_mfma_f32_16x16x32_bf16 v[68:71], v[164:167], v[206:209], v[68:71]
	v_mfma_f32_16x16x32_bf16 v[64:67], v[172:175], v[206:209], v[64:67]
	v_mfma_f32_16x16x32_bf16 v[108:111], v[168:171], v[184:187], v[108:111]
	v_mfma_f32_16x16x32_bf16 v[104:107], v[176:179], v[184:187], v[104:107]
	v_mfma_f32_16x16x32_bf16 v[92:95], v[168:171], v[192:195], v[92:95]
	v_mfma_f32_16x16x32_bf16 v[88:91], v[176:179], v[192:195], v[88:91]
	v_mfma_f32_16x16x32_bf16 v[76:79], v[168:171], v[200:203], v[76:79]
	v_mfma_f32_16x16x32_bf16 v[72:75], v[176:179], v[200:203], v[72:75]
	v_mfma_f32_16x16x32_bf16 v[68:71], v[168:171], v[210:213], v[68:71]
	v_mfma_f32_16x16x32_bf16 v[64:67], v[176:179], v[210:213], v[64:67]
	s_barrier
	s_mov_b64 s[56:57], s[92:93]
	s_mov_b32 m0, s1
	ds_read_b128 v[180:183], v159 offset:16384
	ds_read_b128 v[184:187], v159 offset:17408
	ds_read_b128 v[188:191], v159 offset:18432
	ds_read_b128 v[192:195], v159 offset:19456
	ds_read_b128 v[196:199], v159 offset:20480
	ds_read_b128 v[200:203], v159 offset:21504
	ds_read_b128 v[206:209], v159 offset:22528
	ds_read_b128 v[210:213], v159 offset:23552
	s_nop 0
	v_lshl_add_u64 v[152:153], s[56:57], 0, v[130:131]
	global_load_lds_dwordx4 v[152:153], off
	v_lshl_add_u64 v[152:153], s[56:57], 0, v[134:135]
	s_cselect_b32 s57, s90, s97
	s_cselect_b32 s56, s89, s96
	s_add_u32 s92, s92, 0x80000
	s_mov_b32 m0, vcc_lo
	s_addc_u32 s93, s93, 0
	s_add_i32 s0, s79, s59
	global_load_lds_dwordx4 v[152:153], off
	s_mov_b32 m0, s0
	v_lshl_add_u64 v[152:153], s[92:93], 0, v[130:131]
	global_load_lds_dwordx4 v[152:153], off
	v_lshl_add_u64 v[152:153], s[92:93], 0, v[134:135]
	s_add_i32 m0, s0, 0x2000
	s_mov_b64 s[92:93], s[54:55]
	global_load_lds_dwordx4 v[152:153], off
	s_mov_b32 m0, s17
	v_lshl_add_u64 v[152:153], s[92:93], 0, v[128:129]
	global_load_lds_dwordx4 v[152:153], off
	v_lshl_add_u64 v[152:153], s[92:93], 0, v[132:133]
	s_mov_b32 m0, s67
	s_nop 0
	global_load_lds_dwordx4 v[152:153], off
	s_waitcnt vmcnt(8)
	s_waitcnt lgkmcnt(0)
	s_barrier
; #define PG8_STAGE(bufoff, gbase, voff) do { const char* _gb = (const char*)(gbase); asm volatile("" : "+s"(_gb));     \
;         _Pragma("unroll") for (int _i = 0; _i < 2; ++_i) \
;         __builtin_amdgcn_global_load_lds((const unsigned*)(_gb + (voff)[_i]), (LAS unsigned*)(lds + (bufoff) + ldsw + _i * 8192), 16, 0, 0); } while (0)
; #define PG8_LDA(dst, b, h) do { _Pragma("unroll") for (int m = 0; m < 4; ++m) _Pragma("unroll") for (int k = 0; k < 2; ++k) dst[m][k] = *(const LAS bf16x8*)(lds + PG8_SA(b, h) + aoff + m * 2048 + k * 1024); } while (0)
; #define PG8_LDB(dst, b, h) do { _Pragma("unroll") for (int n = 0; n < 2; ++n) _Pragma("unroll") for (int k = 0; k < 2; ++k) dst[n][k] = *(const LAS bf16x8*)(lds + PG8_SB(b, h) + boff + n * 2048 + k * 1024); } while (0)
; #define PG8_MMA(ai, bj, At, Bt) do { __builtin_amdgcn_s_setprio(1); _Pragma("unroll") for (int m = 0; m < 4; ++m) _Pragma("unroll") for (int n = 0; n < 2; ++n) _Pragma("unroll") for (int k = 0; k < 2; ++k) \
;         acc[ai][bj][m][n] = __builtin_amdgcn_mfma_f32_16x16x32_bf16(Bt[n][k], At[m][k], acc[ai][bj][m][n], 0, 0, 0); __builtin_amdgcn_s_setprio(0); } while (0)
; #define PG8_WAIT_V(n) asm volatile("s_waitcnt vmcnt(" #n ")" ::: "memory")
; #define PG8_WAIT_L(n) asm volatile("s_waitcnt lgkmcnt(" #n ")" ::: "memory")
; #define PG8_BAR __builtin_amdgcn_s_barrier()
; #define PG8_SCHED __builtin_amdgcn_sched_barrier(0)
; template <class Epi>
; __device__ __forceinline__ void gemm_phase(LAS unsigned char* lds, const int wid, const Gemm g, const Epi& E) {
;     ...
;             PG8_WAIT_V(8); PG8_WAIT_L(0); PG8_BAR; PG8_MMA(1, 0, At, B0); PG8_MMA(1, 1, At, B1); PG8_BAR; PG8_SCHED;
;             PG8_LDB(B0, 1, 0); PG8_LDB(B1, 1, 1); PG8_SCHED; PG8_LDA(At, 1, 0); PG8_STAGE(PG8_SA(0, 1), a2 + hstepA, voffA);
;             PG8_WAIT_V(8); PG8_WAIT_L(0); PG8_BAR; PG8_MMA(0, 0, At, B0); PG8_MMA(0, 1, At, B1); PG8_BAR; PG8_SCHED;
	s_waitcnt lgkmcnt(0)
	v_mfma_f32_16x16x32_bf16 v[60:63], v[140:143], v[180:183], v[60:63]
	v_mfma_f32_16x16x32_bf16 v[56:59], v[148:151], v[180:183], v[56:59]
	v_mfma_f32_16x16x32_bf16 v[52:55], v[140:143], v[188:191], v[52:55]
	v_mfma_f32_16x16x32_bf16 v[48:51], v[148:151], v[188:191], v[48:51]
	v_mfma_f32_16x16x32_bf16 v[36:39], v[140:143], v[196:199], v[36:39]
	v_mfma_f32_16x16x32_bf16 v[32:35], v[148:151], v[196:199], v[32:35]
	v_mfma_f32_16x16x32_bf16 v[20:23], v[140:143], v[206:209], v[20:23]
	v_mfma_f32_16x16x32_bf16 v[16:19], v[148:151], v[206:209], v[16:19]
	v_mfma_f32_16x16x32_bf16 v[60:63], v[144:147], v[184:187], v[60:63]
	v_mfma_f32_16x16x32_bf16 v[56:59], v[160:163], v[184:187], v[56:59]
	v_mfma_f32_16x16x32_bf16 v[52:55], v[144:147], v[192:195], v[52:55]
	v_mfma_f32_16x16x32_bf16 v[48:51], v[160:163], v[192:195], v[48:51]
	v_mfma_f32_16x16x32_bf16 v[36:39], v[144:147], v[200:203], v[36:39]
	v_mfma_f32_16x16x32_bf16 v[32:35], v[160:163], v[200:203], v[32:35]
	v_mfma_f32_16x16x32_bf16 v[20:23], v[144:147], v[210:213], v[20:23]
	v_mfma_f32_16x16x32_bf16 v[16:19], v[160:163], v[210:213], v[16:19]
	v_mfma_f32_16x16x32_bf16 v[44:47], v[164:167], v[180:183], v[44:47]
	v_mfma_f32_16x16x32_bf16 v[40:43], v[172:175], v[180:183], v[40:43]
	v_mfma_f32_16x16x32_bf16 v[28:31], v[164:167], v[188:191], v[28:31]
	v_mfma_f32_16x16x32_bf16 v[24:27], v[172:175], v[188:191], v[24:27]
	v_mfma_f32_16x16x32_bf16 v[12:15], v[164:167], v[196:199], v[12:15]
	v_mfma_f32_16x16x32_bf16 v[8:11], v[172:175], v[196:199], v[8:11]
	v_mfma_f32_16x16x32_bf16 v[4:7], v[164:167], v[206:209], v[4:7]
	v_mfma_f32_16x16x32_bf16 v[0:3], v[172:175], v[206:209], v[0:3]
	v_mfma_f32_16x16x32_bf16 v[44:47], v[168:171], v[184:187], v[44:47]
	v_mfma_f32_16x16x32_bf16 v[40:43], v[176:179], v[184:187], v[40:43]
	v_mfma_f32_16x16x32_bf16 v[28:31], v[168:171], v[192:195], v[28:31]
	v_mfma_f32_16x16x32_bf16 v[24:27], v[176:179], v[192:195], v[24:27]
	v_mfma_f32_16x16x32_bf16 v[12:15], v[168:171], v[200:203], v[12:15]
	v_mfma_f32_16x16x32_bf16 v[8:11], v[176:179], v[200:203], v[8:11]
	v_mfma_f32_16x16x32_bf16 v[4:7], v[168:171], v[210:213], v[4:7]
	v_mfma_f32_16x16x32_bf16 v[0:3], v[176:179], v[210:213], v[0:3]
	s_barrier
	s_add_i32 s0, 0, 0x18000
	v_add_u32_e32 v152, s0, v156
	s_add_i32 s1, 0, 0x1c000
	ds_read_b128 v[140:143], v152
	ds_read_b128 v[144:147], v152 offset:1024
	ds_read_b128 v[148:151], v152 offset:2048
	ds_read_b128 v[160:163], v152 offset:3072
	v_add_u32_e32 v152, s1, v156
	ds_read_b128 v[164:167], v152
	ds_read_b128 v[168:171], v152 offset:1024
	ds_read_b128 v[172:175], v152 offset:2048
	ds_read_b128 v[176:179], v152 offset:3072
	s_add_u32 s54, s54, 0x40000
	s_addc_u32 s55, s55, 0
	s_mov_b32 m0, s68
	ds_read_b128 v[180:183], v159 offset:32768
	ds_read_b128 v[184:187], v159 offset:33792
	ds_read_b128 v[188:191], v159 offset:34816
	ds_read_b128 v[192:195], v159 offset:35840
	ds_read_b128 v[196:199], v159 offset:36864
	ds_read_b128 v[200:203], v159 offset:37888
	ds_read_b128 v[206:209], v159 offset:38912
	ds_read_b128 v[210:213], v159 offset:39936
	s_nop 0
	v_lshl_add_u64 v[152:153], s[54:55], 0, v[128:129]
	global_load_lds_dwordx4 v[152:153], off
	v_lshl_add_u64 v[152:153], s[54:55], 0, v[132:133]
	s_mov_b32 m0, s69
	s_nop 0
	global_load_lds_dwordx4 v[152:153], off
	s_waitcnt vmcnt(8)
	s_waitcnt lgkmcnt(0)
	s_barrier
	s_waitcnt lgkmcnt(0)
	v_mfma_f32_16x16x32_bf16 v[124:127], v[140:143], v[180:183], v[124:127]
	v_mfma_f32_16x16x32_bf16 v[120:123], v[148:151], v[180:183], v[120:123]
	v_mfma_f32_16x16x32_bf16 v[116:119], v[140:143], v[188:191], v[116:119]
	v_mfma_f32_16x16x32_bf16 v[112:115], v[148:151], v[188:191], v[112:115]
	v_mfma_f32_16x16x32_bf16 v[100:103], v[140:143], v[196:199], v[100:103]
	v_mfma_f32_16x16x32_bf16 v[96:99], v[148:151], v[196:199], v[96:99]
	v_mfma_f32_16x16x32_bf16 v[84:87], v[140:143], v[206:209], v[84:87]
	v_mfma_f32_16x16x32_bf16 v[80:83], v[148:151], v[206:209], v[80:83]
	v_mfma_f32_16x16x32_bf16 v[124:127], v[144:147], v[184:187], v[124:127]
	v_mfma_f32_16x16x32_bf16 v[120:123], v[160:163], v[184:187], v[120:123]
	v_mfma_f32_16x16x32_bf16 v[116:119], v[144:147], v[192:195], v[116:119]
	v_mfma_f32_16x16x32_bf16 v[112:115], v[160:163], v[192:195], v[112:115]
	v_mfma_f32_16x16x32_bf16 v[100:103], v[144:147], v[200:203], v[100:103]
	v_mfma_f32_16x16x32_bf16 v[96:99], v[160:163], v[200:203], v[96:99]
	v_mfma_f32_16x16x32_bf16 v[84:87], v[144:147], v[210:213], v[84:87]
	v_mfma_f32_16x16x32_bf16 v[80:83], v[160:163], v[210:213], v[80:83]
	v_mfma_f32_16x16x32_bf16 v[108:111], v[164:167], v[180:183], v[108:111]
	v_mfma_f32_16x16x32_bf16 v[104:107], v[172:175], v[180:183], v[104:107]
	v_mfma_f32_16x16x32_bf16 v[92:95], v[164:167], v[188:191], v[92:95]
	v_mfma_f32_16x16x32_bf16 v[88:91], v[172:175], v[188:191], v[88:91]
	v_mfma_f32_16x16x32_bf16 v[76:79], v[164:167], v[196:199], v[76:79]
	v_mfma_f32_16x16x32_bf16 v[72:75], v[172:175], v[196:199], v[72:75]
	v_mfma_f32_16x16x32_bf16 v[68:71], v[164:167], v[206:209], v[68:71]
	v_mfma_f32_16x16x32_bf16 v[64:67], v[172:175], v[206:209], v[64:67]
	v_mfma_f32_16x16x32_bf16 v[108:111], v[168:171], v[184:187], v[108:111]
	v_mfma_f32_16x16x32_bf16 v[104:107], v[176:179], v[184:187], v[104:107]
	v_mfma_f32_16x16x32_bf16 v[92:95], v[168:171], v[192:195], v[92:95]
	v_mfma_f32_16x16x32_bf16 v[88:91], v[176:179], v[192:195], v[88:91]
	v_mfma_f32_16x16x32_bf16 v[76:79], v[168:171], v[200:203], v[76:79]
	v_mfma_f32_16x16x32_bf16 v[72:75], v[176:179], v[200:203], v[72:75]
	v_mfma_f32_16x16x32_bf16 v[68:71], v[168:171], v[210:213], v[68:71]
	v_mfma_f32_16x16x32_bf16 v[64:67], v[176:179], v[210:213], v[64:67]
	s_barrier
; #define PG8_STAGE(bufoff, gbase, voff) do { const char* _gb = (const char*)(gbase); asm volatile("" : "+s"(_gb));     \
;         _Pragma("unroll") for (int _i = 0; _i < 2; ++_i) \
;         __builtin_amdgcn_global_load_lds((const unsigned*)(_gb + (voff)[_i]), (LAS unsigned*)(lds + (bufoff) + ldsw + _i * 8192), 16, 0, 0); } while (0)
; #define PG8_LDA(dst, b, h) do { _Pragma("unroll") for (int m = 0; m < 4; ++m) _Pragma("unroll") for (int k = 0; k < 2; ++k) dst[m][k] = *(const LAS bf16x8*)(lds + PG8_SA(b, h) + aoff + m * 2048 + k * 1024); } while (0)
; #define PG8_MMA(ai, bj, At, Bt) do { __builtin_amdgcn_s_setprio(1); _Pragma("unroll") for (int m = 0; m < 4; ++m) _Pragma("unroll") for (int n = 0; n < 2; ++n) _Pragma("unroll") for (int k = 0; k < 2; ++k) \
;         acc[ai][bj][m][n] = __builtin_amdgcn_mfma_f32_16x16x32_bf16(Bt[n][k], At[m][k], acc[ai][bj][m][n], 0, 0, 0); __builtin_amdgcn_s_setprio(0); } while (0)
; #define PG8_WAIT_V(n) asm volatile("s_waitcnt vmcnt(" #n ")" ::: "memory")
; #define PG8_WAIT_L(n) asm volatile("s_waitcnt lgkmcnt(" #n ")" ::: "memory")
; #define PG8_BAR __builtin_amdgcn_s_barrier()
; #define PG8_SCHED __builtin_amdgcn_sched_barrier(0)
; template <class Epi>
; __device__ __forceinline__ void gemm_phase(LAS unsigned char* lds, const int wid, const Gemm g, const Epi& E) {
;     ...
;             PG8_LDA(At, 1, 1); PG8_STAGE(PG8_SB(1, 0), b3, voffB); PG8_STAGE(PG8_SB(1, 1), b3 + hstepB, voffB); PG8_STAGE(PG8_SA(1, 0), a3, voffA);
;             PG8_WAIT_V(8); PG8_WAIT_L(0); PG8_BAR; PG8_MMA(1, 0, At, B0); PG8_MMA(1, 1, At, B1); PG8_BAR; PG8_SCHED;
;         }
;         if (wr == 0) PG8_BAR;
	s_mov_b64 s[54:55], s[56:57]
	s_add_i32 s0, s0, s59
	ds_read_b128 v[180:183], v159 offset:49152
	ds_read_b128 v[184:187], v159 offset:50176
	ds_read_b128 v[188:191], v159 offset:51200
	ds_read_b128 v[192:195], v159 offset:52224
	ds_read_b128 v[196:199], v159 offset:53248
	ds_read_b128 v[200:203], v159 offset:54272
	ds_read_b128 v[206:209], v159 offset:55296
	ds_read_b128 v[210:213], v159 offset:56320
	s_mov_b32 m0, s0
	v_lshl_add_u64 v[152:153], s[54:55], 0, v[130:131]
	global_load_lds_dwordx4 v[152:153], off
	s_add_i32 m0, s0, 0x2000
	v_lshl_add_u64 v[152:153], s[54:55], 0, v[134:135]
	s_add_u32 s54, s56, 0x80000
	s_addc_u32 s55, s57, 0
	s_add_i32 s0, s1, s59
	global_load_lds_dwordx4 v[152:153], off
	s_mov_b32 m0, s0
	v_lshl_add_u64 v[152:153], s[54:55], 0, v[130:131]
	global_load_lds_dwordx4 v[152:153], off
	v_lshl_add_u64 v[152:153], s[54:55], 0, v[134:135]
	s_add_i32 m0, s0, 0x2000
	s_nop 0
	global_load_lds_dwordx4 v[152:153], off
	s_mov_b32 m0, s73
	v_lshl_add_u64 v[152:153], s[52:53], 0, v[128:129]
	global_load_lds_dwordx4 v[152:153], off
	v_lshl_add_u64 v[152:153], s[52:53], 0, v[132:133]
	s_mov_b32 m0, s74
	s_nop 0
	global_load_lds_dwordx4 v[152:153], off
	s_waitcnt vmcnt(8)
	s_waitcnt lgkmcnt(0)
	s_barrier
	s_waitcnt lgkmcnt(0)
	v_mfma_f32_16x16x32_bf16 v[60:63], v[140:143], v[180:183], v[60:63]
	v_mfma_f32_16x16x32_bf16 v[56:59], v[148:151], v[180:183], v[56:59]
	v_mfma_f32_16x16x32_bf16 v[52:55], v[140:143], v[188:191], v[52:55]
	v_mfma_f32_16x16x32_bf16 v[48:51], v[148:151], v[188:191], v[48:51]
	v_mfma_f32_16x16x32_bf16 v[36:39], v[140:143], v[196:199], v[36:39]
	v_mfma_f32_16x16x32_bf16 v[32:35], v[148:151], v[196:199], v[32:35]
	v_mfma_f32_16x16x32_bf16 v[20:23], v[140:143], v[206:209], v[20:23]
	v_mfma_f32_16x16x32_bf16 v[16:19], v[148:151], v[206:209], v[16:19]
	v_mfma_f32_16x16x32_bf16 v[60:63], v[144:147], v[184:187], v[60:63]
	v_mfma_f32_16x16x32_bf16 v[56:59], v[160:163], v[184:187], v[56:59]
	v_mfma_f32_16x16x32_bf16 v[52:55], v[144:147], v[192:195], v[52:55]
	v_mfma_f32_16x16x32_bf16 v[48:51], v[160:163], v[192:195], v[48:51]
	v_mfma_f32_16x16x32_bf16 v[36:39], v[144:147], v[200:203], v[36:39]
	v_mfma_f32_16x16x32_bf16 v[32:35], v[160:163], v[200:203], v[32:35]
	v_mfma_f32_16x16x32_bf16 v[20:23], v[144:147], v[210:213], v[20:23]
	v_mfma_f32_16x16x32_bf16 v[16:19], v[160:163], v[210:213], v[16:19]
	v_mfma_f32_16x16x32_bf16 v[44:47], v[164:167], v[180:183], v[44:47]
	v_mfma_f32_16x16x32_bf16 v[40:43], v[172:175], v[180:183], v[40:43]
	v_mfma_f32_16x16x32_bf16 v[28:31], v[164:167], v[188:191], v[28:31]
	v_mfma_f32_16x16x32_bf16 v[24:27], v[172:175], v[188:191], v[24:27]
	v_mfma_f32_16x16x32_bf16 v[12:15], v[164:167], v[196:199], v[12:15]
	v_mfma_f32_16x16x32_bf16 v[8:11], v[172:175], v[196:199], v[8:11]
	v_mfma_f32_16x16x32_bf16 v[4:7], v[164:167], v[206:209], v[4:7]
	v_mfma_f32_16x16x32_bf16 v[0:3], v[172:175], v[206:209], v[0:3]
	v_mfma_f32_16x16x32_bf16 v[44:47], v[168:171], v[184:187], v[44:47]
	v_mfma_f32_16x16x32_bf16 v[40:43], v[176:179], v[184:187], v[40:43]
	v_mfma_f32_16x16x32_bf16 v[28:31], v[168:171], v[192:195], v[28:31]
	v_mfma_f32_16x16x32_bf16 v[24:27], v[176:179], v[192:195], v[24:27]
	v_mfma_f32_16x16x32_bf16 v[12:15], v[168:171], v[200:203], v[12:15]
	v_mfma_f32_16x16x32_bf16 v[8:11], v[176:179], v[200:203], v[8:11]
	v_mfma_f32_16x16x32_bf16 v[4:7], v[168:171], v[210:213], v[4:7]
	v_mfma_f32_16x16x32_bf16 v[0:3], v[176:179], v[210:213], v[0:3]
	s_barrier
	s_add_u32 s6, s6, 0x100
	s_addc_u32 s7, s7, 0
	s_cmp_gt_u32 s91, 29
	s_cbranch_scc0 .LBB0_2599
	s_and_b64 vcc, exec, s[12:13]
	s_cbranch_vccz .LBB0_2602
	s_barrier

; #define PG8_STAGE(bufoff, gbase, voff) do { const char* _gb = (const char*)(gbase); asm volatile("" : "+s"(_gb));     \
;         _Pragma("unroll") for (int _i = 0; _i < 2; ++_i) \
;         __builtin_amdgcn_global_load_lds((const unsigned*)(_gb + (voff)[_i]), (LAS unsigned*)(lds + (bufoff) + ldsw + _i * 8192), 16, 0, 0); } while (0)
; #define PG8_LDA(dst, b, h) do { _Pragma("unroll") for (int m = 0; m < 4; ++m) _Pragma("unroll") for (int k = 0; k < 2; ++k) dst[m][k] = *(const LAS bf16x8*)(lds + PG8_SA(b, h) + aoff + m * 2048 + k * 1024); } while (0)
; #define PG8_LDB(dst, b, h) do { _Pragma("unroll") for (int n = 0; n < 2; ++n) _Pragma("unroll") for (int k = 0; k < 2; ++k) dst[n][k] = *(const LAS bf16x8*)(lds + PG8_SB(b, h) + boff + n * 2048 + k * 1024); } while (0)
; #define PG8_MMA(ai, bj, At, Bt) do { __builtin_amdgcn_s_setprio(1); _Pragma("unroll") for (int m = 0; m < 4; ++m) _Pragma("unroll") for (int n = 0; n < 2; ++n) _Pragma("unroll") for (int k = 0; k < 2; ++k) \
;         acc[ai][bj][m][n] = __builtin_amdgcn_mfma_f32_16x16x32_bf16(Bt[n][k], At[m][k], acc[ai][bj][m][n], 0, 0, 0); __builtin_amdgcn_s_setprio(0); } while (0)
; #define PG8_WAIT_V(n) asm volatile("s_waitcnt vmcnt(" #n ")" ::: "memory")
; #define PG8_WAIT_L(n) asm volatile("s_waitcnt lgkmcnt(" #n ")" ::: "memory")
; #define PG8_BAR __builtin_amdgcn_s_barrier()
; template <class Epi>
; __device__ __forceinline__ void gemm_phase(LAS unsigned char* lds, const int wid, const Gemm g, const Epi& E) {
;     ...
;             const bool last = (t == nt - 2);
;             const char* a1 = PG8_AP(cA, t + 1);
;             const char* a2 = last ? PG8_AP(nA, 0) : PG8_AP(cA, t + 2); const char* b2 = last ? PG8_BP(nB, 0) : PG8_BP(cB, t + 2);
;             const char* a3 = last ? PG8_AP(nA, 1) : PG8_AP(cA, t + 3); const char* b3 = last ? PG8_BP(nB, 1) : PG8_BP(cB, t + 3);
;             PG8_LDB(B0, 0, 0); PG8_LDB(B1, 0, 1); PG8_SCHED; PG8_LDA(At, 0, 0); PG8_STAGE(PG8_SA(1, 1), a1 + hstepA, voffA);
;             PG8_WAIT_V(8); PG8_WAIT_L(0); PG8_BAR; PG8_MMA(0, 0, At, B0); PG8_MMA(0, 1, At, B1); PG8_BAR; PG8_SCHED;
;             PG8_LDA(At, 0, 1); PG8_STAGE(PG8_SB(0, 0), b2, voffB); PG8_STAGE(PG8_SB(0, 1), b2 + hstepB, voffB); PG8_STAGE(PG8_SA(0, 0), a2, voffA);
;             PG8_WAIT_V(8); PG8_WAIT_L(0); PG8_BAR; PG8_MMA(1, 0, At, B0); PG8_MMA(1, 1, At, B1); PG8_BAR; PG8_SCHED;
.LBB0_2769:
	ds_read_b128 v[104:107], v163
	ds_read_b128 v[108:111], v163 offset:1024
	ds_read_b128 v[148:151], v163 offset:2048
	ds_read_b128 v[152:155], v163 offset:3072
	ds_read_b128 v[156:159], v164
	ds_read_b128 v[168:171], v164 offset:1024
	ds_read_b128 v[172:175], v164 offset:2048
	ds_read_b128 v[176:179], v164 offset:3072
	s_add_u32 s0, s4, 0xfffe0080
	s_addc_u32 s1, s5, -1
	s_add_u32 s40, s75, 0xffffff80
	s_addc_u32 s41, s76, -1
	s_add_u32 s44, s4, 0xfffe0100
	s_addc_u32 s45, s5, -1
	s_add_i32 s81, s65, s47
	s_add_i32 m0, s52, 0xc000
	s_add_i32 s80, s52, 0xe000
	s_add_i32 s82, s81, 0x2000
	s_cmp_eq_u32 s77, 2
	s_cselect_b32 s43, s29, s1
	s_cselect_b32 s42, s39, s0
	s_cselect_b32 s79, s31, s41
	s_cselect_b32 s78, s30, s40
	s_cselect_b32 s41, s72, s45
	s_cselect_b32 s40, s71, s44
	s_mov_b64 s[44:45], s[4:5]
	ds_read_b128 v[180:183], v165
	ds_read_b128 v[184:187], v165 offset:1024
	ds_read_b128 v[188:191], v165 offset:2048
	ds_read_b128 v[192:195], v165 offset:3072
	ds_read_b128 v[196:199], v165 offset:4096
	ds_read_b128 v[200:203], v165 offset:5120
	ds_read_b128 v[206:209], v165 offset:6144
	ds_read_b128 v[210:213], v165 offset:7168
	s_nop 0
	v_lshl_add_u64 v[204:205], s[44:45], 0, v[136:137]
	global_load_lds_dwordx4 v[204:205], off
	v_lshl_add_u64 v[204:205], s[44:45], 0, v[140:141]
	s_mov_b32 m0, s80
	s_nop 0
	global_load_lds_dwordx4 v[204:205], off
	s_waitcnt vmcnt(8)
	s_waitcnt lgkmcnt(0)
	s_barrier
	s_waitcnt lgkmcnt(0)
	v_mfma_f32_16x16x32_bf16 v[132:135], v[104:107], v[180:183], v[132:135]
	v_mfma_f32_16x16x32_bf16 v[128:131], v[148:151], v[180:183], v[128:131]
	v_mfma_f32_16x16x32_bf16 v[124:127], v[104:107], v[188:191], v[124:127]
	v_mfma_f32_16x16x32_bf16 v[120:123], v[148:151], v[188:191], v[120:123]
	v_mfma_f32_16x16x32_bf16 v[116:119], v[104:107], v[196:199], v[116:119]
	v_mfma_f32_16x16x32_bf16 v[112:115], v[148:151], v[196:199], v[112:115]
	v_mfma_f32_16x16x32_bf16 v[100:103], v[104:107], v[206:209], v[100:103]
	v_mfma_f32_16x16x32_bf16 v[96:99], v[148:151], v[206:209], v[96:99]
	v_mfma_f32_16x16x32_bf16 v[132:135], v[108:111], v[184:187], v[132:135]
	v_mfma_f32_16x16x32_bf16 v[128:131], v[152:155], v[184:187], v[128:131]
	v_mfma_f32_16x16x32_bf16 v[124:127], v[108:111], v[192:195], v[124:127]
	v_mfma_f32_16x16x32_bf16 v[120:123], v[152:155], v[192:195], v[120:123]
	v_mfma_f32_16x16x32_bf16 v[116:119], v[108:111], v[200:203], v[116:119]
	v_mfma_f32_16x16x32_bf16 v[112:115], v[152:155], v[200:203], v[112:115]
	v_mfma_f32_16x16x32_bf16 v[100:103], v[108:111], v[210:213], v[100:103]
	v_mfma_f32_16x16x32_bf16 v[96:99], v[152:155], v[210:213], v[96:99]
	v_mfma_f32_16x16x32_bf16 v[60:63], v[156:159], v[180:183], v[60:63]
	v_mfma_f32_16x16x32_bf16 v[56:59], v[172:175], v[180:183], v[56:59]
	v_mfma_f32_16x16x32_bf16 v[52:55], v[156:159], v[188:191], v[52:55]
	v_mfma_f32_16x16x32_bf16 v[48:51], v[172:175], v[188:191], v[48:51]
	v_mfma_f32_16x16x32_bf16 v[44:47], v[156:159], v[196:199], v[44:47]
	v_mfma_f32_16x16x32_bf16 v[40:43], v[172:175], v[196:199], v[40:43]
	v_mfma_f32_16x16x32_bf16 v[36:39], v[156:159], v[206:209], v[36:39]
	v_mfma_f32_16x16x32_bf16 v[32:35], v[172:175], v[206:209], v[32:35]
	v_mfma_f32_16x16x32_bf16 v[60:63], v[168:171], v[184:187], v[60:63]
	v_mfma_f32_16x16x32_bf16 v[56:59], v[176:179], v[184:187], v[56:59]
	v_mfma_f32_16x16x32_bf16 v[52:55], v[168:171], v[192:195], v[52:55]
	v_mfma_f32_16x16x32_bf16 v[48:51], v[176:179], v[192:195], v[48:51]
	v_mfma_f32_16x16x32_bf16 v[44:47], v[168:171], v[200:203], v[44:47]
	v_mfma_f32_16x16x32_bf16 v[40:43], v[176:179], v[200:203], v[40:43]
	v_mfma_f32_16x16x32_bf16 v[36:39], v[168:171], v[210:213], v[36:39]
	v_mfma_f32_16x16x32_bf16 v[32:35], v[176:179], v[210:213], v[32:35]
	s_barrier
	s_mov_b64 s[44:45], s[78:79]
	s_mov_b32 m0, s81
	ds_read_b128 v[180:183], v165 offset:16384
	ds_read_b128 v[184:187], v165 offset:17408
	ds_read_b128 v[188:191], v165 offset:18432
	ds_read_b128 v[192:195], v165 offset:19456
	ds_read_b128 v[196:199], v165 offset:20480
	ds_read_b128 v[200:203], v165 offset:21504
	ds_read_b128 v[206:209], v165 offset:22528
	ds_read_b128 v[210:213], v165 offset:23552
	s_nop 0
	v_lshl_add_u64 v[204:205], s[44:45], 0, v[138:139]
	global_load_lds_dwordx4 v[204:205], off
	v_lshl_add_u64 v[204:205], s[44:45], 0, v[142:143]
	s_cselect_b32 s45, s74, s76
	s_cselect_b32 s44, s73, s75
	s_add_u32 s78, s78, 0x18000
	s_mov_b32 m0, s82
	s_addc_u32 s79, s79, 0
	s_add_i32 s0, s66, s47
	global_load_lds_dwordx4 v[204:205], off
	s_mov_b32 m0, s0
	v_lshl_add_u64 v[204:205], s[78:79], 0, v[138:139]
	global_load_lds_dwordx4 v[204:205], off
	v_lshl_add_u64 v[204:205], s[78:79], 0, v[142:143]
	s_add_i32 m0, s0, 0x2000
	s_mov_b64 s[78:79], s[42:43]
	global_load_lds_dwordx4 v[204:205], off
	s_mov_b32 m0, s52
	v_lshl_add_u64 v[204:205], s[78:79], 0, v[136:137]
	global_load_lds_dwordx4 v[204:205], off
	v_lshl_add_u64 v[204:205], s[78:79], 0, v[140:141]
	s_mov_b32 m0, s53
	s_nop 0
	global_load_lds_dwordx4 v[204:205], off
	s_waitcnt vmcnt(8)
	s_waitcnt lgkmcnt(0)
	s_barrier
; #define PG8_STAGE(bufoff, gbase, voff) do { const char* _gb = (const char*)(gbase); asm volatile("" : "+s"(_gb));     \
;         _Pragma("unroll") for (int _i = 0; _i < 2; ++_i) \
;         __builtin_amdgcn_global_load_lds((const unsigned*)(_gb + (voff)[_i]), (LAS unsigned*)(lds + (bufoff) + ldsw + _i * 8192), 16, 0, 0); } while (0)
; #define PG8_LDA(dst, b, h) do { _Pragma("unroll") for (int m = 0; m < 4; ++m) _Pragma("unroll") for (int k = 0; k < 2; ++k) dst[m][k] = *(const LAS bf16x8*)(lds + PG8_SA(b, h) + aoff + m * 2048 + k * 1024); } while (0)
; #define PG8_LDB(dst, b, h) do { _Pragma("unroll") for (int n = 0; n < 2; ++n) _Pragma("unroll") for (int k = 0; k < 2; ++k) dst[n][k] = *(const LAS bf16x8*)(lds + PG8_SB(b, h) + boff + n * 2048 + k * 1024); } while (0)
; #define PG8_MMA(ai, bj, At, Bt) do { __builtin_amdgcn_s_setprio(1); _Pragma("unroll") for (int m = 0; m < 4; ++m) _Pragma("unroll") for (int n = 0; n < 2; ++n) _Pragma("unroll") for (int k = 0; k < 2; ++k) \
;         acc[ai][bj][m][n] = __builtin_amdgcn_mfma_f32_16x16x32_bf16(Bt[n][k], At[m][k], acc[ai][bj][m][n], 0, 0, 0); __builtin_amdgcn_s_setprio(0); } while (0)
; #define PG8_WAIT_V(n) asm volatile("s_waitcnt vmcnt(" #n ")" ::: "memory")
; #define PG8_WAIT_L(n) asm volatile("s_waitcnt lgkmcnt(" #n ")" ::: "memory")
; #define PG8_BAR __builtin_amdgcn_s_barrier()
; #define PG8_SCHED __builtin_amdgcn_sched_barrier(0)
; template <class Epi>
; __device__ __forceinline__ void gemm_phase(LAS unsigned char* lds, const int wid, const Gemm g, const Epi& E) {
;     ...
;             PG8_WAIT_V(8); PG8_WAIT_L(0); PG8_BAR; PG8_MMA(1, 0, At, B0); PG8_MMA(1, 1, At, B1); PG8_BAR; PG8_SCHED;
;             PG8_LDB(B0, 1, 0); PG8_LDB(B1, 1, 1); PG8_SCHED; PG8_LDA(At, 1, 0); PG8_STAGE(PG8_SA(0, 1), a2 + hstepA, voffA);
;             PG8_WAIT_V(8); PG8_WAIT_L(0); PG8_BAR; PG8_MMA(0, 0, At, B0); PG8_MMA(0, 1, At, B1); PG8_BAR; PG8_SCHED;
	s_waitcnt lgkmcnt(0)
	v_mfma_f32_16x16x32_bf16 v[92:95], v[104:107], v[180:183], v[92:95]
	v_mfma_f32_16x16x32_bf16 v[88:91], v[148:151], v[180:183], v[88:91]
	v_mfma_f32_16x16x32_bf16 v[84:87], v[104:107], v[188:191], v[84:87]
	v_mfma_f32_16x16x32_bf16 v[80:83], v[148:151], v[188:191], v[80:83]
	v_mfma_f32_16x16x32_bf16 v[76:79], v[104:107], v[196:199], v[76:79]
	v_mfma_f32_16x16x32_bf16 v[72:75], v[148:151], v[196:199], v[72:75]
	v_mfma_f32_16x16x32_bf16 v[68:71], v[104:107], v[206:209], v[68:71]
	v_mfma_f32_16x16x32_bf16 v[64:67], v[148:151], v[206:209], v[64:67]
	v_mfma_f32_16x16x32_bf16 v[92:95], v[108:111], v[184:187], v[92:95]
	v_mfma_f32_16x16x32_bf16 v[88:91], v[152:155], v[184:187], v[88:91]
	v_mfma_f32_16x16x32_bf16 v[84:87], v[108:111], v[192:195], v[84:87]
	v_mfma_f32_16x16x32_bf16 v[80:83], v[152:155], v[192:195], v[80:83]
	v_mfma_f32_16x16x32_bf16 v[76:79], v[108:111], v[200:203], v[76:79]
	v_mfma_f32_16x16x32_bf16 v[72:75], v[152:155], v[200:203], v[72:75]
	v_mfma_f32_16x16x32_bf16 v[68:71], v[108:111], v[210:213], v[68:71]
	v_mfma_f32_16x16x32_bf16 v[64:67], v[152:155], v[210:213], v[64:67]
	v_mfma_f32_16x16x32_bf16 v[28:31], v[156:159], v[180:183], v[28:31]
	v_mfma_f32_16x16x32_bf16 v[24:27], v[172:175], v[180:183], v[24:27]
	v_mfma_f32_16x16x32_bf16 v[20:23], v[156:159], v[188:191], v[20:23]
	v_mfma_f32_16x16x32_bf16 v[16:19], v[172:175], v[188:191], v[16:19]
	v_mfma_f32_16x16x32_bf16 v[12:15], v[156:159], v[196:199], v[12:15]
	v_mfma_f32_16x16x32_bf16 v[8:11], v[172:175], v[196:199], v[8:11]
	v_mfma_f32_16x16x32_bf16 v[4:7], v[156:159], v[206:209], v[4:7]
	v_mfma_f32_16x16x32_bf16 v[0:3], v[172:175], v[206:209], v[0:3]
	v_mfma_f32_16x16x32_bf16 v[28:31], v[168:171], v[184:187], v[28:31]
	v_mfma_f32_16x16x32_bf16 v[24:27], v[176:179], v[184:187], v[24:27]
	v_mfma_f32_16x16x32_bf16 v[20:23], v[168:171], v[192:195], v[20:23]
	v_mfma_f32_16x16x32_bf16 v[16:19], v[176:179], v[192:195], v[16:19]
	v_mfma_f32_16x16x32_bf16 v[12:15], v[168:171], v[200:203], v[12:15]
	v_mfma_f32_16x16x32_bf16 v[8:11], v[176:179], v[200:203], v[8:11]
	v_mfma_f32_16x16x32_bf16 v[4:7], v[168:171], v[210:213], v[4:7]
	v_mfma_f32_16x16x32_bf16 v[0:3], v[176:179], v[210:213], v[0:3]
	s_barrier
	s_add_i32 s0, 0, 0x18000
	s_add_i32 s1, 0, 0x1c000
	v_add_u32_e32 v152, s0, v162
	v_add_u32_e32 v167, s1, v162
	ds_read_b128 v[104:107], v152
	ds_read_b128 v[108:111], v152 offset:1024
	ds_read_b128 v[148:151], v152 offset:2048
	ds_read_b128 v[152:155], v152 offset:3072
	ds_read_b128 v[156:159], v167
	ds_read_b128 v[168:171], v167 offset:1024
	ds_read_b128 v[172:175], v167 offset:2048
	ds_read_b128 v[176:179], v167 offset:3072
	s_add_u32 s42, s42, 0x20000
	s_addc_u32 s43, s43, 0
	s_mov_b32 m0, s54
	ds_read_b128 v[180:183], v165 offset:32768
	ds_read_b128 v[184:187], v165 offset:33792
	ds_read_b128 v[188:191], v165 offset:34816
	ds_read_b128 v[192:195], v165 offset:35840
	ds_read_b128 v[196:199], v165 offset:36864
	ds_read_b128 v[200:203], v165 offset:37888
	ds_read_b128 v[206:209], v165 offset:38912
	ds_read_b128 v[210:213], v165 offset:39936
	s_nop 0
	v_lshl_add_u64 v[204:205], s[42:43], 0, v[136:137]
	global_load_lds_dwordx4 v[204:205], off
	v_lshl_add_u64 v[204:205], s[42:43], 0, v[140:141]
	s_mov_b32 m0, s55
	s_nop 0
	global_load_lds_dwordx4 v[204:205], off
	s_waitcnt vmcnt(8)
	s_waitcnt lgkmcnt(0)
	s_barrier
	s_waitcnt lgkmcnt(0)
	v_mfma_f32_16x16x32_bf16 v[132:135], v[104:107], v[180:183], v[132:135]
	v_mfma_f32_16x16x32_bf16 v[128:131], v[148:151], v[180:183], v[128:131]
	v_mfma_f32_16x16x32_bf16 v[124:127], v[104:107], v[188:191], v[124:127]
	v_mfma_f32_16x16x32_bf16 v[120:123], v[148:151], v[188:191], v[120:123]
	v_mfma_f32_16x16x32_bf16 v[116:119], v[104:107], v[196:199], v[116:119]
	v_mfma_f32_16x16x32_bf16 v[112:115], v[148:151], v[196:199], v[112:115]
	v_mfma_f32_16x16x32_bf16 v[100:103], v[104:107], v[206:209], v[100:103]
	v_mfma_f32_16x16x32_bf16 v[96:99], v[148:151], v[206:209], v[96:99]
	v_mfma_f32_16x16x32_bf16 v[132:135], v[108:111], v[184:187], v[132:135]
	v_mfma_f32_16x16x32_bf16 v[128:131], v[152:155], v[184:187], v[128:131]
	v_mfma_f32_16x16x32_bf16 v[124:127], v[108:111], v[192:195], v[124:127]
	v_mfma_f32_16x16x32_bf16 v[120:123], v[152:155], v[192:195], v[120:123]
	v_mfma_f32_16x16x32_bf16 v[116:119], v[108:111], v[200:203], v[116:119]
	v_mfma_f32_16x16x32_bf16 v[112:115], v[152:155], v[200:203], v[112:115]
	v_mfma_f32_16x16x32_bf16 v[100:103], v[108:111], v[210:213], v[100:103]
	v_mfma_f32_16x16x32_bf16 v[96:99], v[152:155], v[210:213], v[96:99]
	v_mfma_f32_16x16x32_bf16 v[60:63], v[156:159], v[180:183], v[60:63]
	v_mfma_f32_16x16x32_bf16 v[56:59], v[172:175], v[180:183], v[56:59]
	v_mfma_f32_16x16x32_bf16 v[52:55], v[156:159], v[188:191], v[52:55]
	v_mfma_f32_16x16x32_bf16 v[48:51], v[172:175], v[188:191], v[48:51]
	v_mfma_f32_16x16x32_bf16 v[44:47], v[156:159], v[196:199], v[44:47]
	v_mfma_f32_16x16x32_bf16 v[40:43], v[172:175], v[196:199], v[40:43]
	v_mfma_f32_16x16x32_bf16 v[36:39], v[156:159], v[206:209], v[36:39]
	v_mfma_f32_16x16x32_bf16 v[32:35], v[172:175], v[206:209], v[32:35]
	v_mfma_f32_16x16x32_bf16 v[60:63], v[168:171], v[184:187], v[60:63]
	v_mfma_f32_16x16x32_bf16 v[56:59], v[176:179], v[184:187], v[56:59]
	v_mfma_f32_16x16x32_bf16 v[52:55], v[168:171], v[192:195], v[52:55]
	v_mfma_f32_16x16x32_bf16 v[48:51], v[176:179], v[192:195], v[48:51]
	v_mfma_f32_16x16x32_bf16 v[44:47], v[168:171], v[200:203], v[44:47]
	v_mfma_f32_16x16x32_bf16 v[40:43], v[176:179], v[200:203], v[40:43]
	v_mfma_f32_16x16x32_bf16 v[36:39], v[168:171], v[210:213], v[36:39]
	v_mfma_f32_16x16x32_bf16 v[32:35], v[176:179], v[210:213], v[32:35]
	s_barrier
; #define PG8_STAGE(bufoff, gbase, voff) do { const char* _gb = (const char*)(gbase); asm volatile("" : "+s"(_gb));     \
;         _Pragma("unroll") for (int _i = 0; _i < 2; ++_i) \
;         __builtin_amdgcn_global_load_lds((const unsigned*)(_gb + (voff)[_i]), (LAS unsigned*)(lds + (bufoff) + ldsw + _i * 8192), 16, 0, 0); } while (0)
; #define PG8_LDA(dst, b, h) do { _Pragma("unroll") for (int m = 0; m < 4; ++m) _Pragma("unroll") for (int k = 0; k < 2; ++k) dst[m][k] = *(const LAS bf16x8*)(lds + PG8_SA(b, h) + aoff + m * 2048 + k * 1024); } while (0)
; #define PG8_MMA(ai, bj, At, Bt) do { __builtin_amdgcn_s_setprio(1); _Pragma("unroll") for (int m = 0; m < 4; ++m) _Pragma("unroll") for (int n = 0; n < 2; ++n) _Pragma("unroll") for (int k = 0; k < 2; ++k) \
;         acc[ai][bj][m][n] = __builtin_amdgcn_mfma_f32_16x16x32_bf16(Bt[n][k], At[m][k], acc[ai][bj][m][n], 0, 0, 0); __builtin_amdgcn_s_setprio(0); } while (0)
; #define PG8_WAIT_V(n) asm volatile("s_waitcnt vmcnt(" #n ")" ::: "memory")
; #define PG8_WAIT_L(n) asm volatile("s_waitcnt lgkmcnt(" #n ")" ::: "memory")
; #define PG8_BAR __builtin_amdgcn_s_barrier()
; #define PG8_SCHED __builtin_amdgcn_sched_barrier(0)
; template <class Epi>
; __device__ __forceinline__ void gemm_phase(LAS unsigned char* lds, const int wid, const Gemm g, const Epi& E) {
;     ...
;             PG8_LDA(At, 1, 1); PG8_STAGE(PG8_SB(1, 0), b3, voffB); PG8_STAGE(PG8_SB(1, 1), b3 + hstepB, voffB); PG8_STAGE(PG8_SA(1, 0), a3, voffA);
;             PG8_WAIT_V(8); PG8_WAIT_L(0); PG8_BAR; PG8_MMA(1, 0, At, B0); PG8_MMA(1, 1, At, B1); PG8_BAR; PG8_SCHED;
;         }
;         if (wr == 0) PG8_BAR;
	s_mov_b64 s[42:43], s[44:45]
	s_add_i32 s0, s0, s47
	ds_read_b128 v[180:183], v165 offset:49152
	ds_read_b128 v[184:187], v165 offset:50176
	ds_read_b128 v[188:191], v165 offset:51200
	ds_read_b128 v[192:195], v165 offset:52224
	ds_read_b128 v[196:199], v165 offset:53248
	ds_read_b128 v[200:203], v165 offset:54272
	ds_read_b128 v[206:209], v165 offset:55296
	ds_read_b128 v[210:213], v165 offset:56320
	s_mov_b32 m0, s0
	v_lshl_add_u64 v[204:205], s[42:43], 0, v[138:139]
	global_load_lds_dwordx4 v[204:205], off
	s_add_i32 m0, s0, 0x2000
	v_lshl_add_u64 v[204:205], s[42:43], 0, v[142:143]
	s_add_u32 s42, s44, 0x18000
	s_addc_u32 s43, s45, 0
	s_add_i32 s0, s1, s47
	global_load_lds_dwordx4 v[204:205], off
	s_mov_b32 m0, s0
	v_lshl_add_u64 v[204:205], s[42:43], 0, v[138:139]
	global_load_lds_dwordx4 v[204:205], off
	v_lshl_add_u64 v[204:205], s[42:43], 0, v[142:143]
	s_add_i32 m0, s0, 0x2000
	s_nop 0
	global_load_lds_dwordx4 v[204:205], off
	s_mov_b32 m0, s61
	v_lshl_add_u64 v[204:205], s[40:41], 0, v[136:137]
	global_load_lds_dwordx4 v[204:205], off
	v_lshl_add_u64 v[204:205], s[40:41], 0, v[140:141]
	s_mov_b32 m0, s62
	s_nop 0
	global_load_lds_dwordx4 v[204:205], off
	s_waitcnt vmcnt(8)
	s_waitcnt lgkmcnt(0)
	s_barrier
	s_waitcnt lgkmcnt(0)
	v_mfma_f32_16x16x32_bf16 v[92:95], v[104:107], v[180:183], v[92:95]
	v_mfma_f32_16x16x32_bf16 v[88:91], v[148:151], v[180:183], v[88:91]
	v_mfma_f32_16x16x32_bf16 v[84:87], v[104:107], v[188:191], v[84:87]
	v_mfma_f32_16x16x32_bf16 v[80:83], v[148:151], v[188:191], v[80:83]
	v_mfma_f32_16x16x32_bf16 v[76:79], v[104:107], v[196:199], v[76:79]
	v_mfma_f32_16x16x32_bf16 v[72:75], v[148:151], v[196:199], v[72:75]
	v_mfma_f32_16x16x32_bf16 v[68:71], v[104:107], v[206:209], v[68:71]
	v_mfma_f32_16x16x32_bf16 v[64:67], v[148:151], v[206:209], v[64:67]
	v_mfma_f32_16x16x32_bf16 v[92:95], v[108:111], v[184:187], v[92:95]
	v_mfma_f32_16x16x32_bf16 v[88:91], v[152:155], v[184:187], v[88:91]
	v_mfma_f32_16x16x32_bf16 v[84:87], v[108:111], v[192:195], v[84:87]
	v_mfma_f32_16x16x32_bf16 v[80:83], v[152:155], v[192:195], v[80:83]
	v_mfma_f32_16x16x32_bf16 v[76:79], v[108:111], v[200:203], v[76:79]
	v_mfma_f32_16x16x32_bf16 v[72:75], v[152:155], v[200:203], v[72:75]
	v_mfma_f32_16x16x32_bf16 v[68:71], v[108:111], v[210:213], v[68:71]
	v_mfma_f32_16x16x32_bf16 v[64:67], v[152:155], v[210:213], v[64:67]
	v_mfma_f32_16x16x32_bf16 v[28:31], v[156:159], v[180:183], v[28:31]
	v_mfma_f32_16x16x32_bf16 v[24:27], v[172:175], v[180:183], v[24:27]
	v_mfma_f32_16x16x32_bf16 v[20:23], v[156:159], v[188:191], v[20:23]
	v_mfma_f32_16x16x32_bf16 v[16:19], v[172:175], v[188:191], v[16:19]
	v_mfma_f32_16x16x32_bf16 v[12:15], v[156:159], v[196:199], v[12:15]
	v_mfma_f32_16x16x32_bf16 v[8:11], v[172:175], v[196:199], v[8:11]
	v_mfma_f32_16x16x32_bf16 v[4:7], v[156:159], v[206:209], v[4:7]
	v_mfma_f32_16x16x32_bf16 v[0:3], v[172:175], v[206:209], v[0:3]
	v_mfma_f32_16x16x32_bf16 v[28:31], v[168:171], v[184:187], v[28:31]
	v_mfma_f32_16x16x32_bf16 v[24:27], v[176:179], v[184:187], v[24:27]
	v_mfma_f32_16x16x32_bf16 v[20:23], v[168:171], v[192:195], v[20:23]
	v_mfma_f32_16x16x32_bf16 v[16:19], v[176:179], v[192:195], v[16:19]
	v_mfma_f32_16x16x32_bf16 v[12:15], v[168:171], v[200:203], v[12:15]
	v_mfma_f32_16x16x32_bf16 v[8:11], v[176:179], v[200:203], v[8:11]
	v_mfma_f32_16x16x32_bf16 v[4:7], v[168:171], v[210:213], v[4:7]
	v_mfma_f32_16x16x32_bf16 v[0:3], v[176:179], v[210:213], v[0:3]
	s_barrier
	s_add_i32 s77, s77, 2
	s_add_u32 s75, s75, 0x100
	s_addc_u32 s76, s76, 0
	s_add_u32 s4, s4, 0x100
	s_addc_u32 s5, s5, 0
	s_cmp_gt_u32 s77, 3
	s_cbranch_scc0 .LBB0_2769
	s_and_b64 vcc, exec, s[14:15]
	s_cbranch_vccz .LBB0_2772
	s_barrier

; #define PG8_STAGE(bufoff, gbase, voff) do { const char* _gb = (const char*)(gbase); asm volatile("" : "+s"(_gb));     \
;         _Pragma("unroll") for (int _i = 0; _i < 2; ++_i) \
;         __builtin_amdgcn_global_load_lds((const unsigned*)(_gb + (voff)[_i]), (LAS unsigned*)(lds + (bufoff) + ldsw + _i * 8192), 16, 0, 0); } while (0)
; #define PG8_LDA(dst, b, h) do { _Pragma("unroll") for (int m = 0; m < 4; ++m) _Pragma("unroll") for (int k = 0; k < 2; ++k) dst[m][k] = *(const LAS bf16x8*)(lds + PG8_SA(b, h) + aoff + m * 2048 + k * 1024); } while (0)
; #define PG8_LDB(dst, b, h) do { _Pragma("unroll") for (int n = 0; n < 2; ++n) _Pragma("unroll") for (int k = 0; k < 2; ++k) dst[n][k] = *(const LAS bf16x8*)(lds + PG8_SB(b, h) + boff + n * 2048 + k * 1024); } while (0)
; #define PG8_MMA(ai, bj, At, Bt) do { __builtin_amdgcn_s_setprio(1); _Pragma("unroll") for (int m = 0; m < 4; ++m) _Pragma("unroll") for (int n = 0; n < 2; ++n) _Pragma("unroll") for (int k = 0; k < 2; ++k) \
;         acc[ai][bj][m][n] = __builtin_amdgcn_mfma_f32_16x16x32_bf16(Bt[n][k], At[m][k], acc[ai][bj][m][n], 0, 0, 0); __builtin_amdgcn_s_setprio(0); } while (0)
; #define PG8_WAIT_V(n) asm volatile("s_waitcnt vmcnt(" #n ")" ::: "memory")
; #define PG8_WAIT_L(n) asm volatile("s_waitcnt lgkmcnt(" #n ")" ::: "memory")
; #define PG8_BAR __builtin_amdgcn_s_barrier()
; template <class Epi>
; __device__ __forceinline__ void gemm_phase(LAS unsigned char* lds, const int wid, const Gemm g, const Epi& E) {
;     ...
;             const bool last = (t == nt - 2);
;             const char* a1 = PG8_AP(cA, t + 1);
;             const char* a2 = last ? PG8_AP(nA, 0) : PG8_AP(cA, t + 2); const char* b2 = last ? PG8_BP(nB, 0) : PG8_BP(cB, t + 2);
;             const char* a3 = last ? PG8_AP(nA, 1) : PG8_AP(cA, t + 3); const char* b3 = last ? PG8_BP(nB, 1) : PG8_BP(cB, t + 3);
;             PG8_LDB(B0, 0, 0); PG8_LDB(B1, 0, 1); PG8_SCHED; PG8_LDA(At, 0, 0); PG8_STAGE(PG8_SA(1, 1), a1 + hstepA, voffA);
;             PG8_WAIT_V(8); PG8_WAIT_L(0); PG8_BAR; PG8_MMA(0, 0, At, B0); PG8_MMA(0, 1, At, B1); PG8_BAR; PG8_SCHED;
;             PG8_LDA(At, 0, 1); PG8_STAGE(PG8_SB(0, 0), b2, voffB); PG8_STAGE(PG8_SB(0, 1), b2 + hstepB, voffB); PG8_STAGE(PG8_SA(0, 0), a2, voffA);
;             PG8_WAIT_V(8); PG8_WAIT_L(0); PG8_BAR; PG8_MMA(1, 0, At, B0); PG8_MMA(1, 1, At, B1); PG8_BAR; PG8_SCHED;
.LBB0_2972:
	s_add_u32 s0, s40, s46
	s_addc_u32 s1, s41, 0
	s_add_u32 s47, s0, 0x100
	s_addc_u32 s50, s1, 0
	s_and_b64 s[48:49], s[44:45], exec
	s_cselect_b32 s53, s27, s50
	s_cselect_b32 s52, s79, s47
	s_add_u32 s48, s38, s46
	s_addc_u32 s49, s39, 0
	s_add_u32 s50, s48, 0x100
	s_addc_u32 s51, s49, 0
	s_and_b64 s[46:47], s[44:45], exec
	s_cselect_b32 s55, s25, s51
	s_cselect_b32 s54, s80, s50
	s_add_u32 s50, s0, 0x180
	s_addc_u32 s51, s1, 0
	s_and_b64 s[46:47], s[44:45], exec
	s_cselect_b32 s46, s81, s50
	s_cselect_b32 s47, s82, s51
	s_add_u32 s48, s48, 0x180
	s_addc_u32 s49, s49, 0
	s_add_u32 s58, s0, 0x20080
	s_addc_u32 s59, s1, 0
	s_add_i32 s94, s76, s23
	s_add_i32 m0, s65, 0xc000
	s_add_i32 s0, s65, 0xe000
	s_add_i32 s91, s94, 0x2000
	ds_read_b128 v[140:143], v157
	ds_read_b128 v[144:147], v157 offset:1024
	ds_read_b128 v[148:151], v157 offset:2048
	ds_read_b128 v[162:165], v157 offset:3072
	ds_read_b128 v[166:169], v158
	ds_read_b128 v[170:173], v158 offset:1024
	ds_read_b128 v[174:177], v158 offset:2048
	ds_read_b128 v[178:181], v158 offset:3072
	s_add_u32 s56, s54, 0x10000
	s_addc_u32 s57, s55, 0
	s_add_i32 s90, s77, s23
	s_add_i32 s89, s90, 0x2000
	s_add_i32 s88, 0, 0x18000
	s_add_i32 s87, 0, 0x1c000
	s_add_u32 s50, s52, 0x20000
	s_addc_u32 s51, s53, 0
	s_and_b64 s[44:45], s[44:45], exec
	s_cselect_b32 s49, s84, s49
	s_cselect_b32 s48, s83, s48
	s_add_i32 s86, s88, s23
	s_add_i32 s85, s86, 0x2000
	s_add_u32 s44, s48, 0x10000
	s_addc_u32 s45, s49, 0
	s_add_i32 s93, s87, s23
	s_add_i32 s92, s93, 0x2000
	ds_read_b128 v[182:185], v159
	ds_read_b128 v[186:189], v159 offset:1024
	ds_read_b128 v[190:193], v159 offset:2048
	ds_read_b128 v[194:197], v159 offset:3072
	ds_read_b128 v[198:201], v159 offset:4096
	ds_read_b128 v[206:209], v159 offset:5120
	ds_read_b128 v[210:213], v159 offset:6144
	ds_read_b128 v[214:217], v159 offset:7168
	s_nop 0
	v_lshl_add_u64 v[202:203], s[58:59], 0, v[134:135]
	global_load_lds_dwordx4 v[202:203], off
	v_lshl_add_u64 v[202:203], s[58:59], 0, v[130:131]
	s_mov_b32 m0, s0
	s_nop 0
	global_load_lds_dwordx4 v[202:203], off
	s_waitcnt vmcnt(8)
	s_waitcnt lgkmcnt(0)
	s_barrier
	s_waitcnt lgkmcnt(0)
	v_mfma_f32_16x16x32_bf16 v[124:127], v[140:143], v[182:185], v[124:127]
	v_mfma_f32_16x16x32_bf16 v[120:123], v[148:151], v[182:185], v[120:123]
	v_mfma_f32_16x16x32_bf16 v[108:111], v[140:143], v[190:193], v[108:111]
	v_mfma_f32_16x16x32_bf16 v[104:107], v[148:151], v[190:193], v[104:107]
	v_mfma_f32_16x16x32_bf16 v[92:95], v[140:143], v[198:201], v[92:95]
	v_mfma_f32_16x16x32_bf16 v[88:91], v[148:151], v[198:201], v[88:91]
	v_mfma_f32_16x16x32_bf16 v[76:79], v[140:143], v[210:213], v[76:79]
	v_mfma_f32_16x16x32_bf16 v[72:75], v[148:151], v[210:213], v[72:75]
	v_mfma_f32_16x16x32_bf16 v[124:127], v[144:147], v[186:189], v[124:127]
	v_mfma_f32_16x16x32_bf16 v[120:123], v[162:165], v[186:189], v[120:123]
	v_mfma_f32_16x16x32_bf16 v[108:111], v[144:147], v[194:197], v[108:111]
	v_mfma_f32_16x16x32_bf16 v[104:107], v[162:165], v[194:197], v[104:107]
	v_mfma_f32_16x16x32_bf16 v[92:95], v[144:147], v[206:209], v[92:95]
	v_mfma_f32_16x16x32_bf16 v[88:91], v[162:165], v[206:209], v[88:91]
	v_mfma_f32_16x16x32_bf16 v[76:79], v[144:147], v[214:217], v[76:79]
	v_mfma_f32_16x16x32_bf16 v[72:75], v[162:165], v[214:217], v[72:75]
	v_mfma_f32_16x16x32_bf16 v[116:119], v[166:169], v[182:185], v[116:119]
	v_mfma_f32_16x16x32_bf16 v[112:115], v[174:177], v[182:185], v[112:115]
	v_mfma_f32_16x16x32_bf16 v[100:103], v[166:169], v[190:193], v[100:103]
	v_mfma_f32_16x16x32_bf16 v[96:99], v[174:177], v[190:193], v[96:99]
	v_mfma_f32_16x16x32_bf16 v[84:87], v[166:169], v[198:201], v[84:87]
	v_mfma_f32_16x16x32_bf16 v[80:83], v[174:177], v[198:201], v[80:83]
	v_mfma_f32_16x16x32_bf16 v[68:71], v[166:169], v[210:213], v[68:71]
	v_mfma_f32_16x16x32_bf16 v[64:67], v[174:177], v[210:213], v[64:67]
	v_mfma_f32_16x16x32_bf16 v[116:119], v[170:173], v[186:189], v[116:119]
	v_mfma_f32_16x16x32_bf16 v[112:115], v[178:181], v[186:189], v[112:115]
	v_mfma_f32_16x16x32_bf16 v[100:103], v[170:173], v[194:197], v[100:103]
	v_mfma_f32_16x16x32_bf16 v[96:99], v[178:181], v[194:197], v[96:99]
	v_mfma_f32_16x16x32_bf16 v[84:87], v[170:173], v[206:209], v[84:87]
	v_mfma_f32_16x16x32_bf16 v[80:83], v[178:181], v[206:209], v[80:83]
	v_mfma_f32_16x16x32_bf16 v[68:71], v[170:173], v[214:217], v[68:71]
	v_mfma_f32_16x16x32_bf16 v[64:67], v[178:181], v[214:217], v[64:67]
	s_barrier
	s_mov_b32 m0, s94
	ds_read_b128 v[182:185], v159 offset:16384
	ds_read_b128 v[186:189], v159 offset:17408
	ds_read_b128 v[190:193], v159 offset:18432
	ds_read_b128 v[194:197], v159 offset:19456
	ds_read_b128 v[198:201], v159 offset:20480
	ds_read_b128 v[206:209], v159 offset:21504
	ds_read_b128 v[210:213], v159 offset:22528
	ds_read_b128 v[214:217], v159 offset:23552
	s_nop 0
	v_lshl_add_u64 v[202:203], s[54:55], 0, v[132:133]
	global_load_lds_dwordx4 v[202:203], off
	v_lshl_add_u64 v[202:203], s[54:55], 0, v[128:129]
	s_mov_b32 m0, s91
	s_nop 0
	global_load_lds_dwordx4 v[202:203], off
	s_mov_b32 m0, s90
	v_lshl_add_u64 v[202:203], s[56:57], 0, v[132:133]
	global_load_lds_dwordx4 v[202:203], off
	v_lshl_add_u64 v[202:203], s[56:57], 0, v[128:129]
	s_mov_b32 m0, s89
	s_nop 0
	global_load_lds_dwordx4 v[202:203], off
	s_mov_b32 m0, s65
	v_lshl_add_u64 v[202:203], s[52:53], 0, v[134:135]
	global_load_lds_dwordx4 v[202:203], off
	v_lshl_add_u64 v[202:203], s[52:53], 0, v[130:131]
	s_mov_b32 m0, s66
	s_nop 0
	global_load_lds_dwordx4 v[202:203], off
	s_waitcnt vmcnt(8)
	s_waitcnt lgkmcnt(0)
	s_barrier
; #define PG8_STAGE(bufoff, gbase, voff) do { const char* _gb = (const char*)(gbase); asm volatile("" : "+s"(_gb));     \
;         _Pragma("unroll") for (int _i = 0; _i < 2; ++_i) \
;         __builtin_amdgcn_global_load_lds((const unsigned*)(_gb + (voff)[_i]), (LAS unsigned*)(lds + (bufoff) + ldsw + _i * 8192), 16, 0, 0); } while (0)
; #define PG8_LDA(dst, b, h) do { _Pragma("unroll") for (int m = 0; m < 4; ++m) _Pragma("unroll") for (int k = 0; k < 2; ++k) dst[m][k] = *(const LAS bf16x8*)(lds + PG8_SA(b, h) + aoff + m * 2048 + k * 1024); } while (0)
; #define PG8_LDB(dst, b, h) do { _Pragma("unroll") for (int n = 0; n < 2; ++n) _Pragma("unroll") for (int k = 0; k < 2; ++k) dst[n][k] = *(const LAS bf16x8*)(lds + PG8_SB(b, h) + boff + n * 2048 + k * 1024); } while (0)
; #define PG8_MMA(ai, bj, At, Bt) do { __builtin_amdgcn_s_setprio(1); _Pragma("unroll") for (int m = 0; m < 4; ++m) _Pragma("unroll") for (int n = 0; n < 2; ++n) _Pragma("unroll") for (int k = 0; k < 2; ++k) \
;         acc[ai][bj][m][n] = __builtin_amdgcn_mfma_f32_16x16x32_bf16(Bt[n][k], At[m][k], acc[ai][bj][m][n], 0, 0, 0); __builtin_amdgcn_s_setprio(0); } while (0)
; #define PG8_WAIT_V(n) asm volatile("s_waitcnt vmcnt(" #n ")" ::: "memory")
; #define PG8_WAIT_L(n) asm volatile("s_waitcnt lgkmcnt(" #n ")" ::: "memory")
; #define PG8_BAR __builtin_amdgcn_s_barrier()
; #define PG8_SCHED __builtin_amdgcn_sched_barrier(0)
; template <class Epi>
; __device__ __forceinline__ void gemm_phase(LAS unsigned char* lds, const int wid, const Gemm g, const Epi& E) {
;     ...
;             PG8_WAIT_V(8); PG8_WAIT_L(0); PG8_BAR; PG8_MMA(1, 0, At, B0); PG8_MMA(1, 1, At, B1); PG8_BAR; PG8_SCHED;
;             PG8_LDB(B0, 1, 0); PG8_LDB(B1, 1, 1); PG8_SCHED; PG8_LDA(At, 1, 0); PG8_STAGE(PG8_SA(0, 1), a2 + hstepA, voffA);
;             PG8_WAIT_V(8); PG8_WAIT_L(0); PG8_BAR; PG8_MMA(0, 0, At, B0); PG8_MMA(0, 1, At, B1); PG8_BAR; PG8_SCHED;
	s_waitcnt lgkmcnt(0)
	v_mfma_f32_16x16x32_bf16 v[60:63], v[140:143], v[182:185], v[60:63]
	v_mfma_f32_16x16x32_bf16 v[56:59], v[148:151], v[182:185], v[56:59]
	v_mfma_f32_16x16x32_bf16 v[44:47], v[140:143], v[190:193], v[44:47]
	v_mfma_f32_16x16x32_bf16 v[40:43], v[148:151], v[190:193], v[40:43]
	v_mfma_f32_16x16x32_bf16 v[28:31], v[140:143], v[198:201], v[28:31]
	v_mfma_f32_16x16x32_bf16 v[24:27], v[148:151], v[198:201], v[24:27]
	v_mfma_f32_16x16x32_bf16 v[12:15], v[140:143], v[210:213], v[12:15]
	v_mfma_f32_16x16x32_bf16 v[8:11], v[148:151], v[210:213], v[8:11]
	v_mfma_f32_16x16x32_bf16 v[60:63], v[144:147], v[186:189], v[60:63]
	v_mfma_f32_16x16x32_bf16 v[56:59], v[162:165], v[186:189], v[56:59]
	v_mfma_f32_16x16x32_bf16 v[44:47], v[144:147], v[194:197], v[44:47]
	v_mfma_f32_16x16x32_bf16 v[40:43], v[162:165], v[194:197], v[40:43]
	v_mfma_f32_16x16x32_bf16 v[28:31], v[144:147], v[206:209], v[28:31]
	v_mfma_f32_16x16x32_bf16 v[24:27], v[162:165], v[206:209], v[24:27]
	v_mfma_f32_16x16x32_bf16 v[12:15], v[144:147], v[214:217], v[12:15]
	v_mfma_f32_16x16x32_bf16 v[8:11], v[162:165], v[214:217], v[8:11]
	v_mfma_f32_16x16x32_bf16 v[52:55], v[166:169], v[182:185], v[52:55]
	v_mfma_f32_16x16x32_bf16 v[48:51], v[174:177], v[182:185], v[48:51]
	v_mfma_f32_16x16x32_bf16 v[36:39], v[166:169], v[190:193], v[36:39]
	v_mfma_f32_16x16x32_bf16 v[32:35], v[174:177], v[190:193], v[32:35]
	v_mfma_f32_16x16x32_bf16 v[20:23], v[166:169], v[198:201], v[20:23]
	v_mfma_f32_16x16x32_bf16 v[16:19], v[174:177], v[198:201], v[16:19]
	v_mfma_f32_16x16x32_bf16 v[4:7], v[166:169], v[210:213], v[4:7]
	v_mfma_f32_16x16x32_bf16 v[0:3], v[174:177], v[210:213], v[0:3]
	v_mfma_f32_16x16x32_bf16 v[52:55], v[170:173], v[186:189], v[52:55]
	v_mfma_f32_16x16x32_bf16 v[48:51], v[178:181], v[186:189], v[48:51]
	v_mfma_f32_16x16x32_bf16 v[36:39], v[170:173], v[194:197], v[36:39]
	v_mfma_f32_16x16x32_bf16 v[32:35], v[178:181], v[194:197], v[32:35]
	v_mfma_f32_16x16x32_bf16 v[20:23], v[170:173], v[206:209], v[20:23]
	v_mfma_f32_16x16x32_bf16 v[16:19], v[178:181], v[206:209], v[16:19]
	v_mfma_f32_16x16x32_bf16 v[4:7], v[170:173], v[214:217], v[4:7]
	v_mfma_f32_16x16x32_bf16 v[0:3], v[178:181], v[214:217], v[0:3]
	s_barrier
	v_add_u32_e32 v161, s88, v156
	ds_read_b128 v[140:143], v161
	ds_read_b128 v[144:147], v161 offset:1024
	ds_read_b128 v[148:151], v161 offset:2048
	ds_read_b128 v[162:165], v161 offset:3072
	v_add_u32_e32 v161, s87, v156
	ds_read_b128 v[166:169], v161
	ds_read_b128 v[170:173], v161 offset:1024
	ds_read_b128 v[174:177], v161 offset:2048
	ds_read_b128 v[178:181], v161 offset:3072
	s_mov_b32 m0, s67
	ds_read_b128 v[182:185], v159 offset:32768
	ds_read_b128 v[186:189], v159 offset:33792
	ds_read_b128 v[190:193], v159 offset:34816
	ds_read_b128 v[194:197], v159 offset:35840
	ds_read_b128 v[198:201], v159 offset:36864
	ds_read_b128 v[206:209], v159 offset:37888
	ds_read_b128 v[210:213], v159 offset:38912
	ds_read_b128 v[214:217], v159 offset:39936
	s_nop 0
	v_lshl_add_u64 v[202:203], s[50:51], 0, v[134:135]
	global_load_lds_dwordx4 v[202:203], off
	v_lshl_add_u64 v[202:203], s[50:51], 0, v[130:131]
	s_mov_b32 m0, s68
	s_nop 0
	global_load_lds_dwordx4 v[202:203], off
	s_waitcnt vmcnt(8)
	s_waitcnt lgkmcnt(0)
	s_barrier
	s_waitcnt lgkmcnt(0)
	v_mfma_f32_16x16x32_bf16 v[124:127], v[140:143], v[182:185], v[124:127]
	v_mfma_f32_16x16x32_bf16 v[120:123], v[148:151], v[182:185], v[120:123]
	v_mfma_f32_16x16x32_bf16 v[108:111], v[140:143], v[190:193], v[108:111]
	v_mfma_f32_16x16x32_bf16 v[104:107], v[148:151], v[190:193], v[104:107]
	v_mfma_f32_16x16x32_bf16 v[92:95], v[140:143], v[198:201], v[92:95]
	v_mfma_f32_16x16x32_bf16 v[88:91], v[148:151], v[198:201], v[88:91]
	v_mfma_f32_16x16x32_bf16 v[76:79], v[140:143], v[210:213], v[76:79]
	v_mfma_f32_16x16x32_bf16 v[72:75], v[148:151], v[210:213], v[72:75]
	v_mfma_f32_16x16x32_bf16 v[124:127], v[144:147], v[186:189], v[124:127]
	v_mfma_f32_16x16x32_bf16 v[120:123], v[162:165], v[186:189], v[120:123]
	v_mfma_f32_16x16x32_bf16 v[108:111], v[144:147], v[194:197], v[108:111]
	v_mfma_f32_16x16x32_bf16 v[104:107], v[162:165], v[194:197], v[104:107]
	v_mfma_f32_16x16x32_bf16 v[92:95], v[144:147], v[206:209], v[92:95]
	v_mfma_f32_16x16x32_bf16 v[88:91], v[162:165], v[206:209], v[88:91]
	v_mfma_f32_16x16x32_bf16 v[76:79], v[144:147], v[214:217], v[76:79]
	v_mfma_f32_16x16x32_bf16 v[72:75], v[162:165], v[214:217], v[72:75]
	v_mfma_f32_16x16x32_bf16 v[116:119], v[166:169], v[182:185], v[116:119]
	v_mfma_f32_16x16x32_bf16 v[112:115], v[174:177], v[182:185], v[112:115]
	v_mfma_f32_16x16x32_bf16 v[100:103], v[166:169], v[190:193], v[100:103]
	v_mfma_f32_16x16x32_bf16 v[96:99], v[174:177], v[190:193], v[96:99]
	v_mfma_f32_16x16x32_bf16 v[84:87], v[166:169], v[198:201], v[84:87]
	v_mfma_f32_16x16x32_bf16 v[80:83], v[174:177], v[198:201], v[80:83]
	v_mfma_f32_16x16x32_bf16 v[68:71], v[166:169], v[210:213], v[68:71]
	v_mfma_f32_16x16x32_bf16 v[64:67], v[174:177], v[210:213], v[64:67]
	v_mfma_f32_16x16x32_bf16 v[116:119], v[170:173], v[186:189], v[116:119]
	v_mfma_f32_16x16x32_bf16 v[112:115], v[178:181], v[186:189], v[112:115]
	v_mfma_f32_16x16x32_bf16 v[100:103], v[170:173], v[194:197], v[100:103]
	v_mfma_f32_16x16x32_bf16 v[96:99], v[178:181], v[194:197], v[96:99]
	v_mfma_f32_16x16x32_bf16 v[84:87], v[170:173], v[206:209], v[84:87]
	v_mfma_f32_16x16x32_bf16 v[80:83], v[178:181], v[206:209], v[80:83]
	v_mfma_f32_16x16x32_bf16 v[68:71], v[170:173], v[214:217], v[68:71]
	v_mfma_f32_16x16x32_bf16 v[64:67], v[178:181], v[214:217], v[64:67]
	s_barrier
; #define PG8_STAGE(bufoff, gbase, voff) do { const char* _gb = (const char*)(gbase); asm volatile("" : "+s"(_gb));     \
;         _Pragma("unroll") for (int _i = 0; _i < 2; ++_i) \
;         __builtin_amdgcn_global_load_lds((const unsigned*)(_gb + (voff)[_i]), (LAS unsigned*)(lds + (bufoff) + ldsw + _i * 8192), 16, 0, 0); } while (0)
; #define PG8_LDA(dst, b, h) do { _Pragma("unroll") for (int m = 0; m < 4; ++m) _Pragma("unroll") for (int k = 0; k < 2; ++k) dst[m][k] = *(const LAS bf16x8*)(lds + PG8_SA(b, h) + aoff + m * 2048 + k * 1024); } while (0)
; #define PG8_MMA(ai, bj, At, Bt) do { __builtin_amdgcn_s_setprio(1); _Pragma("unroll") for (int m = 0; m < 4; ++m) _Pragma("unroll") for (int n = 0; n < 2; ++n) _Pragma("unroll") for (int k = 0; k < 2; ++k) \
;         acc[ai][bj][m][n] = __builtin_amdgcn_mfma_f32_16x16x32_bf16(Bt[n][k], At[m][k], acc[ai][bj][m][n], 0, 0, 0); __builtin_amdgcn_s_setprio(0); } while (0)
; #define PG8_WAIT_V(n) asm volatile("s_waitcnt vmcnt(" #n ")" ::: "memory")
; #define PG8_WAIT_L(n) asm volatile("s_waitcnt lgkmcnt(" #n ")" ::: "memory")
; #define PG8_BAR __builtin_amdgcn_s_barrier()
; #define PG8_SCHED __builtin_amdgcn_sched_barrier(0)
; template <class Epi>
; __device__ __forceinline__ void gemm_phase(LAS unsigned char* lds, const int wid, const Gemm g, const Epi& E) {
;     ...
;             PG8_LDA(At, 1, 1); PG8_STAGE(PG8_SB(1, 0), b3, voffB); PG8_STAGE(PG8_SB(1, 1), b3 + hstepB, voffB); PG8_STAGE(PG8_SA(1, 0), a3, voffA);
;             PG8_WAIT_V(8); PG8_WAIT_L(0); PG8_BAR; PG8_MMA(1, 0, At, B0); PG8_MMA(1, 1, At, B1); PG8_BAR; PG8_SCHED;
;         }
;         if (wr == 0) PG8_BAR;
	s_mov_b32 m0, s86
	ds_read_b128 v[182:185], v159 offset:49152
	ds_read_b128 v[186:189], v159 offset:50176
	ds_read_b128 v[190:193], v159 offset:51200
	ds_read_b128 v[194:197], v159 offset:52224
	ds_read_b128 v[198:201], v159 offset:53248
	ds_read_b128 v[206:209], v159 offset:54272
	ds_read_b128 v[210:213], v159 offset:55296
	ds_read_b128 v[214:217], v159 offset:56320
	s_nop 0
	v_lshl_add_u64 v[202:203], s[48:49], 0, v[132:133]
	global_load_lds_dwordx4 v[202:203], off
	v_lshl_add_u64 v[202:203], s[48:49], 0, v[128:129]
	s_mov_b32 m0, s85
	s_nop 0
	global_load_lds_dwordx4 v[202:203], off
	s_mov_b32 m0, s93
	v_lshl_add_u64 v[202:203], s[44:45], 0, v[132:133]
	global_load_lds_dwordx4 v[202:203], off
	v_lshl_add_u64 v[202:203], s[44:45], 0, v[128:129]
	s_mov_b32 m0, s92
	s_nop 0
	global_load_lds_dwordx4 v[202:203], off
	s_mov_b32 m0, s72
	v_lshl_add_u64 v[202:203], s[46:47], 0, v[134:135]
	global_load_lds_dwordx4 v[202:203], off
	v_lshl_add_u64 v[202:203], s[46:47], 0, v[130:131]
	s_mov_b32 m0, s73
	s_nop 0
	global_load_lds_dwordx4 v[202:203], off
	s_waitcnt vmcnt(8)
	s_waitcnt lgkmcnt(0)
	s_barrier
	s_waitcnt lgkmcnt(0)
	v_mfma_f32_16x16x32_bf16 v[60:63], v[140:143], v[182:185], v[60:63]
	v_mfma_f32_16x16x32_bf16 v[56:59], v[148:151], v[182:185], v[56:59]
	v_mfma_f32_16x16x32_bf16 v[44:47], v[140:143], v[190:193], v[44:47]
	v_mfma_f32_16x16x32_bf16 v[40:43], v[148:151], v[190:193], v[40:43]
	v_mfma_f32_16x16x32_bf16 v[28:31], v[140:143], v[198:201], v[28:31]
	v_mfma_f32_16x16x32_bf16 v[24:27], v[148:151], v[198:201], v[24:27]
	v_mfma_f32_16x16x32_bf16 v[12:15], v[140:143], v[210:213], v[12:15]
	v_mfma_f32_16x16x32_bf16 v[8:11], v[148:151], v[210:213], v[8:11]
	v_mfma_f32_16x16x32_bf16 v[60:63], v[144:147], v[186:189], v[60:63]
	v_mfma_f32_16x16x32_bf16 v[56:59], v[162:165], v[186:189], v[56:59]
	v_mfma_f32_16x16x32_bf16 v[44:47], v[144:147], v[194:197], v[44:47]
	v_mfma_f32_16x16x32_bf16 v[40:43], v[162:165], v[194:197], v[40:43]
	v_mfma_f32_16x16x32_bf16 v[28:31], v[144:147], v[206:209], v[28:31]
	v_mfma_f32_16x16x32_bf16 v[24:27], v[162:165], v[206:209], v[24:27]
	v_mfma_f32_16x16x32_bf16 v[12:15], v[144:147], v[214:217], v[12:15]
	v_mfma_f32_16x16x32_bf16 v[8:11], v[162:165], v[214:217], v[8:11]
	v_mfma_f32_16x16x32_bf16 v[52:55], v[166:169], v[182:185], v[52:55]
	v_mfma_f32_16x16x32_bf16 v[48:51], v[174:177], v[182:185], v[48:51]
	v_mfma_f32_16x16x32_bf16 v[36:39], v[166:169], v[190:193], v[36:39]
	v_mfma_f32_16x16x32_bf16 v[32:35], v[174:177], v[190:193], v[32:35]
	v_mfma_f32_16x16x32_bf16 v[20:23], v[166:169], v[198:201], v[20:23]
	v_mfma_f32_16x16x32_bf16 v[16:19], v[174:177], v[198:201], v[16:19]
	v_mfma_f32_16x16x32_bf16 v[4:7], v[166:169], v[210:213], v[4:7]
	v_mfma_f32_16x16x32_bf16 v[0:3], v[174:177], v[210:213], v[0:3]
	v_mfma_f32_16x16x32_bf16 v[52:55], v[170:173], v[186:189], v[52:55]
	v_mfma_f32_16x16x32_bf16 v[48:51], v[178:181], v[186:189], v[48:51]
	v_mfma_f32_16x16x32_bf16 v[36:39], v[170:173], v[194:197], v[36:39]
	v_mfma_f32_16x16x32_bf16 v[32:35], v[178:181], v[194:197], v[32:35]
	v_mfma_f32_16x16x32_bf16 v[20:23], v[170:173], v[206:209], v[20:23]
	v_mfma_f32_16x16x32_bf16 v[16:19], v[178:181], v[206:209], v[16:19]
	v_mfma_f32_16x16x32_bf16 v[4:7], v[170:173], v[214:217], v[4:7]
	v_mfma_f32_16x16x32_bf16 v[0:3], v[178:181], v[214:217], v[0:3]
	s_barrier
	s_movk_i32 s46, 0x100
	s_andn2_b64 vcc, exec, s[42:43]
	s_mov_b64 s[44:45], -1
	s_mov_b64 s[42:43], 0
	s_cbranch_vccz .LBB0_2972
	s_and_b64 vcc, exec, s[8:9]
	s_cbranch_vccz .LBB0_2975
	s_barrier

; #define PG8_STAGE(bufoff, gbase, voff) do { const char* _gb = (const char*)(gbase); asm volatile("" : "+s"(_gb));     \
;         _Pragma("unroll") for (int _i = 0; _i < 2; ++_i) \
;         __builtin_amdgcn_global_load_lds((const unsigned*)(_gb + (voff)[_i]), (LAS unsigned*)(lds + (bufoff) + ldsw + _i * 8192), 16, 0, 0); } while (0)
; #define PG8_LDA(dst, b, h) do { _Pragma("unroll") for (int m = 0; m < 4; ++m) _Pragma("unroll") for (int k = 0; k < 2; ++k) dst[m][k] = *(const LAS bf16x8*)(lds + PG8_SA(b, h) + aoff + m * 2048 + k * 1024); } while (0)
; #define PG8_LDB(dst, b, h) do { _Pragma("unroll") for (int n = 0; n < 2; ++n) _Pragma("unroll") for (int k = 0; k < 2; ++k) dst[n][k] = *(const LAS bf16x8*)(lds + PG8_SB(b, h) + boff + n * 2048 + k * 1024); } while (0)
; #define PG8_MMA(ai, bj, At, Bt) do { __builtin_amdgcn_s_setprio(1); _Pragma("unroll") for (int m = 0; m < 4; ++m) _Pragma("unroll") for (int n = 0; n < 2; ++n) _Pragma("unroll") for (int k = 0; k < 2; ++k) \
;         acc[ai][bj][m][n] = __builtin_amdgcn_mfma_f32_16x16x32_bf16(Bt[n][k], At[m][k], acc[ai][bj][m][n], 0, 0, 0); __builtin_amdgcn_s_setprio(0); } while (0)
; #define PG8_WAIT_V(n) asm volatile("s_waitcnt vmcnt(" #n ")" ::: "memory")
; #define PG8_WAIT_L(n) asm volatile("s_waitcnt lgkmcnt(" #n ")" ::: "memory")
; #define PG8_BAR __builtin_amdgcn_s_barrier()
; template <class Epi>
; __device__ __forceinline__ void gemm_phase(LAS unsigned char* lds, const int wid, const Gemm g, const Epi& E) {
;     ...
;             const bool last = (t == nt - 2);
;             const char* a1 = PG8_AP(cA, t + 1);
;             const char* a2 = last ? PG8_AP(nA, 0) : PG8_AP(cA, t + 2); const char* b2 = last ? PG8_BP(nB, 0) : PG8_BP(cB, t + 2);
;             const char* a3 = last ? PG8_AP(nA, 1) : PG8_AP(cA, t + 3); const char* b3 = last ? PG8_BP(nB, 1) : PG8_BP(cB, t + 3);
;             PG8_LDB(B0, 0, 0); PG8_LDB(B1, 0, 1); PG8_SCHED; PG8_LDA(At, 0, 0); PG8_STAGE(PG8_SA(1, 1), a1 + hstepA, voffA);
;             PG8_WAIT_V(8); PG8_WAIT_L(0); PG8_BAR; PG8_MMA(0, 0, At, B0); PG8_MMA(0, 1, At, B1); PG8_BAR; PG8_SCHED;
;             PG8_LDA(At, 0, 1); PG8_STAGE(PG8_SB(0, 0), b2, voffB); PG8_STAGE(PG8_SB(0, 1), b2 + hstepB, voffB); PG8_STAGE(PG8_SA(0, 0), a2, voffA);
;             PG8_WAIT_V(8); PG8_WAIT_L(0); PG8_BAR; PG8_MMA(1, 0, At, B0); PG8_MMA(1, 1, At, B1); PG8_BAR; PG8_SCHED;
.LBB0_3248:
	ds_read_b128 v[140:143], v149
	ds_read_b128 v[152:155], v149 offset:1024
	ds_read_b128 v[156:159], v149 offset:2048
	ds_read_b128 v[160:163], v149 offset:3072
	ds_read_b128 v[164:167], v150
	ds_read_b128 v[168:171], v150 offset:1024
	ds_read_b128 v[172:175], v150 offset:2048
	ds_read_b128 v[176:179], v150 offset:3072
	s_add_u32 s28, s26, 0xfff50080
	s_addc_u32 s29, s27, -1
	s_add_u32 s34, s63, 0xffffff80
	s_addc_u32 s35, s64, -1
	s_add_u32 s68, s26, 0xfff50100
	s_addc_u32 s69, s27, -1
	s_add_i32 s71, s53, s23
	s_add_i32 m0, s42, 0xc000
	s_add_i32 s70, s42, 0xe000
	s_add_i32 s72, s71, 0x2000
	s_cmp_eq_u32 s65, 40
	s_cselect_b32 s31, s3, s29
	s_cselect_b32 s30, s2, s28
	s_cselect_b32 s67, s25, s35
	s_cselect_b32 s66, s24, s34
	s_cselect_b32 s29, s60, s69
	s_cselect_b32 s28, s59, s68
	s_mov_b64 s[34:35], s[26:27]
	ds_read_b128 v[180:183], v151
	ds_read_b128 v[184:187], v151 offset:1024
	ds_read_b128 v[188:191], v151 offset:2048
	ds_read_b128 v[192:195], v151 offset:3072
	ds_read_b128 v[196:199], v151 offset:4096
	ds_read_b128 v[200:203], v151 offset:5120
	ds_read_b128 v[204:207], v151 offset:6144
	ds_read_b128 v[208:211], v151 offset:7168
	s_nop 0
	v_lshl_add_u64 v[144:145], s[34:35], 0, v[134:135]
	global_load_lds_dwordx4 v[144:145], off
	v_lshl_add_u64 v[144:145], s[34:35], 0, v[130:131]
	s_mov_b32 m0, s70
	s_nop 0
	global_load_lds_dwordx4 v[144:145], off
	s_waitcnt vmcnt(8)
	s_waitcnt lgkmcnt(0)
	s_barrier
	s_waitcnt lgkmcnt(0)
	v_mfma_f32_16x16x32_bf16 v[124:127], v[140:143], v[180:183], v[124:127]
	v_mfma_f32_16x16x32_bf16 v[120:123], v[156:159], v[180:183], v[120:123]
	v_mfma_f32_16x16x32_bf16 v[108:111], v[140:143], v[188:191], v[108:111]
	v_mfma_f32_16x16x32_bf16 v[104:107], v[156:159], v[188:191], v[104:107]
	v_mfma_f32_16x16x32_bf16 v[92:95], v[140:143], v[196:199], v[92:95]
	v_mfma_f32_16x16x32_bf16 v[88:91], v[156:159], v[196:199], v[88:91]
	v_mfma_f32_16x16x32_bf16 v[76:79], v[140:143], v[204:207], v[76:79]
	v_mfma_f32_16x16x32_bf16 v[72:75], v[156:159], v[204:207], v[72:75]
	v_mfma_f32_16x16x32_bf16 v[124:127], v[152:155], v[184:187], v[124:127]
	v_mfma_f32_16x16x32_bf16 v[120:123], v[160:163], v[184:187], v[120:123]
	v_mfma_f32_16x16x32_bf16 v[108:111], v[152:155], v[192:195], v[108:111]
	v_mfma_f32_16x16x32_bf16 v[104:107], v[160:163], v[192:195], v[104:107]
	v_mfma_f32_16x16x32_bf16 v[92:95], v[152:155], v[200:203], v[92:95]
	v_mfma_f32_16x16x32_bf16 v[88:91], v[160:163], v[200:203], v[88:91]
	v_mfma_f32_16x16x32_bf16 v[76:79], v[152:155], v[208:211], v[76:79]
	v_mfma_f32_16x16x32_bf16 v[72:75], v[160:163], v[208:211], v[72:75]
	v_mfma_f32_16x16x32_bf16 v[116:119], v[164:167], v[180:183], v[116:119]
	v_mfma_f32_16x16x32_bf16 v[112:115], v[172:175], v[180:183], v[112:115]
	v_mfma_f32_16x16x32_bf16 v[100:103], v[164:167], v[188:191], v[100:103]
	v_mfma_f32_16x16x32_bf16 v[96:99], v[172:175], v[188:191], v[96:99]
	v_mfma_f32_16x16x32_bf16 v[84:87], v[164:167], v[196:199], v[84:87]
	v_mfma_f32_16x16x32_bf16 v[80:83], v[172:175], v[196:199], v[80:83]
	v_mfma_f32_16x16x32_bf16 v[68:71], v[164:167], v[204:207], v[68:71]
	v_mfma_f32_16x16x32_bf16 v[64:67], v[172:175], v[204:207], v[64:67]
	v_mfma_f32_16x16x32_bf16 v[116:119], v[168:171], v[184:187], v[116:119]
	v_mfma_f32_16x16x32_bf16 v[112:115], v[176:179], v[184:187], v[112:115]
	v_mfma_f32_16x16x32_bf16 v[100:103], v[168:171], v[192:195], v[100:103]
	v_mfma_f32_16x16x32_bf16 v[96:99], v[176:179], v[192:195], v[96:99]
	v_mfma_f32_16x16x32_bf16 v[84:87], v[168:171], v[200:203], v[84:87]
	v_mfma_f32_16x16x32_bf16 v[80:83], v[176:179], v[200:203], v[80:83]
	v_mfma_f32_16x16x32_bf16 v[68:71], v[168:171], v[208:211], v[68:71]
	v_mfma_f32_16x16x32_bf16 v[64:67], v[176:179], v[208:211], v[64:67]
	s_barrier
	s_mov_b64 s[34:35], s[66:67]
	s_mov_b32 m0, s71
	ds_read_b128 v[180:183], v151 offset:16384
	ds_read_b128 v[184:187], v151 offset:17408
	ds_read_b128 v[188:191], v151 offset:18432
	ds_read_b128 v[192:195], v151 offset:19456
	ds_read_b128 v[196:199], v151 offset:20480
	ds_read_b128 v[200:203], v151 offset:21504
	ds_read_b128 v[204:207], v151 offset:22528
	ds_read_b128 v[208:211], v151 offset:23552
	s_nop 0
	v_lshl_add_u64 v[144:145], s[34:35], 0, v[132:133]
	global_load_lds_dwordx4 v[144:145], off
	v_lshl_add_u64 v[144:145], s[34:35], 0, v[128:129]
	s_cselect_b32 s35, s62, s64
	s_cselect_b32 s34, s61, s63
	s_add_u32 s66, s66, 0xb0000
	s_mov_b32 m0, s72
	s_addc_u32 s67, s67, 0
	s_add_i32 s68, s54, s23
	global_load_lds_dwordx4 v[144:145], off
	s_mov_b32 m0, s68
	v_lshl_add_u64 v[144:145], s[66:67], 0, v[132:133]
	global_load_lds_dwordx4 v[144:145], off
	v_lshl_add_u64 v[144:145], s[66:67], 0, v[128:129]
	s_add_i32 m0, s68, 0x2000
	s_mov_b64 s[66:67], s[30:31]
	global_load_lds_dwordx4 v[144:145], off
	s_mov_b32 m0, s42
	v_lshl_add_u64 v[144:145], s[66:67], 0, v[134:135]
	global_load_lds_dwordx4 v[144:145], off
	v_lshl_add_u64 v[144:145], s[66:67], 0, v[130:131]
	s_mov_b32 m0, s43
	s_nop 0
	global_load_lds_dwordx4 v[144:145], off
	s_waitcnt vmcnt(8)
	s_waitcnt lgkmcnt(0)
	s_barrier
; #define PG8_STAGE(bufoff, gbase, voff) do { const char* _gb = (const char*)(gbase); asm volatile("" : "+s"(_gb));     \
;         _Pragma("unroll") for (int _i = 0; _i < 2; ++_i) \
;         __builtin_amdgcn_global_load_lds((const unsigned*)(_gb + (voff)[_i]), (LAS unsigned*)(lds + (bufoff) + ldsw + _i * 8192), 16, 0, 0); } while (0)
; #define PG8_LDA(dst, b, h) do { _Pragma("unroll") for (int m = 0; m < 4; ++m) _Pragma("unroll") for (int k = 0; k < 2; ++k) dst[m][k] = *(const LAS bf16x8*)(lds + PG8_SA(b, h) + aoff + m * 2048 + k * 1024); } while (0)
; #define PG8_LDB(dst, b, h) do { _Pragma("unroll") for (int n = 0; n < 2; ++n) _Pragma("unroll") for (int k = 0; k < 2; ++k) dst[n][k] = *(const LAS bf16x8*)(lds + PG8_SB(b, h) + boff + n * 2048 + k * 1024); } while (0)
; #define PG8_MMA(ai, bj, At, Bt) do { __builtin_amdgcn_s_setprio(1); _Pragma("unroll") for (int m = 0; m < 4; ++m) _Pragma("unroll") for (int n = 0; n < 2; ++n) _Pragma("unroll") for (int k = 0; k < 2; ++k) \
;         acc[ai][bj][m][n] = __builtin_amdgcn_mfma_f32_16x16x32_bf16(Bt[n][k], At[m][k], acc[ai][bj][m][n], 0, 0, 0); __builtin_amdgcn_s_setprio(0); } while (0)
; #define PG8_WAIT_V(n) asm volatile("s_waitcnt vmcnt(" #n ")" ::: "memory")
; #define PG8_WAIT_L(n) asm volatile("s_waitcnt lgkmcnt(" #n ")" ::: "memory")
; #define PG8_BAR __builtin_amdgcn_s_barrier()
; #define PG8_SCHED __builtin_amdgcn_sched_barrier(0)
; template <class Epi>
; __device__ __forceinline__ void gemm_phase(LAS unsigned char* lds, const int wid, const Gemm g, const Epi& E) {
;     ...
;             PG8_WAIT_V(8); PG8_WAIT_L(0); PG8_BAR; PG8_MMA(1, 0, At, B0); PG8_MMA(1, 1, At, B1); PG8_BAR; PG8_SCHED;
;             PG8_LDB(B0, 1, 0); PG8_LDB(B1, 1, 1); PG8_SCHED; PG8_LDA(At, 1, 0); PG8_STAGE(PG8_SA(0, 1), a2 + hstepA, voffA);
;             PG8_WAIT_V(8); PG8_WAIT_L(0); PG8_BAR; PG8_MMA(0, 0, At, B0); PG8_MMA(0, 1, At, B1); PG8_BAR; PG8_SCHED;
	s_waitcnt lgkmcnt(0)
	v_mfma_f32_16x16x32_bf16 v[60:63], v[140:143], v[180:183], v[60:63]
	v_mfma_f32_16x16x32_bf16 v[56:59], v[156:159], v[180:183], v[56:59]
	v_mfma_f32_16x16x32_bf16 v[44:47], v[140:143], v[188:191], v[44:47]
	v_mfma_f32_16x16x32_bf16 v[40:43], v[156:159], v[188:191], v[40:43]
	v_mfma_f32_16x16x32_bf16 v[28:31], v[140:143], v[196:199], v[28:31]
	v_mfma_f32_16x16x32_bf16 v[24:27], v[156:159], v[196:199], v[24:27]
	v_mfma_f32_16x16x32_bf16 v[12:15], v[140:143], v[204:207], v[12:15]
	v_mfma_f32_16x16x32_bf16 v[8:11], v[156:159], v[204:207], v[8:11]
	v_mfma_f32_16x16x32_bf16 v[60:63], v[152:155], v[184:187], v[60:63]
	v_mfma_f32_16x16x32_bf16 v[56:59], v[160:163], v[184:187], v[56:59]
	v_mfma_f32_16x16x32_bf16 v[44:47], v[152:155], v[192:195], v[44:47]
	v_mfma_f32_16x16x32_bf16 v[40:43], v[160:163], v[192:195], v[40:43]
	v_mfma_f32_16x16x32_bf16 v[28:31], v[152:155], v[200:203], v[28:31]
	v_mfma_f32_16x16x32_bf16 v[24:27], v[160:163], v[200:203], v[24:27]
	v_mfma_f32_16x16x32_bf16 v[12:15], v[152:155], v[208:211], v[12:15]
	v_mfma_f32_16x16x32_bf16 v[8:11], v[160:163], v[208:211], v[8:11]
	v_mfma_f32_16x16x32_bf16 v[52:55], v[164:167], v[180:183], v[52:55]
	v_mfma_f32_16x16x32_bf16 v[48:51], v[172:175], v[180:183], v[48:51]
	v_mfma_f32_16x16x32_bf16 v[36:39], v[164:167], v[188:191], v[36:39]
	v_mfma_f32_16x16x32_bf16 v[32:35], v[172:175], v[188:191], v[32:35]
	v_mfma_f32_16x16x32_bf16 v[20:23], v[164:167], v[196:199], v[20:23]
	v_mfma_f32_16x16x32_bf16 v[16:19], v[172:175], v[196:199], v[16:19]
	v_mfma_f32_16x16x32_bf16 v[4:7], v[164:167], v[204:207], v[4:7]
	v_mfma_f32_16x16x32_bf16 v[0:3], v[172:175], v[204:207], v[0:3]
	v_mfma_f32_16x16x32_bf16 v[52:55], v[168:171], v[184:187], v[52:55]
	v_mfma_f32_16x16x32_bf16 v[48:51], v[176:179], v[184:187], v[48:51]
	v_mfma_f32_16x16x32_bf16 v[36:39], v[168:171], v[192:195], v[36:39]
	v_mfma_f32_16x16x32_bf16 v[32:35], v[176:179], v[192:195], v[32:35]
	v_mfma_f32_16x16x32_bf16 v[20:23], v[168:171], v[200:203], v[20:23]
	v_mfma_f32_16x16x32_bf16 v[16:19], v[176:179], v[200:203], v[16:19]
	v_mfma_f32_16x16x32_bf16 v[4:7], v[168:171], v[208:211], v[4:7]
	v_mfma_f32_16x16x32_bf16 v[0:3], v[176:179], v[208:211], v[0:3]
	s_barrier
	s_add_i32 s66, 0, 0x18000
	v_add_u32_e32 v144, s66, v148
	s_add_i32 s67, 0, 0x1c000
	ds_read_b128 v[140:143], v144
	ds_read_b128 v[152:155], v144 offset:1024
	ds_read_b128 v[156:159], v144 offset:2048
	ds_read_b128 v[160:163], v144 offset:3072
	v_add_u32_e32 v144, s67, v148
	ds_read_b128 v[164:167], v144
	ds_read_b128 v[168:171], v144 offset:1024
	ds_read_b128 v[172:175], v144 offset:2048
	ds_read_b128 v[176:179], v144 offset:3072
	s_add_u32 s30, s30, 0xb0000
	s_addc_u32 s31, s31, 0
	s_mov_b32 m0, s44
	ds_read_b128 v[180:183], v151 offset:32768
	ds_read_b128 v[184:187], v151 offset:33792
	ds_read_b128 v[188:191], v151 offset:34816
	ds_read_b128 v[192:195], v151 offset:35840
	ds_read_b128 v[196:199], v151 offset:36864
	ds_read_b128 v[200:203], v151 offset:37888
	ds_read_b128 v[204:207], v151 offset:38912
	ds_read_b128 v[208:211], v151 offset:39936
	s_nop 0
	v_lshl_add_u64 v[144:145], s[30:31], 0, v[134:135]
	global_load_lds_dwordx4 v[144:145], off
	v_lshl_add_u64 v[144:145], s[30:31], 0, v[130:131]
	s_mov_b32 m0, s45
	s_nop 0
	global_load_lds_dwordx4 v[144:145], off
	s_waitcnt vmcnt(8)
	s_waitcnt lgkmcnt(0)
	s_barrier
	s_waitcnt lgkmcnt(0)
	v_mfma_f32_16x16x32_bf16 v[124:127], v[140:143], v[180:183], v[124:127]
	v_mfma_f32_16x16x32_bf16 v[120:123], v[156:159], v[180:183], v[120:123]
	v_mfma_f32_16x16x32_bf16 v[108:111], v[140:143], v[188:191], v[108:111]
	v_mfma_f32_16x16x32_bf16 v[104:107], v[156:159], v[188:191], v[104:107]
	v_mfma_f32_16x16x32_bf16 v[92:95], v[140:143], v[196:199], v[92:95]
	v_mfma_f32_16x16x32_bf16 v[88:91], v[156:159], v[196:199], v[88:91]
	v_mfma_f32_16x16x32_bf16 v[76:79], v[140:143], v[204:207], v[76:79]
	v_mfma_f32_16x16x32_bf16 v[72:75], v[156:159], v[204:207], v[72:75]
	v_mfma_f32_16x16x32_bf16 v[124:127], v[152:155], v[184:187], v[124:127]
	v_mfma_f32_16x16x32_bf16 v[120:123], v[160:163], v[184:187], v[120:123]
	v_mfma_f32_16x16x32_bf16 v[108:111], v[152:155], v[192:195], v[108:111]
	v_mfma_f32_16x16x32_bf16 v[104:107], v[160:163], v[192:195], v[104:107]
	v_mfma_f32_16x16x32_bf16 v[92:95], v[152:155], v[200:203], v[92:95]
	v_mfma_f32_16x16x32_bf16 v[88:91], v[160:163], v[200:203], v[88:91]
	v_mfma_f32_16x16x32_bf16 v[76:79], v[152:155], v[208:211], v[76:79]
	v_mfma_f32_16x16x32_bf16 v[72:75], v[160:163], v[208:211], v[72:75]
	v_mfma_f32_16x16x32_bf16 v[116:119], v[164:167], v[180:183], v[116:119]
	v_mfma_f32_16x16x32_bf16 v[112:115], v[172:175], v[180:183], v[112:115]
	v_mfma_f32_16x16x32_bf16 v[100:103], v[164:167], v[188:191], v[100:103]
	v_mfma_f32_16x16x32_bf16 v[96:99], v[172:175], v[188:191], v[96:99]
	v_mfma_f32_16x16x32_bf16 v[84:87], v[164:167], v[196:199], v[84:87]
	v_mfma_f32_16x16x32_bf16 v[80:83], v[172:175], v[196:199], v[80:83]
	v_mfma_f32_16x16x32_bf16 v[68:71], v[164:167], v[204:207], v[68:71]
	v_mfma_f32_16x16x32_bf16 v[64:67], v[172:175], v[204:207], v[64:67]
	v_mfma_f32_16x16x32_bf16 v[116:119], v[168:171], v[184:187], v[116:119]
	v_mfma_f32_16x16x32_bf16 v[112:115], v[176:179], v[184:187], v[112:115]
	v_mfma_f32_16x16x32_bf16 v[100:103], v[168:171], v[192:195], v[100:103]
	v_mfma_f32_16x16x32_bf16 v[96:99], v[176:179], v[192:195], v[96:99]
	v_mfma_f32_16x16x32_bf16 v[84:87], v[168:171], v[200:203], v[84:87]
	v_mfma_f32_16x16x32_bf16 v[80:83], v[176:179], v[200:203], v[80:83]
	v_mfma_f32_16x16x32_bf16 v[68:71], v[168:171], v[208:211], v[68:71]
	v_mfma_f32_16x16x32_bf16 v[64:67], v[176:179], v[208:211], v[64:67]
	s_barrier
; #define PG8_STAGE(bufoff, gbase, voff) do { const char* _gb = (const char*)(gbase); asm volatile("" : "+s"(_gb));     \
;         _Pragma("unroll") for (int _i = 0; _i < 2; ++_i) \
;         __builtin_amdgcn_global_load_lds((const unsigned*)(_gb + (voff)[_i]), (LAS unsigned*)(lds + (bufoff) + ldsw + _i * 8192), 16, 0, 0); } while (0)
; #define PG8_LDA(dst, b, h) do { _Pragma("unroll") for (int m = 0; m < 4; ++m) _Pragma("unroll") for (int k = 0; k < 2; ++k) dst[m][k] = *(const LAS bf16x8*)(lds + PG8_SA(b, h) + aoff + m * 2048 + k * 1024); } while (0)
; #define PG8_MMA(ai, bj, At, Bt) do { __builtin_amdgcn_s_setprio(1); _Pragma("unroll") for (int m = 0; m < 4; ++m) _Pragma("unroll") for (int n = 0; n < 2; ++n) _Pragma("unroll") for (int k = 0; k < 2; ++k) \
;         acc[ai][bj][m][n] = __builtin_amdgcn_mfma_f32_16x16x32_bf16(Bt[n][k], At[m][k], acc[ai][bj][m][n], 0, 0, 0); __builtin_amdgcn_s_setprio(0); } while (0)
; #define PG8_WAIT_V(n) asm volatile("s_waitcnt vmcnt(" #n ")" ::: "memory")
; #define PG8_WAIT_L(n) asm volatile("s_waitcnt lgkmcnt(" #n ")" ::: "memory")
; #define PG8_BAR __builtin_amdgcn_s_barrier()
; #define PG8_SCHED __builtin_amdgcn_sched_barrier(0)
; template <class Epi>
; __device__ __forceinline__ void gemm_phase(LAS unsigned char* lds, const int wid, const Gemm g, const Epi& E) {
;     ...
;             PG8_LDA(At, 1, 1); PG8_STAGE(PG8_SB(1, 0), b3, voffB); PG8_STAGE(PG8_SB(1, 1), b3 + hstepB, voffB); PG8_STAGE(PG8_SA(1, 0), a3, voffA);
;             PG8_WAIT_V(8); PG8_WAIT_L(0); PG8_BAR; PG8_MMA(1, 0, At, B0); PG8_MMA(1, 1, At, B1); PG8_BAR; PG8_SCHED;
;         }
;         if (wr == 0) PG8_BAR;
	s_mov_b64 s[30:31], s[34:35]
	s_add_i32 s66, s66, s23
	ds_read_b128 v[180:183], v151 offset:49152
	ds_read_b128 v[184:187], v151 offset:50176
	ds_read_b128 v[188:191], v151 offset:51200
	ds_read_b128 v[192:195], v151 offset:52224
	ds_read_b128 v[196:199], v151 offset:53248
	ds_read_b128 v[200:203], v151 offset:54272
	ds_read_b128 v[204:207], v151 offset:55296
	ds_read_b128 v[208:211], v151 offset:56320
	s_mov_b32 m0, s66
	v_lshl_add_u64 v[144:145], s[30:31], 0, v[132:133]
	global_load_lds_dwordx4 v[144:145], off
	s_add_i32 m0, s66, 0x2000
	v_lshl_add_u64 v[144:145], s[30:31], 0, v[128:129]
	s_add_u32 s30, s34, 0xb0000
	s_addc_u32 s31, s35, 0
	s_add_i32 s34, s67, s23
	global_load_lds_dwordx4 v[144:145], off
	s_mov_b32 m0, s34
	v_lshl_add_u64 v[144:145], s[30:31], 0, v[132:133]
	global_load_lds_dwordx4 v[144:145], off
	v_lshl_add_u64 v[144:145], s[30:31], 0, v[128:129]
	s_add_i32 m0, s34, 0x2000
	s_nop 0
	global_load_lds_dwordx4 v[144:145], off
	s_mov_b32 m0, s49
	v_lshl_add_u64 v[144:145], s[28:29], 0, v[134:135]
	global_load_lds_dwordx4 v[144:145], off
	v_lshl_add_u64 v[144:145], s[28:29], 0, v[130:131]
	s_mov_b32 m0, s50
	s_nop 0
	global_load_lds_dwordx4 v[144:145], off
	s_waitcnt vmcnt(8)
	s_waitcnt lgkmcnt(0)
	s_barrier
	s_waitcnt lgkmcnt(0)
	v_mfma_f32_16x16x32_bf16 v[60:63], v[140:143], v[180:183], v[60:63]
	v_mfma_f32_16x16x32_bf16 v[56:59], v[156:159], v[180:183], v[56:59]
	v_mfma_f32_16x16x32_bf16 v[44:47], v[140:143], v[188:191], v[44:47]
	v_mfma_f32_16x16x32_bf16 v[40:43], v[156:159], v[188:191], v[40:43]
	v_mfma_f32_16x16x32_bf16 v[28:31], v[140:143], v[196:199], v[28:31]
	v_mfma_f32_16x16x32_bf16 v[24:27], v[156:159], v[196:199], v[24:27]
	v_mfma_f32_16x16x32_bf16 v[12:15], v[140:143], v[204:207], v[12:15]
	v_mfma_f32_16x16x32_bf16 v[8:11], v[156:159], v[204:207], v[8:11]
	v_mfma_f32_16x16x32_bf16 v[60:63], v[152:155], v[184:187], v[60:63]
	v_mfma_f32_16x16x32_bf16 v[56:59], v[160:163], v[184:187], v[56:59]
	v_mfma_f32_16x16x32_bf16 v[44:47], v[152:155], v[192:195], v[44:47]
	v_mfma_f32_16x16x32_bf16 v[40:43], v[160:163], v[192:195], v[40:43]
	v_mfma_f32_16x16x32_bf16 v[28:31], v[152:155], v[200:203], v[28:31]
	v_mfma_f32_16x16x32_bf16 v[24:27], v[160:163], v[200:203], v[24:27]
	v_mfma_f32_16x16x32_bf16 v[12:15], v[152:155], v[208:211], v[12:15]
	v_mfma_f32_16x16x32_bf16 v[8:11], v[160:163], v[208:211], v[8:11]
	v_mfma_f32_16x16x32_bf16 v[52:55], v[164:167], v[180:183], v[52:55]
	v_mfma_f32_16x16x32_bf16 v[48:51], v[172:175], v[180:183], v[48:51]
	v_mfma_f32_16x16x32_bf16 v[36:39], v[164:167], v[188:191], v[36:39]
	v_mfma_f32_16x16x32_bf16 v[32:35], v[172:175], v[188:191], v[32:35]
	v_mfma_f32_16x16x32_bf16 v[20:23], v[164:167], v[196:199], v[20:23]
	v_mfma_f32_16x16x32_bf16 v[16:19], v[172:175], v[196:199], v[16:19]
	v_mfma_f32_16x16x32_bf16 v[4:7], v[164:167], v[204:207], v[4:7]
	v_mfma_f32_16x16x32_bf16 v[0:3], v[172:175], v[204:207], v[0:3]
	v_mfma_f32_16x16x32_bf16 v[52:55], v[168:171], v[184:187], v[52:55]
	v_mfma_f32_16x16x32_bf16 v[48:51], v[176:179], v[184:187], v[48:51]
	v_mfma_f32_16x16x32_bf16 v[36:39], v[168:171], v[192:195], v[36:39]
	v_mfma_f32_16x16x32_bf16 v[32:35], v[176:179], v[192:195], v[32:35]
	v_mfma_f32_16x16x32_bf16 v[20:23], v[168:171], v[200:203], v[20:23]
	v_mfma_f32_16x16x32_bf16 v[16:19], v[176:179], v[200:203], v[16:19]
	v_mfma_f32_16x16x32_bf16 v[4:7], v[168:171], v[208:211], v[4:7]
	v_mfma_f32_16x16x32_bf16 v[0:3], v[176:179], v[208:211], v[0:3]
	s_barrier
	s_add_i32 s65, s65, 2
	s_add_u32 s63, s63, 0x100
	s_addc_u32 s64, s64, 0
	s_add_u32 s26, s26, 0x100
	s_addc_u32 s27, s27, 0
	s_cmp_gt_u32 s65, 41
	s_cbranch_scc0 .LBB0_3248
	s_and_b64 vcc, exec, s[10:11]
	s_cbranch_vccz .LBB0_3251
	s_barrier
